# MFMA snake order: within each 2x2 operand group swap the last two MFMAs so only one of A/B changes between consecutive MFMAs (all K-loops)
# speedup vs baseline: 1.0140x; 1.0140x over previous
; #define PG8_STAGE(bufoff, gbase, voff) do { _Pragma("unroll") for (int _i = 0; _i < 2; ++_i) \
;         __builtin_amdgcn_global_load_lds((const unsigned*)((const char*)(gbase) + (voff)[_i]), (PG8_LAS unsigned*)(lds + (bufoff) + ldsw + _i * 8192), 16, 0, 0); } while (0)
; #define PG8_LDA(dst, b, h) do { _Pragma("unroll") for (int m = 0; m < 4; ++m) _Pragma("unroll") for (int k = 0; k < 2; ++k) dst[m][k] = *(const PG8_LAS bf16x8*)(lds + PG8_SA(b, h) + aoff + m * 2048 + k * 1024); } while (0)
; #define PG8_WAIT_V(n) asm volatile("s_waitcnt vmcnt(" #n ")" ::: "memory")
; #define PG8_WAIT_L(n) asm volatile("s_waitcnt lgkmcnt(" #n ")" ::: "memory")
; #define PG8_BAR __builtin_amdgcn_s_barrier()
; template <class Epi, class Sched, bool ALIGN_EPI = false, bool SP2 = false>
; __device__ __forceinline__ void gemm_phase(PG8_LAS unsigned char* lds, const Gemm g, const Sched& S, const Epi& E, int wave_in) {
;     ...
;         for (int t = 0; t < nt; t += 2) {
;             const bool last = (t == nt - 2);
;             const char* a1 = cA + (size_t)(t + 1) * kstep;
;             const char* a2 = last ? nA : cA + (size_t)(t + 2) * kstep; const char* b2 = last ? nB : cB + (size_t)(t + 2) * kstep;
;             const char* a3 = a2 + kstep; const char* b3 = b2 + kstep;
;             if (last && has_next) S.a_ready(nxt);
;             if constexpr (SP2) {
;             PG8_LDB(B0, 0, 0); PG8_LDB(B1, 0, 1); PG8_SCHED; PG8_LDA(At, 0, 0); PG8_STAGE(PG8_SA(1, 1), a1 + hstep, voffA);
;             PG8_WAIT_V(8); PG8_WAIT_L(0); PG8_BAR; PG8_MMA(0, 0, At, B0); PG8_MMA(0, 1, At, B1); PG8_BAR; PG8_SCHED;
;             PG8_LDA(At, 0, 1); PG8_STAGE(PG8_SB(0, 0), b2, voffB); PG8_STAGE(PG8_SB(0, 1), b2 + hstep, voffB); PG8_STAGE(PG8_SA(0, 0), a2, voffA);
;             PG8_WAIT_V(8); PG8_WAIT_L(0); PG8_BAR; PG8_MMA(1, 0, At, B0); PG8_MMA(1, 1, At, B1); PG8_BAR; PG8_SCHED;
;             PG8_LDB(B0, 1, 0); PG8_LDB(B1, 1, 1); PG8_SCHED; PG8_LDA(At, 1, 0); PG8_STAGE(PG8_SA(0, 1), a2 + hstep, voffA);
;             PG8_WAIT_V(8); PG8_WAIT_L(0); PG8_BAR; PG8_MMA(0, 0, At, B0); PG8_MMA(0, 1, At, B1); PG8_BAR; PG8_SCHED;
;             PG8_LDA(At, 1, 1); PG8_STAGE(PG8_SB(1, 0), b3, voffB); PG8_STAGE(PG8_SB(1, 1), b3 + hstep, voffB); PG8_STAGE(PG8_SA(1, 0), a3, voffA);
;             PG8_WAIT_V(8); PG8_WAIT_L(0); PG8_BAR; PG8_MMA(1, 0, At, B0); PG8_MMA(1, 1, At, B1); PG8_BAR; PG8_SCHED;
.LBB0_253:
	s_ashr_i32 s23, s22, 31
	s_lshl_b64 s[24:25], s[22:23], 19
	s_add_u32 s24, s62, s24
	s_addc_u32 s25, s63, s25
	s_and_b64 s[26:27], s[18:19], exec
	s_cselect_b32 s23, s25, s37
	s_cselect_b32 s29, s24, s36
	s_ashr_i32 s21, s20, 31
	s_lshl_b64 s[26:27], s[20:21], 19
	s_add_u32 s26, s64, s26
	s_addc_u32 s27, s65, s27
	s_and_b64 s[38:39], s[18:19], exec
	s_cselect_b32 s21, s27, s35
	s_cselect_b32 s31, s26, s34
	s_add_u32 s76, s34, 0x100
	s_addc_u32 s77, s35, 0
	s_add_u32 s34, s36, 0x40080
	s_addc_u32 s35, s37, 0
	s_mov_b32 s78, -2
	v_add_u32_e32 v174, s43, v160
	v_add_u32_e32 v190, s44, v160
	ds_read_b128 v[162:165], v174
	ds_read_b128 v[166:169], v174 offset:1024
	ds_read_b128 v[170:173], v174 offset:2048
	ds_read_b128 v[174:177], v174 offset:3072
	ds_read_b128 v[178:181], v190
	ds_read_b128 v[182:185], v190 offset:1024
	ds_read_b128 v[186:189], v190 offset:2048
	ds_read_b128 v[190:193], v190 offset:3072
	s_add_u32 s36, s34, 0xfffc0080
	s_addc_u32 s37, s35, -1
	s_cmp_eq_u32 s78, 12
	s_cselect_b32 s39, s23, s37
	s_cselect_b32 s38, s29, s36
	s_cselect_b32 s37, s21, s77
	s_cselect_b32 s36, s31, s76
	v_lshl_add_u64 v[226:227], s[34:35], 0, v[156:157]
	s_add_i32 m0, s67, 0xc000
	ds_read_b128 v[194:197], v161
	ds_read_b128 v[198:201], v161 offset:1024
	ds_read_b128 v[202:205], v161 offset:2048
	ds_read_b128 v[206:209], v161 offset:3072
	ds_read_b128 v[210:213], v161 offset:4096
	ds_read_b128 v[214:217], v161 offset:5120
	ds_read_b128 v[218:221], v161 offset:6144
	ds_read_b128 v[222:225], v161 offset:7168
	global_load_lds_dwordx4 v[226:227], off
	v_lshl_add_u64 v[226:227], s[34:35], 0, v[154:155]
	s_add_i32 m0, s67, 0xe000
	s_nop 0
	global_load_lds_dwordx4 v[226:227], off
	s_waitcnt vmcnt(8)
	s_waitcnt lgkmcnt(0)
	s_barrier
	s_setprio 1
	s_waitcnt lgkmcnt(0)
	v_mfma_f32_16x16x32_bf16 v[124:127], v[162:165], v[194:197], 0
	v_mfma_f32_16x16x32_bf16 v[120:123], v[170:173], v[194:197], 0
	v_mfma_f32_16x16x32_bf16 v[108:111], v[170:173], v[202:205], 0
	v_mfma_f32_16x16x32_bf16 v[116:119], v[162:165], v[202:205], 0
	v_mfma_f32_16x16x32_bf16 v[100:103], v[162:165], v[210:213], 0
	v_mfma_f32_16x16x32_bf16 v[92:95], v[170:173], v[210:213], 0
	v_mfma_f32_16x16x32_bf16 v[76:79], v[170:173], v[218:221], 0
	v_mfma_f32_16x16x32_bf16 v[84:87], v[162:165], v[218:221], 0
	v_mfma_f32_16x16x32_bf16 v[124:127], v[166:169], v[198:201], v[124:127]
	v_mfma_f32_16x16x32_bf16 v[120:123], v[174:177], v[198:201], v[120:123]
	v_mfma_f32_16x16x32_bf16 v[108:111], v[174:177], v[206:209], v[108:111]
	v_mfma_f32_16x16x32_bf16 v[116:119], v[166:169], v[206:209], v[116:119]
	v_mfma_f32_16x16x32_bf16 v[100:103], v[166:169], v[214:217], v[100:103]
	v_mfma_f32_16x16x32_bf16 v[92:95], v[174:177], v[214:217], v[92:95]
	v_mfma_f32_16x16x32_bf16 v[76:79], v[174:177], v[222:225], v[76:79]
	v_mfma_f32_16x16x32_bf16 v[84:87], v[166:169], v[222:225], v[84:87]
	s_setprio 0
	s_setprio 1
	v_mfma_f32_16x16x32_bf16 v[112:115], v[178:181], v[194:197], 0
	v_mfma_f32_16x16x32_bf16 v[104:107], v[186:189], v[194:197], 0
	v_mfma_f32_16x16x32_bf16 v[88:91], v[186:189], v[202:205], 0
	v_mfma_f32_16x16x32_bf16 v[96:99], v[178:181], v[202:205], 0
	v_mfma_f32_16x16x32_bf16 v[80:83], v[178:181], v[210:213], 0
	v_mfma_f32_16x16x32_bf16 v[72:75], v[186:189], v[210:213], 0
	v_mfma_f32_16x16x32_bf16 v[64:67], v[186:189], v[218:221], 0
	v_mfma_f32_16x16x32_bf16 v[68:71], v[178:181], v[218:221], 0
	v_mfma_f32_16x16x32_bf16 v[112:115], v[182:185], v[198:201], v[112:115]
	v_mfma_f32_16x16x32_bf16 v[104:107], v[190:193], v[198:201], v[104:107]
	v_mfma_f32_16x16x32_bf16 v[88:91], v[190:193], v[206:209], v[88:91]
	v_mfma_f32_16x16x32_bf16 v[96:99], v[182:185], v[206:209], v[96:99]
	v_mfma_f32_16x16x32_bf16 v[80:83], v[182:185], v[214:217], v[80:83]
	v_mfma_f32_16x16x32_bf16 v[72:75], v[190:193], v[214:217], v[72:75]
	v_mfma_f32_16x16x32_bf16 v[64:67], v[190:193], v[222:225], v[64:67]
	v_mfma_f32_16x16x32_bf16 v[68:71], v[182:185], v[222:225], v[68:71]
	s_setprio 0
	s_barrier
	s_add_i32 s79, s43, s66
	v_lshl_add_u64 v[226:227], s[36:37], 0, v[132:133]
	s_mov_b32 m0, s79
	ds_read_b128 v[194:197], v161 offset:16384
	ds_read_b128 v[198:201], v161 offset:17408
	ds_read_b128 v[202:205], v161 offset:18432
	ds_read_b128 v[206:209], v161 offset:19456
	ds_read_b128 v[210:213], v161 offset:20480
	ds_read_b128 v[214:217], v161 offset:21504
	ds_read_b128 v[218:221], v161 offset:22528
	ds_read_b128 v[222:225], v161 offset:23552
	global_load_lds_dwordx4 v[226:227], off
	s_add_i32 m0, s79, 0x2000
	s_add_u32 s80, s36, 0x40000
	v_lshl_add_u64 v[228:229], s[36:37], 0, v[136:137]
	s_addc_u32 s81, s37, 0
	s_add_i32 s79, s44, s66
	global_load_lds_dwordx4 v[228:229], off
	v_lshl_add_u64 v[230:231], s[80:81], 0, v[132:133]
	s_mov_b32 m0, s79
	v_lshl_add_u64 v[232:233], s[38:39], 0, v[134:135]
	global_load_lds_dwordx4 v[230:231], off
	v_lshl_add_u64 v[230:231], s[80:81], 0, v[136:137]
	s_add_i32 m0, s79, 0x2000
	s_nop 0
	global_load_lds_dwordx4 v[230:231], off
	v_lshl_add_u64 v[230:231], s[38:39], 0, v[130:131]
	s_mov_b32 m0, s67
	s_nop 0
	global_load_lds_dwordx4 v[230:231], off
	s_mov_b32 m0, s68
	s_nop 0
	global_load_lds_dwordx4 v[232:233], off
	s_waitcnt vmcnt(8)
	s_waitcnt lgkmcnt(0)
	s_barrier
; #define PG8_STAGE(bufoff, gbase, voff) do { _Pragma("unroll") for (int _i = 0; _i < 2; ++_i) \
;         __builtin_amdgcn_global_load_lds((const unsigned*)((const char*)(gbase) + (voff)[_i]), (PG8_LAS unsigned*)(lds + (bufoff) + ldsw + _i * 8192), 16, 0, 0); } while (0)
; #define PG8_LDA(dst, b, h) do { _Pragma("unroll") for (int m = 0; m < 4; ++m) _Pragma("unroll") for (int k = 0; k < 2; ++k) dst[m][k] = *(const PG8_LAS bf16x8*)(lds + PG8_SA(b, h) + aoff + m * 2048 + k * 1024); } while (0)
; #define PG8_LDB(dst, b, h) do { _Pragma("unroll") for (int n = 0; n < 2; ++n) _Pragma("unroll") for (int k = 0; k < 2; ++k) dst[n][k] = *(const PG8_LAS bf16x8*)(lds + PG8_SB(b, h) + boff + n * 2048 + k * 1024); } while (0)
; #define PG8_MMA(ai, bj, At, Bt) do { __builtin_amdgcn_s_setprio(1); _Pragma("unroll") for (int m = 0; m < 4; ++m) _Pragma("unroll") for (int n = 0; n < 2; ++n) _Pragma("unroll") for (int k = 0; k < 2; ++k) \
;         acc[ai][bj][m][n] = __builtin_amdgcn_mfma_f32_16x16x32_bf16(Bt[n][k], At[m][k], acc[ai][bj][m][n], 0, 0, 0); __builtin_amdgcn_s_setprio(0); } while (0)
; #define PG8_BAR __builtin_amdgcn_s_barrier()
; template <class Epi, class Sched, bool ALIGN_EPI = false, bool SP2 = false>
; __device__ __forceinline__ void gemm_phase(PG8_LAS unsigned char* lds, const Gemm g, const Sched& S, const Epi& E, int wave_in) {
;     ...
;             PG8_LDB(B0, 0, 0); PG8_LDB(B1, 0, 1); PG8_SCHED; PG8_LDA(At, 0, 0); PG8_STAGE(PG8_SA(1, 1), a1 + hstep, voffA);
;             PG8_WAIT_V(8); PG8_WAIT_L(0); PG8_BAR; PG8_MMA(0, 0, At, B0); PG8_MMA(0, 1, At, B1); PG8_BAR; PG8_SCHED;
;             PG8_LDA(At, 0, 1); PG8_STAGE(PG8_SB(0, 0), b2, voffB); PG8_STAGE(PG8_SB(0, 1), b2 + hstep, voffB); PG8_STAGE(PG8_SA(0, 0), a2, voffA);
;             PG8_WAIT_V(8); PG8_WAIT_L(0); PG8_BAR; PG8_MMA(1, 0, At, B0); PG8_MMA(1, 1, At, B1); PG8_BAR; PG8_SCHED;
;             PG8_LDB(B0, 1, 0); PG8_LDB(B1, 1, 1); PG8_SCHED; PG8_LDA(At, 1, 0); PG8_STAGE(PG8_SA(0, 1), a2 + hstep, voffA);
;             PG8_WAIT_V(8); PG8_WAIT_L(0); PG8_BAR; PG8_MMA(0, 0, At, B0); PG8_MMA(0, 1, At, B1); PG8_BAR; PG8_SCHED;
;             PG8_LDA(At, 1, 1); PG8_STAGE(PG8_SB(1, 0), b3, voffB); PG8_STAGE(PG8_SB(1, 1), b3 + hstep, voffB); PG8_STAGE(PG8_SA(1, 0), a3, voffA);
;             PG8_WAIT_V(8); PG8_WAIT_L(0); PG8_BAR; PG8_MMA(1, 0, At, B0); PG8_MMA(1, 1, At, B1); PG8_BAR; PG8_SCHED;
	s_setprio 1
	s_waitcnt lgkmcnt(0)
	v_mfma_f32_16x16x32_bf16 v[60:63], v[162:165], v[194:197], 0
	v_mfma_f32_16x16x32_bf16 v[56:59], v[170:173], v[194:197], 0
	v_mfma_f32_16x16x32_bf16 v[44:47], v[170:173], v[202:205], 0
	v_mfma_f32_16x16x32_bf16 v[52:55], v[162:165], v[202:205], 0
	v_mfma_f32_16x16x32_bf16 v[36:39], v[162:165], v[210:213], 0
	v_mfma_f32_16x16x32_bf16 v[28:31], v[170:173], v[210:213], 0
	v_mfma_f32_16x16x32_bf16 v[12:15], v[170:173], v[218:221], 0
	v_mfma_f32_16x16x32_bf16 v[20:23], v[162:165], v[218:221], 0
	v_mfma_f32_16x16x32_bf16 v[60:63], v[166:169], v[198:201], v[60:63]
	v_mfma_f32_16x16x32_bf16 v[56:59], v[174:177], v[198:201], v[56:59]
	v_mfma_f32_16x16x32_bf16 v[44:47], v[174:177], v[206:209], v[44:47]
	v_mfma_f32_16x16x32_bf16 v[52:55], v[166:169], v[206:209], v[52:55]
	v_mfma_f32_16x16x32_bf16 v[36:39], v[166:169], v[214:217], v[36:39]
	v_mfma_f32_16x16x32_bf16 v[28:31], v[174:177], v[214:217], v[28:31]
	v_mfma_f32_16x16x32_bf16 v[12:15], v[174:177], v[222:225], v[12:15]
	v_mfma_f32_16x16x32_bf16 v[20:23], v[166:169], v[222:225], v[20:23]
	s_setprio 0
	s_setprio 1
	v_mfma_f32_16x16x32_bf16 v[48:51], v[178:181], v[194:197], 0
	v_mfma_f32_16x16x32_bf16 v[40:43], v[186:189], v[194:197], 0
	v_mfma_f32_16x16x32_bf16 v[24:27], v[186:189], v[202:205], 0
	v_mfma_f32_16x16x32_bf16 v[32:35], v[178:181], v[202:205], 0
	v_mfma_f32_16x16x32_bf16 v[16:19], v[178:181], v[210:213], 0
	v_mfma_f32_16x16x32_bf16 v[8:11], v[186:189], v[210:213], 0
	v_mfma_f32_16x16x32_bf16 v[0:3], v[186:189], v[218:221], 0
	v_mfma_f32_16x16x32_bf16 v[4:7], v[178:181], v[218:221], 0
	v_mfma_f32_16x16x32_bf16 v[48:51], v[182:185], v[198:201], v[48:51]
	v_mfma_f32_16x16x32_bf16 v[40:43], v[190:193], v[198:201], v[40:43]
	v_mfma_f32_16x16x32_bf16 v[24:27], v[190:193], v[206:209], v[24:27]
	v_mfma_f32_16x16x32_bf16 v[32:35], v[182:185], v[206:209], v[32:35]
	v_mfma_f32_16x16x32_bf16 v[16:19], v[182:185], v[214:217], v[16:19]
	v_mfma_f32_16x16x32_bf16 v[8:11], v[190:193], v[214:217], v[8:11]
	v_mfma_f32_16x16x32_bf16 v[0:3], v[190:193], v[222:225], v[0:3]
	v_mfma_f32_16x16x32_bf16 v[4:7], v[182:185], v[222:225], v[4:7]
	s_setprio 0
	s_barrier
	v_add_u32_e32 v174, s45, v160
	v_add_u32_e32 v190, s46, v160
	ds_read_b128 v[162:165], v174
	ds_read_b128 v[166:169], v174 offset:1024
	ds_read_b128 v[170:173], v174 offset:2048
	ds_read_b128 v[174:177], v174 offset:3072
	ds_read_b128 v[178:181], v190
	ds_read_b128 v[182:185], v190 offset:1024
	ds_read_b128 v[186:189], v190 offset:2048
	ds_read_b128 v[190:193], v190 offset:3072
	s_add_u32 s38, s38, 0x40000
	s_addc_u32 s39, s39, 0
	s_mov_b32 m0, s69
	v_lshl_add_u64 v[234:235], s[38:39], 0, v[130:131]
	ds_read_b128 v[194:197], v161 offset:32768
	ds_read_b128 v[198:201], v161 offset:33792
	ds_read_b128 v[202:205], v161 offset:34816
	ds_read_b128 v[206:209], v161 offset:35840
	ds_read_b128 v[210:213], v161 offset:36864
	ds_read_b128 v[214:217], v161 offset:37888
	ds_read_b128 v[218:221], v161 offset:38912
	ds_read_b128 v[222:225], v161 offset:39936
	global_load_lds_dwordx4 v[234:235], off
	v_lshl_add_u64 v[234:235], s[38:39], 0, v[134:135]
	s_mov_b32 m0, s70
	s_nop 0
	global_load_lds_dwordx4 v[234:235], off
	s_waitcnt vmcnt(8)
	s_waitcnt lgkmcnt(0)
	s_barrier
	s_setprio 1
	s_waitcnt lgkmcnt(0)
	v_mfma_f32_16x16x32_bf16 v[124:127], v[162:165], v[194:197], v[124:127]
	v_mfma_f32_16x16x32_bf16 v[120:123], v[170:173], v[194:197], v[120:123]
	v_mfma_f32_16x16x32_bf16 v[108:111], v[170:173], v[202:205], v[108:111]
	v_mfma_f32_16x16x32_bf16 v[116:119], v[162:165], v[202:205], v[116:119]
	v_mfma_f32_16x16x32_bf16 v[100:103], v[162:165], v[210:213], v[100:103]
	v_mfma_f32_16x16x32_bf16 v[92:95], v[170:173], v[210:213], v[92:95]
	v_mfma_f32_16x16x32_bf16 v[76:79], v[170:173], v[218:221], v[76:79]
	v_mfma_f32_16x16x32_bf16 v[84:87], v[162:165], v[218:221], v[84:87]
	v_mfma_f32_16x16x32_bf16 v[124:127], v[166:169], v[198:201], v[124:127]
	v_mfma_f32_16x16x32_bf16 v[120:123], v[174:177], v[198:201], v[120:123]
	v_mfma_f32_16x16x32_bf16 v[108:111], v[174:177], v[206:209], v[108:111]
	v_mfma_f32_16x16x32_bf16 v[116:119], v[166:169], v[206:209], v[116:119]
	v_mfma_f32_16x16x32_bf16 v[100:103], v[166:169], v[214:217], v[100:103]
	v_mfma_f32_16x16x32_bf16 v[92:95], v[174:177], v[214:217], v[92:95]
	v_mfma_f32_16x16x32_bf16 v[76:79], v[174:177], v[222:225], v[76:79]
	v_mfma_f32_16x16x32_bf16 v[84:87], v[166:169], v[222:225], v[84:87]
	s_setprio 0
	s_setprio 1
	v_mfma_f32_16x16x32_bf16 v[112:115], v[178:181], v[194:197], v[112:115]
	v_mfma_f32_16x16x32_bf16 v[104:107], v[186:189], v[194:197], v[104:107]
	v_mfma_f32_16x16x32_bf16 v[88:91], v[186:189], v[202:205], v[88:91]
	v_mfma_f32_16x16x32_bf16 v[96:99], v[178:181], v[202:205], v[96:99]
	v_mfma_f32_16x16x32_bf16 v[80:83], v[178:181], v[210:213], v[80:83]
	v_mfma_f32_16x16x32_bf16 v[72:75], v[186:189], v[210:213], v[72:75]
	v_mfma_f32_16x16x32_bf16 v[64:67], v[186:189], v[218:221], v[64:67]
	v_mfma_f32_16x16x32_bf16 v[68:71], v[178:181], v[218:221], v[68:71]
	v_mfma_f32_16x16x32_bf16 v[112:115], v[182:185], v[198:201], v[112:115]
	v_mfma_f32_16x16x32_bf16 v[104:107], v[190:193], v[198:201], v[104:107]
	v_mfma_f32_16x16x32_bf16 v[88:91], v[190:193], v[206:209], v[88:91]
	v_mfma_f32_16x16x32_bf16 v[96:99], v[182:185], v[206:209], v[96:99]
	v_mfma_f32_16x16x32_bf16 v[80:83], v[182:185], v[214:217], v[80:83]
	v_mfma_f32_16x16x32_bf16 v[72:75], v[190:193], v[214:217], v[72:75]
	v_mfma_f32_16x16x32_bf16 v[64:67], v[190:193], v[222:225], v[64:67]
	v_mfma_f32_16x16x32_bf16 v[68:71], v[182:185], v[222:225], v[68:71]
	s_setprio 0
	s_barrier
; #define PG8_STAGE(bufoff, gbase, voff) do { _Pragma("unroll") for (int _i = 0; _i < 2; ++_i) \
;         __builtin_amdgcn_global_load_lds((const unsigned*)((const char*)(gbase) + (voff)[_i]), (PG8_LAS unsigned*)(lds + (bufoff) + ldsw + _i * 8192), 16, 0, 0); } while (0)
; #define PG8_LDA(dst, b, h) do { _Pragma("unroll") for (int m = 0; m < 4; ++m) _Pragma("unroll") for (int k = 0; k < 2; ++k) dst[m][k] = *(const PG8_LAS bf16x8*)(lds + PG8_SA(b, h) + aoff + m * 2048 + k * 1024); } while (0)
; #define PG8_LDB(dst, b, h) do { _Pragma("unroll") for (int n = 0; n < 2; ++n) _Pragma("unroll") for (int k = 0; k < 2; ++k) dst[n][k] = *(const PG8_LAS bf16x8*)(lds + PG8_SB(b, h) + boff + n * 2048 + k * 1024); } while (0)
; #define PG8_MMA(ai, bj, At, Bt) do { __builtin_amdgcn_s_setprio(1); _Pragma("unroll") for (int m = 0; m < 4; ++m) _Pragma("unroll") for (int n = 0; n < 2; ++n) _Pragma("unroll") for (int k = 0; k < 2; ++k) \
;         acc[ai][bj][m][n] = __builtin_amdgcn_mfma_f32_16x16x32_bf16(Bt[n][k], At[m][k], acc[ai][bj][m][n], 0, 0, 0); __builtin_amdgcn_s_setprio(0); } while (0)
; #define PG8_BAR __builtin_amdgcn_s_barrier()
; template <class Epi, class Sched, bool ALIGN_EPI = false, bool SP2 = false>
; __device__ __forceinline__ void gemm_phase(PG8_LAS unsigned char* lds, const Gemm g, const Sched& S, const Epi& E, int wave_in) {
;     ...
;             PG8_LDB(B0, 0, 0); PG8_LDB(B1, 0, 1); PG8_SCHED; PG8_LDA(At, 0, 0); PG8_STAGE(PG8_SA(1, 1), a1 + hstep, voffA);
;             PG8_WAIT_V(8); PG8_WAIT_L(0); PG8_BAR; PG8_MMA(0, 0, At, B0); PG8_MMA(0, 1, At, B1); PG8_BAR; PG8_SCHED;
;             PG8_LDA(At, 0, 1); PG8_STAGE(PG8_SB(0, 0), b2, voffB); PG8_STAGE(PG8_SB(0, 1), b2 + hstep, voffB); PG8_STAGE(PG8_SA(0, 0), a2, voffA);
;             PG8_WAIT_V(8); PG8_WAIT_L(0); PG8_BAR; PG8_MMA(1, 0, At, B0); PG8_MMA(1, 1, At, B1); PG8_BAR; PG8_SCHED;
;             PG8_LDB(B0, 1, 0); PG8_LDB(B1, 1, 1); PG8_SCHED; PG8_LDA(At, 1, 0); PG8_STAGE(PG8_SA(0, 1), a2 + hstep, voffA);
;             PG8_WAIT_V(8); PG8_WAIT_L(0); PG8_BAR; PG8_MMA(0, 0, At, B0); PG8_MMA(0, 1, At, B1); PG8_BAR; PG8_SCHED;
;             PG8_LDA(At, 1, 1); PG8_STAGE(PG8_SB(1, 0), b3, voffB); PG8_STAGE(PG8_SB(1, 1), b3 + hstep, voffB); PG8_STAGE(PG8_SA(1, 0), a3, voffA);
;             PG8_WAIT_V(8); PG8_WAIT_L(0); PG8_BAR; PG8_MMA(1, 0, At, B0); PG8_MMA(1, 1, At, B1); PG8_BAR; PG8_SCHED;
	s_add_i32 s38, s45, s66
	v_lshl_add_u64 v[226:227], v[226:227], 0, s[6:7]
	s_mov_b32 m0, s38
	ds_read_b128 v[194:197], v161 offset:49152
	ds_read_b128 v[198:201], v161 offset:50176
	ds_read_b128 v[202:205], v161 offset:51200
	ds_read_b128 v[206:209], v161 offset:52224
	ds_read_b128 v[210:213], v161 offset:53248
	ds_read_b128 v[214:217], v161 offset:54272
	ds_read_b128 v[218:221], v161 offset:55296
	ds_read_b128 v[222:225], v161 offset:56320
	global_load_lds_dwordx4 v[226:227], off
	s_add_i32 m0, s38, 0x2000
	s_add_u32 s36, s36, 0x40080
	v_lshl_add_u64 v[226:227], v[228:229], 0, s[6:7]
	s_addc_u32 s37, s37, 0
	s_add_i32 s38, s46, s66
	global_load_lds_dwordx4 v[226:227], off
	v_lshl_add_u64 v[226:227], s[36:37], 0, v[132:133]
	s_mov_b32 m0, s38
	s_nop 0
	global_load_lds_dwordx4 v[226:227], off
	v_lshl_add_u64 v[226:227], s[36:37], 0, v[136:137]
	s_add_i32 m0, s38, 0x2000
	s_nop 0
	global_load_lds_dwordx4 v[226:227], off
	v_lshl_add_u64 v[226:227], v[230:231], 0, s[6:7]
	s_mov_b32 m0, s73
	s_nop 0
	global_load_lds_dwordx4 v[226:227], off
	v_lshl_add_u64 v[226:227], v[232:233], 0, s[6:7]
	s_mov_b32 m0, s74
	s_nop 0
	global_load_lds_dwordx4 v[226:227], off
	s_waitcnt vmcnt(8)
	s_waitcnt lgkmcnt(0)
	s_barrier
	s_setprio 1
	s_waitcnt lgkmcnt(0)
	v_mfma_f32_16x16x32_bf16 v[60:63], v[162:165], v[194:197], v[60:63]
	v_mfma_f32_16x16x32_bf16 v[56:59], v[170:173], v[194:197], v[56:59]
	v_mfma_f32_16x16x32_bf16 v[44:47], v[170:173], v[202:205], v[44:47]
	v_mfma_f32_16x16x32_bf16 v[52:55], v[162:165], v[202:205], v[52:55]
	v_mfma_f32_16x16x32_bf16 v[36:39], v[162:165], v[210:213], v[36:39]
	v_mfma_f32_16x16x32_bf16 v[28:31], v[170:173], v[210:213], v[28:31]
	v_mfma_f32_16x16x32_bf16 v[12:15], v[170:173], v[218:221], v[12:15]
	v_mfma_f32_16x16x32_bf16 v[20:23], v[162:165], v[218:221], v[20:23]
	v_mfma_f32_16x16x32_bf16 v[60:63], v[166:169], v[198:201], v[60:63]
	v_mfma_f32_16x16x32_bf16 v[56:59], v[174:177], v[198:201], v[56:59]
	v_mfma_f32_16x16x32_bf16 v[44:47], v[174:177], v[206:209], v[44:47]
	v_mfma_f32_16x16x32_bf16 v[52:55], v[166:169], v[206:209], v[52:55]
	v_mfma_f32_16x16x32_bf16 v[36:39], v[166:169], v[214:217], v[36:39]
	v_mfma_f32_16x16x32_bf16 v[28:31], v[174:177], v[214:217], v[28:31]
	v_mfma_f32_16x16x32_bf16 v[12:15], v[174:177], v[222:225], v[12:15]
	v_mfma_f32_16x16x32_bf16 v[20:23], v[166:169], v[222:225], v[20:23]
	s_setprio 0
	s_setprio 1
	v_mfma_f32_16x16x32_bf16 v[48:51], v[178:181], v[194:197], v[48:51]
	v_mfma_f32_16x16x32_bf16 v[40:43], v[186:189], v[194:197], v[40:43]
	v_mfma_f32_16x16x32_bf16 v[24:27], v[186:189], v[202:205], v[24:27]
	v_mfma_f32_16x16x32_bf16 v[32:35], v[178:181], v[202:205], v[32:35]
	v_mfma_f32_16x16x32_bf16 v[16:19], v[178:181], v[210:213], v[16:19]
	v_mfma_f32_16x16x32_bf16 v[8:11], v[186:189], v[210:213], v[8:11]
	v_mfma_f32_16x16x32_bf16 v[0:3], v[186:189], v[218:221], v[0:3]
	v_mfma_f32_16x16x32_bf16 v[4:7], v[178:181], v[218:221], v[4:7]
	v_mfma_f32_16x16x32_bf16 v[48:51], v[182:185], v[198:201], v[48:51]
	v_mfma_f32_16x16x32_bf16 v[40:43], v[190:193], v[198:201], v[40:43]
	v_mfma_f32_16x16x32_bf16 v[24:27], v[190:193], v[206:209], v[24:27]
	v_mfma_f32_16x16x32_bf16 v[32:35], v[182:185], v[206:209], v[32:35]
	v_mfma_f32_16x16x32_bf16 v[16:19], v[182:185], v[214:217], v[16:19]
	v_mfma_f32_16x16x32_bf16 v[8:11], v[190:193], v[214:217], v[8:11]
	v_mfma_f32_16x16x32_bf16 v[0:3], v[190:193], v[222:225], v[0:3]
	v_mfma_f32_16x16x32_bf16 v[4:7], v[182:185], v[222:225], v[4:7]
	s_setprio 0
	s_barrier
	s_add_i32 s78, s78, 2
	s_add_u32 s76, s76, 0x100
	s_addc_u32 s77, s77, 0
	s_add_u32 s34, s34, 0x100
	s_addc_u32 s35, s35, 0
	s_cmp_gt_u32 s78, 13
	s_cbranch_scc1 .Lkexit_0
.LBB0_254:
	v_add_u32_e32 v174, s43, v160
	v_add_u32_e32 v190, s44, v160
	ds_read_b128 v[162:165], v174
	ds_read_b128 v[166:169], v174 offset:1024
	ds_read_b128 v[170:173], v174 offset:2048
	ds_read_b128 v[174:177], v174 offset:3072
	ds_read_b128 v[178:181], v190
	ds_read_b128 v[182:185], v190 offset:1024
	ds_read_b128 v[186:189], v190 offset:2048
	ds_read_b128 v[190:193], v190 offset:3072
	s_add_u32 s36, s34, 0xfffc0080
	s_addc_u32 s37, s35, -1
	s_cmp_eq_u32 s78, 12
	s_cselect_b32 s39, s23, s37
	s_cselect_b32 s38, s29, s36
	s_cselect_b32 s37, s21, s77
	s_cselect_b32 s36, s31, s76
	v_lshl_add_u64 v[226:227], s[34:35], 0, v[156:157]
	s_add_i32 m0, s67, 0xc000
	ds_read_b128 v[194:197], v161
	ds_read_b128 v[198:201], v161 offset:1024
	ds_read_b128 v[202:205], v161 offset:2048
	ds_read_b128 v[206:209], v161 offset:3072
	ds_read_b128 v[210:213], v161 offset:4096
	ds_read_b128 v[214:217], v161 offset:5120
	ds_read_b128 v[218:221], v161 offset:6144
	ds_read_b128 v[222:225], v161 offset:7168
	global_load_lds_dwordx4 v[226:227], off
	v_lshl_add_u64 v[226:227], s[34:35], 0, v[154:155]
	s_add_i32 m0, s67, 0xe000
	s_nop 0
	global_load_lds_dwordx4 v[226:227], off
	s_waitcnt vmcnt(8)
	s_waitcnt lgkmcnt(0)
	s_barrier
; #define PG8_STAGE(bufoff, gbase, voff) do { _Pragma("unroll") for (int _i = 0; _i < 2; ++_i) \
;         __builtin_amdgcn_global_load_lds((const unsigned*)((const char*)(gbase) + (voff)[_i]), (PG8_LAS unsigned*)(lds + (bufoff) + ldsw + _i * 8192), 16, 0, 0); } while (0)
; #define PG8_LDA(dst, b, h) do { _Pragma("unroll") for (int m = 0; m < 4; ++m) _Pragma("unroll") for (int k = 0; k < 2; ++k) dst[m][k] = *(const PG8_LAS bf16x8*)(lds + PG8_SA(b, h) + aoff + m * 2048 + k * 1024); } while (0)
; #define PG8_LDB(dst, b, h) do { _Pragma("unroll") for (int n = 0; n < 2; ++n) _Pragma("unroll") for (int k = 0; k < 2; ++k) dst[n][k] = *(const PG8_LAS bf16x8*)(lds + PG8_SB(b, h) + boff + n * 2048 + k * 1024); } while (0)
; #define PG8_MMA(ai, bj, At, Bt) do { __builtin_amdgcn_s_setprio(1); _Pragma("unroll") for (int m = 0; m < 4; ++m) _Pragma("unroll") for (int n = 0; n < 2; ++n) _Pragma("unroll") for (int k = 0; k < 2; ++k) \
;         acc[ai][bj][m][n] = __builtin_amdgcn_mfma_f32_16x16x32_bf16(Bt[n][k], At[m][k], acc[ai][bj][m][n], 0, 0, 0); __builtin_amdgcn_s_setprio(0); } while (0)
; #define PG8_BAR __builtin_amdgcn_s_barrier()
; template <class Epi, class Sched, bool ALIGN_EPI = false, bool SP2 = false>
; __device__ __forceinline__ void gemm_phase(PG8_LAS unsigned char* lds, const Gemm g, const Sched& S, const Epi& E, int wave_in) {
;     ...
;             PG8_LDB(B0, 0, 0); PG8_LDB(B1, 0, 1); PG8_SCHED; PG8_LDA(At, 0, 0); PG8_STAGE(PG8_SA(1, 1), a1 + hstep, voffA);
;             PG8_WAIT_V(8); PG8_WAIT_L(0); PG8_BAR; PG8_MMA(0, 0, At, B0); PG8_MMA(0, 1, At, B1); PG8_BAR; PG8_SCHED;
;             PG8_LDA(At, 0, 1); PG8_STAGE(PG8_SB(0, 0), b2, voffB); PG8_STAGE(PG8_SB(0, 1), b2 + hstep, voffB); PG8_STAGE(PG8_SA(0, 0), a2, voffA);
;             PG8_WAIT_V(8); PG8_WAIT_L(0); PG8_BAR; PG8_MMA(1, 0, At, B0); PG8_MMA(1, 1, At, B1); PG8_BAR; PG8_SCHED;
;             PG8_LDB(B0, 1, 0); PG8_LDB(B1, 1, 1); PG8_SCHED; PG8_LDA(At, 1, 0); PG8_STAGE(PG8_SA(0, 1), a2 + hstep, voffA);
;             PG8_WAIT_V(8); PG8_WAIT_L(0); PG8_BAR; PG8_MMA(0, 0, At, B0); PG8_MMA(0, 1, At, B1); PG8_BAR; PG8_SCHED;
;             PG8_LDA(At, 1, 1); PG8_STAGE(PG8_SB(1, 0), b3, voffB); PG8_STAGE(PG8_SB(1, 1), b3 + hstep, voffB); PG8_STAGE(PG8_SA(1, 0), a3, voffA);
;             PG8_WAIT_V(8); PG8_WAIT_L(0); PG8_BAR; PG8_MMA(1, 0, At, B0); PG8_MMA(1, 1, At, B1); PG8_BAR; PG8_SCHED;
	s_setprio 1
	s_waitcnt lgkmcnt(0)
	v_mfma_f32_16x16x32_bf16 v[124:127], v[162:165], v[194:197], v[124:127]
	v_mfma_f32_16x16x32_bf16 v[120:123], v[170:173], v[194:197], v[120:123]
	v_mfma_f32_16x16x32_bf16 v[108:111], v[170:173], v[202:205], v[108:111]
	v_mfma_f32_16x16x32_bf16 v[116:119], v[162:165], v[202:205], v[116:119]
	v_mfma_f32_16x16x32_bf16 v[100:103], v[162:165], v[210:213], v[100:103]
	v_mfma_f32_16x16x32_bf16 v[92:95], v[170:173], v[210:213], v[92:95]
	v_mfma_f32_16x16x32_bf16 v[76:79], v[170:173], v[218:221], v[76:79]
	v_mfma_f32_16x16x32_bf16 v[84:87], v[162:165], v[218:221], v[84:87]
	v_mfma_f32_16x16x32_bf16 v[124:127], v[166:169], v[198:201], v[124:127]
	v_mfma_f32_16x16x32_bf16 v[120:123], v[174:177], v[198:201], v[120:123]
	v_mfma_f32_16x16x32_bf16 v[108:111], v[174:177], v[206:209], v[108:111]
	v_mfma_f32_16x16x32_bf16 v[116:119], v[166:169], v[206:209], v[116:119]
	v_mfma_f32_16x16x32_bf16 v[100:103], v[166:169], v[214:217], v[100:103]
	v_mfma_f32_16x16x32_bf16 v[92:95], v[174:177], v[214:217], v[92:95]
	v_mfma_f32_16x16x32_bf16 v[76:79], v[174:177], v[222:225], v[76:79]
	v_mfma_f32_16x16x32_bf16 v[84:87], v[166:169], v[222:225], v[84:87]
	s_setprio 0
	s_setprio 1
	v_mfma_f32_16x16x32_bf16 v[112:115], v[178:181], v[194:197], v[112:115]
	v_mfma_f32_16x16x32_bf16 v[104:107], v[186:189], v[194:197], v[104:107]
	v_mfma_f32_16x16x32_bf16 v[88:91], v[186:189], v[202:205], v[88:91]
	v_mfma_f32_16x16x32_bf16 v[96:99], v[178:181], v[202:205], v[96:99]
	v_mfma_f32_16x16x32_bf16 v[80:83], v[178:181], v[210:213], v[80:83]
	v_mfma_f32_16x16x32_bf16 v[72:75], v[186:189], v[210:213], v[72:75]
	v_mfma_f32_16x16x32_bf16 v[64:67], v[186:189], v[218:221], v[64:67]
	v_mfma_f32_16x16x32_bf16 v[68:71], v[178:181], v[218:221], v[68:71]
	v_mfma_f32_16x16x32_bf16 v[112:115], v[182:185], v[198:201], v[112:115]
	v_mfma_f32_16x16x32_bf16 v[104:107], v[190:193], v[198:201], v[104:107]
	v_mfma_f32_16x16x32_bf16 v[88:91], v[190:193], v[206:209], v[88:91]
	v_mfma_f32_16x16x32_bf16 v[96:99], v[182:185], v[206:209], v[96:99]
	v_mfma_f32_16x16x32_bf16 v[80:83], v[182:185], v[214:217], v[80:83]
	v_mfma_f32_16x16x32_bf16 v[72:75], v[190:193], v[214:217], v[72:75]
	v_mfma_f32_16x16x32_bf16 v[64:67], v[190:193], v[222:225], v[64:67]
	v_mfma_f32_16x16x32_bf16 v[68:71], v[182:185], v[222:225], v[68:71]
	s_setprio 0
	s_barrier
	s_add_i32 s79, s43, s66
	v_lshl_add_u64 v[226:227], s[36:37], 0, v[132:133]
	s_mov_b32 m0, s79
	ds_read_b128 v[194:197], v161 offset:16384
	ds_read_b128 v[198:201], v161 offset:17408
	ds_read_b128 v[202:205], v161 offset:18432
	ds_read_b128 v[206:209], v161 offset:19456
	ds_read_b128 v[210:213], v161 offset:20480
	ds_read_b128 v[214:217], v161 offset:21504
	ds_read_b128 v[218:221], v161 offset:22528
	ds_read_b128 v[222:225], v161 offset:23552
	global_load_lds_dwordx4 v[226:227], off
	s_add_i32 m0, s79, 0x2000
	s_add_u32 s80, s36, 0x40000
	v_lshl_add_u64 v[228:229], s[36:37], 0, v[136:137]
	s_addc_u32 s81, s37, 0
	s_add_i32 s79, s44, s66
	global_load_lds_dwordx4 v[228:229], off
	v_lshl_add_u64 v[230:231], s[80:81], 0, v[132:133]
	s_mov_b32 m0, s79
	v_lshl_add_u64 v[232:233], s[38:39], 0, v[134:135]
	global_load_lds_dwordx4 v[230:231], off
	v_lshl_add_u64 v[230:231], s[80:81], 0, v[136:137]
	s_add_i32 m0, s79, 0x2000
	s_nop 0
	global_load_lds_dwordx4 v[230:231], off
	v_lshl_add_u64 v[230:231], s[38:39], 0, v[130:131]
	s_mov_b32 m0, s67
	s_nop 0
	global_load_lds_dwordx4 v[230:231], off
	s_mov_b32 m0, s68
	s_nop 0
	global_load_lds_dwordx4 v[232:233], off
	s_waitcnt vmcnt(8)
	s_waitcnt lgkmcnt(0)
	s_barrier
	s_setprio 1
	s_waitcnt lgkmcnt(0)
	v_mfma_f32_16x16x32_bf16 v[60:63], v[162:165], v[194:197], v[60:63]
	v_mfma_f32_16x16x32_bf16 v[56:59], v[170:173], v[194:197], v[56:59]
	v_mfma_f32_16x16x32_bf16 v[44:47], v[170:173], v[202:205], v[44:47]
	v_mfma_f32_16x16x32_bf16 v[52:55], v[162:165], v[202:205], v[52:55]
	v_mfma_f32_16x16x32_bf16 v[36:39], v[162:165], v[210:213], v[36:39]
	v_mfma_f32_16x16x32_bf16 v[28:31], v[170:173], v[210:213], v[28:31]
	v_mfma_f32_16x16x32_bf16 v[12:15], v[170:173], v[218:221], v[12:15]
	v_mfma_f32_16x16x32_bf16 v[20:23], v[162:165], v[218:221], v[20:23]
	v_mfma_f32_16x16x32_bf16 v[60:63], v[166:169], v[198:201], v[60:63]
	v_mfma_f32_16x16x32_bf16 v[56:59], v[174:177], v[198:201], v[56:59]
	v_mfma_f32_16x16x32_bf16 v[44:47], v[174:177], v[206:209], v[44:47]
	v_mfma_f32_16x16x32_bf16 v[52:55], v[166:169], v[206:209], v[52:55]
	v_mfma_f32_16x16x32_bf16 v[36:39], v[166:169], v[214:217], v[36:39]
	v_mfma_f32_16x16x32_bf16 v[28:31], v[174:177], v[214:217], v[28:31]
	v_mfma_f32_16x16x32_bf16 v[12:15], v[174:177], v[222:225], v[12:15]
	v_mfma_f32_16x16x32_bf16 v[20:23], v[166:169], v[222:225], v[20:23]
	s_setprio 0
	s_setprio 1
	v_mfma_f32_16x16x32_bf16 v[48:51], v[178:181], v[194:197], v[48:51]
	v_mfma_f32_16x16x32_bf16 v[40:43], v[186:189], v[194:197], v[40:43]
	v_mfma_f32_16x16x32_bf16 v[24:27], v[186:189], v[202:205], v[24:27]
	v_mfma_f32_16x16x32_bf16 v[32:35], v[178:181], v[202:205], v[32:35]
	v_mfma_f32_16x16x32_bf16 v[16:19], v[178:181], v[210:213], v[16:19]
	v_mfma_f32_16x16x32_bf16 v[8:11], v[186:189], v[210:213], v[8:11]
	v_mfma_f32_16x16x32_bf16 v[0:3], v[186:189], v[218:221], v[0:3]
	v_mfma_f32_16x16x32_bf16 v[4:7], v[178:181], v[218:221], v[4:7]
	v_mfma_f32_16x16x32_bf16 v[48:51], v[182:185], v[198:201], v[48:51]
	v_mfma_f32_16x16x32_bf16 v[40:43], v[190:193], v[198:201], v[40:43]
	v_mfma_f32_16x16x32_bf16 v[24:27], v[190:193], v[206:209], v[24:27]
	v_mfma_f32_16x16x32_bf16 v[32:35], v[182:185], v[206:209], v[32:35]
	v_mfma_f32_16x16x32_bf16 v[16:19], v[182:185], v[214:217], v[16:19]
	v_mfma_f32_16x16x32_bf16 v[8:11], v[190:193], v[214:217], v[8:11]
	v_mfma_f32_16x16x32_bf16 v[0:3], v[190:193], v[222:225], v[0:3]
	v_mfma_f32_16x16x32_bf16 v[4:7], v[182:185], v[222:225], v[4:7]
	s_setprio 0
	s_barrier
; #define PG8_STAGE(bufoff, gbase, voff) do { _Pragma("unroll") for (int _i = 0; _i < 2; ++_i) \
;         __builtin_amdgcn_global_load_lds((const unsigned*)((const char*)(gbase) + (voff)[_i]), (PG8_LAS unsigned*)(lds + (bufoff) + ldsw + _i * 8192), 16, 0, 0); } while (0)
; #define PG8_LDA(dst, b, h) do { _Pragma("unroll") for (int m = 0; m < 4; ++m) _Pragma("unroll") for (int k = 0; k < 2; ++k) dst[m][k] = *(const PG8_LAS bf16x8*)(lds + PG8_SA(b, h) + aoff + m * 2048 + k * 1024); } while (0)
; #define PG8_LDB(dst, b, h) do { _Pragma("unroll") for (int n = 0; n < 2; ++n) _Pragma("unroll") for (int k = 0; k < 2; ++k) dst[n][k] = *(const PG8_LAS bf16x8*)(lds + PG8_SB(b, h) + boff + n * 2048 + k * 1024); } while (0)
; #define PG8_MMA(ai, bj, At, Bt) do { __builtin_amdgcn_s_setprio(1); _Pragma("unroll") for (int m = 0; m < 4; ++m) _Pragma("unroll") for (int n = 0; n < 2; ++n) _Pragma("unroll") for (int k = 0; k < 2; ++k) \
;         acc[ai][bj][m][n] = __builtin_amdgcn_mfma_f32_16x16x32_bf16(Bt[n][k], At[m][k], acc[ai][bj][m][n], 0, 0, 0); __builtin_amdgcn_s_setprio(0); } while (0)
; #define PG8_WAIT_V(n) asm volatile("s_waitcnt vmcnt(" #n ")" ::: "memory")
; #define PG8_WAIT_L(n) asm volatile("s_waitcnt lgkmcnt(" #n ")" ::: "memory")
; #define PG8_BAR __builtin_amdgcn_s_barrier()
; #define PG8_SCHED __builtin_amdgcn_sched_barrier(0)
; template <class Epi, class Sched, bool ALIGN_EPI = false, bool SP2 = false>
; __device__ __forceinline__ void gemm_phase(PG8_LAS unsigned char* lds, const Gemm g, const Sched& S, const Epi& E, int wave_in) {
;     ...
;             PG8_LDB(B0, 1, 0); PG8_LDB(B1, 1, 1); PG8_SCHED; PG8_LDA(At, 1, 0); PG8_STAGE(PG8_SA(0, 1), a2 + hstep, voffA);
;             PG8_WAIT_V(8); PG8_WAIT_L(0); PG8_BAR; PG8_MMA(0, 0, At, B0); PG8_MMA(0, 1, At, B1); PG8_BAR; PG8_SCHED;
	v_add_u32_e32 v174, s45, v160
	v_add_u32_e32 v190, s46, v160
	ds_read_b128 v[162:165], v174
	ds_read_b128 v[166:169], v174 offset:1024
	ds_read_b128 v[170:173], v174 offset:2048
	ds_read_b128 v[174:177], v174 offset:3072
	ds_read_b128 v[178:181], v190
	ds_read_b128 v[182:185], v190 offset:1024
	ds_read_b128 v[186:189], v190 offset:2048
	ds_read_b128 v[190:193], v190 offset:3072
	s_add_u32 s38, s38, 0x40000
	s_addc_u32 s39, s39, 0
	s_mov_b32 m0, s69
	v_lshl_add_u64 v[234:235], s[38:39], 0, v[130:131]
	ds_read_b128 v[194:197], v161 offset:32768
	ds_read_b128 v[198:201], v161 offset:33792
	ds_read_b128 v[202:205], v161 offset:34816
	ds_read_b128 v[206:209], v161 offset:35840
	ds_read_b128 v[210:213], v161 offset:36864
	ds_read_b128 v[214:217], v161 offset:37888
	ds_read_b128 v[218:221], v161 offset:38912
	ds_read_b128 v[222:225], v161 offset:39936
	global_load_lds_dwordx4 v[234:235], off
	v_lshl_add_u64 v[234:235], s[38:39], 0, v[134:135]
	s_mov_b32 m0, s70
	s_nop 0
	global_load_lds_dwordx4 v[234:235], off
	s_waitcnt vmcnt(8)
	s_waitcnt lgkmcnt(0)
	s_barrier
	s_setprio 1
	s_waitcnt lgkmcnt(0)
	v_mfma_f32_16x16x32_bf16 v[124:127], v[162:165], v[194:197], v[124:127]
	v_mfma_f32_16x16x32_bf16 v[120:123], v[170:173], v[194:197], v[120:123]
	v_mfma_f32_16x16x32_bf16 v[108:111], v[170:173], v[202:205], v[108:111]
	v_mfma_f32_16x16x32_bf16 v[116:119], v[162:165], v[202:205], v[116:119]
	v_mfma_f32_16x16x32_bf16 v[100:103], v[162:165], v[210:213], v[100:103]
	v_mfma_f32_16x16x32_bf16 v[92:95], v[170:173], v[210:213], v[92:95]
	v_mfma_f32_16x16x32_bf16 v[76:79], v[170:173], v[218:221], v[76:79]
	v_mfma_f32_16x16x32_bf16 v[84:87], v[162:165], v[218:221], v[84:87]
	v_mfma_f32_16x16x32_bf16 v[124:127], v[166:169], v[198:201], v[124:127]
	v_mfma_f32_16x16x32_bf16 v[120:123], v[174:177], v[198:201], v[120:123]
	v_mfma_f32_16x16x32_bf16 v[108:111], v[174:177], v[206:209], v[108:111]
	v_mfma_f32_16x16x32_bf16 v[116:119], v[166:169], v[206:209], v[116:119]
	v_mfma_f32_16x16x32_bf16 v[100:103], v[166:169], v[214:217], v[100:103]
	v_mfma_f32_16x16x32_bf16 v[92:95], v[174:177], v[214:217], v[92:95]
	v_mfma_f32_16x16x32_bf16 v[76:79], v[174:177], v[222:225], v[76:79]
	v_mfma_f32_16x16x32_bf16 v[84:87], v[166:169], v[222:225], v[84:87]
	s_setprio 0
	s_setprio 1
	v_mfma_f32_16x16x32_bf16 v[112:115], v[178:181], v[194:197], v[112:115]
	v_mfma_f32_16x16x32_bf16 v[104:107], v[186:189], v[194:197], v[104:107]
	v_mfma_f32_16x16x32_bf16 v[88:91], v[186:189], v[202:205], v[88:91]
	v_mfma_f32_16x16x32_bf16 v[96:99], v[178:181], v[202:205], v[96:99]
	v_mfma_f32_16x16x32_bf16 v[80:83], v[178:181], v[210:213], v[80:83]
	v_mfma_f32_16x16x32_bf16 v[72:75], v[186:189], v[210:213], v[72:75]
	v_mfma_f32_16x16x32_bf16 v[64:67], v[186:189], v[218:221], v[64:67]
	v_mfma_f32_16x16x32_bf16 v[68:71], v[178:181], v[218:221], v[68:71]
	v_mfma_f32_16x16x32_bf16 v[112:115], v[182:185], v[198:201], v[112:115]
	v_mfma_f32_16x16x32_bf16 v[104:107], v[190:193], v[198:201], v[104:107]
	v_mfma_f32_16x16x32_bf16 v[88:91], v[190:193], v[206:209], v[88:91]
	v_mfma_f32_16x16x32_bf16 v[96:99], v[182:185], v[206:209], v[96:99]
	v_mfma_f32_16x16x32_bf16 v[80:83], v[182:185], v[214:217], v[80:83]
	v_mfma_f32_16x16x32_bf16 v[72:75], v[190:193], v[214:217], v[72:75]
	v_mfma_f32_16x16x32_bf16 v[64:67], v[190:193], v[222:225], v[64:67]
	v_mfma_f32_16x16x32_bf16 v[68:71], v[182:185], v[222:225], v[68:71]
	s_setprio 0
	s_barrier
; #define PG8_STAGE(bufoff, gbase, voff) do { _Pragma("unroll") for (int _i = 0; _i < 2; ++_i) \
;         __builtin_amdgcn_global_load_lds((const unsigned*)((const char*)(gbase) + (voff)[_i]), (PG8_LAS unsigned*)(lds + (bufoff) + ldsw + _i * 8192), 16, 0, 0); } while (0)
; #define PG8_LDA(dst, b, h) do { _Pragma("unroll") for (int m = 0; m < 4; ++m) _Pragma("unroll") for (int k = 0; k < 2; ++k) dst[m][k] = *(const PG8_LAS bf16x8*)(lds + PG8_SA(b, h) + aoff + m * 2048 + k * 1024); } while (0)
; #define PG8_MMA(ai, bj, At, Bt) do { __builtin_amdgcn_s_setprio(1); _Pragma("unroll") for (int m = 0; m < 4; ++m) _Pragma("unroll") for (int n = 0; n < 2; ++n) _Pragma("unroll") for (int k = 0; k < 2; ++k) \
;         acc[ai][bj][m][n] = __builtin_amdgcn_mfma_f32_16x16x32_bf16(Bt[n][k], At[m][k], acc[ai][bj][m][n], 0, 0, 0); __builtin_amdgcn_s_setprio(0); } while (0)
; #define PG8_WAIT_V(n) asm volatile("s_waitcnt vmcnt(" #n ")" ::: "memory")
; #define PG8_WAIT_L(n) asm volatile("s_waitcnt lgkmcnt(" #n ")" ::: "memory")
; #define PG8_BAR __builtin_amdgcn_s_barrier()
; #define PG8_SCHED __builtin_amdgcn_sched_barrier(0)
; template <class Epi, class Sched, bool ALIGN_EPI = false, bool SP2 = false>
; __device__ __forceinline__ void gemm_phase(PG8_LAS unsigned char* lds, const Gemm g, const Sched& S, const Epi& E, int wave_in) {
;     ...
;         for (int t = 0; t < nt; t += 2) {
;     ...
;             PG8_LDA(At, 1, 1); PG8_STAGE(PG8_SB(1, 0), b3, voffB); PG8_STAGE(PG8_SB(1, 1), b3 + hstep, voffB); PG8_STAGE(PG8_SA(1, 0), a3, voffA);
;             PG8_WAIT_V(8); PG8_WAIT_L(0); PG8_BAR; PG8_MMA(1, 0, At, B0); PG8_MMA(1, 1, At, B1); PG8_BAR; PG8_SCHED;
	s_add_i32 s38, s45, s66
	v_lshl_add_u64 v[226:227], v[226:227], 0, s[6:7]
	s_mov_b32 m0, s38
	ds_read_b128 v[194:197], v161 offset:49152
	ds_read_b128 v[198:201], v161 offset:50176
	ds_read_b128 v[202:205], v161 offset:51200
	ds_read_b128 v[206:209], v161 offset:52224
	ds_read_b128 v[210:213], v161 offset:53248
	ds_read_b128 v[214:217], v161 offset:54272
	ds_read_b128 v[218:221], v161 offset:55296
	ds_read_b128 v[222:225], v161 offset:56320
	global_load_lds_dwordx4 v[226:227], off
	s_add_i32 m0, s38, 0x2000
	s_add_u32 s36, s36, 0x40080
	v_lshl_add_u64 v[226:227], v[228:229], 0, s[6:7]
	s_addc_u32 s37, s37, 0
	s_add_i32 s38, s46, s66
	global_load_lds_dwordx4 v[226:227], off
	v_lshl_add_u64 v[226:227], s[36:37], 0, v[132:133]
	s_mov_b32 m0, s38
	s_nop 0
	global_load_lds_dwordx4 v[226:227], off
	v_lshl_add_u64 v[226:227], s[36:37], 0, v[136:137]
	s_add_i32 m0, s38, 0x2000
	s_nop 0
	global_load_lds_dwordx4 v[226:227], off
	v_lshl_add_u64 v[226:227], v[230:231], 0, s[6:7]
	s_mov_b32 m0, s73
	s_nop 0
	global_load_lds_dwordx4 v[226:227], off
	v_lshl_add_u64 v[226:227], v[232:233], 0, s[6:7]
	s_mov_b32 m0, s74
	s_nop 0
	global_load_lds_dwordx4 v[226:227], off
	s_waitcnt vmcnt(8)
	s_waitcnt lgkmcnt(0)
	s_barrier
	s_setprio 1
	s_waitcnt lgkmcnt(0)
	v_mfma_f32_16x16x32_bf16 v[60:63], v[162:165], v[194:197], v[60:63]
	v_mfma_f32_16x16x32_bf16 v[56:59], v[170:173], v[194:197], v[56:59]
	v_mfma_f32_16x16x32_bf16 v[44:47], v[170:173], v[202:205], v[44:47]
	v_mfma_f32_16x16x32_bf16 v[52:55], v[162:165], v[202:205], v[52:55]
	v_mfma_f32_16x16x32_bf16 v[36:39], v[162:165], v[210:213], v[36:39]
	v_mfma_f32_16x16x32_bf16 v[28:31], v[170:173], v[210:213], v[28:31]
	v_mfma_f32_16x16x32_bf16 v[12:15], v[170:173], v[218:221], v[12:15]
	v_mfma_f32_16x16x32_bf16 v[20:23], v[162:165], v[218:221], v[20:23]
	v_mfma_f32_16x16x32_bf16 v[60:63], v[166:169], v[198:201], v[60:63]
	v_mfma_f32_16x16x32_bf16 v[56:59], v[174:177], v[198:201], v[56:59]
	v_mfma_f32_16x16x32_bf16 v[44:47], v[174:177], v[206:209], v[44:47]
	v_mfma_f32_16x16x32_bf16 v[52:55], v[166:169], v[206:209], v[52:55]
	v_mfma_f32_16x16x32_bf16 v[36:39], v[166:169], v[214:217], v[36:39]
	v_mfma_f32_16x16x32_bf16 v[28:31], v[174:177], v[214:217], v[28:31]
	v_mfma_f32_16x16x32_bf16 v[12:15], v[174:177], v[222:225], v[12:15]
	v_mfma_f32_16x16x32_bf16 v[20:23], v[166:169], v[222:225], v[20:23]
	s_setprio 0
	s_setprio 1
	v_mfma_f32_16x16x32_bf16 v[48:51], v[178:181], v[194:197], v[48:51]
	v_mfma_f32_16x16x32_bf16 v[40:43], v[186:189], v[194:197], v[40:43]
	v_mfma_f32_16x16x32_bf16 v[24:27], v[186:189], v[202:205], v[24:27]
	v_mfma_f32_16x16x32_bf16 v[32:35], v[178:181], v[202:205], v[32:35]
	v_mfma_f32_16x16x32_bf16 v[16:19], v[178:181], v[210:213], v[16:19]
	v_mfma_f32_16x16x32_bf16 v[8:11], v[186:189], v[210:213], v[8:11]
	v_mfma_f32_16x16x32_bf16 v[0:3], v[186:189], v[218:221], v[0:3]
	v_mfma_f32_16x16x32_bf16 v[4:7], v[178:181], v[218:221], v[4:7]
	v_mfma_f32_16x16x32_bf16 v[48:51], v[182:185], v[198:201], v[48:51]
	v_mfma_f32_16x16x32_bf16 v[40:43], v[190:193], v[198:201], v[40:43]
	v_mfma_f32_16x16x32_bf16 v[24:27], v[190:193], v[206:209], v[24:27]
	v_mfma_f32_16x16x32_bf16 v[32:35], v[182:185], v[206:209], v[32:35]
	v_mfma_f32_16x16x32_bf16 v[16:19], v[182:185], v[214:217], v[16:19]
	v_mfma_f32_16x16x32_bf16 v[8:11], v[190:193], v[214:217], v[8:11]
	v_mfma_f32_16x16x32_bf16 v[0:3], v[190:193], v[222:225], v[0:3]
	v_mfma_f32_16x16x32_bf16 v[4:7], v[182:185], v[222:225], v[4:7]
	s_setprio 0
	s_barrier
	s_add_i32 s78, s78, 2
	s_add_u32 s76, s76, 0x100
	s_addc_u32 s77, s77, 0
	s_add_u32 s34, s34, 0x100
	s_addc_u32 s35, s35, 0
	s_cmp_gt_u32 s78, 13
	s_cbranch_scc0 .LBB0_254

; #define PG8_STAGE(bufoff, gbase, voff) do { _Pragma("unroll") for (int _i = 0; _i < 2; ++_i) \
;         __builtin_amdgcn_global_load_lds((const unsigned*)((const char*)(gbase) + (voff)[_i]), (PG8_LAS unsigned*)(lds + (bufoff) + ldsw + _i * 8192), 16, 0, 0); } while (0)
; #define PG8_LDA(dst, b, h) do { _Pragma("unroll") for (int m = 0; m < 4; ++m) _Pragma("unroll") for (int k = 0; k < 2; ++k) dst[m][k] = *(const PG8_LAS bf16x8*)(lds + PG8_SA(b, h) + aoff + m * 2048 + k * 1024); } while (0)
; #define PG8_LDB(dst, b, h) do { _Pragma("unroll") for (int n = 0; n < 2; ++n) _Pragma("unroll") for (int k = 0; k < 2; ++k) dst[n][k] = *(const PG8_LAS bf16x8*)(lds + PG8_SB(b, h) + boff + n * 2048 + k * 1024); } while (0)
; #define PG8_MMA(ai, bj, At, Bt) do { __builtin_amdgcn_s_setprio(1); _Pragma("unroll") for (int m = 0; m < 4; ++m) _Pragma("unroll") for (int n = 0; n < 2; ++n) _Pragma("unroll") for (int k = 0; k < 2; ++k) \
;         acc[ai][bj][m][n] = __builtin_amdgcn_mfma_f32_16x16x32_bf16(Bt[n][k], At[m][k], acc[ai][bj][m][n], 0, 0, 0); __builtin_amdgcn_s_setprio(0); } while (0)
; #define PG8_WAIT_V(n) asm volatile("s_waitcnt vmcnt(" #n ")" ::: "memory")
; #define PG8_BAR __builtin_amdgcn_s_barrier()
; template <class Epi, class Sched, bool ALIGN_EPI = false, bool SP2 = false>
; __device__ __forceinline__ void gemm_phase(PG8_LAS unsigned char* lds, const Gemm g, const Sched& S, const Epi& E, int wave_in) {
;     ...
;         for (int t = 0; t < nt; t += 2) {
;             const bool last = (t == nt - 2);
;             const char* a1 = cA + (size_t)(t + 1) * kstep;
;             const char* a2 = last ? nA : cA + (size_t)(t + 2) * kstep; const char* b2 = last ? nB : cB + (size_t)(t + 2) * kstep;
;             const char* a3 = a2 + kstep; const char* b3 = b2 + kstep;
;             if (last && has_next) S.a_ready(nxt);
;             if constexpr (SP2) {
;             PG8_LDB(B0, 0, 0); PG8_LDB(B1, 0, 1); PG8_SCHED; PG8_LDA(At, 0, 0); PG8_STAGE(PG8_SA(1, 1), a1 + hstep, voffA);
;             PG8_WAIT_V(8); PG8_WAIT_L(0); PG8_BAR; PG8_MMA(0, 0, At, B0); PG8_MMA(0, 1, At, B1); PG8_BAR; PG8_SCHED;
;             PG8_LDA(At, 0, 1); PG8_STAGE(PG8_SB(0, 0), b2, voffB); PG8_STAGE(PG8_SB(0, 1), b2 + hstep, voffB); PG8_STAGE(PG8_SA(0, 0), a2, voffA);
;             PG8_WAIT_V(8); PG8_WAIT_L(0); PG8_BAR; PG8_MMA(1, 0, At, B0); PG8_MMA(1, 1, At, B1); PG8_BAR; PG8_SCHED;
.LBB0_272:
	s_ashr_i32 s77, s76, 31
	s_lshl_b64 s[8:9], s[76:77], 19
	s_add_u32 s84, s22, s8
	s_addc_u32 s85, s23, s9
	s_and_b64 s[8:9], s[40:41], exec
	s_cselect_b32 s8, s85, s5
	s_cselect_b32 s9, s84, s4
	s_ashr_i32 s95, s94, 31
	s_lshl_b64 s[10:11], s[94:95], 19
	v_readlane_b32 s16, v255, 39
	v_readlane_b32 s17, v255, 40
	s_add_u32 s24, s16, s10
	s_addc_u32 s25, s17, s11
	s_and_b64 s[10:11], s[40:41], exec
	s_cselect_b32 s16, s25, s1
	s_cselect_b32 s17, s24, s0
	s_add_u32 s31, s0, 0x100
	s_addc_u32 s33, s1, 0
	s_add_u32 s0, s4, 0x40080
	s_addc_u32 s1, s5, 0
	s_mov_b32 s34, -2
	s_waitcnt lgkmcnt(0)
	s_add_u32 s4, s0, 0xfffc0080
	s_addc_u32 s5, s1, -1
	s_add_i32 s42, s35, 0x100
	s_cmp_eq_u32 s34, 12
	s_cselect_b32 s11, s8, s5
	s_cselect_b32 s10, s9, s4
	s_cselect_b32 s5, s16, s33
	s_cselect_b32 s4, s17, s31
	s_add_i32 s44, s90, 0x100
	v_add_u32_e32 v168, s42, v177
	v_add_u32_e32 v188, s44, v177
	ds_read_b128 v[156:159], v168
	ds_read_b128 v[160:163], v168 offset:1024
	ds_read_b128 v[164:167], v168 offset:2048
	ds_read_b128 v[168:171], v168 offset:3072
	ds_read_b128 v[172:175], v188
	ds_read_b128 v[180:183], v188 offset:1024
	ds_read_b128 v[184:187], v188 offset:2048
	ds_read_b128 v[188:191], v188 offset:3072
	v_lshl_add_u64 v[230:231], s[0:1], 0, v[154:155]
	s_add_i32 m0, s67, 0xc000
	ds_read_b128 v[198:201], v179
	ds_read_b128 v[202:205], v179 offset:1024
	ds_read_b128 v[206:209], v179 offset:2048
	ds_read_b128 v[210:213], v179 offset:3072
	ds_read_b128 v[214:217], v179 offset:4096
	ds_read_b128 v[218:221], v179 offset:5120
	ds_read_b128 v[222:225], v179 offset:6144
	ds_read_b128 v[226:229], v179 offset:7168
	global_load_lds_dwordx4 v[230:231], off
	v_lshl_add_u64 v[230:231], s[0:1], 0, v[152:153]
	s_add_i32 m0, s67, 0xe000
	s_nop 0
	global_load_lds_dwordx4 v[230:231], off
	s_waitcnt vmcnt(8)
	s_waitcnt lgkmcnt(0)
	s_barrier
	s_setprio 1
	s_waitcnt lgkmcnt(0)
	v_mfma_f32_16x16x32_bf16 v[124:127], v[156:159], v[198:201], 0
	v_mfma_f32_16x16x32_bf16 v[120:123], v[164:167], v[198:201], 0
	v_mfma_f32_16x16x32_bf16 v[104:107], v[164:167], v[206:209], 0
	v_mfma_f32_16x16x32_bf16 v[108:111], v[156:159], v[206:209], 0
	v_mfma_f32_16x16x32_bf16 v[92:95], v[156:159], v[214:217], 0
	v_mfma_f32_16x16x32_bf16 v[88:91], v[164:167], v[214:217], 0
	v_mfma_f32_16x16x32_bf16 v[72:75], v[164:167], v[222:225], 0
	v_mfma_f32_16x16x32_bf16 v[76:79], v[156:159], v[222:225], 0
	v_mfma_f32_16x16x32_bf16 v[124:127], v[160:163], v[202:205], v[124:127]
	v_mfma_f32_16x16x32_bf16 v[120:123], v[168:171], v[202:205], v[120:123]
	v_mfma_f32_16x16x32_bf16 v[104:107], v[168:171], v[210:213], v[104:107]
	v_mfma_f32_16x16x32_bf16 v[108:111], v[160:163], v[210:213], v[108:111]
	v_mfma_f32_16x16x32_bf16 v[92:95], v[160:163], v[218:221], v[92:95]
	v_mfma_f32_16x16x32_bf16 v[88:91], v[168:171], v[218:221], v[88:91]
	v_mfma_f32_16x16x32_bf16 v[72:75], v[168:171], v[226:229], v[72:75]
	v_mfma_f32_16x16x32_bf16 v[76:79], v[160:163], v[226:229], v[76:79]
	s_setprio 0
	s_setprio 1
	v_mfma_f32_16x16x32_bf16 v[116:119], v[172:175], v[198:201], 0
	v_mfma_f32_16x16x32_bf16 v[112:115], v[184:187], v[198:201], 0
	v_mfma_f32_16x16x32_bf16 v[96:99], v[184:187], v[206:209], 0
	v_mfma_f32_16x16x32_bf16 v[100:103], v[172:175], v[206:209], 0
	v_mfma_f32_16x16x32_bf16 v[84:87], v[172:175], v[214:217], 0
	v_mfma_f32_16x16x32_bf16 v[80:83], v[184:187], v[214:217], 0
	v_mfma_f32_16x16x32_bf16 v[64:67], v[184:187], v[222:225], 0
	v_mfma_f32_16x16x32_bf16 v[68:71], v[172:175], v[222:225], 0
	v_mfma_f32_16x16x32_bf16 v[116:119], v[180:183], v[202:205], v[116:119]
	v_mfma_f32_16x16x32_bf16 v[112:115], v[188:191], v[202:205], v[112:115]
	v_mfma_f32_16x16x32_bf16 v[96:99], v[188:191], v[210:213], v[96:99]
	v_mfma_f32_16x16x32_bf16 v[100:103], v[180:183], v[210:213], v[100:103]
	v_mfma_f32_16x16x32_bf16 v[84:87], v[180:183], v[218:221], v[84:87]
	v_mfma_f32_16x16x32_bf16 v[80:83], v[188:191], v[218:221], v[80:83]
	v_mfma_f32_16x16x32_bf16 v[64:67], v[188:191], v[226:229], v[64:67]
	v_mfma_f32_16x16x32_bf16 v[68:71], v[180:183], v[226:229], v[68:71]
	s_setprio 0
	s_barrier
	s_add_i32 s42, s42, s66
	v_lshl_add_u64 v[230:231], s[4:5], 0, v[132:133]
	s_mov_b32 m0, s42
	ds_read_b128 v[198:201], v179 offset:16384
	ds_read_b128 v[202:205], v179 offset:17408
	ds_read_b128 v[206:209], v179 offset:18432
	ds_read_b128 v[210:213], v179 offset:19456
	ds_read_b128 v[214:217], v179 offset:20480
	ds_read_b128 v[218:221], v179 offset:21504
	ds_read_b128 v[222:225], v179 offset:22528
	ds_read_b128 v[226:229], v179 offset:23552
	global_load_lds_dwordx4 v[230:231], off
	s_add_i32 m0, s42, 0x2000
	s_add_u32 s42, s4, 0x40000
	v_lshl_add_u64 v[232:233], s[4:5], 0, v[128:129]
	s_addc_u32 s43, s5, 0
	s_add_i32 s44, s44, s66
	global_load_lds_dwordx4 v[232:233], off
	v_lshl_add_u64 v[234:235], s[42:43], 0, v[132:133]
	s_mov_b32 m0, s44
	v_lshl_add_u64 v[236:237], s[10:11], 0, v[130:131]
	global_load_lds_dwordx4 v[234:235], off
	v_lshl_add_u64 v[234:235], s[42:43], 0, v[128:129]
	s_add_i32 m0, s44, 0x2000
	s_nop 0
	global_load_lds_dwordx4 v[234:235], off
	v_lshl_add_u64 v[234:235], s[10:11], 0, v[134:135]
	s_mov_b32 m0, s67
	s_nop 0
	global_load_lds_dwordx4 v[234:235], off
	s_mov_b32 m0, s78
	s_nop 0
	global_load_lds_dwordx4 v[236:237], off
	s_waitcnt vmcnt(8)
	s_waitcnt lgkmcnt(0)
	s_barrier
; #define PG8_STAGE(bufoff, gbase, voff) do { _Pragma("unroll") for (int _i = 0; _i < 2; ++_i) \
;         __builtin_amdgcn_global_load_lds((const unsigned*)((const char*)(gbase) + (voff)[_i]), (PG8_LAS unsigned*)(lds + (bufoff) + ldsw + _i * 8192), 16, 0, 0); } while (0)
; #define PG8_LDA(dst, b, h) do { _Pragma("unroll") for (int m = 0; m < 4; ++m) _Pragma("unroll") for (int k = 0; k < 2; ++k) dst[m][k] = *(const PG8_LAS bf16x8*)(lds + PG8_SA(b, h) + aoff + m * 2048 + k * 1024); } while (0)
; #define PG8_LDB(dst, b, h) do { _Pragma("unroll") for (int n = 0; n < 2; ++n) _Pragma("unroll") for (int k = 0; k < 2; ++k) dst[n][k] = *(const PG8_LAS bf16x8*)(lds + PG8_SB(b, h) + boff + n * 2048 + k * 1024); } while (0)
; #define PG8_MMA(ai, bj, At, Bt) do { __builtin_amdgcn_s_setprio(1); _Pragma("unroll") for (int m = 0; m < 4; ++m) _Pragma("unroll") for (int n = 0; n < 2; ++n) _Pragma("unroll") for (int k = 0; k < 2; ++k) \
;         acc[ai][bj][m][n] = __builtin_amdgcn_mfma_f32_16x16x32_bf16(Bt[n][k], At[m][k], acc[ai][bj][m][n], 0, 0, 0); __builtin_amdgcn_s_setprio(0); } while (0)
; #define PG8_WAIT_V(n) asm volatile("s_waitcnt vmcnt(" #n ")" ::: "memory")
; #define PG8_WAIT_L(n) asm volatile("s_waitcnt lgkmcnt(" #n ")" ::: "memory")
; #define PG8_BAR __builtin_amdgcn_s_barrier()
; #define PG8_SCHED __builtin_amdgcn_sched_barrier(0)
; template <class Epi, class Sched, bool ALIGN_EPI = false, bool SP2 = false>
; __device__ __forceinline__ void gemm_phase(PG8_LAS unsigned char* lds, const Gemm g, const Sched& S, const Epi& E, int wave_in) {
;     ...
;             PG8_LDB(B0, 0, 0); PG8_LDB(B1, 0, 1); PG8_SCHED; PG8_LDA(At, 0, 0); PG8_STAGE(PG8_SA(1, 1), a1 + hstep, voffA);
;             PG8_WAIT_V(8); PG8_WAIT_L(0); PG8_BAR; PG8_MMA(0, 0, At, B0); PG8_MMA(0, 1, At, B1); PG8_BAR; PG8_SCHED;
;             PG8_LDA(At, 0, 1); PG8_STAGE(PG8_SB(0, 0), b2, voffB); PG8_STAGE(PG8_SB(0, 1), b2 + hstep, voffB); PG8_STAGE(PG8_SA(0, 0), a2, voffA);
;             PG8_WAIT_V(8); PG8_WAIT_L(0); PG8_BAR; PG8_MMA(1, 0, At, B0); PG8_MMA(1, 1, At, B1); PG8_BAR; PG8_SCHED;
;             PG8_LDB(B0, 1, 0); PG8_LDB(B1, 1, 1); PG8_SCHED; PG8_LDA(At, 1, 0); PG8_STAGE(PG8_SA(0, 1), a2 + hstep, voffA);
;             PG8_WAIT_V(8); PG8_WAIT_L(0); PG8_BAR; PG8_MMA(0, 0, At, B0); PG8_MMA(0, 1, At, B1); PG8_BAR; PG8_SCHED;
	s_setprio 1
	s_waitcnt lgkmcnt(0)
	v_mfma_f32_16x16x32_bf16 v[60:63], v[156:159], v[198:201], 0
	v_mfma_f32_16x16x32_bf16 v[56:59], v[164:167], v[198:201], 0
	v_mfma_f32_16x16x32_bf16 v[40:43], v[164:167], v[206:209], 0
	v_mfma_f32_16x16x32_bf16 v[44:47], v[156:159], v[206:209], 0
	v_mfma_f32_16x16x32_bf16 v[28:31], v[156:159], v[214:217], 0
	v_mfma_f32_16x16x32_bf16 v[24:27], v[164:167], v[214:217], 0
	v_mfma_f32_16x16x32_bf16 v[8:11], v[164:167], v[222:225], 0
	v_mfma_f32_16x16x32_bf16 v[12:15], v[156:159], v[222:225], 0
	v_mfma_f32_16x16x32_bf16 v[60:63], v[160:163], v[202:205], v[60:63]
	v_mfma_f32_16x16x32_bf16 v[56:59], v[168:171], v[202:205], v[56:59]
	v_mfma_f32_16x16x32_bf16 v[40:43], v[168:171], v[210:213], v[40:43]
	v_mfma_f32_16x16x32_bf16 v[44:47], v[160:163], v[210:213], v[44:47]
	v_mfma_f32_16x16x32_bf16 v[28:31], v[160:163], v[218:221], v[28:31]
	v_mfma_f32_16x16x32_bf16 v[24:27], v[168:171], v[218:221], v[24:27]
	v_mfma_f32_16x16x32_bf16 v[8:11], v[168:171], v[226:229], v[8:11]
	v_mfma_f32_16x16x32_bf16 v[12:15], v[160:163], v[226:229], v[12:15]
	s_setprio 0
	s_setprio 1
	v_mfma_f32_16x16x32_bf16 v[52:55], v[172:175], v[198:201], 0
	v_mfma_f32_16x16x32_bf16 v[48:51], v[184:187], v[198:201], 0
	v_mfma_f32_16x16x32_bf16 v[32:35], v[184:187], v[206:209], 0
	v_mfma_f32_16x16x32_bf16 v[36:39], v[172:175], v[206:209], 0
	v_mfma_f32_16x16x32_bf16 v[20:23], v[172:175], v[214:217], 0
	v_mfma_f32_16x16x32_bf16 v[16:19], v[184:187], v[214:217], 0
	v_mfma_f32_16x16x32_bf16 v[0:3], v[184:187], v[222:225], 0
	v_mfma_f32_16x16x32_bf16 v[4:7], v[172:175], v[222:225], 0
	v_mfma_f32_16x16x32_bf16 v[52:55], v[180:183], v[202:205], v[52:55]
	v_mfma_f32_16x16x32_bf16 v[48:51], v[188:191], v[202:205], v[48:51]
	v_mfma_f32_16x16x32_bf16 v[32:35], v[188:191], v[210:213], v[32:35]
	v_mfma_f32_16x16x32_bf16 v[36:39], v[180:183], v[210:213], v[36:39]
	v_mfma_f32_16x16x32_bf16 v[20:23], v[180:183], v[218:221], v[20:23]
	v_mfma_f32_16x16x32_bf16 v[16:19], v[188:191], v[218:221], v[16:19]
	v_mfma_f32_16x16x32_bf16 v[0:3], v[188:191], v[226:229], v[0:3]
	v_mfma_f32_16x16x32_bf16 v[4:7], v[180:183], v[226:229], v[4:7]
	s_setprio 0
	s_barrier
	s_add_i32 s42, s65, 0x100
	s_add_i32 s43, s52, 0x100
	v_add_u32_e32 v168, s42, v177
	v_add_u32_e32 v188, s43, v177
	ds_read_b128 v[156:159], v168
	ds_read_b128 v[160:163], v168 offset:1024
	ds_read_b128 v[164:167], v168 offset:2048
	ds_read_b128 v[168:171], v168 offset:3072
	ds_read_b128 v[172:175], v188
	ds_read_b128 v[180:183], v188 offset:1024
	ds_read_b128 v[184:187], v188 offset:2048
	ds_read_b128 v[188:191], v188 offset:3072
	s_add_u32 s10, s10, 0x40000
	s_addc_u32 s11, s11, 0
	s_mov_b32 m0, s79
	v_lshl_add_u64 v[238:239], s[10:11], 0, v[134:135]
	ds_read_b128 v[198:201], v179 offset:32768
	ds_read_b128 v[202:205], v179 offset:33792
	ds_read_b128 v[206:209], v179 offset:34816
	ds_read_b128 v[210:213], v179 offset:35840
	ds_read_b128 v[214:217], v179 offset:36864
	ds_read_b128 v[218:221], v179 offset:37888
	ds_read_b128 v[222:225], v179 offset:38912
	ds_read_b128 v[226:229], v179 offset:39936
	global_load_lds_dwordx4 v[238:239], off
	v_lshl_add_u64 v[238:239], s[10:11], 0, v[130:131]
	s_mov_b32 m0, s82
	s_nop 0
	global_load_lds_dwordx4 v[238:239], off
	s_waitcnt vmcnt(8)
	s_waitcnt lgkmcnt(0)
	s_barrier
	s_setprio 1
	s_waitcnt lgkmcnt(0)
	v_mfma_f32_16x16x32_bf16 v[124:127], v[156:159], v[198:201], v[124:127]
	v_mfma_f32_16x16x32_bf16 v[120:123], v[164:167], v[198:201], v[120:123]
	v_mfma_f32_16x16x32_bf16 v[104:107], v[164:167], v[206:209], v[104:107]
	v_mfma_f32_16x16x32_bf16 v[108:111], v[156:159], v[206:209], v[108:111]
	v_mfma_f32_16x16x32_bf16 v[92:95], v[156:159], v[214:217], v[92:95]
	v_mfma_f32_16x16x32_bf16 v[88:91], v[164:167], v[214:217], v[88:91]
	v_mfma_f32_16x16x32_bf16 v[72:75], v[164:167], v[222:225], v[72:75]
	v_mfma_f32_16x16x32_bf16 v[76:79], v[156:159], v[222:225], v[76:79]
	v_mfma_f32_16x16x32_bf16 v[124:127], v[160:163], v[202:205], v[124:127]
	v_mfma_f32_16x16x32_bf16 v[120:123], v[168:171], v[202:205], v[120:123]
	v_mfma_f32_16x16x32_bf16 v[104:107], v[168:171], v[210:213], v[104:107]
	v_mfma_f32_16x16x32_bf16 v[108:111], v[160:163], v[210:213], v[108:111]
	v_mfma_f32_16x16x32_bf16 v[92:95], v[160:163], v[218:221], v[92:95]
	v_mfma_f32_16x16x32_bf16 v[88:91], v[168:171], v[218:221], v[88:91]
	v_mfma_f32_16x16x32_bf16 v[72:75], v[168:171], v[226:229], v[72:75]
	v_mfma_f32_16x16x32_bf16 v[76:79], v[160:163], v[226:229], v[76:79]
	s_setprio 0
	s_setprio 1
	v_mfma_f32_16x16x32_bf16 v[116:119], v[172:175], v[198:201], v[116:119]
	v_mfma_f32_16x16x32_bf16 v[112:115], v[184:187], v[198:201], v[112:115]
	v_mfma_f32_16x16x32_bf16 v[96:99], v[184:187], v[206:209], v[96:99]
	v_mfma_f32_16x16x32_bf16 v[100:103], v[172:175], v[206:209], v[100:103]
	v_mfma_f32_16x16x32_bf16 v[84:87], v[172:175], v[214:217], v[84:87]
	v_mfma_f32_16x16x32_bf16 v[80:83], v[184:187], v[214:217], v[80:83]
	v_mfma_f32_16x16x32_bf16 v[64:67], v[184:187], v[222:225], v[64:67]
	v_mfma_f32_16x16x32_bf16 v[68:71], v[172:175], v[222:225], v[68:71]
	v_mfma_f32_16x16x32_bf16 v[116:119], v[180:183], v[202:205], v[116:119]
	v_mfma_f32_16x16x32_bf16 v[112:115], v[188:191], v[202:205], v[112:115]
	v_mfma_f32_16x16x32_bf16 v[96:99], v[188:191], v[210:213], v[96:99]
	v_mfma_f32_16x16x32_bf16 v[100:103], v[180:183], v[210:213], v[100:103]
	v_mfma_f32_16x16x32_bf16 v[84:87], v[180:183], v[218:221], v[84:87]
	v_mfma_f32_16x16x32_bf16 v[80:83], v[188:191], v[218:221], v[80:83]
	v_mfma_f32_16x16x32_bf16 v[64:67], v[188:191], v[226:229], v[64:67]
	v_mfma_f32_16x16x32_bf16 v[68:71], v[180:183], v[226:229], v[68:71]
	s_setprio 0
	s_barrier
; #define PG8_STAGE(bufoff, gbase, voff) do { _Pragma("unroll") for (int _i = 0; _i < 2; ++_i) \
;         __builtin_amdgcn_global_load_lds((const unsigned*)((const char*)(gbase) + (voff)[_i]), (PG8_LAS unsigned*)(lds + (bufoff) + ldsw + _i * 8192), 16, 0, 0); } while (0)
; #define PG8_LDA(dst, b, h) do { _Pragma("unroll") for (int m = 0; m < 4; ++m) _Pragma("unroll") for (int k = 0; k < 2; ++k) dst[m][k] = *(const PG8_LAS bf16x8*)(lds + PG8_SA(b, h) + aoff + m * 2048 + k * 1024); } while (0)
; #define PG8_LDB(dst, b, h) do { _Pragma("unroll") for (int n = 0; n < 2; ++n) _Pragma("unroll") for (int k = 0; k < 2; ++k) dst[n][k] = *(const PG8_LAS bf16x8*)(lds + PG8_SB(b, h) + boff + n * 2048 + k * 1024); } while (0)
; #define PG8_MMA(ai, bj, At, Bt) do { __builtin_amdgcn_s_setprio(1); _Pragma("unroll") for (int m = 0; m < 4; ++m) _Pragma("unroll") for (int n = 0; n < 2; ++n) _Pragma("unroll") for (int k = 0; k < 2; ++k) \
;         acc[ai][bj][m][n] = __builtin_amdgcn_mfma_f32_16x16x32_bf16(Bt[n][k], At[m][k], acc[ai][bj][m][n], 0, 0, 0); __builtin_amdgcn_s_setprio(0); } while (0)
; #define PG8_WAIT_V(n) asm volatile("s_waitcnt vmcnt(" #n ")" ::: "memory")
; #define PG8_WAIT_L(n) asm volatile("s_waitcnt lgkmcnt(" #n ")" ::: "memory")
; #define PG8_BAR __builtin_amdgcn_s_barrier()
; #define PG8_SCHED __builtin_amdgcn_sched_barrier(0)
; template <class Epi, class Sched, bool ALIGN_EPI = false, bool SP2 = false>
; __device__ __forceinline__ void gemm_phase(PG8_LAS unsigned char* lds, const Gemm g, const Sched& S, const Epi& E, int wave_in) {
;     ...
;         for (int t = 0; t < nt; t += 2) {
;             const bool last = (t == nt - 2);
;             const char* a1 = cA + (size_t)(t + 1) * kstep;
;             const char* a2 = last ? nA : cA + (size_t)(t + 2) * kstep; const char* b2 = last ? nB : cB + (size_t)(t + 2) * kstep;
;             const char* a3 = a2 + kstep; const char* b3 = b2 + kstep;
;             if (last && has_next) S.a_ready(nxt);
;             if constexpr (SP2) {
;             PG8_LDB(B0, 0, 0); PG8_LDB(B1, 0, 1); PG8_SCHED; PG8_LDA(At, 0, 0); PG8_STAGE(PG8_SA(1, 1), a1 + hstep, voffA);
;     ...
;             PG8_LDA(At, 1, 1); PG8_STAGE(PG8_SB(1, 0), b3, voffB); PG8_STAGE(PG8_SB(1, 1), b3 + hstep, voffB); PG8_STAGE(PG8_SA(1, 0), a3, voffA);
;             PG8_WAIT_V(8); PG8_WAIT_L(0); PG8_BAR; PG8_MMA(1, 0, At, B0); PG8_MMA(1, 1, At, B1); PG8_BAR; PG8_SCHED;
	s_add_i32 s10, s42, s66
	v_lshl_add_u64 v[230:231], v[230:231], 0, s[88:89]
	s_mov_b32 m0, s10
	ds_read_b128 v[198:201], v179 offset:49152
	ds_read_b128 v[202:205], v179 offset:50176
	ds_read_b128 v[206:209], v179 offset:51200
	ds_read_b128 v[210:213], v179 offset:52224
	ds_read_b128 v[214:217], v179 offset:53248
	ds_read_b128 v[218:221], v179 offset:54272
	ds_read_b128 v[222:225], v179 offset:55296
	ds_read_b128 v[226:229], v179 offset:56320
	global_load_lds_dwordx4 v[230:231], off
	s_add_i32 m0, s10, 0x2000
	s_add_u32 s4, s4, 0x40080
	v_lshl_add_u64 v[230:231], v[232:233], 0, s[88:89]
	s_addc_u32 s5, s5, 0
	s_add_i32 s10, s43, s66
	global_load_lds_dwordx4 v[230:231], off
	v_lshl_add_u64 v[230:231], s[4:5], 0, v[132:133]
	s_mov_b32 m0, s10
	s_nop 0
	global_load_lds_dwordx4 v[230:231], off
	v_lshl_add_u64 v[230:231], s[4:5], 0, v[128:129]
	s_add_i32 m0, s10, 0x2000
	s_nop 0
	global_load_lds_dwordx4 v[230:231], off
	v_lshl_add_u64 v[230:231], v[234:235], 0, s[88:89]
	s_mov_b32 m0, s72
	s_nop 0
	global_load_lds_dwordx4 v[230:231], off
	v_lshl_add_u64 v[230:231], v[236:237], 0, s[88:89]
	s_mov_b32 m0, s73
	s_nop 0
	global_load_lds_dwordx4 v[230:231], off
	s_waitcnt vmcnt(8)
	s_waitcnt lgkmcnt(0)
	s_barrier
	s_setprio 1
	s_waitcnt lgkmcnt(0)
	v_mfma_f32_16x16x32_bf16 v[60:63], v[156:159], v[198:201], v[60:63]
	v_mfma_f32_16x16x32_bf16 v[56:59], v[164:167], v[198:201], v[56:59]
	v_mfma_f32_16x16x32_bf16 v[40:43], v[164:167], v[206:209], v[40:43]
	v_mfma_f32_16x16x32_bf16 v[44:47], v[156:159], v[206:209], v[44:47]
	v_mfma_f32_16x16x32_bf16 v[28:31], v[156:159], v[214:217], v[28:31]
	v_mfma_f32_16x16x32_bf16 v[24:27], v[164:167], v[214:217], v[24:27]
	v_mfma_f32_16x16x32_bf16 v[8:11], v[164:167], v[222:225], v[8:11]
	v_mfma_f32_16x16x32_bf16 v[12:15], v[156:159], v[222:225], v[12:15]
	v_mfma_f32_16x16x32_bf16 v[60:63], v[160:163], v[202:205], v[60:63]
	v_mfma_f32_16x16x32_bf16 v[56:59], v[168:171], v[202:205], v[56:59]
	v_mfma_f32_16x16x32_bf16 v[40:43], v[168:171], v[210:213], v[40:43]
	v_mfma_f32_16x16x32_bf16 v[44:47], v[160:163], v[210:213], v[44:47]
	v_mfma_f32_16x16x32_bf16 v[28:31], v[160:163], v[218:221], v[28:31]
	v_mfma_f32_16x16x32_bf16 v[24:27], v[168:171], v[218:221], v[24:27]
	v_mfma_f32_16x16x32_bf16 v[8:11], v[168:171], v[226:229], v[8:11]
	v_mfma_f32_16x16x32_bf16 v[12:15], v[160:163], v[226:229], v[12:15]
	s_setprio 0
	s_setprio 1
	v_mfma_f32_16x16x32_bf16 v[52:55], v[172:175], v[198:201], v[52:55]
	v_mfma_f32_16x16x32_bf16 v[48:51], v[184:187], v[198:201], v[48:51]
	v_mfma_f32_16x16x32_bf16 v[32:35], v[184:187], v[206:209], v[32:35]
	v_mfma_f32_16x16x32_bf16 v[36:39], v[172:175], v[206:209], v[36:39]
	v_mfma_f32_16x16x32_bf16 v[20:23], v[172:175], v[214:217], v[20:23]
	v_mfma_f32_16x16x32_bf16 v[16:19], v[184:187], v[214:217], v[16:19]
	v_mfma_f32_16x16x32_bf16 v[0:3], v[184:187], v[222:225], v[0:3]
	v_mfma_f32_16x16x32_bf16 v[4:7], v[172:175], v[222:225], v[4:7]
	v_mfma_f32_16x16x32_bf16 v[52:55], v[180:183], v[202:205], v[52:55]
	v_mfma_f32_16x16x32_bf16 v[48:51], v[188:191], v[202:205], v[48:51]
	v_mfma_f32_16x16x32_bf16 v[32:35], v[188:191], v[210:213], v[32:35]
	v_mfma_f32_16x16x32_bf16 v[36:39], v[180:183], v[210:213], v[36:39]
	v_mfma_f32_16x16x32_bf16 v[20:23], v[180:183], v[218:221], v[20:23]
	v_mfma_f32_16x16x32_bf16 v[16:19], v[188:191], v[218:221], v[16:19]
	v_mfma_f32_16x16x32_bf16 v[0:3], v[188:191], v[226:229], v[0:3]
	v_mfma_f32_16x16x32_bf16 v[4:7], v[180:183], v[226:229], v[4:7]
	s_setprio 0
	s_barrier
	s_add_i32 s34, s34, 2
	s_add_u32 s31, s31, 0x100
	s_addc_u32 s33, s33, 0
	s_add_u32 s0, s0, 0x100
	s_addc_u32 s1, s1, 0
	s_cmp_gt_u32 s34, 13
	s_cbranch_scc1 .Lkexit_1
.LBB0_273:
	s_add_u32 s4, s0, 0xfffc0080
	s_addc_u32 s5, s1, -1
	s_add_i32 s42, s35, 0x100
	s_cmp_eq_u32 s34, 12
	s_cselect_b32 s11, s8, s5
	s_cselect_b32 s10, s9, s4
	s_cselect_b32 s5, s16, s33
	s_cselect_b32 s4, s17, s31
	s_add_i32 s44, s90, 0x100
	v_add_u32_e32 v168, s42, v177
	v_add_u32_e32 v188, s44, v177
	ds_read_b128 v[156:159], v168
	ds_read_b128 v[160:163], v168 offset:1024
	ds_read_b128 v[164:167], v168 offset:2048
	ds_read_b128 v[168:171], v168 offset:3072
	ds_read_b128 v[172:175], v188
	ds_read_b128 v[180:183], v188 offset:1024
	ds_read_b128 v[184:187], v188 offset:2048
	ds_read_b128 v[188:191], v188 offset:3072
	v_lshl_add_u64 v[230:231], s[0:1], 0, v[154:155]
	s_add_i32 m0, s67, 0xc000
	ds_read_b128 v[198:201], v179
	ds_read_b128 v[202:205], v179 offset:1024
	ds_read_b128 v[206:209], v179 offset:2048
	ds_read_b128 v[210:213], v179 offset:3072
	ds_read_b128 v[214:217], v179 offset:4096
	ds_read_b128 v[218:221], v179 offset:5120
	ds_read_b128 v[222:225], v179 offset:6144
	ds_read_b128 v[226:229], v179 offset:7168
	global_load_lds_dwordx4 v[230:231], off
	v_lshl_add_u64 v[230:231], s[0:1], 0, v[152:153]
	s_add_i32 m0, s67, 0xe000
	s_nop 0
	global_load_lds_dwordx4 v[230:231], off
	s_waitcnt vmcnt(8)
	s_waitcnt lgkmcnt(0)
	s_barrier
; #define PG8_STAGE(bufoff, gbase, voff) do { _Pragma("unroll") for (int _i = 0; _i < 2; ++_i) \
;         __builtin_amdgcn_global_load_lds((const unsigned*)((const char*)(gbase) + (voff)[_i]), (PG8_LAS unsigned*)(lds + (bufoff) + ldsw + _i * 8192), 16, 0, 0); } while (0)
; #define PG8_LDA(dst, b, h) do { _Pragma("unroll") for (int m = 0; m < 4; ++m) _Pragma("unroll") for (int k = 0; k < 2; ++k) dst[m][k] = *(const PG8_LAS bf16x8*)(lds + PG8_SA(b, h) + aoff + m * 2048 + k * 1024); } while (0)
; #define PG8_LDB(dst, b, h) do { _Pragma("unroll") for (int n = 0; n < 2; ++n) _Pragma("unroll") for (int k = 0; k < 2; ++k) dst[n][k] = *(const PG8_LAS bf16x8*)(lds + PG8_SB(b, h) + boff + n * 2048 + k * 1024); } while (0)
; #define PG8_MMA(ai, bj, At, Bt) do { __builtin_amdgcn_s_setprio(1); _Pragma("unroll") for (int m = 0; m < 4; ++m) _Pragma("unroll") for (int n = 0; n < 2; ++n) _Pragma("unroll") for (int k = 0; k < 2; ++k) \
;         acc[ai][bj][m][n] = __builtin_amdgcn_mfma_f32_16x16x32_bf16(Bt[n][k], At[m][k], acc[ai][bj][m][n], 0, 0, 0); __builtin_amdgcn_s_setprio(0); } while (0)
; #define PG8_WAIT_V(n) asm volatile("s_waitcnt vmcnt(" #n ")" ::: "memory")
; #define PG8_WAIT_L(n) asm volatile("s_waitcnt lgkmcnt(" #n ")" ::: "memory")
; #define PG8_BAR __builtin_amdgcn_s_barrier()
; #define PG8_SCHED __builtin_amdgcn_sched_barrier(0)
; template <class Epi, class Sched, bool ALIGN_EPI = false, bool SP2 = false>
; __device__ __forceinline__ void gemm_phase(PG8_LAS unsigned char* lds, const Gemm g, const Sched& S, const Epi& E, int wave_in) {
;     ...
;             PG8_LDB(B0, 0, 0); PG8_LDB(B1, 0, 1); PG8_SCHED; PG8_LDA(At, 0, 0); PG8_STAGE(PG8_SA(1, 1), a1 + hstep, voffA);
;             PG8_WAIT_V(8); PG8_WAIT_L(0); PG8_BAR; PG8_MMA(0, 0, At, B0); PG8_MMA(0, 1, At, B1); PG8_BAR; PG8_SCHED;
;             PG8_LDA(At, 0, 1); PG8_STAGE(PG8_SB(0, 0), b2, voffB); PG8_STAGE(PG8_SB(0, 1), b2 + hstep, voffB); PG8_STAGE(PG8_SA(0, 0), a2, voffA);
;             PG8_WAIT_V(8); PG8_WAIT_L(0); PG8_BAR; PG8_MMA(1, 0, At, B0); PG8_MMA(1, 1, At, B1); PG8_BAR; PG8_SCHED;
	s_setprio 1
	s_waitcnt lgkmcnt(0)
	v_mfma_f32_16x16x32_bf16 v[124:127], v[156:159], v[198:201], v[124:127]
	v_mfma_f32_16x16x32_bf16 v[120:123], v[164:167], v[198:201], v[120:123]
	v_mfma_f32_16x16x32_bf16 v[104:107], v[164:167], v[206:209], v[104:107]
	v_mfma_f32_16x16x32_bf16 v[108:111], v[156:159], v[206:209], v[108:111]
	v_mfma_f32_16x16x32_bf16 v[92:95], v[156:159], v[214:217], v[92:95]
	v_mfma_f32_16x16x32_bf16 v[88:91], v[164:167], v[214:217], v[88:91]
	v_mfma_f32_16x16x32_bf16 v[72:75], v[164:167], v[222:225], v[72:75]
	v_mfma_f32_16x16x32_bf16 v[76:79], v[156:159], v[222:225], v[76:79]
	v_mfma_f32_16x16x32_bf16 v[124:127], v[160:163], v[202:205], v[124:127]
	v_mfma_f32_16x16x32_bf16 v[120:123], v[168:171], v[202:205], v[120:123]
	v_mfma_f32_16x16x32_bf16 v[104:107], v[168:171], v[210:213], v[104:107]
	v_mfma_f32_16x16x32_bf16 v[108:111], v[160:163], v[210:213], v[108:111]
	v_mfma_f32_16x16x32_bf16 v[92:95], v[160:163], v[218:221], v[92:95]
	v_mfma_f32_16x16x32_bf16 v[88:91], v[168:171], v[218:221], v[88:91]
	v_mfma_f32_16x16x32_bf16 v[72:75], v[168:171], v[226:229], v[72:75]
	v_mfma_f32_16x16x32_bf16 v[76:79], v[160:163], v[226:229], v[76:79]
	s_setprio 0
	s_setprio 1
	v_mfma_f32_16x16x32_bf16 v[116:119], v[172:175], v[198:201], v[116:119]
	v_mfma_f32_16x16x32_bf16 v[112:115], v[184:187], v[198:201], v[112:115]
	v_mfma_f32_16x16x32_bf16 v[96:99], v[184:187], v[206:209], v[96:99]
	v_mfma_f32_16x16x32_bf16 v[100:103], v[172:175], v[206:209], v[100:103]
	v_mfma_f32_16x16x32_bf16 v[84:87], v[172:175], v[214:217], v[84:87]
	v_mfma_f32_16x16x32_bf16 v[80:83], v[184:187], v[214:217], v[80:83]
	v_mfma_f32_16x16x32_bf16 v[64:67], v[184:187], v[222:225], v[64:67]
	v_mfma_f32_16x16x32_bf16 v[68:71], v[172:175], v[222:225], v[68:71]
	v_mfma_f32_16x16x32_bf16 v[116:119], v[180:183], v[202:205], v[116:119]
	v_mfma_f32_16x16x32_bf16 v[112:115], v[188:191], v[202:205], v[112:115]
	v_mfma_f32_16x16x32_bf16 v[96:99], v[188:191], v[210:213], v[96:99]
	v_mfma_f32_16x16x32_bf16 v[100:103], v[180:183], v[210:213], v[100:103]
	v_mfma_f32_16x16x32_bf16 v[84:87], v[180:183], v[218:221], v[84:87]
	v_mfma_f32_16x16x32_bf16 v[80:83], v[188:191], v[218:221], v[80:83]
	v_mfma_f32_16x16x32_bf16 v[64:67], v[188:191], v[226:229], v[64:67]
	v_mfma_f32_16x16x32_bf16 v[68:71], v[180:183], v[226:229], v[68:71]
	s_setprio 0
	s_barrier
	s_add_i32 s42, s42, s66
	v_lshl_add_u64 v[230:231], s[4:5], 0, v[132:133]
	s_mov_b32 m0, s42
	ds_read_b128 v[198:201], v179 offset:16384
	ds_read_b128 v[202:205], v179 offset:17408
	ds_read_b128 v[206:209], v179 offset:18432
	ds_read_b128 v[210:213], v179 offset:19456
	ds_read_b128 v[214:217], v179 offset:20480
	ds_read_b128 v[218:221], v179 offset:21504
	ds_read_b128 v[222:225], v179 offset:22528
	ds_read_b128 v[226:229], v179 offset:23552
	global_load_lds_dwordx4 v[230:231], off
	s_add_i32 m0, s42, 0x2000
	s_add_u32 s42, s4, 0x40000
	v_lshl_add_u64 v[232:233], s[4:5], 0, v[128:129]
	s_addc_u32 s43, s5, 0
	s_add_i32 s44, s44, s66
	global_load_lds_dwordx4 v[232:233], off
	v_lshl_add_u64 v[234:235], s[42:43], 0, v[132:133]
	s_mov_b32 m0, s44
	v_lshl_add_u64 v[236:237], s[10:11], 0, v[130:131]
	global_load_lds_dwordx4 v[234:235], off
	v_lshl_add_u64 v[234:235], s[42:43], 0, v[128:129]
	s_add_i32 m0, s44, 0x2000
	s_nop 0
	global_load_lds_dwordx4 v[234:235], off
	v_lshl_add_u64 v[234:235], s[10:11], 0, v[134:135]
	s_mov_b32 m0, s67
	s_nop 0
	global_load_lds_dwordx4 v[234:235], off
	s_mov_b32 m0, s78
	s_nop 0
	global_load_lds_dwordx4 v[236:237], off
	s_waitcnt vmcnt(8)
	s_waitcnt lgkmcnt(0)
	s_barrier
	s_setprio 1
	s_waitcnt lgkmcnt(0)
	v_mfma_f32_16x16x32_bf16 v[60:63], v[156:159], v[198:201], v[60:63]
	v_mfma_f32_16x16x32_bf16 v[56:59], v[164:167], v[198:201], v[56:59]
	v_mfma_f32_16x16x32_bf16 v[40:43], v[164:167], v[206:209], v[40:43]
	v_mfma_f32_16x16x32_bf16 v[44:47], v[156:159], v[206:209], v[44:47]
	v_mfma_f32_16x16x32_bf16 v[28:31], v[156:159], v[214:217], v[28:31]
	v_mfma_f32_16x16x32_bf16 v[24:27], v[164:167], v[214:217], v[24:27]
	v_mfma_f32_16x16x32_bf16 v[8:11], v[164:167], v[222:225], v[8:11]
	v_mfma_f32_16x16x32_bf16 v[12:15], v[156:159], v[222:225], v[12:15]
	v_mfma_f32_16x16x32_bf16 v[60:63], v[160:163], v[202:205], v[60:63]
	v_mfma_f32_16x16x32_bf16 v[56:59], v[168:171], v[202:205], v[56:59]
	v_mfma_f32_16x16x32_bf16 v[40:43], v[168:171], v[210:213], v[40:43]
	v_mfma_f32_16x16x32_bf16 v[44:47], v[160:163], v[210:213], v[44:47]
	v_mfma_f32_16x16x32_bf16 v[28:31], v[160:163], v[218:221], v[28:31]
	v_mfma_f32_16x16x32_bf16 v[24:27], v[168:171], v[218:221], v[24:27]
	v_mfma_f32_16x16x32_bf16 v[8:11], v[168:171], v[226:229], v[8:11]
	v_mfma_f32_16x16x32_bf16 v[12:15], v[160:163], v[226:229], v[12:15]
	s_setprio 0
	s_setprio 1
	v_mfma_f32_16x16x32_bf16 v[52:55], v[172:175], v[198:201], v[52:55]
	v_mfma_f32_16x16x32_bf16 v[48:51], v[184:187], v[198:201], v[48:51]
	v_mfma_f32_16x16x32_bf16 v[32:35], v[184:187], v[206:209], v[32:35]
	v_mfma_f32_16x16x32_bf16 v[36:39], v[172:175], v[206:209], v[36:39]
	v_mfma_f32_16x16x32_bf16 v[20:23], v[172:175], v[214:217], v[20:23]
	v_mfma_f32_16x16x32_bf16 v[16:19], v[184:187], v[214:217], v[16:19]
	v_mfma_f32_16x16x32_bf16 v[0:3], v[184:187], v[222:225], v[0:3]
	v_mfma_f32_16x16x32_bf16 v[4:7], v[172:175], v[222:225], v[4:7]
	v_mfma_f32_16x16x32_bf16 v[52:55], v[180:183], v[202:205], v[52:55]
	v_mfma_f32_16x16x32_bf16 v[48:51], v[188:191], v[202:205], v[48:51]
	v_mfma_f32_16x16x32_bf16 v[32:35], v[188:191], v[210:213], v[32:35]
	v_mfma_f32_16x16x32_bf16 v[36:39], v[180:183], v[210:213], v[36:39]
	v_mfma_f32_16x16x32_bf16 v[20:23], v[180:183], v[218:221], v[20:23]
	v_mfma_f32_16x16x32_bf16 v[16:19], v[188:191], v[218:221], v[16:19]
	v_mfma_f32_16x16x32_bf16 v[0:3], v[188:191], v[226:229], v[0:3]
	v_mfma_f32_16x16x32_bf16 v[4:7], v[180:183], v[226:229], v[4:7]
	s_setprio 0
	s_barrier
; #define PG8_STAGE(bufoff, gbase, voff) do { _Pragma("unroll") for (int _i = 0; _i < 2; ++_i) \
;         __builtin_amdgcn_global_load_lds((const unsigned*)((const char*)(gbase) + (voff)[_i]), (PG8_LAS unsigned*)(lds + (bufoff) + ldsw + _i * 8192), 16, 0, 0); } while (0)
; #define PG8_LDA(dst, b, h) do { _Pragma("unroll") for (int m = 0; m < 4; ++m) _Pragma("unroll") for (int k = 0; k < 2; ++k) dst[m][k] = *(const PG8_LAS bf16x8*)(lds + PG8_SA(b, h) + aoff + m * 2048 + k * 1024); } while (0)
; #define PG8_LDB(dst, b, h) do { _Pragma("unroll") for (int n = 0; n < 2; ++n) _Pragma("unroll") for (int k = 0; k < 2; ++k) dst[n][k] = *(const PG8_LAS bf16x8*)(lds + PG8_SB(b, h) + boff + n * 2048 + k * 1024); } while (0)
; #define PG8_MMA(ai, bj, At, Bt) do { __builtin_amdgcn_s_setprio(1); _Pragma("unroll") for (int m = 0; m < 4; ++m) _Pragma("unroll") for (int n = 0; n < 2; ++n) _Pragma("unroll") for (int k = 0; k < 2; ++k) \
;         acc[ai][bj][m][n] = __builtin_amdgcn_mfma_f32_16x16x32_bf16(Bt[n][k], At[m][k], acc[ai][bj][m][n], 0, 0, 0); __builtin_amdgcn_s_setprio(0); } while (0)
; #define PG8_WAIT_V(n) asm volatile("s_waitcnt vmcnt(" #n ")" ::: "memory")
; #define PG8_WAIT_L(n) asm volatile("s_waitcnt lgkmcnt(" #n ")" ::: "memory")
; #define PG8_BAR __builtin_amdgcn_s_barrier()
; #define PG8_SCHED __builtin_amdgcn_sched_barrier(0)
; template <class Epi, class Sched, bool ALIGN_EPI = false, bool SP2 = false>
; __device__ __forceinline__ void gemm_phase(PG8_LAS unsigned char* lds, const Gemm g, const Sched& S, const Epi& E, int wave_in) {
;     ...
;             PG8_LDB(B0, 1, 0); PG8_LDB(B1, 1, 1); PG8_SCHED; PG8_LDA(At, 1, 0); PG8_STAGE(PG8_SA(0, 1), a2 + hstep, voffA);
;             PG8_WAIT_V(8); PG8_WAIT_L(0); PG8_BAR; PG8_MMA(0, 0, At, B0); PG8_MMA(0, 1, At, B1); PG8_BAR; PG8_SCHED;
	s_add_i32 s42, s65, 0x100
	s_add_i32 s43, s52, 0x100
	v_add_u32_e32 v168, s42, v177
	v_add_u32_e32 v188, s43, v177
	ds_read_b128 v[156:159], v168
	ds_read_b128 v[160:163], v168 offset:1024
	ds_read_b128 v[164:167], v168 offset:2048
	ds_read_b128 v[168:171], v168 offset:3072
	ds_read_b128 v[172:175], v188
	ds_read_b128 v[180:183], v188 offset:1024
	ds_read_b128 v[184:187], v188 offset:2048
	ds_read_b128 v[188:191], v188 offset:3072
	s_add_u32 s10, s10, 0x40000
	s_addc_u32 s11, s11, 0
	s_mov_b32 m0, s79
	v_lshl_add_u64 v[238:239], s[10:11], 0, v[134:135]
	ds_read_b128 v[198:201], v179 offset:32768
	ds_read_b128 v[202:205], v179 offset:33792
	ds_read_b128 v[206:209], v179 offset:34816
	ds_read_b128 v[210:213], v179 offset:35840
	ds_read_b128 v[214:217], v179 offset:36864
	ds_read_b128 v[218:221], v179 offset:37888
	ds_read_b128 v[222:225], v179 offset:38912
	ds_read_b128 v[226:229], v179 offset:39936
	global_load_lds_dwordx4 v[238:239], off
	v_lshl_add_u64 v[238:239], s[10:11], 0, v[130:131]
	s_mov_b32 m0, s82
	s_nop 0
	global_load_lds_dwordx4 v[238:239], off
	s_waitcnt vmcnt(8)
	s_waitcnt lgkmcnt(0)
	s_barrier
	s_setprio 1
	s_waitcnt lgkmcnt(0)
	v_mfma_f32_16x16x32_bf16 v[124:127], v[156:159], v[198:201], v[124:127]
	v_mfma_f32_16x16x32_bf16 v[120:123], v[164:167], v[198:201], v[120:123]
	v_mfma_f32_16x16x32_bf16 v[104:107], v[164:167], v[206:209], v[104:107]
	v_mfma_f32_16x16x32_bf16 v[108:111], v[156:159], v[206:209], v[108:111]
	v_mfma_f32_16x16x32_bf16 v[92:95], v[156:159], v[214:217], v[92:95]
	v_mfma_f32_16x16x32_bf16 v[88:91], v[164:167], v[214:217], v[88:91]
	v_mfma_f32_16x16x32_bf16 v[72:75], v[164:167], v[222:225], v[72:75]
	v_mfma_f32_16x16x32_bf16 v[76:79], v[156:159], v[222:225], v[76:79]
	v_mfma_f32_16x16x32_bf16 v[124:127], v[160:163], v[202:205], v[124:127]
	v_mfma_f32_16x16x32_bf16 v[120:123], v[168:171], v[202:205], v[120:123]
	v_mfma_f32_16x16x32_bf16 v[104:107], v[168:171], v[210:213], v[104:107]
	v_mfma_f32_16x16x32_bf16 v[108:111], v[160:163], v[210:213], v[108:111]
	v_mfma_f32_16x16x32_bf16 v[92:95], v[160:163], v[218:221], v[92:95]
	v_mfma_f32_16x16x32_bf16 v[88:91], v[168:171], v[218:221], v[88:91]
	v_mfma_f32_16x16x32_bf16 v[72:75], v[168:171], v[226:229], v[72:75]
	v_mfma_f32_16x16x32_bf16 v[76:79], v[160:163], v[226:229], v[76:79]
	s_setprio 0
	s_setprio 1
	v_mfma_f32_16x16x32_bf16 v[116:119], v[172:175], v[198:201], v[116:119]
	v_mfma_f32_16x16x32_bf16 v[112:115], v[184:187], v[198:201], v[112:115]
	v_mfma_f32_16x16x32_bf16 v[96:99], v[184:187], v[206:209], v[96:99]
	v_mfma_f32_16x16x32_bf16 v[100:103], v[172:175], v[206:209], v[100:103]
	v_mfma_f32_16x16x32_bf16 v[84:87], v[172:175], v[214:217], v[84:87]
	v_mfma_f32_16x16x32_bf16 v[80:83], v[184:187], v[214:217], v[80:83]
	v_mfma_f32_16x16x32_bf16 v[64:67], v[184:187], v[222:225], v[64:67]
	v_mfma_f32_16x16x32_bf16 v[68:71], v[172:175], v[222:225], v[68:71]
	v_mfma_f32_16x16x32_bf16 v[116:119], v[180:183], v[202:205], v[116:119]
	v_mfma_f32_16x16x32_bf16 v[112:115], v[188:191], v[202:205], v[112:115]
	v_mfma_f32_16x16x32_bf16 v[96:99], v[188:191], v[210:213], v[96:99]
	v_mfma_f32_16x16x32_bf16 v[100:103], v[180:183], v[210:213], v[100:103]
	v_mfma_f32_16x16x32_bf16 v[84:87], v[180:183], v[218:221], v[84:87]
	v_mfma_f32_16x16x32_bf16 v[80:83], v[188:191], v[218:221], v[80:83]
	v_mfma_f32_16x16x32_bf16 v[64:67], v[188:191], v[226:229], v[64:67]
	v_mfma_f32_16x16x32_bf16 v[68:71], v[180:183], v[226:229], v[68:71]
	s_setprio 0
	s_barrier
; #define PG8_STAGE(bufoff, gbase, voff) do { _Pragma("unroll") for (int _i = 0; _i < 2; ++_i) \
;         __builtin_amdgcn_global_load_lds((const unsigned*)((const char*)(gbase) + (voff)[_i]), (PG8_LAS unsigned*)(lds + (bufoff) + ldsw + _i * 8192), 16, 0, 0); } while (0)
; #define PG8_LDA(dst, b, h) do { _Pragma("unroll") for (int m = 0; m < 4; ++m) _Pragma("unroll") for (int k = 0; k < 2; ++k) dst[m][k] = *(const PG8_LAS bf16x8*)(lds + PG8_SA(b, h) + aoff + m * 2048 + k * 1024); } while (0)
; #define PG8_MMA(ai, bj, At, Bt) do { __builtin_amdgcn_s_setprio(1); _Pragma("unroll") for (int m = 0; m < 4; ++m) _Pragma("unroll") for (int n = 0; n < 2; ++n) _Pragma("unroll") for (int k = 0; k < 2; ++k) \
;         acc[ai][bj][m][n] = __builtin_amdgcn_mfma_f32_16x16x32_bf16(Bt[n][k], At[m][k], acc[ai][bj][m][n], 0, 0, 0); __builtin_amdgcn_s_setprio(0); } while (0)
; #define PG8_WAIT_V(n) asm volatile("s_waitcnt vmcnt(" #n ")" ::: "memory")
; #define PG8_WAIT_L(n) asm volatile("s_waitcnt lgkmcnt(" #n ")" ::: "memory")
; #define PG8_BAR __builtin_amdgcn_s_barrier()
; #define PG8_SCHED __builtin_amdgcn_sched_barrier(0)
; template <class Epi, class Sched, bool ALIGN_EPI = false, bool SP2 = false>
; __device__ __forceinline__ void gemm_phase(PG8_LAS unsigned char* lds, const Gemm g, const Sched& S, const Epi& E, int wave_in) {
;     ...
;         for (int t = 0; t < nt; t += 2) {
;     ...
;             PG8_LDA(At, 1, 1); PG8_STAGE(PG8_SB(1, 0), b3, voffB); PG8_STAGE(PG8_SB(1, 1), b3 + hstep, voffB); PG8_STAGE(PG8_SA(1, 0), a3, voffA);
;             PG8_WAIT_V(8); PG8_WAIT_L(0); PG8_BAR; PG8_MMA(1, 0, At, B0); PG8_MMA(1, 1, At, B1); PG8_BAR; PG8_SCHED;
	s_add_i32 s10, s42, s66
	v_lshl_add_u64 v[230:231], v[230:231], 0, s[88:89]
	s_mov_b32 m0, s10
	ds_read_b128 v[198:201], v179 offset:49152
	ds_read_b128 v[202:205], v179 offset:50176
	ds_read_b128 v[206:209], v179 offset:51200
	ds_read_b128 v[210:213], v179 offset:52224
	ds_read_b128 v[214:217], v179 offset:53248
	ds_read_b128 v[218:221], v179 offset:54272
	ds_read_b128 v[222:225], v179 offset:55296
	ds_read_b128 v[226:229], v179 offset:56320
	global_load_lds_dwordx4 v[230:231], off
	s_add_i32 m0, s10, 0x2000
	s_add_u32 s4, s4, 0x40080
	v_lshl_add_u64 v[230:231], v[232:233], 0, s[88:89]
	s_addc_u32 s5, s5, 0
	s_add_i32 s10, s43, s66
	global_load_lds_dwordx4 v[230:231], off
	v_lshl_add_u64 v[230:231], s[4:5], 0, v[132:133]
	s_mov_b32 m0, s10
	s_nop 0
	global_load_lds_dwordx4 v[230:231], off
	v_lshl_add_u64 v[230:231], s[4:5], 0, v[128:129]
	s_add_i32 m0, s10, 0x2000
	s_nop 0
	global_load_lds_dwordx4 v[230:231], off
	v_lshl_add_u64 v[230:231], v[234:235], 0, s[88:89]
	s_mov_b32 m0, s72
	s_nop 0
	global_load_lds_dwordx4 v[230:231], off
	v_lshl_add_u64 v[230:231], v[236:237], 0, s[88:89]
	s_mov_b32 m0, s73
	s_nop 0
	global_load_lds_dwordx4 v[230:231], off
	s_waitcnt vmcnt(8)
	s_waitcnt lgkmcnt(0)
	s_barrier
	s_setprio 1
	s_waitcnt lgkmcnt(0)
	v_mfma_f32_16x16x32_bf16 v[60:63], v[156:159], v[198:201], v[60:63]
	v_mfma_f32_16x16x32_bf16 v[56:59], v[164:167], v[198:201], v[56:59]
	v_mfma_f32_16x16x32_bf16 v[40:43], v[164:167], v[206:209], v[40:43]
	v_mfma_f32_16x16x32_bf16 v[44:47], v[156:159], v[206:209], v[44:47]
	v_mfma_f32_16x16x32_bf16 v[28:31], v[156:159], v[214:217], v[28:31]
	v_mfma_f32_16x16x32_bf16 v[24:27], v[164:167], v[214:217], v[24:27]
	v_mfma_f32_16x16x32_bf16 v[8:11], v[164:167], v[222:225], v[8:11]
	v_mfma_f32_16x16x32_bf16 v[12:15], v[156:159], v[222:225], v[12:15]
	v_mfma_f32_16x16x32_bf16 v[60:63], v[160:163], v[202:205], v[60:63]
	v_mfma_f32_16x16x32_bf16 v[56:59], v[168:171], v[202:205], v[56:59]
	v_mfma_f32_16x16x32_bf16 v[40:43], v[168:171], v[210:213], v[40:43]
	v_mfma_f32_16x16x32_bf16 v[44:47], v[160:163], v[210:213], v[44:47]
	v_mfma_f32_16x16x32_bf16 v[28:31], v[160:163], v[218:221], v[28:31]
	v_mfma_f32_16x16x32_bf16 v[24:27], v[168:171], v[218:221], v[24:27]
	v_mfma_f32_16x16x32_bf16 v[8:11], v[168:171], v[226:229], v[8:11]
	v_mfma_f32_16x16x32_bf16 v[12:15], v[160:163], v[226:229], v[12:15]
	s_setprio 0
	s_setprio 1
	v_mfma_f32_16x16x32_bf16 v[52:55], v[172:175], v[198:201], v[52:55]
	v_mfma_f32_16x16x32_bf16 v[48:51], v[184:187], v[198:201], v[48:51]
	v_mfma_f32_16x16x32_bf16 v[32:35], v[184:187], v[206:209], v[32:35]
	v_mfma_f32_16x16x32_bf16 v[36:39], v[172:175], v[206:209], v[36:39]
	v_mfma_f32_16x16x32_bf16 v[20:23], v[172:175], v[214:217], v[20:23]
	v_mfma_f32_16x16x32_bf16 v[16:19], v[184:187], v[214:217], v[16:19]
	v_mfma_f32_16x16x32_bf16 v[0:3], v[184:187], v[222:225], v[0:3]
	v_mfma_f32_16x16x32_bf16 v[4:7], v[172:175], v[222:225], v[4:7]
	v_mfma_f32_16x16x32_bf16 v[52:55], v[180:183], v[202:205], v[52:55]
	v_mfma_f32_16x16x32_bf16 v[48:51], v[188:191], v[202:205], v[48:51]
	v_mfma_f32_16x16x32_bf16 v[32:35], v[188:191], v[210:213], v[32:35]
	v_mfma_f32_16x16x32_bf16 v[36:39], v[180:183], v[210:213], v[36:39]
	v_mfma_f32_16x16x32_bf16 v[20:23], v[180:183], v[218:221], v[20:23]
	v_mfma_f32_16x16x32_bf16 v[16:19], v[188:191], v[218:221], v[16:19]
	v_mfma_f32_16x16x32_bf16 v[0:3], v[188:191], v[226:229], v[0:3]
	v_mfma_f32_16x16x32_bf16 v[4:7], v[180:183], v[226:229], v[4:7]
	s_setprio 0
	s_barrier
	s_add_i32 s34, s34, 2
	s_add_u32 s31, s31, 0x100
	s_addc_u32 s33, s33, 0
	s_add_u32 s0, s0, 0x100
	s_addc_u32 s1, s1, 0
	s_cmp_gt_u32 s34, 13
	s_cbranch_scc0 .LBB0_273

; #define PG8_WAIT_V(n) asm volatile("s_waitcnt vmcnt(" #n ")" ::: "memory")
; template <class Epi, class Sched, bool ALIGN_EPI = false, bool SP2 = false>
; __device__ __forceinline__ void gemm_phase(PG8_LAS unsigned char* lds, const Gemm g, const Sched& S, const Epi& E, int wave_in) {
;     ...
;         for (int t = 0; t < nt; t += 2) {
;             const bool last = (t == nt - 2);
;             const char* a1 = cA + (size_t)(t + 1) * kstep;
;             const char* a2 = last ? nA : cA + (size_t)(t + 2) * kstep; const char* b2 = last ? nB : cB + (size_t)(t + 2) * kstep;
;             const char* a3 = a2 + kstep; const char* b3 = b2 + kstep;
;             if (last && has_next) S.a_ready(nxt);
;             if constexpr (SP2) {
;             PG8_LDB(B0, 0, 0); PG8_LDB(B1, 0, 1); PG8_SCHED; PG8_LDA(At, 0, 0); PG8_STAGE(PG8_SA(1, 1), a1 + hstep, voffA);
;             PG8_WAIT_V(8); PG8_WAIT_L(0); PG8_BAR; PG8_MMA(0, 0, At, B0); PG8_MMA(0, 1, At, B1); PG8_BAR; PG8_SCHED;
;             PG8_LDA(At, 0, 1); PG8_STAGE(PG8_SB(0, 0), b2, voffB); PG8_STAGE(PG8_SB(0, 1), b2 + hstep, voffB); PG8_STAGE(PG8_SA(0, 0), a2, voffA);
; __global__ void __launch_bounds__(512, 2) fwd_megakernel(Args a) {
;     ...
;             for (int cq = 0; cq < (grouped ? 2 : DEPTH * 64); ++cq) {
;                 const int ci = grouped ? (((cq * 8 + (gj >> 2)) >> 2) << 5) | (grp << 2) | ((cq * 8 + (gj >> 2)) & 3) : cq;
;                 const int l2 = ci >> 6, isvw = (ci >> 5) & 1, bh = ci & 31, b = bh >> 2, h = bh & 3; unsigned char* wl2 = ws + WS_W + (size_t)l2 * W_LAYER;
;                 const bf16* Khd = (const bf16*)(ws + (isvw ? WS_VT : WS_KB) + (size_t)l2 * 4 * MiB) + (size_t)(b * 4 + h) * 65536;
;                 const bf16* Whd = (const bf16*)(wl2 + (isvw ? W_O : W_Q)) + (size_t)h * D * 256;
;                 pg8::Gemm g{isvw ? Whd : Khd, isvw ? Khd : Whd, isvw ? D : 256, isvw ? 256 : D, 256, 0, 0};
;                 pg8::StaticOrder S; S.init(g.M, g.N, G, grouped ? (gj & 3) : (bx + G - (4 * ci) % G) % G);
;                 bf16* Od = (bf16*)(ws + (isvw ? WS_VWT : WS_GT) + (size_t)l2 * 16 * MiB + (size_t)b * 2 * MiB) + (isvw ? (size_t)h * 256 : (size_t)h * 256 * D);
;                 pg8::EpiBf16S E{Od, D, (size_t)256 * D, (size_t)256, nullptr, 1.0f, 1 << 30, nullptr, 1 << 30};
;                 pg8::gemm_phase<pg8::EpiBf16S, pg8::StaticOrder, GEMM_ALIGN, GEMM_SP2>(lds, g, S, E, wave_s);
.LBB0_484:
	s_ashr_i32 s15, s14, 31
	s_lshl_b64 s[16:17], s[14:15], 17
	s_add_u32 s16, s47, s16
	s_addc_u32 s17, s46, s17
	s_and_b64 s[18:19], s[10:11], exec
	s_cselect_b32 s15, s17, s25
	s_cselect_b32 s21, s16, s24
	s_ashr_i32 s13, s12, 31
	s_lshl_b64 s[18:19], s[12:13], 17
	s_add_u32 s18, s63, s18
	s_addc_u32 s19, s62, s19
	s_and_b64 s[38:39], s[10:11], exec
	s_cselect_b32 s13, s19, s23
	s_cselect_b32 s27, s18, s22
	s_mov_b32 s34, 0
	s_mov_b64 s[38:39], -1
	s_mov_b64 s[40:41], 0
	s_add_u32 s53, s24, s34
	s_addc_u32 s66, s25, 0
	s_add_u32 s44, s53, 0x100
	s_addc_u32 s45, s66, 0
	s_and_b64 s[42:43], s[40:41], exec
	s_cselect_b32 s45, s15, s45
	s_cselect_b32 s44, s21, s44
	s_add_u32 s34, s22, s34
	s_addc_u32 s42, s23, 0
	s_add_u32 s34, s34, 0x100
	s_addc_u32 s42, s42, 0
	s_add_i32 s97, s35, 0x100
	s_and_b64 s[40:41], s[40:41], exec
	s_cselect_b32 s61, s13, s42
	s_cselect_b32 s60, s27, s34
	s_add_i32 s41, s90, 0x100
	s_add_u32 s76, s53, 0x10080
	s_addc_u32 s77, s66, 0
	s_add_i32 s96, s97, s72
	s_add_i32 m0, s75, 0xc000
	s_add_i32 vcc_hi, s75, 0xe000
	s_add_i32 s81, s96, 0x2000
	s_add_u32 s66, s60, 0x10000
	v_add_u32_e32 v166, s97, v152
	v_add_u32_e32 v182, s41, v152
	s_addc_u32 s67, s61, 0
	s_add_i32 s95, s41, s72
	ds_read_b128 v[154:157], v166
	ds_read_b128 v[158:161], v166 offset:1024
	ds_read_b128 v[162:165], v166 offset:2048
	ds_read_b128 v[166:169], v166 offset:3072
	ds_read_b128 v[170:173], v182
	ds_read_b128 v[174:177], v182 offset:1024
	ds_read_b128 v[178:181], v182 offset:2048
	ds_read_b128 v[182:185], v182 offset:3072
	s_add_i32 s94, s95, 0x2000
	s_add_i32 s71, s65, 0x100
	s_add_i32 s69, s52, 0x100
	s_add_u32 s42, s44, 0x10000
	s_addc_u32 s43, s45, 0
	s_add_i32 s53, s71, s72
	s_add_i32 s34, s53, 0x2000
	s_add_u32 s40, s60, 0x10080
	s_addc_u32 s41, s61, 0
	s_add_i32 vcc_lo, s69, s72
	s_add_i32 s97, vcc_lo, 0x2000
	v_lshl_add_u64 v[190:191], s[76:77], 0, v[134:135]
	ds_read_b128 v[186:189], v153
	ds_read_b128 v[198:201], v153 offset:1024
	ds_read_b128 v[202:205], v153 offset:2048
	ds_read_b128 v[206:209], v153 offset:3072
	ds_read_b128 v[210:213], v153 offset:4096
	ds_read_b128 v[214:217], v153 offset:5120
	ds_read_b128 v[218:221], v153 offset:6144
	ds_read_b128 v[222:225], v153 offset:7168
	global_load_lds_dwordx4 v[190:191], off
	v_lshl_add_u64 v[190:191], s[76:77], 0, v[130:131]
	s_mov_b32 m0, vcc_hi
	s_nop 0
	global_load_lds_dwordx4 v[190:191], off
	s_waitcnt vmcnt(8)
	s_waitcnt lgkmcnt(0)
	s_barrier
	s_setprio 1
	s_waitcnt lgkmcnt(0)
	v_mfma_f32_16x16x32_bf16 v[124:127], v[154:157], v[186:189], 0
	v_mfma_f32_16x16x32_bf16 v[120:123], v[162:165], v[186:189], 0
	v_mfma_f32_16x16x32_bf16 v[108:111], v[162:165], v[202:205], 0
	v_mfma_f32_16x16x32_bf16 v[116:119], v[154:157], v[202:205], 0
	v_mfma_f32_16x16x32_bf16 v[100:103], v[154:157], v[210:213], 0
	v_mfma_f32_16x16x32_bf16 v[92:95], v[162:165], v[210:213], 0
	v_mfma_f32_16x16x32_bf16 v[76:79], v[162:165], v[218:221], 0
	v_mfma_f32_16x16x32_bf16 v[84:87], v[154:157], v[218:221], 0
	v_mfma_f32_16x16x32_bf16 v[124:127], v[158:161], v[198:201], v[124:127]
	v_mfma_f32_16x16x32_bf16 v[120:123], v[166:169], v[198:201], v[120:123]
	v_mfma_f32_16x16x32_bf16 v[108:111], v[166:169], v[206:209], v[108:111]
	v_mfma_f32_16x16x32_bf16 v[116:119], v[158:161], v[206:209], v[116:119]
	v_mfma_f32_16x16x32_bf16 v[100:103], v[158:161], v[214:217], v[100:103]
	v_mfma_f32_16x16x32_bf16 v[92:95], v[166:169], v[214:217], v[92:95]
	v_mfma_f32_16x16x32_bf16 v[76:79], v[166:169], v[222:225], v[76:79]
	v_mfma_f32_16x16x32_bf16 v[84:87], v[158:161], v[222:225], v[84:87]
	s_setprio 0
	s_setprio 1
	v_mfma_f32_16x16x32_bf16 v[112:115], v[170:173], v[186:189], 0
	v_mfma_f32_16x16x32_bf16 v[104:107], v[178:181], v[186:189], 0
	v_mfma_f32_16x16x32_bf16 v[88:91], v[178:181], v[202:205], 0
	v_mfma_f32_16x16x32_bf16 v[96:99], v[170:173], v[202:205], 0
	v_mfma_f32_16x16x32_bf16 v[80:83], v[170:173], v[210:213], 0
	v_mfma_f32_16x16x32_bf16 v[72:75], v[178:181], v[210:213], 0
	v_mfma_f32_16x16x32_bf16 v[64:67], v[178:181], v[218:221], 0
	v_mfma_f32_16x16x32_bf16 v[68:71], v[170:173], v[218:221], 0
	v_mfma_f32_16x16x32_bf16 v[112:115], v[174:177], v[198:201], v[112:115]
	v_mfma_f32_16x16x32_bf16 v[104:107], v[182:185], v[198:201], v[104:107]
	v_mfma_f32_16x16x32_bf16 v[88:91], v[182:185], v[206:209], v[88:91]
	v_mfma_f32_16x16x32_bf16 v[96:99], v[174:177], v[206:209], v[96:99]
	v_mfma_f32_16x16x32_bf16 v[80:83], v[174:177], v[214:217], v[80:83]
	v_mfma_f32_16x16x32_bf16 v[72:75], v[182:185], v[214:217], v[72:75]
	v_mfma_f32_16x16x32_bf16 v[64:67], v[182:185], v[222:225], v[64:67]
	v_mfma_f32_16x16x32_bf16 v[68:71], v[174:177], v[222:225], v[68:71]
	s_setprio 0
	s_barrier
	s_mov_b32 m0, s96
	v_lshl_add_u64 v[190:191], s[60:61], 0, v[132:133]
	ds_read_b128 v[186:189], v153 offset:16384
	ds_read_b128 v[198:201], v153 offset:17408
	ds_read_b128 v[202:205], v153 offset:18432
	ds_read_b128 v[206:209], v153 offset:19456
	ds_read_b128 v[210:213], v153 offset:20480
	ds_read_b128 v[214:217], v153 offset:21504
	ds_read_b128 v[218:221], v153 offset:22528
	ds_read_b128 v[222:225], v153 offset:23552
	global_load_lds_dwordx4 v[190:191], off
	v_lshl_add_u64 v[226:227], s[60:61], 0, v[128:129]
	s_mov_b32 m0, s81
	v_lshl_add_u64 v[228:229], s[66:67], 0, v[132:133]
	global_load_lds_dwordx4 v[226:227], off
	s_mov_b32 m0, s95
	v_lshl_add_u64 v[230:231], s[44:45], 0, v[130:131]
	global_load_lds_dwordx4 v[228:229], off
	v_lshl_add_u64 v[228:229], s[66:67], 0, v[128:129]
	s_mov_b32 m0, s94
	s_nop 0
	global_load_lds_dwordx4 v[228:229], off
	v_lshl_add_u64 v[228:229], s[44:45], 0, v[134:135]
	s_mov_b32 m0, s75
	s_nop 0
	global_load_lds_dwordx4 v[228:229], off
	s_mov_b32 m0, s78
	s_nop 0
	global_load_lds_dwordx4 v[230:231], off
	s_waitcnt vmcnt(8)
	s_waitcnt lgkmcnt(0)
	s_barrier
; #define PG8_STAGE(bufoff, gbase, voff) do { _Pragma("unroll") for (int _i = 0; _i < 2; ++_i) \
;         __builtin_amdgcn_global_load_lds((const unsigned*)((const char*)(gbase) + (voff)[_i]), (PG8_LAS unsigned*)(lds + (bufoff) + ldsw + _i * 8192), 16, 0, 0); } while (0)
; #define PG8_LDA(dst, b, h) do { _Pragma("unroll") for (int m = 0; m < 4; ++m) _Pragma("unroll") for (int k = 0; k < 2; ++k) dst[m][k] = *(const PG8_LAS bf16x8*)(lds + PG8_SA(b, h) + aoff + m * 2048 + k * 1024); } while (0)
; #define PG8_LDB(dst, b, h) do { _Pragma("unroll") for (int n = 0; n < 2; ++n) _Pragma("unroll") for (int k = 0; k < 2; ++k) dst[n][k] = *(const PG8_LAS bf16x8*)(lds + PG8_SB(b, h) + boff + n * 2048 + k * 1024); } while (0)
; #define PG8_MMA(ai, bj, At, Bt) do { __builtin_amdgcn_s_setprio(1); _Pragma("unroll") for (int m = 0; m < 4; ++m) _Pragma("unroll") for (int n = 0; n < 2; ++n) _Pragma("unroll") for (int k = 0; k < 2; ++k) \
;         acc[ai][bj][m][n] = __builtin_amdgcn_mfma_f32_16x16x32_bf16(Bt[n][k], At[m][k], acc[ai][bj][m][n], 0, 0, 0); __builtin_amdgcn_s_setprio(0); } while (0)
; #define PG8_WAIT_V(n) asm volatile("s_waitcnt vmcnt(" #n ")" ::: "memory")
; #define PG8_WAIT_L(n) asm volatile("s_waitcnt lgkmcnt(" #n ")" ::: "memory")
; #define PG8_BAR __builtin_amdgcn_s_barrier()
; #define PG8_SCHED __builtin_amdgcn_sched_barrier(0)
; template <class Epi, class Sched, bool ALIGN_EPI = false, bool SP2 = false>
; __device__ __forceinline__ void gemm_phase(PG8_LAS unsigned char* lds, const Gemm g, const Sched& S, const Epi& E, int wave_in) {
;     ...
;             PG8_LDB(B0, 0, 0); PG8_LDB(B1, 0, 1); PG8_SCHED; PG8_LDA(At, 0, 0); PG8_STAGE(PG8_SA(1, 1), a1 + hstep, voffA);
;             PG8_WAIT_V(8); PG8_WAIT_L(0); PG8_BAR; PG8_MMA(0, 0, At, B0); PG8_MMA(0, 1, At, B1); PG8_BAR; PG8_SCHED;
;             PG8_LDA(At, 0, 1); PG8_STAGE(PG8_SB(0, 0), b2, voffB); PG8_STAGE(PG8_SB(0, 1), b2 + hstep, voffB); PG8_STAGE(PG8_SA(0, 0), a2, voffA);
;             PG8_WAIT_V(8); PG8_WAIT_L(0); PG8_BAR; PG8_MMA(1, 0, At, B0); PG8_MMA(1, 1, At, B1); PG8_BAR; PG8_SCHED;
;             PG8_LDB(B0, 1, 0); PG8_LDB(B1, 1, 1); PG8_SCHED; PG8_LDA(At, 1, 0); PG8_STAGE(PG8_SA(0, 1), a2 + hstep, voffA);
;             PG8_WAIT_V(8); PG8_WAIT_L(0); PG8_BAR; PG8_MMA(0, 0, At, B0); PG8_MMA(0, 1, At, B1); PG8_BAR; PG8_SCHED;
	s_setprio 1
	s_waitcnt lgkmcnt(0)
	v_mfma_f32_16x16x32_bf16 v[60:63], v[154:157], v[186:189], 0
	v_mfma_f32_16x16x32_bf16 v[56:59], v[162:165], v[186:189], 0
	v_mfma_f32_16x16x32_bf16 v[44:47], v[162:165], v[202:205], 0
	v_mfma_f32_16x16x32_bf16 v[52:55], v[154:157], v[202:205], 0
	v_mfma_f32_16x16x32_bf16 v[36:39], v[154:157], v[210:213], 0
	v_mfma_f32_16x16x32_bf16 v[28:31], v[162:165], v[210:213], 0
	v_mfma_f32_16x16x32_bf16 v[12:15], v[162:165], v[218:221], 0
	v_mfma_f32_16x16x32_bf16 v[20:23], v[154:157], v[218:221], 0
	v_mfma_f32_16x16x32_bf16 v[60:63], v[158:161], v[198:201], v[60:63]
	v_mfma_f32_16x16x32_bf16 v[56:59], v[166:169], v[198:201], v[56:59]
	v_mfma_f32_16x16x32_bf16 v[44:47], v[166:169], v[206:209], v[44:47]
	v_mfma_f32_16x16x32_bf16 v[52:55], v[158:161], v[206:209], v[52:55]
	v_mfma_f32_16x16x32_bf16 v[36:39], v[158:161], v[214:217], v[36:39]
	v_mfma_f32_16x16x32_bf16 v[28:31], v[166:169], v[214:217], v[28:31]
	v_mfma_f32_16x16x32_bf16 v[12:15], v[166:169], v[222:225], v[12:15]
	v_mfma_f32_16x16x32_bf16 v[20:23], v[158:161], v[222:225], v[20:23]
	s_setprio 0
	s_setprio 1
	v_mfma_f32_16x16x32_bf16 v[48:51], v[170:173], v[186:189], 0
	v_mfma_f32_16x16x32_bf16 v[40:43], v[178:181], v[186:189], 0
	v_mfma_f32_16x16x32_bf16 v[24:27], v[178:181], v[202:205], 0
	v_mfma_f32_16x16x32_bf16 v[32:35], v[170:173], v[202:205], 0
	v_mfma_f32_16x16x32_bf16 v[16:19], v[170:173], v[210:213], 0
	v_mfma_f32_16x16x32_bf16 v[8:11], v[178:181], v[210:213], 0
	v_mfma_f32_16x16x32_bf16 v[0:3], v[178:181], v[218:221], 0
	v_mfma_f32_16x16x32_bf16 v[4:7], v[170:173], v[218:221], 0
	v_mfma_f32_16x16x32_bf16 v[48:51], v[174:177], v[198:201], v[48:51]
	v_mfma_f32_16x16x32_bf16 v[40:43], v[182:185], v[198:201], v[40:43]
	v_mfma_f32_16x16x32_bf16 v[24:27], v[182:185], v[206:209], v[24:27]
	v_mfma_f32_16x16x32_bf16 v[32:35], v[174:177], v[206:209], v[32:35]
	v_mfma_f32_16x16x32_bf16 v[16:19], v[174:177], v[214:217], v[16:19]
	v_mfma_f32_16x16x32_bf16 v[8:11], v[182:185], v[214:217], v[8:11]
	v_mfma_f32_16x16x32_bf16 v[0:3], v[182:185], v[222:225], v[0:3]
	v_mfma_f32_16x16x32_bf16 v[4:7], v[174:177], v[222:225], v[4:7]
	s_setprio 0
	s_barrier
	v_add_u32_e32 v166, s71, v152
	v_add_u32_e32 v182, s69, v152
	ds_read_b128 v[154:157], v166
	ds_read_b128 v[158:161], v166 offset:1024
	ds_read_b128 v[162:165], v166 offset:2048
	ds_read_b128 v[166:169], v166 offset:3072
	ds_read_b128 v[170:173], v182
	ds_read_b128 v[174:177], v182 offset:1024
	ds_read_b128 v[178:181], v182 offset:2048
	ds_read_b128 v[182:185], v182 offset:3072
	s_mov_b32 m0, s79
	v_lshl_add_u64 v[232:233], s[42:43], 0, v[134:135]
	ds_read_b128 v[186:189], v153 offset:32768
	ds_read_b128 v[198:201], v153 offset:33792
	ds_read_b128 v[202:205], v153 offset:34816
	ds_read_b128 v[206:209], v153 offset:35840
	ds_read_b128 v[210:213], v153 offset:36864
	ds_read_b128 v[214:217], v153 offset:37888
	ds_read_b128 v[218:221], v153 offset:38912
	ds_read_b128 v[222:225], v153 offset:39936
	global_load_lds_dwordx4 v[232:233], off
	v_lshl_add_u64 v[232:233], s[42:43], 0, v[130:131]
	s_mov_b32 m0, s82
	s_nop 0
	global_load_lds_dwordx4 v[232:233], off
	s_waitcnt vmcnt(8)
	s_waitcnt lgkmcnt(0)
	s_barrier
	s_setprio 1
	s_waitcnt lgkmcnt(0)
	v_mfma_f32_16x16x32_bf16 v[124:127], v[154:157], v[186:189], v[124:127]
	v_mfma_f32_16x16x32_bf16 v[120:123], v[162:165], v[186:189], v[120:123]
	v_mfma_f32_16x16x32_bf16 v[108:111], v[162:165], v[202:205], v[108:111]
	v_mfma_f32_16x16x32_bf16 v[116:119], v[154:157], v[202:205], v[116:119]
	v_mfma_f32_16x16x32_bf16 v[100:103], v[154:157], v[210:213], v[100:103]
	v_mfma_f32_16x16x32_bf16 v[92:95], v[162:165], v[210:213], v[92:95]
	v_mfma_f32_16x16x32_bf16 v[76:79], v[162:165], v[218:221], v[76:79]
	v_mfma_f32_16x16x32_bf16 v[84:87], v[154:157], v[218:221], v[84:87]
	v_mfma_f32_16x16x32_bf16 v[124:127], v[158:161], v[198:201], v[124:127]
	v_mfma_f32_16x16x32_bf16 v[120:123], v[166:169], v[198:201], v[120:123]
	v_mfma_f32_16x16x32_bf16 v[108:111], v[166:169], v[206:209], v[108:111]
	v_mfma_f32_16x16x32_bf16 v[116:119], v[158:161], v[206:209], v[116:119]
	v_mfma_f32_16x16x32_bf16 v[100:103], v[158:161], v[214:217], v[100:103]
	v_mfma_f32_16x16x32_bf16 v[92:95], v[166:169], v[214:217], v[92:95]
	v_mfma_f32_16x16x32_bf16 v[76:79], v[166:169], v[222:225], v[76:79]
	v_mfma_f32_16x16x32_bf16 v[84:87], v[158:161], v[222:225], v[84:87]
	s_setprio 0
	s_setprio 1
	v_mfma_f32_16x16x32_bf16 v[112:115], v[170:173], v[186:189], v[112:115]
	v_mfma_f32_16x16x32_bf16 v[104:107], v[178:181], v[186:189], v[104:107]
	v_mfma_f32_16x16x32_bf16 v[88:91], v[178:181], v[202:205], v[88:91]
	v_mfma_f32_16x16x32_bf16 v[96:99], v[170:173], v[202:205], v[96:99]
	v_mfma_f32_16x16x32_bf16 v[80:83], v[170:173], v[210:213], v[80:83]
	v_mfma_f32_16x16x32_bf16 v[72:75], v[178:181], v[210:213], v[72:75]
	v_mfma_f32_16x16x32_bf16 v[64:67], v[178:181], v[218:221], v[64:67]
	v_mfma_f32_16x16x32_bf16 v[68:71], v[170:173], v[218:221], v[68:71]
	v_mfma_f32_16x16x32_bf16 v[112:115], v[174:177], v[198:201], v[112:115]
	v_mfma_f32_16x16x32_bf16 v[104:107], v[182:185], v[198:201], v[104:107]
	v_mfma_f32_16x16x32_bf16 v[88:91], v[182:185], v[206:209], v[88:91]
	v_mfma_f32_16x16x32_bf16 v[96:99], v[174:177], v[206:209], v[96:99]
	v_mfma_f32_16x16x32_bf16 v[80:83], v[174:177], v[214:217], v[80:83]
	v_mfma_f32_16x16x32_bf16 v[72:75], v[182:185], v[214:217], v[72:75]
	v_mfma_f32_16x16x32_bf16 v[64:67], v[182:185], v[222:225], v[64:67]
	v_mfma_f32_16x16x32_bf16 v[68:71], v[174:177], v[222:225], v[68:71]
	s_setprio 0
	s_barrier
; #define PG8_STAGE(bufoff, gbase, voff) do { _Pragma("unroll") for (int _i = 0; _i < 2; ++_i) \
;         __builtin_amdgcn_global_load_lds((const unsigned*)((const char*)(gbase) + (voff)[_i]), (PG8_LAS unsigned*)(lds + (bufoff) + ldsw + _i * 8192), 16, 0, 0); } while (0)
; #define PG8_LDA(dst, b, h) do { _Pragma("unroll") for (int m = 0; m < 4; ++m) _Pragma("unroll") for (int k = 0; k < 2; ++k) dst[m][k] = *(const PG8_LAS bf16x8*)(lds + PG8_SA(b, h) + aoff + m * 2048 + k * 1024); } while (0)
; #define PG8_LDB(dst, b, h) do { _Pragma("unroll") for (int n = 0; n < 2; ++n) _Pragma("unroll") for (int k = 0; k < 2; ++k) dst[n][k] = *(const PG8_LAS bf16x8*)(lds + PG8_SB(b, h) + boff + n * 2048 + k * 1024); } while (0)
; #define PG8_MMA(ai, bj, At, Bt) do { __builtin_amdgcn_s_setprio(1); _Pragma("unroll") for (int m = 0; m < 4; ++m) _Pragma("unroll") for (int n = 0; n < 2; ++n) _Pragma("unroll") for (int k = 0; k < 2; ++k) \
;         acc[ai][bj][m][n] = __builtin_amdgcn_mfma_f32_16x16x32_bf16(Bt[n][k], At[m][k], acc[ai][bj][m][n], 0, 0, 0); __builtin_amdgcn_s_setprio(0); } while (0)
; #define PG8_BAR __builtin_amdgcn_s_barrier()
; template <class Epi, class Sched, bool ALIGN_EPI = false, bool SP2 = false>
; __device__ __forceinline__ void gemm_phase(PG8_LAS unsigned char* lds, const Gemm g, const Sched& S, const Epi& E, int wave_in) {
;     ...
;             PG8_LDB(B0, 0, 0); PG8_LDB(B1, 0, 1); PG8_SCHED; PG8_LDA(At, 0, 0); PG8_STAGE(PG8_SA(1, 1), a1 + hstep, voffA);
;             PG8_WAIT_V(8); PG8_WAIT_L(0); PG8_BAR; PG8_MMA(0, 0, At, B0); PG8_MMA(0, 1, At, B1); PG8_BAR; PG8_SCHED;
;             PG8_LDA(At, 0, 1); PG8_STAGE(PG8_SB(0, 0), b2, voffB); PG8_STAGE(PG8_SB(0, 1), b2 + hstep, voffB); PG8_STAGE(PG8_SA(0, 0), a2, voffA);
;             PG8_WAIT_V(8); PG8_WAIT_L(0); PG8_BAR; PG8_MMA(1, 0, At, B0); PG8_MMA(1, 1, At, B1); PG8_BAR; PG8_SCHED;
;             PG8_LDB(B0, 1, 0); PG8_LDB(B1, 1, 1); PG8_SCHED; PG8_LDA(At, 1, 0); PG8_STAGE(PG8_SA(0, 1), a2 + hstep, voffA);
;             PG8_WAIT_V(8); PG8_WAIT_L(0); PG8_BAR; PG8_MMA(0, 0, At, B0); PG8_MMA(0, 1, At, B1); PG8_BAR; PG8_SCHED;
;             PG8_LDA(At, 1, 1); PG8_STAGE(PG8_SB(1, 0), b3, voffB); PG8_STAGE(PG8_SB(1, 1), b3 + hstep, voffB); PG8_STAGE(PG8_SA(1, 0), a3, voffA);
;             PG8_WAIT_V(8); PG8_WAIT_L(0); PG8_BAR; PG8_MMA(1, 0, At, B0); PG8_MMA(1, 1, At, B1); PG8_BAR; PG8_SCHED;
	s_mov_b32 m0, s53
	v_lshl_add_u64 v[190:191], v[190:191], 0, s[88:89]
	ds_read_b128 v[186:189], v153 offset:49152
	ds_read_b128 v[198:201], v153 offset:50176
	ds_read_b128 v[202:205], v153 offset:51200
	ds_read_b128 v[206:209], v153 offset:52224
	ds_read_b128 v[210:213], v153 offset:53248
	ds_read_b128 v[214:217], v153 offset:54272
	ds_read_b128 v[218:221], v153 offset:55296
	ds_read_b128 v[222:225], v153 offset:56320
	global_load_lds_dwordx4 v[190:191], off
	v_lshl_add_u64 v[190:191], v[226:227], 0, s[88:89]
	s_mov_b32 m0, s34
	s_nop 0
	global_load_lds_dwordx4 v[190:191], off
	v_lshl_add_u64 v[190:191], s[40:41], 0, v[132:133]
	s_mov_b32 m0, vcc_lo
	s_nop 0
	global_load_lds_dwordx4 v[190:191], off
	v_lshl_add_u64 v[190:191], s[40:41], 0, v[128:129]
	s_mov_b32 m0, s97
	s_nop 0
	global_load_lds_dwordx4 v[190:191], off
	v_lshl_add_u64 v[190:191], v[228:229], 0, s[88:89]
	s_mov_b32 m0, s85
	s_nop 0
	global_load_lds_dwordx4 v[190:191], off
	v_lshl_add_u64 v[190:191], v[230:231], 0, s[88:89]
	s_mov_b32 m0, s92
	s_nop 0
	global_load_lds_dwordx4 v[190:191], off
	s_waitcnt vmcnt(8)
	s_waitcnt lgkmcnt(0)
	s_barrier
	s_setprio 1
	s_waitcnt lgkmcnt(0)
	v_mfma_f32_16x16x32_bf16 v[60:63], v[154:157], v[186:189], v[60:63]
	v_mfma_f32_16x16x32_bf16 v[56:59], v[162:165], v[186:189], v[56:59]
	v_mfma_f32_16x16x32_bf16 v[44:47], v[162:165], v[202:205], v[44:47]
	v_mfma_f32_16x16x32_bf16 v[52:55], v[154:157], v[202:205], v[52:55]
	v_mfma_f32_16x16x32_bf16 v[36:39], v[154:157], v[210:213], v[36:39]
	v_mfma_f32_16x16x32_bf16 v[28:31], v[162:165], v[210:213], v[28:31]
	v_mfma_f32_16x16x32_bf16 v[12:15], v[162:165], v[218:221], v[12:15]
	v_mfma_f32_16x16x32_bf16 v[20:23], v[154:157], v[218:221], v[20:23]
	v_mfma_f32_16x16x32_bf16 v[60:63], v[158:161], v[198:201], v[60:63]
	v_mfma_f32_16x16x32_bf16 v[56:59], v[166:169], v[198:201], v[56:59]
	v_mfma_f32_16x16x32_bf16 v[44:47], v[166:169], v[206:209], v[44:47]
	v_mfma_f32_16x16x32_bf16 v[52:55], v[158:161], v[206:209], v[52:55]
	v_mfma_f32_16x16x32_bf16 v[36:39], v[158:161], v[214:217], v[36:39]
	v_mfma_f32_16x16x32_bf16 v[28:31], v[166:169], v[214:217], v[28:31]
	v_mfma_f32_16x16x32_bf16 v[12:15], v[166:169], v[222:225], v[12:15]
	v_mfma_f32_16x16x32_bf16 v[20:23], v[158:161], v[222:225], v[20:23]
	s_setprio 0
	s_setprio 1
	v_mfma_f32_16x16x32_bf16 v[48:51], v[170:173], v[186:189], v[48:51]
	v_mfma_f32_16x16x32_bf16 v[40:43], v[178:181], v[186:189], v[40:43]
	v_mfma_f32_16x16x32_bf16 v[24:27], v[178:181], v[202:205], v[24:27]
	v_mfma_f32_16x16x32_bf16 v[32:35], v[170:173], v[202:205], v[32:35]
	v_mfma_f32_16x16x32_bf16 v[16:19], v[170:173], v[210:213], v[16:19]
	v_mfma_f32_16x16x32_bf16 v[8:11], v[178:181], v[210:213], v[8:11]
	v_mfma_f32_16x16x32_bf16 v[0:3], v[178:181], v[218:221], v[0:3]
	v_mfma_f32_16x16x32_bf16 v[4:7], v[170:173], v[218:221], v[4:7]
	v_mfma_f32_16x16x32_bf16 v[48:51], v[174:177], v[198:201], v[48:51]
	v_mfma_f32_16x16x32_bf16 v[40:43], v[182:185], v[198:201], v[40:43]
	v_mfma_f32_16x16x32_bf16 v[24:27], v[182:185], v[206:209], v[24:27]
	v_mfma_f32_16x16x32_bf16 v[32:35], v[174:177], v[206:209], v[32:35]
	v_mfma_f32_16x16x32_bf16 v[16:19], v[174:177], v[214:217], v[16:19]
	v_mfma_f32_16x16x32_bf16 v[8:11], v[182:185], v[214:217], v[8:11]
	v_mfma_f32_16x16x32_bf16 v[0:3], v[182:185], v[222:225], v[0:3]
	v_mfma_f32_16x16x32_bf16 v[4:7], v[174:177], v[222:225], v[4:7]
	s_setprio 0
	s_barrier
	s_movk_i32 s34, 0x100
	s_andn2_b64 vcc, exec, s[38:39]
	s_mov_b64 s[40:41], -1
	s_mov_b64 s[38:39], 0
	s_cbranch_vccnz .Lkexit_2
.LBB0_485:
	s_add_u32 s53, s24, s34
	s_addc_u32 s66, s25, 0
	s_add_u32 s44, s53, 0x100
	s_addc_u32 s45, s66, 0
	s_and_b64 s[42:43], s[40:41], exec
	s_cselect_b32 s45, s15, s45
	s_cselect_b32 s44, s21, s44
	s_add_u32 s34, s22, s34
	s_addc_u32 s42, s23, 0
	s_add_u32 s34, s34, 0x100
	s_addc_u32 s42, s42, 0
	s_add_i32 s97, s35, 0x100
	s_and_b64 s[40:41], s[40:41], exec
	s_cselect_b32 s61, s13, s42
	s_cselect_b32 s60, s27, s34
	s_add_i32 s41, s90, 0x100
	s_add_u32 s76, s53, 0x10080
	s_addc_u32 s77, s66, 0
	s_add_i32 s96, s97, s72
	s_add_i32 m0, s75, 0xc000
	s_add_i32 vcc_hi, s75, 0xe000
	s_add_i32 s81, s96, 0x2000
	s_add_u32 s66, s60, 0x10000
	v_add_u32_e32 v166, s97, v152
	v_add_u32_e32 v182, s41, v152
	s_addc_u32 s67, s61, 0
	s_add_i32 s95, s41, s72
	ds_read_b128 v[154:157], v166
	ds_read_b128 v[158:161], v166 offset:1024
	ds_read_b128 v[162:165], v166 offset:2048
	ds_read_b128 v[166:169], v166 offset:3072
	ds_read_b128 v[170:173], v182
	ds_read_b128 v[174:177], v182 offset:1024
	ds_read_b128 v[178:181], v182 offset:2048
	ds_read_b128 v[182:185], v182 offset:3072
	s_add_i32 s94, s95, 0x2000
	s_add_i32 s71, s65, 0x100
	s_add_i32 s69, s52, 0x100
	s_add_u32 s42, s44, 0x10000
	s_addc_u32 s43, s45, 0
	s_add_i32 s53, s71, s72
	s_add_i32 s34, s53, 0x2000
	s_add_u32 s40, s60, 0x10080
	s_addc_u32 s41, s61, 0
	s_add_i32 vcc_lo, s69, s72
	s_add_i32 s97, vcc_lo, 0x2000
	v_lshl_add_u64 v[190:191], s[76:77], 0, v[134:135]
	ds_read_b128 v[186:189], v153
	ds_read_b128 v[198:201], v153 offset:1024
	ds_read_b128 v[202:205], v153 offset:2048
	ds_read_b128 v[206:209], v153 offset:3072
	ds_read_b128 v[210:213], v153 offset:4096
	ds_read_b128 v[214:217], v153 offset:5120
	ds_read_b128 v[218:221], v153 offset:6144
	ds_read_b128 v[222:225], v153 offset:7168
	global_load_lds_dwordx4 v[190:191], off
	v_lshl_add_u64 v[190:191], s[76:77], 0, v[130:131]
	s_mov_b32 m0, vcc_hi
	s_nop 0
	global_load_lds_dwordx4 v[190:191], off
	s_waitcnt vmcnt(8)
	s_waitcnt lgkmcnt(0)
	s_barrier
; #define PG8_STAGE(bufoff, gbase, voff) do { _Pragma("unroll") for (int _i = 0; _i < 2; ++_i) \
;         __builtin_amdgcn_global_load_lds((const unsigned*)((const char*)(gbase) + (voff)[_i]), (PG8_LAS unsigned*)(lds + (bufoff) + ldsw + _i * 8192), 16, 0, 0); } while (0)
; #define PG8_LDA(dst, b, h) do { _Pragma("unroll") for (int m = 0; m < 4; ++m) _Pragma("unroll") for (int k = 0; k < 2; ++k) dst[m][k] = *(const PG8_LAS bf16x8*)(lds + PG8_SA(b, h) + aoff + m * 2048 + k * 1024); } while (0)
; #define PG8_LDB(dst, b, h) do { _Pragma("unroll") for (int n = 0; n < 2; ++n) _Pragma("unroll") for (int k = 0; k < 2; ++k) dst[n][k] = *(const PG8_LAS bf16x8*)(lds + PG8_SB(b, h) + boff + n * 2048 + k * 1024); } while (0)
; #define PG8_MMA(ai, bj, At, Bt) do { __builtin_amdgcn_s_setprio(1); _Pragma("unroll") for (int m = 0; m < 4; ++m) _Pragma("unroll") for (int n = 0; n < 2; ++n) _Pragma("unroll") for (int k = 0; k < 2; ++k) \
;         acc[ai][bj][m][n] = __builtin_amdgcn_mfma_f32_16x16x32_bf16(Bt[n][k], At[m][k], acc[ai][bj][m][n], 0, 0, 0); __builtin_amdgcn_s_setprio(0); } while (0)
; #define PG8_WAIT_V(n) asm volatile("s_waitcnt vmcnt(" #n ")" ::: "memory")
; #define PG8_WAIT_L(n) asm volatile("s_waitcnt lgkmcnt(" #n ")" ::: "memory")
; #define PG8_BAR __builtin_amdgcn_s_barrier()
; #define PG8_SCHED __builtin_amdgcn_sched_barrier(0)
; template <class Epi, class Sched, bool ALIGN_EPI = false, bool SP2 = false>
; __device__ __forceinline__ void gemm_phase(PG8_LAS unsigned char* lds, const Gemm g, const Sched& S, const Epi& E, int wave_in) {
;     ...
;             PG8_LDB(B0, 0, 0); PG8_LDB(B1, 0, 1); PG8_SCHED; PG8_LDA(At, 0, 0); PG8_STAGE(PG8_SA(1, 1), a1 + hstep, voffA);
;             PG8_WAIT_V(8); PG8_WAIT_L(0); PG8_BAR; PG8_MMA(0, 0, At, B0); PG8_MMA(0, 1, At, B1); PG8_BAR; PG8_SCHED;
;             PG8_LDA(At, 0, 1); PG8_STAGE(PG8_SB(0, 0), b2, voffB); PG8_STAGE(PG8_SB(0, 1), b2 + hstep, voffB); PG8_STAGE(PG8_SA(0, 0), a2, voffA);
;             PG8_WAIT_V(8); PG8_WAIT_L(0); PG8_BAR; PG8_MMA(1, 0, At, B0); PG8_MMA(1, 1, At, B1); PG8_BAR; PG8_SCHED;
	s_setprio 1
	s_waitcnt lgkmcnt(0)
	v_mfma_f32_16x16x32_bf16 v[124:127], v[154:157], v[186:189], v[124:127]
	v_mfma_f32_16x16x32_bf16 v[120:123], v[162:165], v[186:189], v[120:123]
	v_mfma_f32_16x16x32_bf16 v[108:111], v[162:165], v[202:205], v[108:111]
	v_mfma_f32_16x16x32_bf16 v[116:119], v[154:157], v[202:205], v[116:119]
	v_mfma_f32_16x16x32_bf16 v[100:103], v[154:157], v[210:213], v[100:103]
	v_mfma_f32_16x16x32_bf16 v[92:95], v[162:165], v[210:213], v[92:95]
	v_mfma_f32_16x16x32_bf16 v[76:79], v[162:165], v[218:221], v[76:79]
	v_mfma_f32_16x16x32_bf16 v[84:87], v[154:157], v[218:221], v[84:87]
	v_mfma_f32_16x16x32_bf16 v[124:127], v[158:161], v[198:201], v[124:127]
	v_mfma_f32_16x16x32_bf16 v[120:123], v[166:169], v[198:201], v[120:123]
	v_mfma_f32_16x16x32_bf16 v[108:111], v[166:169], v[206:209], v[108:111]
	v_mfma_f32_16x16x32_bf16 v[116:119], v[158:161], v[206:209], v[116:119]
	v_mfma_f32_16x16x32_bf16 v[100:103], v[158:161], v[214:217], v[100:103]
	v_mfma_f32_16x16x32_bf16 v[92:95], v[166:169], v[214:217], v[92:95]
	v_mfma_f32_16x16x32_bf16 v[76:79], v[166:169], v[222:225], v[76:79]
	v_mfma_f32_16x16x32_bf16 v[84:87], v[158:161], v[222:225], v[84:87]
	s_setprio 0
	s_setprio 1
	v_mfma_f32_16x16x32_bf16 v[112:115], v[170:173], v[186:189], v[112:115]
	v_mfma_f32_16x16x32_bf16 v[104:107], v[178:181], v[186:189], v[104:107]
	v_mfma_f32_16x16x32_bf16 v[88:91], v[178:181], v[202:205], v[88:91]
	v_mfma_f32_16x16x32_bf16 v[96:99], v[170:173], v[202:205], v[96:99]
	v_mfma_f32_16x16x32_bf16 v[80:83], v[170:173], v[210:213], v[80:83]
	v_mfma_f32_16x16x32_bf16 v[72:75], v[178:181], v[210:213], v[72:75]
	v_mfma_f32_16x16x32_bf16 v[64:67], v[178:181], v[218:221], v[64:67]
	v_mfma_f32_16x16x32_bf16 v[68:71], v[170:173], v[218:221], v[68:71]
	v_mfma_f32_16x16x32_bf16 v[112:115], v[174:177], v[198:201], v[112:115]
	v_mfma_f32_16x16x32_bf16 v[104:107], v[182:185], v[198:201], v[104:107]
	v_mfma_f32_16x16x32_bf16 v[88:91], v[182:185], v[206:209], v[88:91]
	v_mfma_f32_16x16x32_bf16 v[96:99], v[174:177], v[206:209], v[96:99]
	v_mfma_f32_16x16x32_bf16 v[80:83], v[174:177], v[214:217], v[80:83]
	v_mfma_f32_16x16x32_bf16 v[72:75], v[182:185], v[214:217], v[72:75]
	v_mfma_f32_16x16x32_bf16 v[64:67], v[182:185], v[222:225], v[64:67]
	v_mfma_f32_16x16x32_bf16 v[68:71], v[174:177], v[222:225], v[68:71]
	s_setprio 0
	s_barrier
	s_mov_b32 m0, s96
	v_lshl_add_u64 v[190:191], s[60:61], 0, v[132:133]
	ds_read_b128 v[186:189], v153 offset:16384
	ds_read_b128 v[198:201], v153 offset:17408
	ds_read_b128 v[202:205], v153 offset:18432
	ds_read_b128 v[206:209], v153 offset:19456
	ds_read_b128 v[210:213], v153 offset:20480
	ds_read_b128 v[214:217], v153 offset:21504
	ds_read_b128 v[218:221], v153 offset:22528
	ds_read_b128 v[222:225], v153 offset:23552
	global_load_lds_dwordx4 v[190:191], off
	v_lshl_add_u64 v[226:227], s[60:61], 0, v[128:129]
	s_mov_b32 m0, s81
	v_lshl_add_u64 v[228:229], s[66:67], 0, v[132:133]
	global_load_lds_dwordx4 v[226:227], off
	s_mov_b32 m0, s95
	v_lshl_add_u64 v[230:231], s[44:45], 0, v[130:131]
	global_load_lds_dwordx4 v[228:229], off
	v_lshl_add_u64 v[228:229], s[66:67], 0, v[128:129]
	s_mov_b32 m0, s94
	s_nop 0
	global_load_lds_dwordx4 v[228:229], off
	v_lshl_add_u64 v[228:229], s[44:45], 0, v[134:135]
	s_mov_b32 m0, s75
	s_nop 0
	global_load_lds_dwordx4 v[228:229], off
	s_mov_b32 m0, s78
	s_nop 0
	global_load_lds_dwordx4 v[230:231], off
	s_waitcnt vmcnt(8)
	s_waitcnt lgkmcnt(0)
	s_barrier
	s_setprio 1
	s_waitcnt lgkmcnt(0)
	v_mfma_f32_16x16x32_bf16 v[60:63], v[154:157], v[186:189], v[60:63]
	v_mfma_f32_16x16x32_bf16 v[56:59], v[162:165], v[186:189], v[56:59]
	v_mfma_f32_16x16x32_bf16 v[44:47], v[162:165], v[202:205], v[44:47]
	v_mfma_f32_16x16x32_bf16 v[52:55], v[154:157], v[202:205], v[52:55]
	v_mfma_f32_16x16x32_bf16 v[36:39], v[154:157], v[210:213], v[36:39]
	v_mfma_f32_16x16x32_bf16 v[28:31], v[162:165], v[210:213], v[28:31]
	v_mfma_f32_16x16x32_bf16 v[12:15], v[162:165], v[218:221], v[12:15]
	v_mfma_f32_16x16x32_bf16 v[20:23], v[154:157], v[218:221], v[20:23]
	v_mfma_f32_16x16x32_bf16 v[60:63], v[158:161], v[198:201], v[60:63]
	v_mfma_f32_16x16x32_bf16 v[56:59], v[166:169], v[198:201], v[56:59]
	v_mfma_f32_16x16x32_bf16 v[44:47], v[166:169], v[206:209], v[44:47]
	v_mfma_f32_16x16x32_bf16 v[52:55], v[158:161], v[206:209], v[52:55]
	v_mfma_f32_16x16x32_bf16 v[36:39], v[158:161], v[214:217], v[36:39]
	v_mfma_f32_16x16x32_bf16 v[28:31], v[166:169], v[214:217], v[28:31]
	v_mfma_f32_16x16x32_bf16 v[12:15], v[166:169], v[222:225], v[12:15]
	v_mfma_f32_16x16x32_bf16 v[20:23], v[158:161], v[222:225], v[20:23]
	s_setprio 0
	s_setprio 1
	v_mfma_f32_16x16x32_bf16 v[48:51], v[170:173], v[186:189], v[48:51]
	v_mfma_f32_16x16x32_bf16 v[40:43], v[178:181], v[186:189], v[40:43]
	v_mfma_f32_16x16x32_bf16 v[24:27], v[178:181], v[202:205], v[24:27]
	v_mfma_f32_16x16x32_bf16 v[32:35], v[170:173], v[202:205], v[32:35]
	v_mfma_f32_16x16x32_bf16 v[16:19], v[170:173], v[210:213], v[16:19]
	v_mfma_f32_16x16x32_bf16 v[8:11], v[178:181], v[210:213], v[8:11]
	v_mfma_f32_16x16x32_bf16 v[0:3], v[178:181], v[218:221], v[0:3]
	v_mfma_f32_16x16x32_bf16 v[4:7], v[170:173], v[218:221], v[4:7]
	v_mfma_f32_16x16x32_bf16 v[48:51], v[174:177], v[198:201], v[48:51]
	v_mfma_f32_16x16x32_bf16 v[40:43], v[182:185], v[198:201], v[40:43]
	v_mfma_f32_16x16x32_bf16 v[24:27], v[182:185], v[206:209], v[24:27]
	v_mfma_f32_16x16x32_bf16 v[32:35], v[174:177], v[206:209], v[32:35]
	v_mfma_f32_16x16x32_bf16 v[16:19], v[174:177], v[214:217], v[16:19]
	v_mfma_f32_16x16x32_bf16 v[8:11], v[182:185], v[214:217], v[8:11]
	v_mfma_f32_16x16x32_bf16 v[0:3], v[182:185], v[222:225], v[0:3]
	v_mfma_f32_16x16x32_bf16 v[4:7], v[174:177], v[222:225], v[4:7]
	s_setprio 0
	s_barrier
; #define PG8_STAGE(bufoff, gbase, voff) do { _Pragma("unroll") for (int _i = 0; _i < 2; ++_i) \
;         __builtin_amdgcn_global_load_lds((const unsigned*)((const char*)(gbase) + (voff)[_i]), (PG8_LAS unsigned*)(lds + (bufoff) + ldsw + _i * 8192), 16, 0, 0); } while (0)
; #define PG8_LDA(dst, b, h) do { _Pragma("unroll") for (int m = 0; m < 4; ++m) _Pragma("unroll") for (int k = 0; k < 2; ++k) dst[m][k] = *(const PG8_LAS bf16x8*)(lds + PG8_SA(b, h) + aoff + m * 2048 + k * 1024); } while (0)
; #define PG8_LDB(dst, b, h) do { _Pragma("unroll") for (int n = 0; n < 2; ++n) _Pragma("unroll") for (int k = 0; k < 2; ++k) dst[n][k] = *(const PG8_LAS bf16x8*)(lds + PG8_SB(b, h) + boff + n * 2048 + k * 1024); } while (0)
; #define PG8_MMA(ai, bj, At, Bt) do { __builtin_amdgcn_s_setprio(1); _Pragma("unroll") for (int m = 0; m < 4; ++m) _Pragma("unroll") for (int n = 0; n < 2; ++n) _Pragma("unroll") for (int k = 0; k < 2; ++k) \
;         acc[ai][bj][m][n] = __builtin_amdgcn_mfma_f32_16x16x32_bf16(Bt[n][k], At[m][k], acc[ai][bj][m][n], 0, 0, 0); __builtin_amdgcn_s_setprio(0); } while (0)
; #define PG8_WAIT_V(n) asm volatile("s_waitcnt vmcnt(" #n ")" ::: "memory")
; #define PG8_WAIT_L(n) asm volatile("s_waitcnt lgkmcnt(" #n ")" ::: "memory")
; #define PG8_BAR __builtin_amdgcn_s_barrier()
; #define PG8_SCHED __builtin_amdgcn_sched_barrier(0)
; template <class Epi, class Sched, bool ALIGN_EPI = false, bool SP2 = false>
; __device__ __forceinline__ void gemm_phase(PG8_LAS unsigned char* lds, const Gemm g, const Sched& S, const Epi& E, int wave_in) {
;     ...
;             PG8_LDB(B0, 1, 0); PG8_LDB(B1, 1, 1); PG8_SCHED; PG8_LDA(At, 1, 0); PG8_STAGE(PG8_SA(0, 1), a2 + hstep, voffA);
;             PG8_WAIT_V(8); PG8_WAIT_L(0); PG8_BAR; PG8_MMA(0, 0, At, B0); PG8_MMA(0, 1, At, B1); PG8_BAR; PG8_SCHED;
;             PG8_LDA(At, 1, 1); PG8_STAGE(PG8_SB(1, 0), b3, voffB); PG8_STAGE(PG8_SB(1, 1), b3 + hstep, voffB); PG8_STAGE(PG8_SA(1, 0), a3, voffA);
;             PG8_WAIT_V(8); PG8_WAIT_L(0); PG8_BAR; PG8_MMA(1, 0, At, B0); PG8_MMA(1, 1, At, B1); PG8_BAR; PG8_SCHED;
	v_add_u32_e32 v166, s71, v152
	v_add_u32_e32 v182, s69, v152
	ds_read_b128 v[154:157], v166
	ds_read_b128 v[158:161], v166 offset:1024
	ds_read_b128 v[162:165], v166 offset:2048
	ds_read_b128 v[166:169], v166 offset:3072
	ds_read_b128 v[170:173], v182
	ds_read_b128 v[174:177], v182 offset:1024
	ds_read_b128 v[178:181], v182 offset:2048
	ds_read_b128 v[182:185], v182 offset:3072
	s_mov_b32 m0, s79
	v_lshl_add_u64 v[232:233], s[42:43], 0, v[134:135]
	ds_read_b128 v[186:189], v153 offset:32768
	ds_read_b128 v[198:201], v153 offset:33792
	ds_read_b128 v[202:205], v153 offset:34816
	ds_read_b128 v[206:209], v153 offset:35840
	ds_read_b128 v[210:213], v153 offset:36864
	ds_read_b128 v[214:217], v153 offset:37888
	ds_read_b128 v[218:221], v153 offset:38912
	ds_read_b128 v[222:225], v153 offset:39936
	global_load_lds_dwordx4 v[232:233], off
	v_lshl_add_u64 v[232:233], s[42:43], 0, v[130:131]
	s_mov_b32 m0, s82
	s_nop 0
	global_load_lds_dwordx4 v[232:233], off
	s_waitcnt vmcnt(8)
	s_waitcnt lgkmcnt(0)
	s_barrier
	s_setprio 1
	s_waitcnt lgkmcnt(0)
	v_mfma_f32_16x16x32_bf16 v[124:127], v[154:157], v[186:189], v[124:127]
	v_mfma_f32_16x16x32_bf16 v[120:123], v[162:165], v[186:189], v[120:123]
	v_mfma_f32_16x16x32_bf16 v[108:111], v[162:165], v[202:205], v[108:111]
	v_mfma_f32_16x16x32_bf16 v[116:119], v[154:157], v[202:205], v[116:119]
	v_mfma_f32_16x16x32_bf16 v[100:103], v[154:157], v[210:213], v[100:103]
	v_mfma_f32_16x16x32_bf16 v[92:95], v[162:165], v[210:213], v[92:95]
	v_mfma_f32_16x16x32_bf16 v[76:79], v[162:165], v[218:221], v[76:79]
	v_mfma_f32_16x16x32_bf16 v[84:87], v[154:157], v[218:221], v[84:87]
	v_mfma_f32_16x16x32_bf16 v[124:127], v[158:161], v[198:201], v[124:127]
	v_mfma_f32_16x16x32_bf16 v[120:123], v[166:169], v[198:201], v[120:123]
	v_mfma_f32_16x16x32_bf16 v[108:111], v[166:169], v[206:209], v[108:111]
	v_mfma_f32_16x16x32_bf16 v[116:119], v[158:161], v[206:209], v[116:119]
	v_mfma_f32_16x16x32_bf16 v[100:103], v[158:161], v[214:217], v[100:103]
	v_mfma_f32_16x16x32_bf16 v[92:95], v[166:169], v[214:217], v[92:95]
	v_mfma_f32_16x16x32_bf16 v[76:79], v[166:169], v[222:225], v[76:79]
	v_mfma_f32_16x16x32_bf16 v[84:87], v[158:161], v[222:225], v[84:87]
	s_setprio 0
	s_setprio 1
	v_mfma_f32_16x16x32_bf16 v[112:115], v[170:173], v[186:189], v[112:115]
	v_mfma_f32_16x16x32_bf16 v[104:107], v[178:181], v[186:189], v[104:107]
	v_mfma_f32_16x16x32_bf16 v[88:91], v[178:181], v[202:205], v[88:91]
	v_mfma_f32_16x16x32_bf16 v[96:99], v[170:173], v[202:205], v[96:99]
	v_mfma_f32_16x16x32_bf16 v[80:83], v[170:173], v[210:213], v[80:83]
	v_mfma_f32_16x16x32_bf16 v[72:75], v[178:181], v[210:213], v[72:75]
	v_mfma_f32_16x16x32_bf16 v[64:67], v[178:181], v[218:221], v[64:67]
	v_mfma_f32_16x16x32_bf16 v[68:71], v[170:173], v[218:221], v[68:71]
	v_mfma_f32_16x16x32_bf16 v[112:115], v[174:177], v[198:201], v[112:115]
	v_mfma_f32_16x16x32_bf16 v[104:107], v[182:185], v[198:201], v[104:107]
	v_mfma_f32_16x16x32_bf16 v[88:91], v[182:185], v[206:209], v[88:91]
	v_mfma_f32_16x16x32_bf16 v[96:99], v[174:177], v[206:209], v[96:99]
	v_mfma_f32_16x16x32_bf16 v[80:83], v[174:177], v[214:217], v[80:83]
	v_mfma_f32_16x16x32_bf16 v[72:75], v[182:185], v[214:217], v[72:75]
	v_mfma_f32_16x16x32_bf16 v[64:67], v[182:185], v[222:225], v[64:67]
	v_mfma_f32_16x16x32_bf16 v[68:71], v[174:177], v[222:225], v[68:71]
	s_setprio 0
	s_barrier
	s_mov_b32 m0, s53
	v_lshl_add_u64 v[190:191], v[190:191], 0, s[88:89]
	ds_read_b128 v[186:189], v153 offset:49152
	ds_read_b128 v[198:201], v153 offset:50176
	ds_read_b128 v[202:205], v153 offset:51200
	ds_read_b128 v[206:209], v153 offset:52224
	ds_read_b128 v[210:213], v153 offset:53248
	ds_read_b128 v[214:217], v153 offset:54272
	ds_read_b128 v[218:221], v153 offset:55296
	ds_read_b128 v[222:225], v153 offset:56320
	global_load_lds_dwordx4 v[190:191], off
	v_lshl_add_u64 v[190:191], v[226:227], 0, s[88:89]
	s_mov_b32 m0, s34
	s_nop 0
	global_load_lds_dwordx4 v[190:191], off
	v_lshl_add_u64 v[190:191], s[40:41], 0, v[132:133]
	s_mov_b32 m0, vcc_lo
	s_nop 0
	global_load_lds_dwordx4 v[190:191], off
	v_lshl_add_u64 v[190:191], s[40:41], 0, v[128:129]
	s_mov_b32 m0, s97
	s_nop 0
	global_load_lds_dwordx4 v[190:191], off
	v_lshl_add_u64 v[190:191], v[228:229], 0, s[88:89]
	s_mov_b32 m0, s85
	s_nop 0
	global_load_lds_dwordx4 v[190:191], off
	v_lshl_add_u64 v[190:191], v[230:231], 0, s[88:89]
	s_mov_b32 m0, s92
	s_nop 0
	global_load_lds_dwordx4 v[190:191], off
	s_waitcnt vmcnt(8)
	s_waitcnt lgkmcnt(0)
	s_barrier
	s_setprio 1
	s_waitcnt lgkmcnt(0)
	v_mfma_f32_16x16x32_bf16 v[60:63], v[154:157], v[186:189], v[60:63]
	v_mfma_f32_16x16x32_bf16 v[56:59], v[162:165], v[186:189], v[56:59]
	v_mfma_f32_16x16x32_bf16 v[44:47], v[162:165], v[202:205], v[44:47]
	v_mfma_f32_16x16x32_bf16 v[52:55], v[154:157], v[202:205], v[52:55]
	v_mfma_f32_16x16x32_bf16 v[36:39], v[154:157], v[210:213], v[36:39]
	v_mfma_f32_16x16x32_bf16 v[28:31], v[162:165], v[210:213], v[28:31]
	v_mfma_f32_16x16x32_bf16 v[12:15], v[162:165], v[218:221], v[12:15]
	v_mfma_f32_16x16x32_bf16 v[20:23], v[154:157], v[218:221], v[20:23]
	v_mfma_f32_16x16x32_bf16 v[60:63], v[158:161], v[198:201], v[60:63]
	v_mfma_f32_16x16x32_bf16 v[56:59], v[166:169], v[198:201], v[56:59]
	v_mfma_f32_16x16x32_bf16 v[44:47], v[166:169], v[206:209], v[44:47]
	v_mfma_f32_16x16x32_bf16 v[52:55], v[158:161], v[206:209], v[52:55]
	v_mfma_f32_16x16x32_bf16 v[36:39], v[158:161], v[214:217], v[36:39]
	v_mfma_f32_16x16x32_bf16 v[28:31], v[166:169], v[214:217], v[28:31]
	v_mfma_f32_16x16x32_bf16 v[12:15], v[166:169], v[222:225], v[12:15]
	v_mfma_f32_16x16x32_bf16 v[20:23], v[158:161], v[222:225], v[20:23]
	s_setprio 0
	s_setprio 1
	v_mfma_f32_16x16x32_bf16 v[48:51], v[170:173], v[186:189], v[48:51]
	v_mfma_f32_16x16x32_bf16 v[40:43], v[178:181], v[186:189], v[40:43]
	v_mfma_f32_16x16x32_bf16 v[24:27], v[178:181], v[202:205], v[24:27]
	v_mfma_f32_16x16x32_bf16 v[32:35], v[170:173], v[202:205], v[32:35]
	v_mfma_f32_16x16x32_bf16 v[16:19], v[170:173], v[210:213], v[16:19]
	v_mfma_f32_16x16x32_bf16 v[8:11], v[178:181], v[210:213], v[8:11]
	v_mfma_f32_16x16x32_bf16 v[0:3], v[178:181], v[218:221], v[0:3]
	v_mfma_f32_16x16x32_bf16 v[4:7], v[170:173], v[218:221], v[4:7]
	v_mfma_f32_16x16x32_bf16 v[48:51], v[174:177], v[198:201], v[48:51]
	v_mfma_f32_16x16x32_bf16 v[40:43], v[182:185], v[198:201], v[40:43]
	v_mfma_f32_16x16x32_bf16 v[24:27], v[182:185], v[206:209], v[24:27]
	v_mfma_f32_16x16x32_bf16 v[32:35], v[174:177], v[206:209], v[32:35]
	v_mfma_f32_16x16x32_bf16 v[16:19], v[174:177], v[214:217], v[16:19]
	v_mfma_f32_16x16x32_bf16 v[8:11], v[182:185], v[214:217], v[8:11]
	v_mfma_f32_16x16x32_bf16 v[0:3], v[182:185], v[222:225], v[0:3]
	v_mfma_f32_16x16x32_bf16 v[4:7], v[174:177], v[222:225], v[4:7]
	s_setprio 0
	s_barrier
	s_movk_i32 s34, 0x100
	s_andn2_b64 vcc, exec, s[38:39]
	s_mov_b64 s[40:41], -1
	s_mov_b64 s[38:39], 0
	s_cbranch_vccz .LBB0_485

; #define PG8_STAGE(bufoff, gbase, voff) do { _Pragma("unroll") for (int _i = 0; _i < 2; ++_i) \
;         __builtin_amdgcn_global_load_lds((const unsigned*)((const char*)(gbase) + (voff)[_i]), (PG8_LAS unsigned*)(lds + (bufoff) + ldsw + _i * 8192), 16, 0, 0); } while (0)
; #define PG8_LDA(dst, b, h) do { _Pragma("unroll") for (int m = 0; m < 4; ++m) _Pragma("unroll") for (int k = 0; k < 2; ++k) dst[m][k] = *(const PG8_LAS bf16x8*)(lds + PG8_SA(b, h) + aoff + m * 2048 + k * 1024); } while (0)
; #define PG8_LDB(dst, b, h) do { _Pragma("unroll") for (int n = 0; n < 2; ++n) _Pragma("unroll") for (int k = 0; k < 2; ++k) dst[n][k] = *(const PG8_LAS bf16x8*)(lds + PG8_SB(b, h) + boff + n * 2048 + k * 1024); } while (0)
; #define PG8_WAIT_V(n) asm volatile("s_waitcnt vmcnt(" #n ")" ::: "memory")
; #define PG8_WAIT_L(n) asm volatile("s_waitcnt lgkmcnt(" #n ")" ::: "memory")
; #define PG8_BAR __builtin_amdgcn_s_barrier()
; #define PG8_SCHED __builtin_amdgcn_sched_barrier(0)
; template <class Epi, class Sched, bool ALIGN_EPI = false, bool SP2 = false>
; __device__ __forceinline__ void gemm_phase(PG8_LAS unsigned char* lds, const Gemm g, const Sched& S, const Epi& E, int wave_in) {
;     ...
;         const char* nA = has_next ? (const char*)g.A + (size_t)(nxt.pm >> g.ash) * g.astride + (size_t)nxt.pm * tstep : cA; const char* nB = has_next ? (const char*)g.Bt + (size_t)(nxt.pm >> g.bsh) * g.bstride + (size_t)nxt.pn * tstep : cB;
;         for (int t = 0; t < nt; t += 2) {
;             const bool last = (t == nt - 2);
;             const char* a1 = cA + (size_t)(t + 1) * kstep;
;             const char* a2 = last ? nA : cA + (size_t)(t + 2) * kstep; const char* b2 = last ? nB : cB + (size_t)(t + 2) * kstep;
;             const char* a3 = a2 + kstep; const char* b3 = b2 + kstep;
;             if (last && has_next) S.a_ready(nxt);
;             if constexpr (SP2) {
;             PG8_LDB(B0, 0, 0); PG8_LDB(B1, 0, 1); PG8_SCHED; PG8_LDA(At, 0, 0); PG8_STAGE(PG8_SA(1, 1), a1 + hstep, voffA);
;             PG8_WAIT_V(8); PG8_WAIT_L(0); PG8_BAR; PG8_MMA(0, 0, At, B0); PG8_MMA(0, 1, At, B1); PG8_BAR; PG8_SCHED;
;             PG8_LDA(At, 0, 1); PG8_STAGE(PG8_SB(0, 0), b2, voffB); PG8_STAGE(PG8_SB(0, 1), b2 + hstep, voffB); PG8_STAGE(PG8_SA(0, 0), a2, voffA);
;             PG8_WAIT_V(8); PG8_WAIT_L(0); PG8_BAR; PG8_MMA(1, 0, At, B0); PG8_MMA(1, 1, At, B1); PG8_BAR; PG8_SCHED;
.LBB0_589:
	s_ashr_i32 s15, s14, 31
	s_lshl_b64 s[20:21], s[14:15], 19
	s_add_u32 s20, s31, s20
	s_addc_u32 s21, s33, s21
	s_and_b64 s[26:27], s[44:45], exec
	s_cselect_b32 s15, s21, s23
	s_cselect_b32 s17, s20, s22
	s_add_u32 s34, s22, 0x100
	s_addc_u32 s44, s23, 0
	s_add_u32 s22, s24, 0x40080
	s_addc_u32 s23, s25, 0
	s_mov_b32 s45, -2
	s_add_u32 s24, s22, 0xfffc0080
	s_addc_u32 s25, s23, -1
	s_add_i32 s53, s35, 0x100
	s_cmp_eq_u32 s45, 12
	s_cselect_b32 s27, s19, s25
	s_cselect_b32 s26, s18, s24
	s_cselect_b32 s25, s15, s44
	s_cselect_b32 s24, s17, s34
	s_add_i32 s69, s90, 0x100
	v_add_u32_e32 v128, s53, v249
	v_add_u32_e32 v156, s69, v249
	ds_read_b128 v[112:115], v128
	ds_read_b128 v[120:123], v128 offset:1024
	ds_read_b128 v[124:127], v128 offset:2048
	ds_read_b128 v[128:131], v128 offset:3072
	ds_read_b128 v[136:139], v156
	ds_read_b128 v[140:143], v156 offset:1024
	ds_read_b128 v[144:147], v156 offset:2048
	ds_read_b128 v[156:159], v156 offset:3072
	v_lshl_add_u64 v[208:209], s[22:23], 0, v[206:207]
	s_add_i32 m0, s39, 0xc000
	ds_read_b128 v[160:163], v251
	ds_read_b128 v[164:167], v251 offset:1024
	ds_read_b128 v[168:171], v251 offset:2048
	ds_read_b128 v[172:175], v251 offset:3072
	ds_read_b128 v[176:179], v251 offset:4096
	ds_read_b128 v[180:183], v251 offset:5120
	ds_read_b128 v[184:187], v251 offset:6144
	ds_read_b128 v[188:191], v251 offset:7168
	global_load_lds_dwordx4 v[208:209], off
	v_lshl_add_u64 v[208:209], s[22:23], 0, v[204:205]
	s_add_i32 m0, s39, 0xe000
	s_nop 0
	global_load_lds_dwordx4 v[208:209], off
	s_waitcnt vmcnt(8)
	s_waitcnt lgkmcnt(0)
	s_barrier
	s_setprio 1
	s_waitcnt lgkmcnt(0)
	v_mfma_f32_16x16x32_bf16 v[152:155], v[112:115], v[160:163], 0
	v_mfma_f32_16x16x32_bf16 v[148:151], v[124:127], v[160:163], 0
	v_mfma_f32_16x16x32_bf16 v[104:107], v[124:127], v[168:171], 0
	v_mfma_f32_16x16x32_bf16 v[108:111], v[112:115], v[168:171], 0
	v_mfma_f32_16x16x32_bf16 v[92:95], v[112:115], v[176:179], 0
	v_mfma_f32_16x16x32_bf16 v[88:91], v[124:127], v[176:179], 0
	v_mfma_f32_16x16x32_bf16 v[72:75], v[124:127], v[184:187], 0
	v_mfma_f32_16x16x32_bf16 v[76:79], v[112:115], v[184:187], 0
	v_mfma_f32_16x16x32_bf16 v[152:155], v[120:123], v[164:167], v[152:155]
	v_mfma_f32_16x16x32_bf16 v[148:151], v[128:131], v[164:167], v[148:151]
	v_mfma_f32_16x16x32_bf16 v[104:107], v[128:131], v[172:175], v[104:107]
	v_mfma_f32_16x16x32_bf16 v[108:111], v[120:123], v[172:175], v[108:111]
	v_mfma_f32_16x16x32_bf16 v[92:95], v[120:123], v[180:183], v[92:95]
	v_mfma_f32_16x16x32_bf16 v[88:91], v[128:131], v[180:183], v[88:91]
	v_mfma_f32_16x16x32_bf16 v[72:75], v[128:131], v[188:191], v[72:75]
	v_mfma_f32_16x16x32_bf16 v[76:79], v[120:123], v[188:191], v[76:79]
	s_setprio 0
	s_setprio 1
	v_mfma_f32_16x16x32_bf16 v[132:135], v[136:139], v[160:163], 0
	v_mfma_f32_16x16x32_bf16 v[116:119], v[144:147], v[160:163], 0
	v_mfma_f32_16x16x32_bf16 v[96:99], v[144:147], v[168:171], 0
	v_mfma_f32_16x16x32_bf16 v[100:103], v[136:139], v[168:171], 0
	v_mfma_f32_16x16x32_bf16 v[84:87], v[136:139], v[176:179], 0
	v_mfma_f32_16x16x32_bf16 v[80:83], v[144:147], v[176:179], 0
	v_mfma_f32_16x16x32_bf16 v[64:67], v[144:147], v[184:187], 0
	v_mfma_f32_16x16x32_bf16 v[68:71], v[136:139], v[184:187], 0
	v_mfma_f32_16x16x32_bf16 v[132:135], v[140:143], v[164:167], v[132:135]
	v_mfma_f32_16x16x32_bf16 v[116:119], v[156:159], v[164:167], v[116:119]
	v_mfma_f32_16x16x32_bf16 v[96:99], v[156:159], v[172:175], v[96:99]
	v_mfma_f32_16x16x32_bf16 v[100:103], v[140:143], v[172:175], v[100:103]
	v_mfma_f32_16x16x32_bf16 v[84:87], v[140:143], v[180:183], v[84:87]
	v_mfma_f32_16x16x32_bf16 v[80:83], v[156:159], v[180:183], v[80:83]
	v_mfma_f32_16x16x32_bf16 v[64:67], v[156:159], v[188:191], v[64:67]
	v_mfma_f32_16x16x32_bf16 v[68:71], v[140:143], v[188:191], v[68:71]
	s_setprio 0
	s_barrier
	s_add_i32 s53, s53, s38
	v_lshl_add_u64 v[208:209], s[24:25], 0, v[192:193]
	s_mov_b32 m0, s53
	ds_read_b128 v[160:163], v251 offset:16384
	ds_read_b128 v[164:167], v251 offset:17408
	ds_read_b128 v[168:171], v251 offset:18432
	ds_read_b128 v[172:175], v251 offset:19456
	ds_read_b128 v[176:179], v251 offset:20480
	ds_read_b128 v[180:183], v251 offset:21504
	ds_read_b128 v[184:187], v251 offset:22528
	ds_read_b128 v[188:191], v251 offset:23552
	global_load_lds_dwordx4 v[208:209], off
	s_add_i32 m0, s53, 0x2000
	s_add_u32 s72, s24, 0x40000
	v_lshl_add_u64 v[210:211], s[24:25], 0, v[198:199]
	s_addc_u32 s73, s25, 0
	s_add_i32 s53, s69, s38
	global_load_lds_dwordx4 v[210:211], off
	v_lshl_add_u64 v[212:213], s[72:73], 0, v[192:193]
	s_mov_b32 m0, s53
	v_lshl_add_u64 v[214:215], s[26:27], 0, v[200:201]
	global_load_lds_dwordx4 v[212:213], off
	v_lshl_add_u64 v[212:213], s[72:73], 0, v[198:199]
	s_add_i32 m0, s53, 0x2000
	s_nop 0
	global_load_lds_dwordx4 v[212:213], off
	v_lshl_add_u64 v[212:213], s[26:27], 0, v[202:203]
	s_mov_b32 m0, s39
	s_nop 0
	global_load_lds_dwordx4 v[212:213], off
	s_mov_b32 m0, s46
	s_nop 0
	global_load_lds_dwordx4 v[214:215], off
	s_waitcnt vmcnt(8)
	s_waitcnt lgkmcnt(0)
	s_barrier
; #define PG8_STAGE(bufoff, gbase, voff) do { _Pragma("unroll") for (int _i = 0; _i < 2; ++_i) \
;         __builtin_amdgcn_global_load_lds((const unsigned*)((const char*)(gbase) + (voff)[_i]), (PG8_LAS unsigned*)(lds + (bufoff) + ldsw + _i * 8192), 16, 0, 0); } while (0)
; #define PG8_LDA(dst, b, h) do { _Pragma("unroll") for (int m = 0; m < 4; ++m) _Pragma("unroll") for (int k = 0; k < 2; ++k) dst[m][k] = *(const PG8_LAS bf16x8*)(lds + PG8_SA(b, h) + aoff + m * 2048 + k * 1024); } while (0)
; #define PG8_LDB(dst, b, h) do { _Pragma("unroll") for (int n = 0; n < 2; ++n) _Pragma("unroll") for (int k = 0; k < 2; ++k) dst[n][k] = *(const PG8_LAS bf16x8*)(lds + PG8_SB(b, h) + boff + n * 2048 + k * 1024); } while (0)
; #define PG8_MMA(ai, bj, At, Bt) do { __builtin_amdgcn_s_setprio(1); _Pragma("unroll") for (int m = 0; m < 4; ++m) _Pragma("unroll") for (int n = 0; n < 2; ++n) _Pragma("unroll") for (int k = 0; k < 2; ++k) \
;         acc[ai][bj][m][n] = __builtin_amdgcn_mfma_f32_16x16x32_bf16(Bt[n][k], At[m][k], acc[ai][bj][m][n], 0, 0, 0); __builtin_amdgcn_s_setprio(0); } while (0)
; #define PG8_WAIT_V(n) asm volatile("s_waitcnt vmcnt(" #n ")" ::: "memory")
; #define PG8_WAIT_L(n) asm volatile("s_waitcnt lgkmcnt(" #n ")" ::: "memory")
; #define PG8_BAR __builtin_amdgcn_s_barrier()
; #define PG8_SCHED __builtin_amdgcn_sched_barrier(0)
; template <class Epi, class Sched, bool ALIGN_EPI = false, bool SP2 = false>
; __device__ __forceinline__ void gemm_phase(PG8_LAS unsigned char* lds, const Gemm g, const Sched& S, const Epi& E, int wave_in) {
;     ...
;             PG8_WAIT_V(8); PG8_WAIT_L(0); PG8_BAR; PG8_MMA(1, 0, At, B0); PG8_MMA(1, 1, At, B1); PG8_BAR; PG8_SCHED;
;             PG8_LDB(B0, 1, 0); PG8_LDB(B1, 1, 1); PG8_SCHED; PG8_LDA(At, 1, 0); PG8_STAGE(PG8_SA(0, 1), a2 + hstep, voffA);
;             PG8_WAIT_V(8); PG8_WAIT_L(0); PG8_BAR; PG8_MMA(0, 0, At, B0); PG8_MMA(0, 1, At, B1); PG8_BAR; PG8_SCHED;
	s_setprio 1
	s_waitcnt lgkmcnt(0)
	v_mfma_f32_16x16x32_bf16 v[60:63], v[112:115], v[160:163], 0
	v_mfma_f32_16x16x32_bf16 v[56:59], v[124:127], v[160:163], 0
	v_mfma_f32_16x16x32_bf16 v[40:43], v[124:127], v[168:171], 0
	v_mfma_f32_16x16x32_bf16 v[44:47], v[112:115], v[168:171], 0
	v_mfma_f32_16x16x32_bf16 v[28:31], v[112:115], v[176:179], 0
	v_mfma_f32_16x16x32_bf16 v[24:27], v[124:127], v[176:179], 0
	v_mfma_f32_16x16x32_bf16 v[8:11], v[124:127], v[184:187], 0
	v_mfma_f32_16x16x32_bf16 v[12:15], v[112:115], v[184:187], 0
	v_mfma_f32_16x16x32_bf16 v[60:63], v[120:123], v[164:167], v[60:63]
	v_mfma_f32_16x16x32_bf16 v[56:59], v[128:131], v[164:167], v[56:59]
	v_mfma_f32_16x16x32_bf16 v[40:43], v[128:131], v[172:175], v[40:43]
	v_mfma_f32_16x16x32_bf16 v[44:47], v[120:123], v[172:175], v[44:47]
	v_mfma_f32_16x16x32_bf16 v[28:31], v[120:123], v[180:183], v[28:31]
	v_mfma_f32_16x16x32_bf16 v[24:27], v[128:131], v[180:183], v[24:27]
	v_mfma_f32_16x16x32_bf16 v[8:11], v[128:131], v[188:191], v[8:11]
	v_mfma_f32_16x16x32_bf16 v[12:15], v[120:123], v[188:191], v[12:15]
	s_setprio 0
	s_setprio 1
	v_mfma_f32_16x16x32_bf16 v[52:55], v[136:139], v[160:163], 0
	v_mfma_f32_16x16x32_bf16 v[48:51], v[144:147], v[160:163], 0
	v_mfma_f32_16x16x32_bf16 v[32:35], v[144:147], v[168:171], 0
	v_mfma_f32_16x16x32_bf16 v[36:39], v[136:139], v[168:171], 0
	v_mfma_f32_16x16x32_bf16 v[20:23], v[136:139], v[176:179], 0
	v_mfma_f32_16x16x32_bf16 v[16:19], v[144:147], v[176:179], 0
	v_mfma_f32_16x16x32_bf16 v[0:3], v[144:147], v[184:187], 0
	v_mfma_f32_16x16x32_bf16 v[4:7], v[136:139], v[184:187], 0
	v_mfma_f32_16x16x32_bf16 v[52:55], v[140:143], v[164:167], v[52:55]
	v_mfma_f32_16x16x32_bf16 v[48:51], v[156:159], v[164:167], v[48:51]
	v_mfma_f32_16x16x32_bf16 v[32:35], v[156:159], v[172:175], v[32:35]
	v_mfma_f32_16x16x32_bf16 v[36:39], v[140:143], v[172:175], v[36:39]
	v_mfma_f32_16x16x32_bf16 v[20:23], v[140:143], v[180:183], v[20:23]
	v_mfma_f32_16x16x32_bf16 v[16:19], v[156:159], v[180:183], v[16:19]
	v_mfma_f32_16x16x32_bf16 v[0:3], v[156:159], v[188:191], v[0:3]
	v_mfma_f32_16x16x32_bf16 v[4:7], v[140:143], v[188:191], v[4:7]
	s_setprio 0
	s_barrier
	s_add_i32 s53, s65, 0x100
	s_add_i32 s69, s52, 0x100
	v_add_u32_e32 v128, s53, v249
	v_add_u32_e32 v156, s69, v249
	ds_read_b128 v[112:115], v128
	ds_read_b128 v[120:123], v128 offset:1024
	ds_read_b128 v[124:127], v128 offset:2048
	ds_read_b128 v[128:131], v128 offset:3072
	ds_read_b128 v[136:139], v156
	ds_read_b128 v[140:143], v156 offset:1024
	ds_read_b128 v[144:147], v156 offset:2048
	ds_read_b128 v[156:159], v156 offset:3072
	s_add_u32 s26, s26, 0x40000
	s_addc_u32 s27, s27, 0
	s_mov_b32 m0, s47
	v_lshl_add_u64 v[216:217], s[26:27], 0, v[202:203]
	ds_read_b128 v[160:163], v251 offset:32768
	ds_read_b128 v[164:167], v251 offset:33792
	ds_read_b128 v[168:171], v251 offset:34816
	ds_read_b128 v[172:175], v251 offset:35840
	ds_read_b128 v[176:179], v251 offset:36864
	ds_read_b128 v[180:183], v251 offset:37888
	ds_read_b128 v[184:187], v251 offset:38912
	ds_read_b128 v[188:191], v251 offset:39936
	global_load_lds_dwordx4 v[216:217], off
	v_lshl_add_u64 v[216:217], s[26:27], 0, v[200:201]
	s_mov_b32 m0, s60
	s_nop 0
	global_load_lds_dwordx4 v[216:217], off
	s_waitcnt vmcnt(8)
	s_waitcnt lgkmcnt(0)
	s_barrier
	s_setprio 1
	s_waitcnt lgkmcnt(0)
	v_mfma_f32_16x16x32_bf16 v[152:155], v[112:115], v[160:163], v[152:155]
	v_mfma_f32_16x16x32_bf16 v[148:151], v[124:127], v[160:163], v[148:151]
	v_mfma_f32_16x16x32_bf16 v[104:107], v[124:127], v[168:171], v[104:107]
	v_mfma_f32_16x16x32_bf16 v[108:111], v[112:115], v[168:171], v[108:111]
	v_mfma_f32_16x16x32_bf16 v[92:95], v[112:115], v[176:179], v[92:95]
	v_mfma_f32_16x16x32_bf16 v[88:91], v[124:127], v[176:179], v[88:91]
	v_mfma_f32_16x16x32_bf16 v[72:75], v[124:127], v[184:187], v[72:75]
	v_mfma_f32_16x16x32_bf16 v[76:79], v[112:115], v[184:187], v[76:79]
	v_mfma_f32_16x16x32_bf16 v[152:155], v[120:123], v[164:167], v[152:155]
	v_mfma_f32_16x16x32_bf16 v[148:151], v[128:131], v[164:167], v[148:151]
	v_mfma_f32_16x16x32_bf16 v[104:107], v[128:131], v[172:175], v[104:107]
	v_mfma_f32_16x16x32_bf16 v[108:111], v[120:123], v[172:175], v[108:111]
	v_mfma_f32_16x16x32_bf16 v[92:95], v[120:123], v[180:183], v[92:95]
	v_mfma_f32_16x16x32_bf16 v[88:91], v[128:131], v[180:183], v[88:91]
	v_mfma_f32_16x16x32_bf16 v[72:75], v[128:131], v[188:191], v[72:75]
	v_mfma_f32_16x16x32_bf16 v[76:79], v[120:123], v[188:191], v[76:79]
	s_setprio 0
	s_setprio 1
	v_mfma_f32_16x16x32_bf16 v[132:135], v[136:139], v[160:163], v[132:135]
	v_mfma_f32_16x16x32_bf16 v[116:119], v[144:147], v[160:163], v[116:119]
	v_mfma_f32_16x16x32_bf16 v[96:99], v[144:147], v[168:171], v[96:99]
	v_mfma_f32_16x16x32_bf16 v[100:103], v[136:139], v[168:171], v[100:103]
	v_mfma_f32_16x16x32_bf16 v[84:87], v[136:139], v[176:179], v[84:87]
	v_mfma_f32_16x16x32_bf16 v[80:83], v[144:147], v[176:179], v[80:83]
	v_mfma_f32_16x16x32_bf16 v[64:67], v[144:147], v[184:187], v[64:67]
	v_mfma_f32_16x16x32_bf16 v[68:71], v[136:139], v[184:187], v[68:71]
	v_mfma_f32_16x16x32_bf16 v[132:135], v[140:143], v[164:167], v[132:135]
	v_mfma_f32_16x16x32_bf16 v[116:119], v[156:159], v[164:167], v[116:119]
	v_mfma_f32_16x16x32_bf16 v[96:99], v[156:159], v[172:175], v[96:99]
	v_mfma_f32_16x16x32_bf16 v[100:103], v[140:143], v[172:175], v[100:103]
	v_mfma_f32_16x16x32_bf16 v[84:87], v[140:143], v[180:183], v[84:87]
	v_mfma_f32_16x16x32_bf16 v[80:83], v[156:159], v[180:183], v[80:83]
	v_mfma_f32_16x16x32_bf16 v[64:67], v[156:159], v[188:191], v[64:67]
	v_mfma_f32_16x16x32_bf16 v[68:71], v[140:143], v[188:191], v[68:71]
	s_setprio 0
	s_barrier
; #define PG8_STAGE(bufoff, gbase, voff) do { _Pragma("unroll") for (int _i = 0; _i < 2; ++_i) \
;         __builtin_amdgcn_global_load_lds((const unsigned*)((const char*)(gbase) + (voff)[_i]), (PG8_LAS unsigned*)(lds + (bufoff) + ldsw + _i * 8192), 16, 0, 0); } while (0)
; #define PG8_LDA(dst, b, h) do { _Pragma("unroll") for (int m = 0; m < 4; ++m) _Pragma("unroll") for (int k = 0; k < 2; ++k) dst[m][k] = *(const PG8_LAS bf16x8*)(lds + PG8_SA(b, h) + aoff + m * 2048 + k * 1024); } while (0)
; #define PG8_LDB(dst, b, h) do { _Pragma("unroll") for (int n = 0; n < 2; ++n) _Pragma("unroll") for (int k = 0; k < 2; ++k) dst[n][k] = *(const PG8_LAS bf16x8*)(lds + PG8_SB(b, h) + boff + n * 2048 + k * 1024); } while (0)
; #define PG8_MMA(ai, bj, At, Bt) do { __builtin_amdgcn_s_setprio(1); _Pragma("unroll") for (int m = 0; m < 4; ++m) _Pragma("unroll") for (int n = 0; n < 2; ++n) _Pragma("unroll") for (int k = 0; k < 2; ++k) \
;         acc[ai][bj][m][n] = __builtin_amdgcn_mfma_f32_16x16x32_bf16(Bt[n][k], At[m][k], acc[ai][bj][m][n], 0, 0, 0); __builtin_amdgcn_s_setprio(0); } while (0)
; #define PG8_WAIT_V(n) asm volatile("s_waitcnt vmcnt(" #n ")" ::: "memory")
; #define PG8_WAIT_L(n) asm volatile("s_waitcnt lgkmcnt(" #n ")" ::: "memory")
; #define PG8_BAR __builtin_amdgcn_s_barrier()
; #define PG8_SCHED __builtin_amdgcn_sched_barrier(0)
; template <class Epi, class Sched, bool ALIGN_EPI = false, bool SP2 = false>
; __device__ __forceinline__ void gemm_phase(PG8_LAS unsigned char* lds, const Gemm g, const Sched& S, const Epi& E, int wave_in) {
;     ...
;             PG8_LDB(B0, 1, 0); PG8_LDB(B1, 1, 1); PG8_SCHED; PG8_LDA(At, 1, 0); PG8_STAGE(PG8_SA(0, 1), a2 + hstep, voffA);
;             PG8_WAIT_V(8); PG8_WAIT_L(0); PG8_BAR; PG8_MMA(0, 0, At, B0); PG8_MMA(0, 1, At, B1); PG8_BAR; PG8_SCHED;
;             PG8_LDA(At, 1, 1); PG8_STAGE(PG8_SB(1, 0), b3, voffB); PG8_STAGE(PG8_SB(1, 1), b3 + hstep, voffB); PG8_STAGE(PG8_SA(1, 0), a3, voffA);
;             PG8_WAIT_V(8); PG8_WAIT_L(0); PG8_BAR; PG8_MMA(1, 0, At, B0); PG8_MMA(1, 1, At, B1); PG8_BAR; PG8_SCHED;
	s_add_i32 s26, s53, s38
	v_lshl_add_u64 v[208:209], v[208:209], 0, s[88:89]
	s_mov_b32 m0, s26
	ds_read_b128 v[160:163], v251 offset:49152
	ds_read_b128 v[164:167], v251 offset:50176
	ds_read_b128 v[168:171], v251 offset:51200
	ds_read_b128 v[172:175], v251 offset:52224
	ds_read_b128 v[176:179], v251 offset:53248
	ds_read_b128 v[180:183], v251 offset:54272
	ds_read_b128 v[184:187], v251 offset:55296
	ds_read_b128 v[188:191], v251 offset:56320
	global_load_lds_dwordx4 v[208:209], off
	s_add_i32 m0, s26, 0x2000
	s_add_u32 s24, s24, 0x40080
	v_lshl_add_u64 v[208:209], v[210:211], 0, s[88:89]
	s_addc_u32 s25, s25, 0
	s_add_i32 s26, s69, s38
	global_load_lds_dwordx4 v[208:209], off
	v_lshl_add_u64 v[208:209], s[24:25], 0, v[192:193]
	s_mov_b32 m0, s26
	s_nop 0
	global_load_lds_dwordx4 v[208:209], off
	v_lshl_add_u64 v[208:209], s[24:25], 0, v[198:199]
	s_add_i32 m0, s26, 0x2000
	s_nop 0
	global_load_lds_dwordx4 v[208:209], off
	v_lshl_add_u64 v[208:209], v[212:213], 0, s[88:89]
	s_mov_b32 m0, s62
	s_nop 0
	global_load_lds_dwordx4 v[208:209], off
	v_lshl_add_u64 v[208:209], v[214:215], 0, s[88:89]
	s_mov_b32 m0, s63
	s_nop 0
	global_load_lds_dwordx4 v[208:209], off
	s_waitcnt vmcnt(8)
	s_waitcnt lgkmcnt(0)
	s_barrier
	s_setprio 1
	s_waitcnt lgkmcnt(0)
	v_mfma_f32_16x16x32_bf16 v[60:63], v[112:115], v[160:163], v[60:63]
	v_mfma_f32_16x16x32_bf16 v[56:59], v[124:127], v[160:163], v[56:59]
	v_mfma_f32_16x16x32_bf16 v[40:43], v[124:127], v[168:171], v[40:43]
	v_mfma_f32_16x16x32_bf16 v[44:47], v[112:115], v[168:171], v[44:47]
	v_mfma_f32_16x16x32_bf16 v[28:31], v[112:115], v[176:179], v[28:31]
	v_mfma_f32_16x16x32_bf16 v[24:27], v[124:127], v[176:179], v[24:27]
	v_mfma_f32_16x16x32_bf16 v[8:11], v[124:127], v[184:187], v[8:11]
	v_mfma_f32_16x16x32_bf16 v[12:15], v[112:115], v[184:187], v[12:15]
	v_mfma_f32_16x16x32_bf16 v[60:63], v[120:123], v[164:167], v[60:63]
	v_mfma_f32_16x16x32_bf16 v[56:59], v[128:131], v[164:167], v[56:59]
	v_mfma_f32_16x16x32_bf16 v[40:43], v[128:131], v[172:175], v[40:43]
	v_mfma_f32_16x16x32_bf16 v[44:47], v[120:123], v[172:175], v[44:47]
	v_mfma_f32_16x16x32_bf16 v[28:31], v[120:123], v[180:183], v[28:31]
	v_mfma_f32_16x16x32_bf16 v[24:27], v[128:131], v[180:183], v[24:27]
	v_mfma_f32_16x16x32_bf16 v[8:11], v[128:131], v[188:191], v[8:11]
	v_mfma_f32_16x16x32_bf16 v[12:15], v[120:123], v[188:191], v[12:15]
	s_setprio 0
	s_setprio 1
	v_mfma_f32_16x16x32_bf16 v[52:55], v[136:139], v[160:163], v[52:55]
	v_mfma_f32_16x16x32_bf16 v[48:51], v[144:147], v[160:163], v[48:51]
	v_mfma_f32_16x16x32_bf16 v[32:35], v[144:147], v[168:171], v[32:35]
	v_mfma_f32_16x16x32_bf16 v[36:39], v[136:139], v[168:171], v[36:39]
	v_mfma_f32_16x16x32_bf16 v[20:23], v[136:139], v[176:179], v[20:23]
	v_mfma_f32_16x16x32_bf16 v[16:19], v[144:147], v[176:179], v[16:19]
	v_mfma_f32_16x16x32_bf16 v[0:3], v[144:147], v[184:187], v[0:3]
	v_mfma_f32_16x16x32_bf16 v[4:7], v[136:139], v[184:187], v[4:7]
	v_mfma_f32_16x16x32_bf16 v[52:55], v[140:143], v[164:167], v[52:55]
	v_mfma_f32_16x16x32_bf16 v[48:51], v[156:159], v[164:167], v[48:51]
	v_mfma_f32_16x16x32_bf16 v[32:35], v[156:159], v[172:175], v[32:35]
	v_mfma_f32_16x16x32_bf16 v[36:39], v[140:143], v[172:175], v[36:39]
	v_mfma_f32_16x16x32_bf16 v[20:23], v[140:143], v[180:183], v[20:23]
	v_mfma_f32_16x16x32_bf16 v[16:19], v[156:159], v[180:183], v[16:19]
	v_mfma_f32_16x16x32_bf16 v[0:3], v[156:159], v[188:191], v[0:3]
	v_mfma_f32_16x16x32_bf16 v[4:7], v[140:143], v[188:191], v[4:7]
	s_setprio 0
	s_barrier
	s_add_i32 s45, s45, 2
	s_add_u32 s34, s34, 0x100
	s_addc_u32 s44, s44, 0
	s_add_u32 s22, s22, 0x100
	s_addc_u32 s23, s23, 0
	s_cmp_gt_u32 s45, 13
	s_cbranch_scc1 .Lkexit_3
.LBB0_590:
	s_add_u32 s24, s22, 0xfffc0080
	s_addc_u32 s25, s23, -1
	s_add_i32 s53, s35, 0x100
	s_cmp_eq_u32 s45, 12
	s_cselect_b32 s27, s19, s25
	s_cselect_b32 s26, s18, s24
	s_cselect_b32 s25, s15, s44
	s_cselect_b32 s24, s17, s34
	s_add_i32 s69, s90, 0x100
	v_add_u32_e32 v128, s53, v249
	v_add_u32_e32 v156, s69, v249
	ds_read_b128 v[112:115], v128
	ds_read_b128 v[120:123], v128 offset:1024
	ds_read_b128 v[124:127], v128 offset:2048
	ds_read_b128 v[128:131], v128 offset:3072
	ds_read_b128 v[136:139], v156
	ds_read_b128 v[140:143], v156 offset:1024
	ds_read_b128 v[144:147], v156 offset:2048
	ds_read_b128 v[156:159], v156 offset:3072
	v_lshl_add_u64 v[208:209], s[22:23], 0, v[206:207]
	s_add_i32 m0, s39, 0xc000
	ds_read_b128 v[160:163], v251
	ds_read_b128 v[164:167], v251 offset:1024
	ds_read_b128 v[168:171], v251 offset:2048
	ds_read_b128 v[172:175], v251 offset:3072
	ds_read_b128 v[176:179], v251 offset:4096
	ds_read_b128 v[180:183], v251 offset:5120
	ds_read_b128 v[184:187], v251 offset:6144
	ds_read_b128 v[188:191], v251 offset:7168
	global_load_lds_dwordx4 v[208:209], off
	v_lshl_add_u64 v[208:209], s[22:23], 0, v[204:205]
	s_add_i32 m0, s39, 0xe000
	s_nop 0
	global_load_lds_dwordx4 v[208:209], off
	s_waitcnt vmcnt(8)
	s_waitcnt lgkmcnt(0)
	s_barrier
; #define PG8_STAGE(bufoff, gbase, voff) do { _Pragma("unroll") for (int _i = 0; _i < 2; ++_i) \
;         __builtin_amdgcn_global_load_lds((const unsigned*)((const char*)(gbase) + (voff)[_i]), (PG8_LAS unsigned*)(lds + (bufoff) + ldsw + _i * 8192), 16, 0, 0); } while (0)
; #define PG8_LDA(dst, b, h) do { _Pragma("unroll") for (int m = 0; m < 4; ++m) _Pragma("unroll") for (int k = 0; k < 2; ++k) dst[m][k] = *(const PG8_LAS bf16x8*)(lds + PG8_SA(b, h) + aoff + m * 2048 + k * 1024); } while (0)
; #define PG8_LDB(dst, b, h) do { _Pragma("unroll") for (int n = 0; n < 2; ++n) _Pragma("unroll") for (int k = 0; k < 2; ++k) dst[n][k] = *(const PG8_LAS bf16x8*)(lds + PG8_SB(b, h) + boff + n * 2048 + k * 1024); } while (0)
; #define PG8_MMA(ai, bj, At, Bt) do { __builtin_amdgcn_s_setprio(1); _Pragma("unroll") for (int m = 0; m < 4; ++m) _Pragma("unroll") for (int n = 0; n < 2; ++n) _Pragma("unroll") for (int k = 0; k < 2; ++k) \
;         acc[ai][bj][m][n] = __builtin_amdgcn_mfma_f32_16x16x32_bf16(Bt[n][k], At[m][k], acc[ai][bj][m][n], 0, 0, 0); __builtin_amdgcn_s_setprio(0); } while (0)
; #define PG8_WAIT_V(n) asm volatile("s_waitcnt vmcnt(" #n ")" ::: "memory")
; #define PG8_WAIT_L(n) asm volatile("s_waitcnt lgkmcnt(" #n ")" ::: "memory")
; #define PG8_BAR __builtin_amdgcn_s_barrier()
; #define PG8_SCHED __builtin_amdgcn_sched_barrier(0)
; template <class Epi, class Sched, bool ALIGN_EPI = false, bool SP2 = false>
; __device__ __forceinline__ void gemm_phase(PG8_LAS unsigned char* lds, const Gemm g, const Sched& S, const Epi& E, int wave_in) {
;     ...
;             PG8_LDB(B0, 0, 0); PG8_LDB(B1, 0, 1); PG8_SCHED; PG8_LDA(At, 0, 0); PG8_STAGE(PG8_SA(1, 1), a1 + hstep, voffA);
;             PG8_WAIT_V(8); PG8_WAIT_L(0); PG8_BAR; PG8_MMA(0, 0, At, B0); PG8_MMA(0, 1, At, B1); PG8_BAR; PG8_SCHED;
;             PG8_LDA(At, 0, 1); PG8_STAGE(PG8_SB(0, 0), b2, voffB); PG8_STAGE(PG8_SB(0, 1), b2 + hstep, voffB); PG8_STAGE(PG8_SA(0, 0), a2, voffA);
;             PG8_WAIT_V(8); PG8_WAIT_L(0); PG8_BAR; PG8_MMA(1, 0, At, B0); PG8_MMA(1, 1, At, B1); PG8_BAR; PG8_SCHED;
	s_setprio 1
	s_waitcnt lgkmcnt(0)
	v_mfma_f32_16x16x32_bf16 v[152:155], v[112:115], v[160:163], v[152:155]
	v_mfma_f32_16x16x32_bf16 v[148:151], v[124:127], v[160:163], v[148:151]
	v_mfma_f32_16x16x32_bf16 v[104:107], v[124:127], v[168:171], v[104:107]
	v_mfma_f32_16x16x32_bf16 v[108:111], v[112:115], v[168:171], v[108:111]
	v_mfma_f32_16x16x32_bf16 v[92:95], v[112:115], v[176:179], v[92:95]
	v_mfma_f32_16x16x32_bf16 v[88:91], v[124:127], v[176:179], v[88:91]
	v_mfma_f32_16x16x32_bf16 v[72:75], v[124:127], v[184:187], v[72:75]
	v_mfma_f32_16x16x32_bf16 v[76:79], v[112:115], v[184:187], v[76:79]
	v_mfma_f32_16x16x32_bf16 v[152:155], v[120:123], v[164:167], v[152:155]
	v_mfma_f32_16x16x32_bf16 v[148:151], v[128:131], v[164:167], v[148:151]
	v_mfma_f32_16x16x32_bf16 v[104:107], v[128:131], v[172:175], v[104:107]
	v_mfma_f32_16x16x32_bf16 v[108:111], v[120:123], v[172:175], v[108:111]
	v_mfma_f32_16x16x32_bf16 v[92:95], v[120:123], v[180:183], v[92:95]
	v_mfma_f32_16x16x32_bf16 v[88:91], v[128:131], v[180:183], v[88:91]
	v_mfma_f32_16x16x32_bf16 v[72:75], v[128:131], v[188:191], v[72:75]
	v_mfma_f32_16x16x32_bf16 v[76:79], v[120:123], v[188:191], v[76:79]
	s_setprio 0
	s_setprio 1
	v_mfma_f32_16x16x32_bf16 v[132:135], v[136:139], v[160:163], v[132:135]
	v_mfma_f32_16x16x32_bf16 v[116:119], v[144:147], v[160:163], v[116:119]
	v_mfma_f32_16x16x32_bf16 v[96:99], v[144:147], v[168:171], v[96:99]
	v_mfma_f32_16x16x32_bf16 v[100:103], v[136:139], v[168:171], v[100:103]
	v_mfma_f32_16x16x32_bf16 v[84:87], v[136:139], v[176:179], v[84:87]
	v_mfma_f32_16x16x32_bf16 v[80:83], v[144:147], v[176:179], v[80:83]
	v_mfma_f32_16x16x32_bf16 v[64:67], v[144:147], v[184:187], v[64:67]
	v_mfma_f32_16x16x32_bf16 v[68:71], v[136:139], v[184:187], v[68:71]
	v_mfma_f32_16x16x32_bf16 v[132:135], v[140:143], v[164:167], v[132:135]
	v_mfma_f32_16x16x32_bf16 v[116:119], v[156:159], v[164:167], v[116:119]
	v_mfma_f32_16x16x32_bf16 v[96:99], v[156:159], v[172:175], v[96:99]
	v_mfma_f32_16x16x32_bf16 v[100:103], v[140:143], v[172:175], v[100:103]
	v_mfma_f32_16x16x32_bf16 v[84:87], v[140:143], v[180:183], v[84:87]
	v_mfma_f32_16x16x32_bf16 v[80:83], v[156:159], v[180:183], v[80:83]
	v_mfma_f32_16x16x32_bf16 v[64:67], v[156:159], v[188:191], v[64:67]
	v_mfma_f32_16x16x32_bf16 v[68:71], v[140:143], v[188:191], v[68:71]
	s_setprio 0
	s_barrier
	s_add_i32 s53, s53, s38
	v_lshl_add_u64 v[208:209], s[24:25], 0, v[192:193]
	s_mov_b32 m0, s53
	ds_read_b128 v[160:163], v251 offset:16384
	ds_read_b128 v[164:167], v251 offset:17408
	ds_read_b128 v[168:171], v251 offset:18432
	ds_read_b128 v[172:175], v251 offset:19456
	ds_read_b128 v[176:179], v251 offset:20480
	ds_read_b128 v[180:183], v251 offset:21504
	ds_read_b128 v[184:187], v251 offset:22528
	ds_read_b128 v[188:191], v251 offset:23552
	global_load_lds_dwordx4 v[208:209], off
	s_add_i32 m0, s53, 0x2000
	s_add_u32 s72, s24, 0x40000
	v_lshl_add_u64 v[210:211], s[24:25], 0, v[198:199]
	s_addc_u32 s73, s25, 0
	s_add_i32 s53, s69, s38
	global_load_lds_dwordx4 v[210:211], off
	v_lshl_add_u64 v[212:213], s[72:73], 0, v[192:193]
	s_mov_b32 m0, s53
	v_lshl_add_u64 v[214:215], s[26:27], 0, v[200:201]
	global_load_lds_dwordx4 v[212:213], off
	v_lshl_add_u64 v[212:213], s[72:73], 0, v[198:199]
	s_add_i32 m0, s53, 0x2000
	s_nop 0
	global_load_lds_dwordx4 v[212:213], off
	v_lshl_add_u64 v[212:213], s[26:27], 0, v[202:203]
	s_mov_b32 m0, s39
	s_nop 0
	global_load_lds_dwordx4 v[212:213], off
	s_mov_b32 m0, s46
	s_nop 0
	global_load_lds_dwordx4 v[214:215], off
	s_waitcnt vmcnt(8)
	s_waitcnt lgkmcnt(0)
	s_barrier
	s_setprio 1
	s_waitcnt lgkmcnt(0)
	v_mfma_f32_16x16x32_bf16 v[60:63], v[112:115], v[160:163], v[60:63]
	v_mfma_f32_16x16x32_bf16 v[56:59], v[124:127], v[160:163], v[56:59]
	v_mfma_f32_16x16x32_bf16 v[40:43], v[124:127], v[168:171], v[40:43]
	v_mfma_f32_16x16x32_bf16 v[44:47], v[112:115], v[168:171], v[44:47]
	v_mfma_f32_16x16x32_bf16 v[28:31], v[112:115], v[176:179], v[28:31]
	v_mfma_f32_16x16x32_bf16 v[24:27], v[124:127], v[176:179], v[24:27]
	v_mfma_f32_16x16x32_bf16 v[8:11], v[124:127], v[184:187], v[8:11]
	v_mfma_f32_16x16x32_bf16 v[12:15], v[112:115], v[184:187], v[12:15]
	v_mfma_f32_16x16x32_bf16 v[60:63], v[120:123], v[164:167], v[60:63]
	v_mfma_f32_16x16x32_bf16 v[56:59], v[128:131], v[164:167], v[56:59]
	v_mfma_f32_16x16x32_bf16 v[40:43], v[128:131], v[172:175], v[40:43]
	v_mfma_f32_16x16x32_bf16 v[44:47], v[120:123], v[172:175], v[44:47]
	v_mfma_f32_16x16x32_bf16 v[28:31], v[120:123], v[180:183], v[28:31]
	v_mfma_f32_16x16x32_bf16 v[24:27], v[128:131], v[180:183], v[24:27]
	v_mfma_f32_16x16x32_bf16 v[8:11], v[128:131], v[188:191], v[8:11]
	v_mfma_f32_16x16x32_bf16 v[12:15], v[120:123], v[188:191], v[12:15]
	s_setprio 0
	s_setprio 1
	v_mfma_f32_16x16x32_bf16 v[52:55], v[136:139], v[160:163], v[52:55]
	v_mfma_f32_16x16x32_bf16 v[48:51], v[144:147], v[160:163], v[48:51]
	v_mfma_f32_16x16x32_bf16 v[32:35], v[144:147], v[168:171], v[32:35]
	v_mfma_f32_16x16x32_bf16 v[36:39], v[136:139], v[168:171], v[36:39]
	v_mfma_f32_16x16x32_bf16 v[20:23], v[136:139], v[176:179], v[20:23]
	v_mfma_f32_16x16x32_bf16 v[16:19], v[144:147], v[176:179], v[16:19]
	v_mfma_f32_16x16x32_bf16 v[0:3], v[144:147], v[184:187], v[0:3]
	v_mfma_f32_16x16x32_bf16 v[4:7], v[136:139], v[184:187], v[4:7]
	v_mfma_f32_16x16x32_bf16 v[52:55], v[140:143], v[164:167], v[52:55]
	v_mfma_f32_16x16x32_bf16 v[48:51], v[156:159], v[164:167], v[48:51]
	v_mfma_f32_16x16x32_bf16 v[32:35], v[156:159], v[172:175], v[32:35]
	v_mfma_f32_16x16x32_bf16 v[36:39], v[140:143], v[172:175], v[36:39]
	v_mfma_f32_16x16x32_bf16 v[20:23], v[140:143], v[180:183], v[20:23]
	v_mfma_f32_16x16x32_bf16 v[16:19], v[156:159], v[180:183], v[16:19]
	v_mfma_f32_16x16x32_bf16 v[0:3], v[156:159], v[188:191], v[0:3]
	v_mfma_f32_16x16x32_bf16 v[4:7], v[140:143], v[188:191], v[4:7]
	s_setprio 0
	s_barrier
; #define PG8_STAGE(bufoff, gbase, voff) do { _Pragma("unroll") for (int _i = 0; _i < 2; ++_i) \
;         __builtin_amdgcn_global_load_lds((const unsigned*)((const char*)(gbase) + (voff)[_i]), (PG8_LAS unsigned*)(lds + (bufoff) + ldsw + _i * 8192), 16, 0, 0); } while (0)
; #define PG8_LDA(dst, b, h) do { _Pragma("unroll") for (int m = 0; m < 4; ++m) _Pragma("unroll") for (int k = 0; k < 2; ++k) dst[m][k] = *(const PG8_LAS bf16x8*)(lds + PG8_SA(b, h) + aoff + m * 2048 + k * 1024); } while (0)
; #define PG8_LDB(dst, b, h) do { _Pragma("unroll") for (int n = 0; n < 2; ++n) _Pragma("unroll") for (int k = 0; k < 2; ++k) dst[n][k] = *(const PG8_LAS bf16x8*)(lds + PG8_SB(b, h) + boff + n * 2048 + k * 1024); } while (0)
; #define PG8_MMA(ai, bj, At, Bt) do { __builtin_amdgcn_s_setprio(1); _Pragma("unroll") for (int m = 0; m < 4; ++m) _Pragma("unroll") for (int n = 0; n < 2; ++n) _Pragma("unroll") for (int k = 0; k < 2; ++k) \
;         acc[ai][bj][m][n] = __builtin_amdgcn_mfma_f32_16x16x32_bf16(Bt[n][k], At[m][k], acc[ai][bj][m][n], 0, 0, 0); __builtin_amdgcn_s_setprio(0); } while (0)
; #define PG8_WAIT_V(n) asm volatile("s_waitcnt vmcnt(" #n ")" ::: "memory")
; #define PG8_WAIT_L(n) asm volatile("s_waitcnt lgkmcnt(" #n ")" ::: "memory")
; #define PG8_BAR __builtin_amdgcn_s_barrier()
; #define PG8_SCHED __builtin_amdgcn_sched_barrier(0)
; template <class Epi, class Sched, bool ALIGN_EPI = false, bool SP2 = false>
; __device__ __forceinline__ void gemm_phase(PG8_LAS unsigned char* lds, const Gemm g, const Sched& S, const Epi& E, int wave_in) {
;     ...
;             PG8_LDB(B0, 1, 0); PG8_LDB(B1, 1, 1); PG8_SCHED; PG8_LDA(At, 1, 0); PG8_STAGE(PG8_SA(0, 1), a2 + hstep, voffA);
;             PG8_WAIT_V(8); PG8_WAIT_L(0); PG8_BAR; PG8_MMA(0, 0, At, B0); PG8_MMA(0, 1, At, B1); PG8_BAR; PG8_SCHED;
	s_add_i32 s53, s65, 0x100
	s_add_i32 s69, s52, 0x100
	v_add_u32_e32 v128, s53, v249
	v_add_u32_e32 v156, s69, v249
	ds_read_b128 v[112:115], v128
	ds_read_b128 v[120:123], v128 offset:1024
	ds_read_b128 v[124:127], v128 offset:2048
	ds_read_b128 v[128:131], v128 offset:3072
	ds_read_b128 v[136:139], v156
	ds_read_b128 v[140:143], v156 offset:1024
	ds_read_b128 v[144:147], v156 offset:2048
	ds_read_b128 v[156:159], v156 offset:3072
	s_add_u32 s26, s26, 0x40000
	s_addc_u32 s27, s27, 0
	s_mov_b32 m0, s47
	v_lshl_add_u64 v[216:217], s[26:27], 0, v[202:203]
	ds_read_b128 v[160:163], v251 offset:32768
	ds_read_b128 v[164:167], v251 offset:33792
	ds_read_b128 v[168:171], v251 offset:34816
	ds_read_b128 v[172:175], v251 offset:35840
	ds_read_b128 v[176:179], v251 offset:36864
	ds_read_b128 v[180:183], v251 offset:37888
	ds_read_b128 v[184:187], v251 offset:38912
	ds_read_b128 v[188:191], v251 offset:39936
	global_load_lds_dwordx4 v[216:217], off
	v_lshl_add_u64 v[216:217], s[26:27], 0, v[200:201]
	s_mov_b32 m0, s60
	s_nop 0
	global_load_lds_dwordx4 v[216:217], off
	s_waitcnt vmcnt(8)
	s_waitcnt lgkmcnt(0)
	s_barrier
	s_setprio 1
	s_waitcnt lgkmcnt(0)
	v_mfma_f32_16x16x32_bf16 v[152:155], v[112:115], v[160:163], v[152:155]
	v_mfma_f32_16x16x32_bf16 v[148:151], v[124:127], v[160:163], v[148:151]
	v_mfma_f32_16x16x32_bf16 v[104:107], v[124:127], v[168:171], v[104:107]
	v_mfma_f32_16x16x32_bf16 v[108:111], v[112:115], v[168:171], v[108:111]
	v_mfma_f32_16x16x32_bf16 v[92:95], v[112:115], v[176:179], v[92:95]
	v_mfma_f32_16x16x32_bf16 v[88:91], v[124:127], v[176:179], v[88:91]
	v_mfma_f32_16x16x32_bf16 v[72:75], v[124:127], v[184:187], v[72:75]
	v_mfma_f32_16x16x32_bf16 v[76:79], v[112:115], v[184:187], v[76:79]
	v_mfma_f32_16x16x32_bf16 v[152:155], v[120:123], v[164:167], v[152:155]
	v_mfma_f32_16x16x32_bf16 v[148:151], v[128:131], v[164:167], v[148:151]
	v_mfma_f32_16x16x32_bf16 v[104:107], v[128:131], v[172:175], v[104:107]
	v_mfma_f32_16x16x32_bf16 v[108:111], v[120:123], v[172:175], v[108:111]
	v_mfma_f32_16x16x32_bf16 v[92:95], v[120:123], v[180:183], v[92:95]
	v_mfma_f32_16x16x32_bf16 v[88:91], v[128:131], v[180:183], v[88:91]
	v_mfma_f32_16x16x32_bf16 v[72:75], v[128:131], v[188:191], v[72:75]
	v_mfma_f32_16x16x32_bf16 v[76:79], v[120:123], v[188:191], v[76:79]
	s_setprio 0
	s_setprio 1
	v_mfma_f32_16x16x32_bf16 v[132:135], v[136:139], v[160:163], v[132:135]
	v_mfma_f32_16x16x32_bf16 v[116:119], v[144:147], v[160:163], v[116:119]
	v_mfma_f32_16x16x32_bf16 v[96:99], v[144:147], v[168:171], v[96:99]
	v_mfma_f32_16x16x32_bf16 v[100:103], v[136:139], v[168:171], v[100:103]
	v_mfma_f32_16x16x32_bf16 v[84:87], v[136:139], v[176:179], v[84:87]
	v_mfma_f32_16x16x32_bf16 v[80:83], v[144:147], v[176:179], v[80:83]
	v_mfma_f32_16x16x32_bf16 v[64:67], v[144:147], v[184:187], v[64:67]
	v_mfma_f32_16x16x32_bf16 v[68:71], v[136:139], v[184:187], v[68:71]
	v_mfma_f32_16x16x32_bf16 v[132:135], v[140:143], v[164:167], v[132:135]
	v_mfma_f32_16x16x32_bf16 v[116:119], v[156:159], v[164:167], v[116:119]
	v_mfma_f32_16x16x32_bf16 v[96:99], v[156:159], v[172:175], v[96:99]
	v_mfma_f32_16x16x32_bf16 v[100:103], v[140:143], v[172:175], v[100:103]
	v_mfma_f32_16x16x32_bf16 v[84:87], v[140:143], v[180:183], v[84:87]
	v_mfma_f32_16x16x32_bf16 v[80:83], v[156:159], v[180:183], v[80:83]
	v_mfma_f32_16x16x32_bf16 v[64:67], v[156:159], v[188:191], v[64:67]
	v_mfma_f32_16x16x32_bf16 v[68:71], v[140:143], v[188:191], v[68:71]
	s_setprio 0
	s_barrier
; #define PG8_STAGE(bufoff, gbase, voff) do { _Pragma("unroll") for (int _i = 0; _i < 2; ++_i) \
;         __builtin_amdgcn_global_load_lds((const unsigned*)((const char*)(gbase) + (voff)[_i]), (PG8_LAS unsigned*)(lds + (bufoff) + ldsw + _i * 8192), 16, 0, 0); } while (0)
; #define PG8_LDA(dst, b, h) do { _Pragma("unroll") for (int m = 0; m < 4; ++m) _Pragma("unroll") for (int k = 0; k < 2; ++k) dst[m][k] = *(const PG8_LAS bf16x8*)(lds + PG8_SA(b, h) + aoff + m * 2048 + k * 1024); } while (0)
; #define PG8_MMA(ai, bj, At, Bt) do { __builtin_amdgcn_s_setprio(1); _Pragma("unroll") for (int m = 0; m < 4; ++m) _Pragma("unroll") for (int n = 0; n < 2; ++n) _Pragma("unroll") for (int k = 0; k < 2; ++k) \
;         acc[ai][bj][m][n] = __builtin_amdgcn_mfma_f32_16x16x32_bf16(Bt[n][k], At[m][k], acc[ai][bj][m][n], 0, 0, 0); __builtin_amdgcn_s_setprio(0); } while (0)
; #define PG8_WAIT_V(n) asm volatile("s_waitcnt vmcnt(" #n ")" ::: "memory")
; #define PG8_WAIT_L(n) asm volatile("s_waitcnt lgkmcnt(" #n ")" ::: "memory")
; #define PG8_BAR __builtin_amdgcn_s_barrier()
; #define PG8_SCHED __builtin_amdgcn_sched_barrier(0)
; template <class Epi, class Sched, bool ALIGN_EPI = false, bool SP2 = false>
; __device__ __forceinline__ void gemm_phase(PG8_LAS unsigned char* lds, const Gemm g, const Sched& S, const Epi& E, int wave_in) {
;     ...
;             PG8_LDA(At, 1, 1); PG8_STAGE(PG8_SB(1, 0), b3, voffB); PG8_STAGE(PG8_SB(1, 1), b3 + hstep, voffB); PG8_STAGE(PG8_SA(1, 0), a3, voffA);
;             PG8_WAIT_V(8); PG8_WAIT_L(0); PG8_BAR; PG8_MMA(1, 0, At, B0); PG8_MMA(1, 1, At, B1); PG8_BAR; PG8_SCHED;
	s_add_i32 s26, s53, s38
	v_lshl_add_u64 v[208:209], v[208:209], 0, s[88:89]
	s_mov_b32 m0, s26
	ds_read_b128 v[160:163], v251 offset:49152
	ds_read_b128 v[164:167], v251 offset:50176
	ds_read_b128 v[168:171], v251 offset:51200
	ds_read_b128 v[172:175], v251 offset:52224
	ds_read_b128 v[176:179], v251 offset:53248
	ds_read_b128 v[180:183], v251 offset:54272
	ds_read_b128 v[184:187], v251 offset:55296
	ds_read_b128 v[188:191], v251 offset:56320
	global_load_lds_dwordx4 v[208:209], off
	s_add_i32 m0, s26, 0x2000
	s_add_u32 s24, s24, 0x40080
	v_lshl_add_u64 v[208:209], v[210:211], 0, s[88:89]
	s_addc_u32 s25, s25, 0
	s_add_i32 s26, s69, s38
	global_load_lds_dwordx4 v[208:209], off
	v_lshl_add_u64 v[208:209], s[24:25], 0, v[192:193]
	s_mov_b32 m0, s26
	s_nop 0
	global_load_lds_dwordx4 v[208:209], off
	v_lshl_add_u64 v[208:209], s[24:25], 0, v[198:199]
	s_add_i32 m0, s26, 0x2000
	s_nop 0
	global_load_lds_dwordx4 v[208:209], off
	v_lshl_add_u64 v[208:209], v[212:213], 0, s[88:89]
	s_mov_b32 m0, s62
	s_nop 0
	global_load_lds_dwordx4 v[208:209], off
	v_lshl_add_u64 v[208:209], v[214:215], 0, s[88:89]
	s_mov_b32 m0, s63
	s_nop 0
	global_load_lds_dwordx4 v[208:209], off
	s_waitcnt vmcnt(8)
	s_waitcnt lgkmcnt(0)
	s_barrier
	s_setprio 1
	s_waitcnt lgkmcnt(0)
	v_mfma_f32_16x16x32_bf16 v[60:63], v[112:115], v[160:163], v[60:63]
	v_mfma_f32_16x16x32_bf16 v[56:59], v[124:127], v[160:163], v[56:59]
	v_mfma_f32_16x16x32_bf16 v[40:43], v[124:127], v[168:171], v[40:43]
	v_mfma_f32_16x16x32_bf16 v[44:47], v[112:115], v[168:171], v[44:47]
	v_mfma_f32_16x16x32_bf16 v[28:31], v[112:115], v[176:179], v[28:31]
	v_mfma_f32_16x16x32_bf16 v[24:27], v[124:127], v[176:179], v[24:27]
	v_mfma_f32_16x16x32_bf16 v[8:11], v[124:127], v[184:187], v[8:11]
	v_mfma_f32_16x16x32_bf16 v[12:15], v[112:115], v[184:187], v[12:15]
	v_mfma_f32_16x16x32_bf16 v[60:63], v[120:123], v[164:167], v[60:63]
	v_mfma_f32_16x16x32_bf16 v[56:59], v[128:131], v[164:167], v[56:59]
	v_mfma_f32_16x16x32_bf16 v[40:43], v[128:131], v[172:175], v[40:43]
	v_mfma_f32_16x16x32_bf16 v[44:47], v[120:123], v[172:175], v[44:47]
	v_mfma_f32_16x16x32_bf16 v[28:31], v[120:123], v[180:183], v[28:31]
	v_mfma_f32_16x16x32_bf16 v[24:27], v[128:131], v[180:183], v[24:27]
	v_mfma_f32_16x16x32_bf16 v[8:11], v[128:131], v[188:191], v[8:11]
	v_mfma_f32_16x16x32_bf16 v[12:15], v[120:123], v[188:191], v[12:15]
	s_setprio 0
	s_setprio 1
	v_mfma_f32_16x16x32_bf16 v[52:55], v[136:139], v[160:163], v[52:55]
	v_mfma_f32_16x16x32_bf16 v[48:51], v[144:147], v[160:163], v[48:51]
	v_mfma_f32_16x16x32_bf16 v[32:35], v[144:147], v[168:171], v[32:35]
	v_mfma_f32_16x16x32_bf16 v[36:39], v[136:139], v[168:171], v[36:39]
	v_mfma_f32_16x16x32_bf16 v[20:23], v[136:139], v[176:179], v[20:23]
	v_mfma_f32_16x16x32_bf16 v[16:19], v[144:147], v[176:179], v[16:19]
	v_mfma_f32_16x16x32_bf16 v[0:3], v[144:147], v[184:187], v[0:3]
	v_mfma_f32_16x16x32_bf16 v[4:7], v[136:139], v[184:187], v[4:7]
	v_mfma_f32_16x16x32_bf16 v[52:55], v[140:143], v[164:167], v[52:55]
	v_mfma_f32_16x16x32_bf16 v[48:51], v[156:159], v[164:167], v[48:51]
	v_mfma_f32_16x16x32_bf16 v[32:35], v[156:159], v[172:175], v[32:35]
	v_mfma_f32_16x16x32_bf16 v[36:39], v[140:143], v[172:175], v[36:39]
	v_mfma_f32_16x16x32_bf16 v[20:23], v[140:143], v[180:183], v[20:23]
	v_mfma_f32_16x16x32_bf16 v[16:19], v[156:159], v[180:183], v[16:19]
	v_mfma_f32_16x16x32_bf16 v[0:3], v[156:159], v[188:191], v[0:3]
	v_mfma_f32_16x16x32_bf16 v[4:7], v[140:143], v[188:191], v[4:7]
	s_setprio 0
	s_barrier
	s_add_i32 s45, s45, 2
	s_add_u32 s34, s34, 0x100
	s_addc_u32 s44, s44, 0
	s_add_u32 s22, s22, 0x100
	s_addc_u32 s23, s23, 0
	s_cmp_gt_u32 s45, 13
	s_cbranch_scc0 .LBB0_590

; #define PG8_STAGE(bufoff, gbase, voff) do { _Pragma("unroll") for (int _i = 0; _i < 2; ++_i) \
;         __builtin_amdgcn_global_load_lds((const unsigned*)((const char*)(gbase) + (voff)[_i]), (PG8_LAS unsigned*)(lds + (bufoff) + ldsw + _i * 8192), 16, 0, 0); } while (0)
; #define PG8_LDA(dst, b, h) do { _Pragma("unroll") for (int m = 0; m < 4; ++m) _Pragma("unroll") for (int k = 0; k < 2; ++k) dst[m][k] = *(const PG8_LAS bf16x8*)(lds + PG8_SA(b, h) + aoff + m * 2048 + k * 1024); } while (0)
; #define PG8_LDB(dst, b, h) do { _Pragma("unroll") for (int n = 0; n < 2; ++n) _Pragma("unroll") for (int k = 0; k < 2; ++k) dst[n][k] = *(const PG8_LAS bf16x8*)(lds + PG8_SB(b, h) + boff + n * 2048 + k * 1024); } while (0)
; #define PG8_WAIT_V(n) asm volatile("s_waitcnt vmcnt(" #n ")" ::: "memory")
; #define PG8_WAIT_L(n) asm volatile("s_waitcnt lgkmcnt(" #n ")" ::: "memory")
; #define PG8_BAR __builtin_amdgcn_s_barrier()
; #define PG8_SCHED __builtin_amdgcn_sched_barrier(0)
; template <class Epi, class Sched, bool ALIGN_EPI = false, bool SP2 = false>
; __device__ __forceinline__ void gemm_phase(PG8_LAS unsigned char* lds, const Gemm g, const Sched& S, const Epi& E, int wave_in) {
;     ...
;         const char* nA = has_next ? (const char*)g.A + (size_t)(nxt.pm >> g.ash) * g.astride + (size_t)nxt.pm * tstep : cA; const char* nB = has_next ? (const char*)g.Bt + (size_t)(nxt.pm >> g.bsh) * g.bstride + (size_t)nxt.pn * tstep : cB;
;         for (int t = 0; t < nt; t += 2) {
;             const bool last = (t == nt - 2);
;             const char* a1 = cA + (size_t)(t + 1) * kstep;
;             const char* a2 = last ? nA : cA + (size_t)(t + 2) * kstep; const char* b2 = last ? nB : cB + (size_t)(t + 2) * kstep;
;             const char* a3 = a2 + kstep; const char* b3 = b2 + kstep;
;             if (last && has_next) S.a_ready(nxt);
;             if constexpr (SP2) {
;             PG8_LDB(B0, 0, 0); PG8_LDB(B1, 0, 1); PG8_SCHED; PG8_LDA(At, 0, 0); PG8_STAGE(PG8_SA(1, 1), a1 + hstep, voffA);
;             PG8_WAIT_V(8); PG8_WAIT_L(0); PG8_BAR; PG8_MMA(0, 0, At, B0); PG8_MMA(0, 1, At, B1); PG8_BAR; PG8_SCHED;
;             PG8_LDA(At, 0, 1); PG8_STAGE(PG8_SB(0, 0), b2, voffB); PG8_STAGE(PG8_SB(0, 1), b2 + hstep, voffB); PG8_STAGE(PG8_SA(0, 0), a2, voffA);
;             PG8_WAIT_V(8); PG8_WAIT_L(0); PG8_BAR; PG8_MMA(1, 0, At, B0); PG8_MMA(1, 1, At, B1); PG8_BAR; PG8_SCHED;
.LBB0_686:
	s_ashr_i32 s17, s16, 31
	s_lshl_b64 s[18:19], s[16:17], 19
	s_add_u32 s18, s8, s18
	s_addc_u32 s19, s9, s19
	s_and_b64 s[20:21], s[42:43], exec
	s_cselect_b32 s17, s19, s25
	s_cselect_b32 s69, s18, s24
	s_ashr_i32 s20, s16, 5
	s_ashr_i32 s21, s20, 31
	s_lshl_b64 s[20:21], s[20:21], 21
	s_add_u32 s26, s31, s20
	s_addc_u32 s27, s33, s21
	s_ashr_i32 s13, s12, 31
	s_lshl_b64 s[20:21], s[12:13], 19
	s_add_u32 s20, s26, s20
	s_addc_u32 s21, s27, s21
	s_and_b64 s[26:27], s[42:43], exec
	s_cselect_b32 s13, s21, s23
	s_cselect_b32 s34, s20, s22
	s_add_u32 s53, s22, 0x100
	s_addc_u32 s71, s23, 0
	s_add_u32 s22, s24, 0x40080
	s_addc_u32 s23, s25, 0
	s_mov_b32 s72, -2
	s_add_u32 s24, s22, 0xfffc0080
	s_addc_u32 s25, s23, -1
	s_add_i32 s73, s35, 0x100
	s_cmp_eq_u32 s72, 12
	s_cselect_b32 s27, s17, s25
	s_cselect_b32 s26, s69, s24
	s_cselect_b32 s25, s13, s71
	s_cselect_b32 s24, s34, s53
	s_add_i32 s76, s90, 0x100
	v_add_u32_e32 v140, s73, v212
	v_add_u32_e32 v168, s76, v212
	ds_read_b128 v[128:131], v140
	ds_read_b128 v[132:135], v140 offset:1024
	ds_read_b128 v[136:139], v140 offset:2048
	ds_read_b128 v[140:143], v140 offset:3072
	ds_read_b128 v[156:159], v168
	ds_read_b128 v[160:163], v168 offset:1024
	ds_read_b128 v[164:167], v168 offset:2048
	ds_read_b128 v[168:171], v168 offset:3072
	v_lshl_add_u64 v[194:195], s[22:23], 0, v[154:155]
	s_add_i32 m0, s39, 0xc000
	ds_read_b128 v[172:175], v227
	ds_read_b128 v[176:179], v227 offset:1024
	ds_read_b128 v[180:183], v227 offset:2048
	ds_read_b128 v[184:187], v227 offset:3072
	ds_read_b128 v[188:191], v227 offset:4096
	ds_read_b128 v[198:201], v227 offset:5120
	ds_read_b128 v[202:205], v227 offset:6144
	ds_read_b128 v[206:209], v227 offset:7168
	global_load_lds_dwordx4 v[194:195], off
	v_lshl_add_u64 v[194:195], s[22:23], 0, v[152:153]
	s_add_i32 m0, s39, 0xe000
	s_nop 0
	global_load_lds_dwordx4 v[194:195], off
	s_waitcnt vmcnt(8)
	s_waitcnt lgkmcnt(0)
	s_barrier
	s_setprio 1
	s_waitcnt lgkmcnt(0)
	v_mfma_f32_16x16x32_bf16 v[124:127], v[128:131], v[172:175], 0
	v_mfma_f32_16x16x32_bf16 v[120:123], v[136:139], v[172:175], 0
	v_mfma_f32_16x16x32_bf16 v[104:107], v[136:139], v[180:183], 0
	v_mfma_f32_16x16x32_bf16 v[108:111], v[128:131], v[180:183], 0
	v_mfma_f32_16x16x32_bf16 v[96:99], v[128:131], v[188:191], 0
	v_mfma_f32_16x16x32_bf16 v[88:91], v[136:139], v[188:191], 0
	v_mfma_f32_16x16x32_bf16 v[72:75], v[136:139], v[202:205], 0
	v_mfma_f32_16x16x32_bf16 v[80:83], v[128:131], v[202:205], 0
	v_mfma_f32_16x16x32_bf16 v[124:127], v[132:135], v[176:179], v[124:127]
	v_mfma_f32_16x16x32_bf16 v[120:123], v[140:143], v[176:179], v[120:123]
	v_mfma_f32_16x16x32_bf16 v[104:107], v[140:143], v[184:187], v[104:107]
	v_mfma_f32_16x16x32_bf16 v[108:111], v[132:135], v[184:187], v[108:111]
	v_mfma_f32_16x16x32_bf16 v[96:99], v[132:135], v[198:201], v[96:99]
	v_mfma_f32_16x16x32_bf16 v[88:91], v[140:143], v[198:201], v[88:91]
	v_mfma_f32_16x16x32_bf16 v[72:75], v[140:143], v[206:209], v[72:75]
	v_mfma_f32_16x16x32_bf16 v[80:83], v[132:135], v[206:209], v[80:83]
	s_setprio 0
	s_setprio 1
	v_mfma_f32_16x16x32_bf16 v[116:119], v[156:159], v[172:175], 0
	v_mfma_f32_16x16x32_bf16 v[112:115], v[164:167], v[172:175], 0
	v_mfma_f32_16x16x32_bf16 v[92:95], v[164:167], v[180:183], 0
	v_mfma_f32_16x16x32_bf16 v[100:103], v[156:159], v[180:183], 0
	v_mfma_f32_16x16x32_bf16 v[84:87], v[156:159], v[188:191], 0
	v_mfma_f32_16x16x32_bf16 v[76:79], v[164:167], v[188:191], 0
	v_mfma_f32_16x16x32_bf16 v[64:67], v[164:167], v[202:205], 0
	v_mfma_f32_16x16x32_bf16 v[68:71], v[156:159], v[202:205], 0
	v_mfma_f32_16x16x32_bf16 v[116:119], v[160:163], v[176:179], v[116:119]
	v_mfma_f32_16x16x32_bf16 v[112:115], v[168:171], v[176:179], v[112:115]
	v_mfma_f32_16x16x32_bf16 v[92:95], v[168:171], v[184:187], v[92:95]
	v_mfma_f32_16x16x32_bf16 v[100:103], v[160:163], v[184:187], v[100:103]
	v_mfma_f32_16x16x32_bf16 v[84:87], v[160:163], v[198:201], v[84:87]
	v_mfma_f32_16x16x32_bf16 v[76:79], v[168:171], v[198:201], v[76:79]
	v_mfma_f32_16x16x32_bf16 v[64:67], v[168:171], v[206:209], v[64:67]
	v_mfma_f32_16x16x32_bf16 v[68:71], v[160:163], v[206:209], v[68:71]
	s_setprio 0
	s_barrier
	s_add_i32 s73, s73, s38
	v_lshl_add_u64 v[194:195], s[24:25], 0, v[148:149]
	s_mov_b32 m0, s73
	ds_read_b128 v[172:175], v227 offset:16384
	ds_read_b128 v[176:179], v227 offset:17408
	ds_read_b128 v[180:183], v227 offset:18432
	ds_read_b128 v[184:187], v227 offset:19456
	ds_read_b128 v[188:191], v227 offset:20480
	ds_read_b128 v[198:201], v227 offset:21504
	ds_read_b128 v[202:205], v227 offset:22528
	ds_read_b128 v[206:209], v227 offset:23552
	global_load_lds_dwordx4 v[194:195], off
	s_add_i32 m0, s73, 0x2000
	s_add_u32 s74, s24, 0x40000
	v_lshl_add_u64 v[196:197], s[24:25], 0, v[144:145]
	s_addc_u32 s75, s25, 0
	s_add_i32 s73, s76, s38
	global_load_lds_dwordx4 v[196:197], off
	v_lshl_add_u64 v[234:235], s[74:75], 0, v[148:149]
	s_mov_b32 m0, s73
	v_lshl_add_u64 v[236:237], s[26:27], 0, v[146:147]
	global_load_lds_dwordx4 v[234:235], off
	v_lshl_add_u64 v[234:235], s[74:75], 0, v[144:145]
	s_add_i32 m0, s73, 0x2000
	s_nop 0
	global_load_lds_dwordx4 v[234:235], off
	v_lshl_add_u64 v[234:235], s[26:27], 0, v[150:151]
	s_mov_b32 m0, s39
	s_nop 0
	global_load_lds_dwordx4 v[234:235], off
	s_mov_b32 m0, s44
	s_nop 0
	global_load_lds_dwordx4 v[236:237], off
	s_waitcnt vmcnt(8)
	s_waitcnt lgkmcnt(0)
	s_barrier
; #define PG8_STAGE(bufoff, gbase, voff) do { _Pragma("unroll") for (int _i = 0; _i < 2; ++_i) \
;         __builtin_amdgcn_global_load_lds((const unsigned*)((const char*)(gbase) + (voff)[_i]), (PG8_LAS unsigned*)(lds + (bufoff) + ldsw + _i * 8192), 16, 0, 0); } while (0)
; #define PG8_LDA(dst, b, h) do { _Pragma("unroll") for (int m = 0; m < 4; ++m) _Pragma("unroll") for (int k = 0; k < 2; ++k) dst[m][k] = *(const PG8_LAS bf16x8*)(lds + PG8_SA(b, h) + aoff + m * 2048 + k * 1024); } while (0)
; #define PG8_LDB(dst, b, h) do { _Pragma("unroll") for (int n = 0; n < 2; ++n) _Pragma("unroll") for (int k = 0; k < 2; ++k) dst[n][k] = *(const PG8_LAS bf16x8*)(lds + PG8_SB(b, h) + boff + n * 2048 + k * 1024); } while (0)
; #define PG8_MMA(ai, bj, At, Bt) do { __builtin_amdgcn_s_setprio(1); _Pragma("unroll") for (int m = 0; m < 4; ++m) _Pragma("unroll") for (int n = 0; n < 2; ++n) _Pragma("unroll") for (int k = 0; k < 2; ++k) \
;         acc[ai][bj][m][n] = __builtin_amdgcn_mfma_f32_16x16x32_bf16(Bt[n][k], At[m][k], acc[ai][bj][m][n], 0, 0, 0); __builtin_amdgcn_s_setprio(0); } while (0)
; #define PG8_WAIT_V(n) asm volatile("s_waitcnt vmcnt(" #n ")" ::: "memory")
; #define PG8_WAIT_L(n) asm volatile("s_waitcnt lgkmcnt(" #n ")" ::: "memory")
; #define PG8_BAR __builtin_amdgcn_s_barrier()
; #define PG8_SCHED __builtin_amdgcn_sched_barrier(0)
; template <class Epi, class Sched, bool ALIGN_EPI = false, bool SP2 = false>
; __device__ __forceinline__ void gemm_phase(PG8_LAS unsigned char* lds, const Gemm g, const Sched& S, const Epi& E, int wave_in) {
;     ...
;             PG8_WAIT_V(8); PG8_WAIT_L(0); PG8_BAR; PG8_MMA(1, 0, At, B0); PG8_MMA(1, 1, At, B1); PG8_BAR; PG8_SCHED;
;             PG8_LDB(B0, 1, 0); PG8_LDB(B1, 1, 1); PG8_SCHED; PG8_LDA(At, 1, 0); PG8_STAGE(PG8_SA(0, 1), a2 + hstep, voffA);
;             PG8_WAIT_V(8); PG8_WAIT_L(0); PG8_BAR; PG8_MMA(0, 0, At, B0); PG8_MMA(0, 1, At, B1); PG8_BAR; PG8_SCHED;
	s_setprio 1
	s_waitcnt lgkmcnt(0)
	v_mfma_f32_16x16x32_bf16 v[60:63], v[128:131], v[172:175], 0
	v_mfma_f32_16x16x32_bf16 v[56:59], v[136:139], v[172:175], 0
	v_mfma_f32_16x16x32_bf16 v[40:43], v[136:139], v[180:183], 0
	v_mfma_f32_16x16x32_bf16 v[48:51], v[128:131], v[180:183], 0
	v_mfma_f32_16x16x32_bf16 v[32:35], v[128:131], v[188:191], 0
	v_mfma_f32_16x16x32_bf16 v[24:27], v[136:139], v[188:191], 0
	v_mfma_f32_16x16x32_bf16 v[8:11], v[136:139], v[202:205], 0
	v_mfma_f32_16x16x32_bf16 v[16:19], v[128:131], v[202:205], 0
	v_mfma_f32_16x16x32_bf16 v[60:63], v[132:135], v[176:179], v[60:63]
	v_mfma_f32_16x16x32_bf16 v[56:59], v[140:143], v[176:179], v[56:59]
	v_mfma_f32_16x16x32_bf16 v[40:43], v[140:143], v[184:187], v[40:43]
	v_mfma_f32_16x16x32_bf16 v[48:51], v[132:135], v[184:187], v[48:51]
	v_mfma_f32_16x16x32_bf16 v[32:35], v[132:135], v[198:201], v[32:35]
	v_mfma_f32_16x16x32_bf16 v[24:27], v[140:143], v[198:201], v[24:27]
	v_mfma_f32_16x16x32_bf16 v[8:11], v[140:143], v[206:209], v[8:11]
	v_mfma_f32_16x16x32_bf16 v[16:19], v[132:135], v[206:209], v[16:19]
	s_setprio 0
	s_setprio 1
	v_mfma_f32_16x16x32_bf16 v[52:55], v[156:159], v[172:175], 0
	v_mfma_f32_16x16x32_bf16 v[44:47], v[164:167], v[172:175], 0
	v_mfma_f32_16x16x32_bf16 v[28:31], v[164:167], v[180:183], 0
	v_mfma_f32_16x16x32_bf16 v[36:39], v[156:159], v[180:183], 0
	v_mfma_f32_16x16x32_bf16 v[20:23], v[156:159], v[188:191], 0
	v_mfma_f32_16x16x32_bf16 v[12:15], v[164:167], v[188:191], 0
	v_mfma_f32_16x16x32_bf16 v[0:3], v[164:167], v[202:205], 0
	v_mfma_f32_16x16x32_bf16 v[4:7], v[156:159], v[202:205], 0
	v_mfma_f32_16x16x32_bf16 v[52:55], v[160:163], v[176:179], v[52:55]
	v_mfma_f32_16x16x32_bf16 v[44:47], v[168:171], v[176:179], v[44:47]
	v_mfma_f32_16x16x32_bf16 v[28:31], v[168:171], v[184:187], v[28:31]
	v_mfma_f32_16x16x32_bf16 v[36:39], v[160:163], v[184:187], v[36:39]
	v_mfma_f32_16x16x32_bf16 v[20:23], v[160:163], v[198:201], v[20:23]
	v_mfma_f32_16x16x32_bf16 v[12:15], v[168:171], v[198:201], v[12:15]
	v_mfma_f32_16x16x32_bf16 v[0:3], v[168:171], v[206:209], v[0:3]
	v_mfma_f32_16x16x32_bf16 v[4:7], v[160:163], v[206:209], v[4:7]
	s_setprio 0
	s_barrier
	s_add_i32 s73, s65, 0x100
	s_add_i32 s74, s52, 0x100
	v_add_u32_e32 v140, s73, v212
	v_add_u32_e32 v168, s74, v212
	ds_read_b128 v[128:131], v140
	ds_read_b128 v[132:135], v140 offset:1024
	ds_read_b128 v[136:139], v140 offset:2048
	ds_read_b128 v[140:143], v140 offset:3072
	ds_read_b128 v[156:159], v168
	ds_read_b128 v[160:163], v168 offset:1024
	ds_read_b128 v[164:167], v168 offset:2048
	ds_read_b128 v[168:171], v168 offset:3072
	s_add_u32 s26, s26, 0x40000
	s_addc_u32 s27, s27, 0
	s_mov_b32 m0, s45
	v_lshl_add_u64 v[238:239], s[26:27], 0, v[150:151]
	ds_read_b128 v[172:175], v227 offset:32768
	ds_read_b128 v[176:179], v227 offset:33792
	ds_read_b128 v[180:183], v227 offset:34816
	ds_read_b128 v[184:187], v227 offset:35840
	ds_read_b128 v[188:191], v227 offset:36864
	ds_read_b128 v[198:201], v227 offset:37888
	ds_read_b128 v[202:205], v227 offset:38912
	ds_read_b128 v[206:209], v227 offset:39936
	global_load_lds_dwordx4 v[238:239], off
	v_lshl_add_u64 v[238:239], s[26:27], 0, v[146:147]
	s_mov_b32 m0, s46
	s_nop 0
	global_load_lds_dwordx4 v[238:239], off
	s_waitcnt vmcnt(8)
	s_waitcnt lgkmcnt(0)
	s_barrier
	s_setprio 1
	s_waitcnt lgkmcnt(0)
	v_mfma_f32_16x16x32_bf16 v[124:127], v[128:131], v[172:175], v[124:127]
	v_mfma_f32_16x16x32_bf16 v[120:123], v[136:139], v[172:175], v[120:123]
	v_mfma_f32_16x16x32_bf16 v[104:107], v[136:139], v[180:183], v[104:107]
	v_mfma_f32_16x16x32_bf16 v[108:111], v[128:131], v[180:183], v[108:111]
	v_mfma_f32_16x16x32_bf16 v[96:99], v[128:131], v[188:191], v[96:99]
	v_mfma_f32_16x16x32_bf16 v[88:91], v[136:139], v[188:191], v[88:91]
	v_mfma_f32_16x16x32_bf16 v[72:75], v[136:139], v[202:205], v[72:75]
	v_mfma_f32_16x16x32_bf16 v[80:83], v[128:131], v[202:205], v[80:83]
	v_mfma_f32_16x16x32_bf16 v[124:127], v[132:135], v[176:179], v[124:127]
	v_mfma_f32_16x16x32_bf16 v[120:123], v[140:143], v[176:179], v[120:123]
	v_mfma_f32_16x16x32_bf16 v[104:107], v[140:143], v[184:187], v[104:107]
	v_mfma_f32_16x16x32_bf16 v[108:111], v[132:135], v[184:187], v[108:111]
	v_mfma_f32_16x16x32_bf16 v[96:99], v[132:135], v[198:201], v[96:99]
	v_mfma_f32_16x16x32_bf16 v[88:91], v[140:143], v[198:201], v[88:91]
	v_mfma_f32_16x16x32_bf16 v[72:75], v[140:143], v[206:209], v[72:75]
	v_mfma_f32_16x16x32_bf16 v[80:83], v[132:135], v[206:209], v[80:83]
	s_setprio 0
	s_setprio 1
	v_mfma_f32_16x16x32_bf16 v[116:119], v[156:159], v[172:175], v[116:119]
	v_mfma_f32_16x16x32_bf16 v[112:115], v[164:167], v[172:175], v[112:115]
	v_mfma_f32_16x16x32_bf16 v[92:95], v[164:167], v[180:183], v[92:95]
	v_mfma_f32_16x16x32_bf16 v[100:103], v[156:159], v[180:183], v[100:103]
	v_mfma_f32_16x16x32_bf16 v[84:87], v[156:159], v[188:191], v[84:87]
	v_mfma_f32_16x16x32_bf16 v[76:79], v[164:167], v[188:191], v[76:79]
	v_mfma_f32_16x16x32_bf16 v[64:67], v[164:167], v[202:205], v[64:67]
	v_mfma_f32_16x16x32_bf16 v[68:71], v[156:159], v[202:205], v[68:71]
	v_mfma_f32_16x16x32_bf16 v[116:119], v[160:163], v[176:179], v[116:119]
	v_mfma_f32_16x16x32_bf16 v[112:115], v[168:171], v[176:179], v[112:115]
	v_mfma_f32_16x16x32_bf16 v[92:95], v[168:171], v[184:187], v[92:95]
	v_mfma_f32_16x16x32_bf16 v[100:103], v[160:163], v[184:187], v[100:103]
	v_mfma_f32_16x16x32_bf16 v[84:87], v[160:163], v[198:201], v[84:87]
	v_mfma_f32_16x16x32_bf16 v[76:79], v[168:171], v[198:201], v[76:79]
	v_mfma_f32_16x16x32_bf16 v[64:67], v[168:171], v[206:209], v[64:67]
	v_mfma_f32_16x16x32_bf16 v[68:71], v[160:163], v[206:209], v[68:71]
	s_setprio 0
	s_barrier
; #define PG8_STAGE(bufoff, gbase, voff) do { _Pragma("unroll") for (int _i = 0; _i < 2; ++_i) \
;         __builtin_amdgcn_global_load_lds((const unsigned*)((const char*)(gbase) + (voff)[_i]), (PG8_LAS unsigned*)(lds + (bufoff) + ldsw + _i * 8192), 16, 0, 0); } while (0)
; #define PG8_LDA(dst, b, h) do { _Pragma("unroll") for (int m = 0; m < 4; ++m) _Pragma("unroll") for (int k = 0; k < 2; ++k) dst[m][k] = *(const PG8_LAS bf16x8*)(lds + PG8_SA(b, h) + aoff + m * 2048 + k * 1024); } while (0)
; #define PG8_LDB(dst, b, h) do { _Pragma("unroll") for (int n = 0; n < 2; ++n) _Pragma("unroll") for (int k = 0; k < 2; ++k) dst[n][k] = *(const PG8_LAS bf16x8*)(lds + PG8_SB(b, h) + boff + n * 2048 + k * 1024); } while (0)
; #define PG8_MMA(ai, bj, At, Bt) do { __builtin_amdgcn_s_setprio(1); _Pragma("unroll") for (int m = 0; m < 4; ++m) _Pragma("unroll") for (int n = 0; n < 2; ++n) _Pragma("unroll") for (int k = 0; k < 2; ++k) \
;         acc[ai][bj][m][n] = __builtin_amdgcn_mfma_f32_16x16x32_bf16(Bt[n][k], At[m][k], acc[ai][bj][m][n], 0, 0, 0); __builtin_amdgcn_s_setprio(0); } while (0)
; #define PG8_WAIT_V(n) asm volatile("s_waitcnt vmcnt(" #n ")" ::: "memory")
; #define PG8_WAIT_L(n) asm volatile("s_waitcnt lgkmcnt(" #n ")" ::: "memory")
; #define PG8_BAR __builtin_amdgcn_s_barrier()
; #define PG8_SCHED __builtin_amdgcn_sched_barrier(0)
; template <class Epi, class Sched, bool ALIGN_EPI = false, bool SP2 = false>
; __device__ __forceinline__ void gemm_phase(PG8_LAS unsigned char* lds, const Gemm g, const Sched& S, const Epi& E, int wave_in) {
;     ...
;             PG8_LDB(B0, 1, 0); PG8_LDB(B1, 1, 1); PG8_SCHED; PG8_LDA(At, 1, 0); PG8_STAGE(PG8_SA(0, 1), a2 + hstep, voffA);
;             PG8_WAIT_V(8); PG8_WAIT_L(0); PG8_BAR; PG8_MMA(0, 0, At, B0); PG8_MMA(0, 1, At, B1); PG8_BAR; PG8_SCHED;
;             PG8_LDA(At, 1, 1); PG8_STAGE(PG8_SB(1, 0), b3, voffB); PG8_STAGE(PG8_SB(1, 1), b3 + hstep, voffB); PG8_STAGE(PG8_SA(1, 0), a3, voffA);
;             PG8_WAIT_V(8); PG8_WAIT_L(0); PG8_BAR; PG8_MMA(1, 0, At, B0); PG8_MMA(1, 1, At, B1); PG8_BAR; PG8_SCHED;
	s_add_i32 s26, s73, s38
	v_lshl_add_u64 v[194:195], v[194:195], 0, s[88:89]
	s_mov_b32 m0, s26
	ds_read_b128 v[172:175], v227 offset:49152
	ds_read_b128 v[176:179], v227 offset:50176
	ds_read_b128 v[180:183], v227 offset:51200
	ds_read_b128 v[184:187], v227 offset:52224
	ds_read_b128 v[188:191], v227 offset:53248
	ds_read_b128 v[198:201], v227 offset:54272
	ds_read_b128 v[202:205], v227 offset:55296
	ds_read_b128 v[206:209], v227 offset:56320
	global_load_lds_dwordx4 v[194:195], off
	s_add_i32 m0, s26, 0x2000
	s_add_u32 s24, s24, 0x40080
	v_lshl_add_u64 v[194:195], v[196:197], 0, s[88:89]
	s_addc_u32 s25, s25, 0
	s_add_i32 s26, s74, s38
	global_load_lds_dwordx4 v[194:195], off
	v_lshl_add_u64 v[194:195], s[24:25], 0, v[148:149]
	s_mov_b32 m0, s26
	s_nop 0
	global_load_lds_dwordx4 v[194:195], off
	v_lshl_add_u64 v[194:195], s[24:25], 0, v[144:145]
	s_add_i32 m0, s26, 0x2000
	s_nop 0
	global_load_lds_dwordx4 v[194:195], off
	v_lshl_add_u64 v[194:195], v[234:235], 0, s[88:89]
	s_mov_b32 m0, s61
	s_nop 0
	global_load_lds_dwordx4 v[194:195], off
	v_lshl_add_u64 v[194:195], v[236:237], 0, s[88:89]
	s_mov_b32 m0, s62
	s_nop 0
	global_load_lds_dwordx4 v[194:195], off
	s_waitcnt vmcnt(8)
	s_waitcnt lgkmcnt(0)
	s_barrier
	s_setprio 1
	s_waitcnt lgkmcnt(0)
	v_mfma_f32_16x16x32_bf16 v[60:63], v[128:131], v[172:175], v[60:63]
	v_mfma_f32_16x16x32_bf16 v[56:59], v[136:139], v[172:175], v[56:59]
	v_mfma_f32_16x16x32_bf16 v[40:43], v[136:139], v[180:183], v[40:43]
	v_mfma_f32_16x16x32_bf16 v[48:51], v[128:131], v[180:183], v[48:51]
	v_mfma_f32_16x16x32_bf16 v[32:35], v[128:131], v[188:191], v[32:35]
	v_mfma_f32_16x16x32_bf16 v[24:27], v[136:139], v[188:191], v[24:27]
	v_mfma_f32_16x16x32_bf16 v[8:11], v[136:139], v[202:205], v[8:11]
	v_mfma_f32_16x16x32_bf16 v[16:19], v[128:131], v[202:205], v[16:19]
	v_mfma_f32_16x16x32_bf16 v[60:63], v[132:135], v[176:179], v[60:63]
	v_mfma_f32_16x16x32_bf16 v[56:59], v[140:143], v[176:179], v[56:59]
	v_mfma_f32_16x16x32_bf16 v[40:43], v[140:143], v[184:187], v[40:43]
	v_mfma_f32_16x16x32_bf16 v[48:51], v[132:135], v[184:187], v[48:51]
	v_mfma_f32_16x16x32_bf16 v[32:35], v[132:135], v[198:201], v[32:35]
	v_mfma_f32_16x16x32_bf16 v[24:27], v[140:143], v[198:201], v[24:27]
	v_mfma_f32_16x16x32_bf16 v[8:11], v[140:143], v[206:209], v[8:11]
	v_mfma_f32_16x16x32_bf16 v[16:19], v[132:135], v[206:209], v[16:19]
	s_setprio 0
	s_setprio 1
	v_mfma_f32_16x16x32_bf16 v[52:55], v[156:159], v[172:175], v[52:55]
	v_mfma_f32_16x16x32_bf16 v[44:47], v[164:167], v[172:175], v[44:47]
	v_mfma_f32_16x16x32_bf16 v[28:31], v[164:167], v[180:183], v[28:31]
	v_mfma_f32_16x16x32_bf16 v[36:39], v[156:159], v[180:183], v[36:39]
	v_mfma_f32_16x16x32_bf16 v[20:23], v[156:159], v[188:191], v[20:23]
	v_mfma_f32_16x16x32_bf16 v[12:15], v[164:167], v[188:191], v[12:15]
	v_mfma_f32_16x16x32_bf16 v[0:3], v[164:167], v[202:205], v[0:3]
	v_mfma_f32_16x16x32_bf16 v[4:7], v[156:159], v[202:205], v[4:7]
	v_mfma_f32_16x16x32_bf16 v[52:55], v[160:163], v[176:179], v[52:55]
	v_mfma_f32_16x16x32_bf16 v[44:47], v[168:171], v[176:179], v[44:47]
	v_mfma_f32_16x16x32_bf16 v[28:31], v[168:171], v[184:187], v[28:31]
	v_mfma_f32_16x16x32_bf16 v[36:39], v[160:163], v[184:187], v[36:39]
	v_mfma_f32_16x16x32_bf16 v[20:23], v[160:163], v[198:201], v[20:23]
	v_mfma_f32_16x16x32_bf16 v[12:15], v[168:171], v[198:201], v[12:15]
	v_mfma_f32_16x16x32_bf16 v[0:3], v[168:171], v[206:209], v[0:3]
	v_mfma_f32_16x16x32_bf16 v[4:7], v[160:163], v[206:209], v[4:7]
	s_setprio 0
	s_barrier
	s_add_i32 s72, s72, 2
	s_add_u32 s53, s53, 0x100
	s_addc_u32 s71, s71, 0
	s_add_u32 s22, s22, 0x100
	s_addc_u32 s23, s23, 0
	s_cmp_gt_u32 s72, 13
	s_cbranch_scc1 .Lkexit_4
.LBB0_687:
	s_add_u32 s24, s22, 0xfffc0080
	s_addc_u32 s25, s23, -1
	s_add_i32 s73, s35, 0x100
	s_cmp_eq_u32 s72, 12
	s_cselect_b32 s27, s17, s25
	s_cselect_b32 s26, s69, s24
	s_cselect_b32 s25, s13, s71
	s_cselect_b32 s24, s34, s53
	s_add_i32 s76, s90, 0x100
	v_add_u32_e32 v140, s73, v212
	v_add_u32_e32 v168, s76, v212
	ds_read_b128 v[128:131], v140
	ds_read_b128 v[132:135], v140 offset:1024
	ds_read_b128 v[136:139], v140 offset:2048
	ds_read_b128 v[140:143], v140 offset:3072
	ds_read_b128 v[156:159], v168
	ds_read_b128 v[160:163], v168 offset:1024
	ds_read_b128 v[164:167], v168 offset:2048
	ds_read_b128 v[168:171], v168 offset:3072
	v_lshl_add_u64 v[194:195], s[22:23], 0, v[154:155]
	s_add_i32 m0, s39, 0xc000
	ds_read_b128 v[172:175], v227
	ds_read_b128 v[176:179], v227 offset:1024
	ds_read_b128 v[180:183], v227 offset:2048
	ds_read_b128 v[184:187], v227 offset:3072
	ds_read_b128 v[188:191], v227 offset:4096
	ds_read_b128 v[198:201], v227 offset:5120
	ds_read_b128 v[202:205], v227 offset:6144
	ds_read_b128 v[206:209], v227 offset:7168
	global_load_lds_dwordx4 v[194:195], off
	v_lshl_add_u64 v[194:195], s[22:23], 0, v[152:153]
	s_add_i32 m0, s39, 0xe000
	s_nop 0
	global_load_lds_dwordx4 v[194:195], off
	s_waitcnt vmcnt(8)
	s_waitcnt lgkmcnt(0)
	s_barrier
; #define PG8_STAGE(bufoff, gbase, voff) do { _Pragma("unroll") for (int _i = 0; _i < 2; ++_i) \
;         __builtin_amdgcn_global_load_lds((const unsigned*)((const char*)(gbase) + (voff)[_i]), (PG8_LAS unsigned*)(lds + (bufoff) + ldsw + _i * 8192), 16, 0, 0); } while (0)
; #define PG8_LDA(dst, b, h) do { _Pragma("unroll") for (int m = 0; m < 4; ++m) _Pragma("unroll") for (int k = 0; k < 2; ++k) dst[m][k] = *(const PG8_LAS bf16x8*)(lds + PG8_SA(b, h) + aoff + m * 2048 + k * 1024); } while (0)
; #define PG8_LDB(dst, b, h) do { _Pragma("unroll") for (int n = 0; n < 2; ++n) _Pragma("unroll") for (int k = 0; k < 2; ++k) dst[n][k] = *(const PG8_LAS bf16x8*)(lds + PG8_SB(b, h) + boff + n * 2048 + k * 1024); } while (0)
; #define PG8_MMA(ai, bj, At, Bt) do { __builtin_amdgcn_s_setprio(1); _Pragma("unroll") for (int m = 0; m < 4; ++m) _Pragma("unroll") for (int n = 0; n < 2; ++n) _Pragma("unroll") for (int k = 0; k < 2; ++k) \
;         acc[ai][bj][m][n] = __builtin_amdgcn_mfma_f32_16x16x32_bf16(Bt[n][k], At[m][k], acc[ai][bj][m][n], 0, 0, 0); __builtin_amdgcn_s_setprio(0); } while (0)
; #define PG8_WAIT_V(n) asm volatile("s_waitcnt vmcnt(" #n ")" ::: "memory")
; #define PG8_WAIT_L(n) asm volatile("s_waitcnt lgkmcnt(" #n ")" ::: "memory")
; #define PG8_BAR __builtin_amdgcn_s_barrier()
; #define PG8_SCHED __builtin_amdgcn_sched_barrier(0)
; template <class Epi, class Sched, bool ALIGN_EPI = false, bool SP2 = false>
; __device__ __forceinline__ void gemm_phase(PG8_LAS unsigned char* lds, const Gemm g, const Sched& S, const Epi& E, int wave_in) {
;     ...
;             PG8_LDB(B0, 0, 0); PG8_LDB(B1, 0, 1); PG8_SCHED; PG8_LDA(At, 0, 0); PG8_STAGE(PG8_SA(1, 1), a1 + hstep, voffA);
;             PG8_WAIT_V(8); PG8_WAIT_L(0); PG8_BAR; PG8_MMA(0, 0, At, B0); PG8_MMA(0, 1, At, B1); PG8_BAR; PG8_SCHED;
;             PG8_LDA(At, 0, 1); PG8_STAGE(PG8_SB(0, 0), b2, voffB); PG8_STAGE(PG8_SB(0, 1), b2 + hstep, voffB); PG8_STAGE(PG8_SA(0, 0), a2, voffA);
;             PG8_WAIT_V(8); PG8_WAIT_L(0); PG8_BAR; PG8_MMA(1, 0, At, B0); PG8_MMA(1, 1, At, B1); PG8_BAR; PG8_SCHED;
	s_setprio 1
	s_waitcnt lgkmcnt(0)
	v_mfma_f32_16x16x32_bf16 v[124:127], v[128:131], v[172:175], v[124:127]
	v_mfma_f32_16x16x32_bf16 v[120:123], v[136:139], v[172:175], v[120:123]
	v_mfma_f32_16x16x32_bf16 v[104:107], v[136:139], v[180:183], v[104:107]
	v_mfma_f32_16x16x32_bf16 v[108:111], v[128:131], v[180:183], v[108:111]
	v_mfma_f32_16x16x32_bf16 v[96:99], v[128:131], v[188:191], v[96:99]
	v_mfma_f32_16x16x32_bf16 v[88:91], v[136:139], v[188:191], v[88:91]
	v_mfma_f32_16x16x32_bf16 v[72:75], v[136:139], v[202:205], v[72:75]
	v_mfma_f32_16x16x32_bf16 v[80:83], v[128:131], v[202:205], v[80:83]
	v_mfma_f32_16x16x32_bf16 v[124:127], v[132:135], v[176:179], v[124:127]
	v_mfma_f32_16x16x32_bf16 v[120:123], v[140:143], v[176:179], v[120:123]
	v_mfma_f32_16x16x32_bf16 v[104:107], v[140:143], v[184:187], v[104:107]
	v_mfma_f32_16x16x32_bf16 v[108:111], v[132:135], v[184:187], v[108:111]
	v_mfma_f32_16x16x32_bf16 v[96:99], v[132:135], v[198:201], v[96:99]
	v_mfma_f32_16x16x32_bf16 v[88:91], v[140:143], v[198:201], v[88:91]
	v_mfma_f32_16x16x32_bf16 v[72:75], v[140:143], v[206:209], v[72:75]
	v_mfma_f32_16x16x32_bf16 v[80:83], v[132:135], v[206:209], v[80:83]
	s_setprio 0
	s_setprio 1
	v_mfma_f32_16x16x32_bf16 v[116:119], v[156:159], v[172:175], v[116:119]
	v_mfma_f32_16x16x32_bf16 v[112:115], v[164:167], v[172:175], v[112:115]
	v_mfma_f32_16x16x32_bf16 v[92:95], v[164:167], v[180:183], v[92:95]
	v_mfma_f32_16x16x32_bf16 v[100:103], v[156:159], v[180:183], v[100:103]
	v_mfma_f32_16x16x32_bf16 v[84:87], v[156:159], v[188:191], v[84:87]
	v_mfma_f32_16x16x32_bf16 v[76:79], v[164:167], v[188:191], v[76:79]
	v_mfma_f32_16x16x32_bf16 v[64:67], v[164:167], v[202:205], v[64:67]
	v_mfma_f32_16x16x32_bf16 v[68:71], v[156:159], v[202:205], v[68:71]
	v_mfma_f32_16x16x32_bf16 v[116:119], v[160:163], v[176:179], v[116:119]
	v_mfma_f32_16x16x32_bf16 v[112:115], v[168:171], v[176:179], v[112:115]
	v_mfma_f32_16x16x32_bf16 v[92:95], v[168:171], v[184:187], v[92:95]
	v_mfma_f32_16x16x32_bf16 v[100:103], v[160:163], v[184:187], v[100:103]
	v_mfma_f32_16x16x32_bf16 v[84:87], v[160:163], v[198:201], v[84:87]
	v_mfma_f32_16x16x32_bf16 v[76:79], v[168:171], v[198:201], v[76:79]
	v_mfma_f32_16x16x32_bf16 v[64:67], v[168:171], v[206:209], v[64:67]
	v_mfma_f32_16x16x32_bf16 v[68:71], v[160:163], v[206:209], v[68:71]
	s_setprio 0
	s_barrier
	s_add_i32 s73, s73, s38
	v_lshl_add_u64 v[194:195], s[24:25], 0, v[148:149]
	s_mov_b32 m0, s73
	ds_read_b128 v[172:175], v227 offset:16384
	ds_read_b128 v[176:179], v227 offset:17408
	ds_read_b128 v[180:183], v227 offset:18432
	ds_read_b128 v[184:187], v227 offset:19456
	ds_read_b128 v[188:191], v227 offset:20480
	ds_read_b128 v[198:201], v227 offset:21504
	ds_read_b128 v[202:205], v227 offset:22528
	ds_read_b128 v[206:209], v227 offset:23552
	global_load_lds_dwordx4 v[194:195], off
	s_add_i32 m0, s73, 0x2000
	s_add_u32 s74, s24, 0x40000
	v_lshl_add_u64 v[196:197], s[24:25], 0, v[144:145]
	s_addc_u32 s75, s25, 0
	s_add_i32 s73, s76, s38
	global_load_lds_dwordx4 v[196:197], off
	v_lshl_add_u64 v[234:235], s[74:75], 0, v[148:149]
	s_mov_b32 m0, s73
	v_lshl_add_u64 v[236:237], s[26:27], 0, v[146:147]
	global_load_lds_dwordx4 v[234:235], off
	v_lshl_add_u64 v[234:235], s[74:75], 0, v[144:145]
	s_add_i32 m0, s73, 0x2000
	s_nop 0
	global_load_lds_dwordx4 v[234:235], off
	v_lshl_add_u64 v[234:235], s[26:27], 0, v[150:151]
	s_mov_b32 m0, s39
	s_nop 0
	global_load_lds_dwordx4 v[234:235], off
	s_mov_b32 m0, s44
	s_nop 0
	global_load_lds_dwordx4 v[236:237], off
	s_waitcnt vmcnt(8)
	s_waitcnt lgkmcnt(0)
	s_barrier
	s_setprio 1
	s_waitcnt lgkmcnt(0)
	v_mfma_f32_16x16x32_bf16 v[60:63], v[128:131], v[172:175], v[60:63]
	v_mfma_f32_16x16x32_bf16 v[56:59], v[136:139], v[172:175], v[56:59]
	v_mfma_f32_16x16x32_bf16 v[40:43], v[136:139], v[180:183], v[40:43]
	v_mfma_f32_16x16x32_bf16 v[48:51], v[128:131], v[180:183], v[48:51]
	v_mfma_f32_16x16x32_bf16 v[32:35], v[128:131], v[188:191], v[32:35]
	v_mfma_f32_16x16x32_bf16 v[24:27], v[136:139], v[188:191], v[24:27]
	v_mfma_f32_16x16x32_bf16 v[8:11], v[136:139], v[202:205], v[8:11]
	v_mfma_f32_16x16x32_bf16 v[16:19], v[128:131], v[202:205], v[16:19]
	v_mfma_f32_16x16x32_bf16 v[60:63], v[132:135], v[176:179], v[60:63]
	v_mfma_f32_16x16x32_bf16 v[56:59], v[140:143], v[176:179], v[56:59]
	v_mfma_f32_16x16x32_bf16 v[40:43], v[140:143], v[184:187], v[40:43]
	v_mfma_f32_16x16x32_bf16 v[48:51], v[132:135], v[184:187], v[48:51]
	v_mfma_f32_16x16x32_bf16 v[32:35], v[132:135], v[198:201], v[32:35]
	v_mfma_f32_16x16x32_bf16 v[24:27], v[140:143], v[198:201], v[24:27]
	v_mfma_f32_16x16x32_bf16 v[8:11], v[140:143], v[206:209], v[8:11]
	v_mfma_f32_16x16x32_bf16 v[16:19], v[132:135], v[206:209], v[16:19]
	s_setprio 0
	s_setprio 1
	v_mfma_f32_16x16x32_bf16 v[52:55], v[156:159], v[172:175], v[52:55]
	v_mfma_f32_16x16x32_bf16 v[44:47], v[164:167], v[172:175], v[44:47]
	v_mfma_f32_16x16x32_bf16 v[28:31], v[164:167], v[180:183], v[28:31]
	v_mfma_f32_16x16x32_bf16 v[36:39], v[156:159], v[180:183], v[36:39]
	v_mfma_f32_16x16x32_bf16 v[20:23], v[156:159], v[188:191], v[20:23]
	v_mfma_f32_16x16x32_bf16 v[12:15], v[164:167], v[188:191], v[12:15]
	v_mfma_f32_16x16x32_bf16 v[0:3], v[164:167], v[202:205], v[0:3]
	v_mfma_f32_16x16x32_bf16 v[4:7], v[156:159], v[202:205], v[4:7]
	v_mfma_f32_16x16x32_bf16 v[52:55], v[160:163], v[176:179], v[52:55]
	v_mfma_f32_16x16x32_bf16 v[44:47], v[168:171], v[176:179], v[44:47]
	v_mfma_f32_16x16x32_bf16 v[28:31], v[168:171], v[184:187], v[28:31]
	v_mfma_f32_16x16x32_bf16 v[36:39], v[160:163], v[184:187], v[36:39]
	v_mfma_f32_16x16x32_bf16 v[20:23], v[160:163], v[198:201], v[20:23]
	v_mfma_f32_16x16x32_bf16 v[12:15], v[168:171], v[198:201], v[12:15]
	v_mfma_f32_16x16x32_bf16 v[0:3], v[168:171], v[206:209], v[0:3]
	v_mfma_f32_16x16x32_bf16 v[4:7], v[160:163], v[206:209], v[4:7]
	s_setprio 0
	s_barrier
; #define PG8_STAGE(bufoff, gbase, voff) do { _Pragma("unroll") for (int _i = 0; _i < 2; ++_i) \
;         __builtin_amdgcn_global_load_lds((const unsigned*)((const char*)(gbase) + (voff)[_i]), (PG8_LAS unsigned*)(lds + (bufoff) + ldsw + _i * 8192), 16, 0, 0); } while (0)
; #define PG8_LDA(dst, b, h) do { _Pragma("unroll") for (int m = 0; m < 4; ++m) _Pragma("unroll") for (int k = 0; k < 2; ++k) dst[m][k] = *(const PG8_LAS bf16x8*)(lds + PG8_SA(b, h) + aoff + m * 2048 + k * 1024); } while (0)
; #define PG8_LDB(dst, b, h) do { _Pragma("unroll") for (int n = 0; n < 2; ++n) _Pragma("unroll") for (int k = 0; k < 2; ++k) dst[n][k] = *(const PG8_LAS bf16x8*)(lds + PG8_SB(b, h) + boff + n * 2048 + k * 1024); } while (0)
; #define PG8_MMA(ai, bj, At, Bt) do { __builtin_amdgcn_s_setprio(1); _Pragma("unroll") for (int m = 0; m < 4; ++m) _Pragma("unroll") for (int n = 0; n < 2; ++n) _Pragma("unroll") for (int k = 0; k < 2; ++k) \
;         acc[ai][bj][m][n] = __builtin_amdgcn_mfma_f32_16x16x32_bf16(Bt[n][k], At[m][k], acc[ai][bj][m][n], 0, 0, 0); __builtin_amdgcn_s_setprio(0); } while (0)
; #define PG8_WAIT_V(n) asm volatile("s_waitcnt vmcnt(" #n ")" ::: "memory")
; #define PG8_WAIT_L(n) asm volatile("s_waitcnt lgkmcnt(" #n ")" ::: "memory")
; #define PG8_BAR __builtin_amdgcn_s_barrier()
; #define PG8_SCHED __builtin_amdgcn_sched_barrier(0)
; template <class Epi, class Sched, bool ALIGN_EPI = false, bool SP2 = false>
; __device__ __forceinline__ void gemm_phase(PG8_LAS unsigned char* lds, const Gemm g, const Sched& S, const Epi& E, int wave_in) {
;     ...
;             PG8_LDB(B0, 1, 0); PG8_LDB(B1, 1, 1); PG8_SCHED; PG8_LDA(At, 1, 0); PG8_STAGE(PG8_SA(0, 1), a2 + hstep, voffA);
;             PG8_WAIT_V(8); PG8_WAIT_L(0); PG8_BAR; PG8_MMA(0, 0, At, B0); PG8_MMA(0, 1, At, B1); PG8_BAR; PG8_SCHED;
	s_add_i32 s73, s65, 0x100
	s_add_i32 s74, s52, 0x100
	v_add_u32_e32 v140, s73, v212
	v_add_u32_e32 v168, s74, v212
	ds_read_b128 v[128:131], v140
	ds_read_b128 v[132:135], v140 offset:1024
	ds_read_b128 v[136:139], v140 offset:2048
	ds_read_b128 v[140:143], v140 offset:3072
	ds_read_b128 v[156:159], v168
	ds_read_b128 v[160:163], v168 offset:1024
	ds_read_b128 v[164:167], v168 offset:2048
	ds_read_b128 v[168:171], v168 offset:3072
	s_add_u32 s26, s26, 0x40000
	s_addc_u32 s27, s27, 0
	s_mov_b32 m0, s45
	v_lshl_add_u64 v[238:239], s[26:27], 0, v[150:151]
	ds_read_b128 v[172:175], v227 offset:32768
	ds_read_b128 v[176:179], v227 offset:33792
	ds_read_b128 v[180:183], v227 offset:34816
	ds_read_b128 v[184:187], v227 offset:35840
	ds_read_b128 v[188:191], v227 offset:36864
	ds_read_b128 v[198:201], v227 offset:37888
	ds_read_b128 v[202:205], v227 offset:38912
	ds_read_b128 v[206:209], v227 offset:39936
	global_load_lds_dwordx4 v[238:239], off
	v_lshl_add_u64 v[238:239], s[26:27], 0, v[146:147]
	s_mov_b32 m0, s46
	s_nop 0
	global_load_lds_dwordx4 v[238:239], off
	s_waitcnt vmcnt(8)
	s_waitcnt lgkmcnt(0)
	s_barrier
	s_setprio 1
	s_waitcnt lgkmcnt(0)
	v_mfma_f32_16x16x32_bf16 v[124:127], v[128:131], v[172:175], v[124:127]
	v_mfma_f32_16x16x32_bf16 v[120:123], v[136:139], v[172:175], v[120:123]
	v_mfma_f32_16x16x32_bf16 v[104:107], v[136:139], v[180:183], v[104:107]
	v_mfma_f32_16x16x32_bf16 v[108:111], v[128:131], v[180:183], v[108:111]
	v_mfma_f32_16x16x32_bf16 v[96:99], v[128:131], v[188:191], v[96:99]
	v_mfma_f32_16x16x32_bf16 v[88:91], v[136:139], v[188:191], v[88:91]
	v_mfma_f32_16x16x32_bf16 v[72:75], v[136:139], v[202:205], v[72:75]
	v_mfma_f32_16x16x32_bf16 v[80:83], v[128:131], v[202:205], v[80:83]
	v_mfma_f32_16x16x32_bf16 v[124:127], v[132:135], v[176:179], v[124:127]
	v_mfma_f32_16x16x32_bf16 v[120:123], v[140:143], v[176:179], v[120:123]
	v_mfma_f32_16x16x32_bf16 v[104:107], v[140:143], v[184:187], v[104:107]
	v_mfma_f32_16x16x32_bf16 v[108:111], v[132:135], v[184:187], v[108:111]
	v_mfma_f32_16x16x32_bf16 v[96:99], v[132:135], v[198:201], v[96:99]
	v_mfma_f32_16x16x32_bf16 v[88:91], v[140:143], v[198:201], v[88:91]
	v_mfma_f32_16x16x32_bf16 v[72:75], v[140:143], v[206:209], v[72:75]
	v_mfma_f32_16x16x32_bf16 v[80:83], v[132:135], v[206:209], v[80:83]
	s_setprio 0
	s_setprio 1
	v_mfma_f32_16x16x32_bf16 v[116:119], v[156:159], v[172:175], v[116:119]
	v_mfma_f32_16x16x32_bf16 v[112:115], v[164:167], v[172:175], v[112:115]
	v_mfma_f32_16x16x32_bf16 v[92:95], v[164:167], v[180:183], v[92:95]
	v_mfma_f32_16x16x32_bf16 v[100:103], v[156:159], v[180:183], v[100:103]
	v_mfma_f32_16x16x32_bf16 v[84:87], v[156:159], v[188:191], v[84:87]
	v_mfma_f32_16x16x32_bf16 v[76:79], v[164:167], v[188:191], v[76:79]
	v_mfma_f32_16x16x32_bf16 v[64:67], v[164:167], v[202:205], v[64:67]
	v_mfma_f32_16x16x32_bf16 v[68:71], v[156:159], v[202:205], v[68:71]
	v_mfma_f32_16x16x32_bf16 v[116:119], v[160:163], v[176:179], v[116:119]
	v_mfma_f32_16x16x32_bf16 v[112:115], v[168:171], v[176:179], v[112:115]
	v_mfma_f32_16x16x32_bf16 v[92:95], v[168:171], v[184:187], v[92:95]
	v_mfma_f32_16x16x32_bf16 v[100:103], v[160:163], v[184:187], v[100:103]
	v_mfma_f32_16x16x32_bf16 v[84:87], v[160:163], v[198:201], v[84:87]
	v_mfma_f32_16x16x32_bf16 v[76:79], v[168:171], v[198:201], v[76:79]
	v_mfma_f32_16x16x32_bf16 v[64:67], v[168:171], v[206:209], v[64:67]
	v_mfma_f32_16x16x32_bf16 v[68:71], v[160:163], v[206:209], v[68:71]
	s_setprio 0
	s_barrier
; #define PG8_STAGE(bufoff, gbase, voff) do { _Pragma("unroll") for (int _i = 0; _i < 2; ++_i) \
;         __builtin_amdgcn_global_load_lds((const unsigned*)((const char*)(gbase) + (voff)[_i]), (PG8_LAS unsigned*)(lds + (bufoff) + ldsw + _i * 8192), 16, 0, 0); } while (0)
; #define PG8_LDA(dst, b, h) do { _Pragma("unroll") for (int m = 0; m < 4; ++m) _Pragma("unroll") for (int k = 0; k < 2; ++k) dst[m][k] = *(const PG8_LAS bf16x8*)(lds + PG8_SA(b, h) + aoff + m * 2048 + k * 1024); } while (0)
; #define PG8_MMA(ai, bj, At, Bt) do { __builtin_amdgcn_s_setprio(1); _Pragma("unroll") for (int m = 0; m < 4; ++m) _Pragma("unroll") for (int n = 0; n < 2; ++n) _Pragma("unroll") for (int k = 0; k < 2; ++k) \
;         acc[ai][bj][m][n] = __builtin_amdgcn_mfma_f32_16x16x32_bf16(Bt[n][k], At[m][k], acc[ai][bj][m][n], 0, 0, 0); __builtin_amdgcn_s_setprio(0); } while (0)
; #define PG8_WAIT_V(n) asm volatile("s_waitcnt vmcnt(" #n ")" ::: "memory")
; #define PG8_WAIT_L(n) asm volatile("s_waitcnt lgkmcnt(" #n ")" ::: "memory")
; #define PG8_BAR __builtin_amdgcn_s_barrier()
; #define PG8_SCHED __builtin_amdgcn_sched_barrier(0)
; template <class Epi, class Sched, bool ALIGN_EPI = false, bool SP2 = false>
; __device__ __forceinline__ void gemm_phase(PG8_LAS unsigned char* lds, const Gemm g, const Sched& S, const Epi& E, int wave_in) {
;     ...
;             PG8_LDA(At, 1, 1); PG8_STAGE(PG8_SB(1, 0), b3, voffB); PG8_STAGE(PG8_SB(1, 1), b3 + hstep, voffB); PG8_STAGE(PG8_SA(1, 0), a3, voffA);
;             PG8_WAIT_V(8); PG8_WAIT_L(0); PG8_BAR; PG8_MMA(1, 0, At, B0); PG8_MMA(1, 1, At, B1); PG8_BAR; PG8_SCHED;
	s_add_i32 s26, s73, s38
	v_lshl_add_u64 v[194:195], v[194:195], 0, s[88:89]
	s_mov_b32 m0, s26
	ds_read_b128 v[172:175], v227 offset:49152
	ds_read_b128 v[176:179], v227 offset:50176
	ds_read_b128 v[180:183], v227 offset:51200
	ds_read_b128 v[184:187], v227 offset:52224
	ds_read_b128 v[188:191], v227 offset:53248
	ds_read_b128 v[198:201], v227 offset:54272
	ds_read_b128 v[202:205], v227 offset:55296
	ds_read_b128 v[206:209], v227 offset:56320
	global_load_lds_dwordx4 v[194:195], off
	s_add_i32 m0, s26, 0x2000
	s_add_u32 s24, s24, 0x40080
	v_lshl_add_u64 v[194:195], v[196:197], 0, s[88:89]
	s_addc_u32 s25, s25, 0
	s_add_i32 s26, s74, s38
	global_load_lds_dwordx4 v[194:195], off
	v_lshl_add_u64 v[194:195], s[24:25], 0, v[148:149]
	s_mov_b32 m0, s26
	s_nop 0
	global_load_lds_dwordx4 v[194:195], off
	v_lshl_add_u64 v[194:195], s[24:25], 0, v[144:145]
	s_add_i32 m0, s26, 0x2000
	s_nop 0
	global_load_lds_dwordx4 v[194:195], off
	v_lshl_add_u64 v[194:195], v[234:235], 0, s[88:89]
	s_mov_b32 m0, s61
	s_nop 0
	global_load_lds_dwordx4 v[194:195], off
	v_lshl_add_u64 v[194:195], v[236:237], 0, s[88:89]
	s_mov_b32 m0, s62
	s_nop 0
	global_load_lds_dwordx4 v[194:195], off
	s_waitcnt vmcnt(8)
	s_waitcnt lgkmcnt(0)
	s_barrier
	s_setprio 1
	s_waitcnt lgkmcnt(0)
	v_mfma_f32_16x16x32_bf16 v[60:63], v[128:131], v[172:175], v[60:63]
	v_mfma_f32_16x16x32_bf16 v[56:59], v[136:139], v[172:175], v[56:59]
	v_mfma_f32_16x16x32_bf16 v[40:43], v[136:139], v[180:183], v[40:43]
	v_mfma_f32_16x16x32_bf16 v[48:51], v[128:131], v[180:183], v[48:51]
	v_mfma_f32_16x16x32_bf16 v[32:35], v[128:131], v[188:191], v[32:35]
	v_mfma_f32_16x16x32_bf16 v[24:27], v[136:139], v[188:191], v[24:27]
	v_mfma_f32_16x16x32_bf16 v[8:11], v[136:139], v[202:205], v[8:11]
	v_mfma_f32_16x16x32_bf16 v[16:19], v[128:131], v[202:205], v[16:19]
	v_mfma_f32_16x16x32_bf16 v[60:63], v[132:135], v[176:179], v[60:63]
	v_mfma_f32_16x16x32_bf16 v[56:59], v[140:143], v[176:179], v[56:59]
	v_mfma_f32_16x16x32_bf16 v[40:43], v[140:143], v[184:187], v[40:43]
	v_mfma_f32_16x16x32_bf16 v[48:51], v[132:135], v[184:187], v[48:51]
	v_mfma_f32_16x16x32_bf16 v[32:35], v[132:135], v[198:201], v[32:35]
	v_mfma_f32_16x16x32_bf16 v[24:27], v[140:143], v[198:201], v[24:27]
	v_mfma_f32_16x16x32_bf16 v[8:11], v[140:143], v[206:209], v[8:11]
	v_mfma_f32_16x16x32_bf16 v[16:19], v[132:135], v[206:209], v[16:19]
	s_setprio 0
	s_setprio 1
	v_mfma_f32_16x16x32_bf16 v[52:55], v[156:159], v[172:175], v[52:55]
	v_mfma_f32_16x16x32_bf16 v[44:47], v[164:167], v[172:175], v[44:47]
	v_mfma_f32_16x16x32_bf16 v[28:31], v[164:167], v[180:183], v[28:31]
	v_mfma_f32_16x16x32_bf16 v[36:39], v[156:159], v[180:183], v[36:39]
	v_mfma_f32_16x16x32_bf16 v[20:23], v[156:159], v[188:191], v[20:23]
	v_mfma_f32_16x16x32_bf16 v[12:15], v[164:167], v[188:191], v[12:15]
	v_mfma_f32_16x16x32_bf16 v[0:3], v[164:167], v[202:205], v[0:3]
	v_mfma_f32_16x16x32_bf16 v[4:7], v[156:159], v[202:205], v[4:7]
	v_mfma_f32_16x16x32_bf16 v[52:55], v[160:163], v[176:179], v[52:55]
	v_mfma_f32_16x16x32_bf16 v[44:47], v[168:171], v[176:179], v[44:47]
	v_mfma_f32_16x16x32_bf16 v[28:31], v[168:171], v[184:187], v[28:31]
	v_mfma_f32_16x16x32_bf16 v[36:39], v[160:163], v[184:187], v[36:39]
	v_mfma_f32_16x16x32_bf16 v[20:23], v[160:163], v[198:201], v[20:23]
	v_mfma_f32_16x16x32_bf16 v[12:15], v[168:171], v[198:201], v[12:15]
	v_mfma_f32_16x16x32_bf16 v[0:3], v[168:171], v[206:209], v[0:3]
	v_mfma_f32_16x16x32_bf16 v[4:7], v[160:163], v[206:209], v[4:7]
	s_setprio 0
	s_barrier
	s_add_i32 s72, s72, 2
	s_add_u32 s53, s53, 0x100
	s_addc_u32 s71, s71, 0
	s_add_u32 s22, s22, 0x100
	s_addc_u32 s23, s23, 0
	s_cmp_gt_u32 s72, 13
	s_cbranch_scc0 .LBB0_687

; #define PG8_STAGE(bufoff, gbase, voff) do { _Pragma("unroll") for (int _i = 0; _i < 2; ++_i) \
;         __builtin_amdgcn_global_load_lds((const unsigned*)((const char*)(gbase) + (voff)[_i]), (PG8_LAS unsigned*)(lds + (bufoff) + ldsw + _i * 8192), 16, 0, 0); } while (0)
; #define PG8_LDA(dst, b, h) do { _Pragma("unroll") for (int m = 0; m < 4; ++m) _Pragma("unroll") for (int k = 0; k < 2; ++k) dst[m][k] = *(const PG8_LAS bf16x8*)(lds + PG8_SA(b, h) + aoff + m * 2048 + k * 1024); } while (0)
; #define PG8_LDB(dst, b, h) do { _Pragma("unroll") for (int n = 0; n < 2; ++n) _Pragma("unroll") for (int k = 0; k < 2; ++k) dst[n][k] = *(const PG8_LAS bf16x8*)(lds + PG8_SB(b, h) + boff + n * 2048 + k * 1024); } while (0)
; #define PG8_MMA(ai, bj, At, Bt) do { __builtin_amdgcn_s_setprio(1); _Pragma("unroll") for (int m = 0; m < 4; ++m) _Pragma("unroll") for (int n = 0; n < 2; ++n) _Pragma("unroll") for (int k = 0; k < 2; ++k) \
;         acc[ai][bj][m][n] = __builtin_amdgcn_mfma_f32_16x16x32_bf16(Bt[n][k], At[m][k], acc[ai][bj][m][n], 0, 0, 0); __builtin_amdgcn_s_setprio(0); } while (0)
; #define PG8_WAIT_V(n) asm volatile("s_waitcnt vmcnt(" #n ")" ::: "memory")
; #define PG8_BAR __builtin_amdgcn_s_barrier()
; template <class Epi, class Sched, bool ALIGN_EPI = false, bool SP2 = false>
; __device__ __forceinline__ void gemm_phase(PG8_LAS unsigned char* lds, const Gemm g, const Sched& S, const Epi& E, int wave_in) {
;     ...
;         for (int t = 0; t < nt; t += 2) {
;             const bool last = (t == nt - 2);
;             const char* a1 = cA + (size_t)(t + 1) * kstep;
;             const char* a2 = last ? nA : cA + (size_t)(t + 2) * kstep; const char* b2 = last ? nB : cB + (size_t)(t + 2) * kstep;
;             const char* a3 = a2 + kstep; const char* b3 = b2 + kstep;
;             if (last && has_next) S.a_ready(nxt);
;             if constexpr (SP2) {
;             PG8_LDB(B0, 0, 0); PG8_LDB(B1, 0, 1); PG8_SCHED; PG8_LDA(At, 0, 0); PG8_STAGE(PG8_SA(1, 1), a1 + hstep, voffA);
;             PG8_WAIT_V(8); PG8_WAIT_L(0); PG8_BAR; PG8_MMA(0, 0, At, B0); PG8_MMA(0, 1, At, B1); PG8_BAR; PG8_SCHED;
;             PG8_LDA(At, 0, 1); PG8_STAGE(PG8_SB(0, 0), b2, voffB); PG8_STAGE(PG8_SB(0, 1), b2 + hstep, voffB); PG8_STAGE(PG8_SA(0, 0), a2, voffA);
;             PG8_WAIT_V(8); PG8_WAIT_L(0); PG8_BAR; PG8_MMA(1, 0, At, B0); PG8_MMA(1, 1, At, B1); PG8_BAR; PG8_SCHED;
.LBB0_803:
	s_add_u32 s15, s22, 0x100
	s_addc_u32 s17, s23, 0
	s_add_u32 s22, s24, 0x40080
	s_addc_u32 s23, s25, 0
	s_mov_b32 s34, -2
	s_add_u32 s24, s22, 0xfffc0080
	s_addc_u32 s25, s23, -1
	s_add_i32 s44, s35, 0x100
	s_cmp_eq_u32 s34, 12
	s_cselect_b32 s27, s19, s25
	s_cselect_b32 s26, s18, s24
	s_cselect_b32 s25, s21, s17
	s_cselect_b32 s24, s20, s15
	s_add_i32 s53, s90, 0x100
	v_add_u32_e32 v128, s44, v249
	v_add_u32_e32 v156, s53, v249
	ds_read_b128 v[112:115], v128
	ds_read_b128 v[120:123], v128 offset:1024
	ds_read_b128 v[124:127], v128 offset:2048
	ds_read_b128 v[128:131], v128 offset:3072
	ds_read_b128 v[136:139], v156
	ds_read_b128 v[140:143], v156 offset:1024
	ds_read_b128 v[144:147], v156 offset:2048
	ds_read_b128 v[156:159], v156 offset:3072
	v_lshl_add_u64 v[194:195], s[22:23], 0, v[206:207]
	s_add_i32 m0, s39, 0xc000
	ds_read_b128 v[160:163], v251
	ds_read_b128 v[164:167], v251 offset:1024
	ds_read_b128 v[168:171], v251 offset:2048
	ds_read_b128 v[172:175], v251 offset:3072
	ds_read_b128 v[176:179], v251 offset:4096
	ds_read_b128 v[180:183], v251 offset:5120
	ds_read_b128 v[184:187], v251 offset:6144
	ds_read_b128 v[188:191], v251 offset:7168
	global_load_lds_dwordx4 v[194:195], off
	v_lshl_add_u64 v[194:195], s[22:23], 0, v[204:205]
	s_add_i32 m0, s39, 0xe000
	s_nop 0
	global_load_lds_dwordx4 v[194:195], off
	s_waitcnt vmcnt(8)
	s_waitcnt lgkmcnt(0)
	s_barrier
	s_setprio 1
	s_waitcnt lgkmcnt(0)
	v_mfma_f32_16x16x32_bf16 v[152:155], v[112:115], v[160:163], 0
	v_mfma_f32_16x16x32_bf16 v[148:151], v[124:127], v[160:163], 0
	v_mfma_f32_16x16x32_bf16 v[104:107], v[124:127], v[168:171], 0
	v_mfma_f32_16x16x32_bf16 v[108:111], v[112:115], v[168:171], 0
	v_mfma_f32_16x16x32_bf16 v[92:95], v[112:115], v[176:179], 0
	v_mfma_f32_16x16x32_bf16 v[88:91], v[124:127], v[176:179], 0
	v_mfma_f32_16x16x32_bf16 v[72:75], v[124:127], v[184:187], 0
	v_mfma_f32_16x16x32_bf16 v[76:79], v[112:115], v[184:187], 0
	v_mfma_f32_16x16x32_bf16 v[152:155], v[120:123], v[164:167], v[152:155]
	v_mfma_f32_16x16x32_bf16 v[148:151], v[128:131], v[164:167], v[148:151]
	v_mfma_f32_16x16x32_bf16 v[104:107], v[128:131], v[172:175], v[104:107]
	v_mfma_f32_16x16x32_bf16 v[108:111], v[120:123], v[172:175], v[108:111]
	v_mfma_f32_16x16x32_bf16 v[92:95], v[120:123], v[180:183], v[92:95]
	v_mfma_f32_16x16x32_bf16 v[88:91], v[128:131], v[180:183], v[88:91]
	v_mfma_f32_16x16x32_bf16 v[72:75], v[128:131], v[188:191], v[72:75]
	v_mfma_f32_16x16x32_bf16 v[76:79], v[120:123], v[188:191], v[76:79]
	s_setprio 0
	s_setprio 1
	v_mfma_f32_16x16x32_bf16 v[132:135], v[136:139], v[160:163], 0
	v_mfma_f32_16x16x32_bf16 v[116:119], v[144:147], v[160:163], 0
	v_mfma_f32_16x16x32_bf16 v[96:99], v[144:147], v[168:171], 0
	v_mfma_f32_16x16x32_bf16 v[100:103], v[136:139], v[168:171], 0
	v_mfma_f32_16x16x32_bf16 v[84:87], v[136:139], v[176:179], 0
	v_mfma_f32_16x16x32_bf16 v[80:83], v[144:147], v[176:179], 0
	v_mfma_f32_16x16x32_bf16 v[64:67], v[144:147], v[184:187], 0
	v_mfma_f32_16x16x32_bf16 v[68:71], v[136:139], v[184:187], 0
	v_mfma_f32_16x16x32_bf16 v[132:135], v[140:143], v[164:167], v[132:135]
	v_mfma_f32_16x16x32_bf16 v[116:119], v[156:159], v[164:167], v[116:119]
	v_mfma_f32_16x16x32_bf16 v[96:99], v[156:159], v[172:175], v[96:99]
	v_mfma_f32_16x16x32_bf16 v[100:103], v[140:143], v[172:175], v[100:103]
	v_mfma_f32_16x16x32_bf16 v[84:87], v[140:143], v[180:183], v[84:87]
	v_mfma_f32_16x16x32_bf16 v[80:83], v[156:159], v[180:183], v[80:83]
	v_mfma_f32_16x16x32_bf16 v[64:67], v[156:159], v[188:191], v[64:67]
	v_mfma_f32_16x16x32_bf16 v[68:71], v[140:143], v[188:191], v[68:71]
	s_setprio 0
	s_barrier
	s_add_i32 s44, s44, s38
	v_lshl_add_u64 v[194:195], s[24:25], 0, v[192:193]
	s_mov_b32 m0, s44
	ds_read_b128 v[160:163], v251 offset:16384
	ds_read_b128 v[164:167], v251 offset:17408
	ds_read_b128 v[168:171], v251 offset:18432
	ds_read_b128 v[172:175], v251 offset:19456
	ds_read_b128 v[176:179], v251 offset:20480
	ds_read_b128 v[180:183], v251 offset:21504
	ds_read_b128 v[184:187], v251 offset:22528
	ds_read_b128 v[188:191], v251 offset:23552
	global_load_lds_dwordx4 v[194:195], off
	s_add_i32 m0, s44, 0x2000
	s_add_u32 s44, s24, 0x40000
	v_lshl_add_u64 v[196:197], s[24:25], 0, v[198:199]
	s_addc_u32 s45, s25, 0
	s_add_i32 s53, s53, s38
	global_load_lds_dwordx4 v[196:197], off
	v_lshl_add_u64 v[208:209], s[44:45], 0, v[192:193]
	s_mov_b32 m0, s53
	v_lshl_add_u64 v[210:211], s[26:27], 0, v[200:201]
	global_load_lds_dwordx4 v[208:209], off
	v_lshl_add_u64 v[208:209], s[44:45], 0, v[198:199]
	s_add_i32 m0, s53, 0x2000
	s_nop 0
	global_load_lds_dwordx4 v[208:209], off
	v_lshl_add_u64 v[208:209], s[26:27], 0, v[202:203]
	s_mov_b32 m0, s39
	s_nop 0
	global_load_lds_dwordx4 v[208:209], off
	s_mov_b32 m0, s46
	s_nop 0
	global_load_lds_dwordx4 v[210:211], off
	s_waitcnt vmcnt(8)
	s_waitcnt lgkmcnt(0)
	s_barrier
; #define PG8_STAGE(bufoff, gbase, voff) do { _Pragma("unroll") for (int _i = 0; _i < 2; ++_i) \
;         __builtin_amdgcn_global_load_lds((const unsigned*)((const char*)(gbase) + (voff)[_i]), (PG8_LAS unsigned*)(lds + (bufoff) + ldsw + _i * 8192), 16, 0, 0); } while (0)
; #define PG8_LDA(dst, b, h) do { _Pragma("unroll") for (int m = 0; m < 4; ++m) _Pragma("unroll") for (int k = 0; k < 2; ++k) dst[m][k] = *(const PG8_LAS bf16x8*)(lds + PG8_SA(b, h) + aoff + m * 2048 + k * 1024); } while (0)
; #define PG8_LDB(dst, b, h) do { _Pragma("unroll") for (int n = 0; n < 2; ++n) _Pragma("unroll") for (int k = 0; k < 2; ++k) dst[n][k] = *(const PG8_LAS bf16x8*)(lds + PG8_SB(b, h) + boff + n * 2048 + k * 1024); } while (0)
; #define PG8_MMA(ai, bj, At, Bt) do { __builtin_amdgcn_s_setprio(1); _Pragma("unroll") for (int m = 0; m < 4; ++m) _Pragma("unroll") for (int n = 0; n < 2; ++n) _Pragma("unroll") for (int k = 0; k < 2; ++k) \
;         acc[ai][bj][m][n] = __builtin_amdgcn_mfma_f32_16x16x32_bf16(Bt[n][k], At[m][k], acc[ai][bj][m][n], 0, 0, 0); __builtin_amdgcn_s_setprio(0); } while (0)
; #define PG8_WAIT_V(n) asm volatile("s_waitcnt vmcnt(" #n ")" ::: "memory")
; #define PG8_WAIT_L(n) asm volatile("s_waitcnt lgkmcnt(" #n ")" ::: "memory")
; #define PG8_BAR __builtin_amdgcn_s_barrier()
; #define PG8_SCHED __builtin_amdgcn_sched_barrier(0)
; template <class Epi, class Sched, bool ALIGN_EPI = false, bool SP2 = false>
; __device__ __forceinline__ void gemm_phase(PG8_LAS unsigned char* lds, const Gemm g, const Sched& S, const Epi& E, int wave_in) {
;     ...
;             PG8_WAIT_V(8); PG8_WAIT_L(0); PG8_BAR; PG8_MMA(1, 0, At, B0); PG8_MMA(1, 1, At, B1); PG8_BAR; PG8_SCHED;
;             PG8_LDB(B0, 1, 0); PG8_LDB(B1, 1, 1); PG8_SCHED; PG8_LDA(At, 1, 0); PG8_STAGE(PG8_SA(0, 1), a2 + hstep, voffA);
;             PG8_WAIT_V(8); PG8_WAIT_L(0); PG8_BAR; PG8_MMA(0, 0, At, B0); PG8_MMA(0, 1, At, B1); PG8_BAR; PG8_SCHED;
	s_setprio 1
	s_waitcnt lgkmcnt(0)
	v_mfma_f32_16x16x32_bf16 v[60:63], v[112:115], v[160:163], 0
	v_mfma_f32_16x16x32_bf16 v[56:59], v[124:127], v[160:163], 0
	v_mfma_f32_16x16x32_bf16 v[40:43], v[124:127], v[168:171], 0
	v_mfma_f32_16x16x32_bf16 v[44:47], v[112:115], v[168:171], 0
	v_mfma_f32_16x16x32_bf16 v[28:31], v[112:115], v[176:179], 0
	v_mfma_f32_16x16x32_bf16 v[24:27], v[124:127], v[176:179], 0
	v_mfma_f32_16x16x32_bf16 v[8:11], v[124:127], v[184:187], 0
	v_mfma_f32_16x16x32_bf16 v[12:15], v[112:115], v[184:187], 0
	v_mfma_f32_16x16x32_bf16 v[60:63], v[120:123], v[164:167], v[60:63]
	v_mfma_f32_16x16x32_bf16 v[56:59], v[128:131], v[164:167], v[56:59]
	v_mfma_f32_16x16x32_bf16 v[40:43], v[128:131], v[172:175], v[40:43]
	v_mfma_f32_16x16x32_bf16 v[44:47], v[120:123], v[172:175], v[44:47]
	v_mfma_f32_16x16x32_bf16 v[28:31], v[120:123], v[180:183], v[28:31]
	v_mfma_f32_16x16x32_bf16 v[24:27], v[128:131], v[180:183], v[24:27]
	v_mfma_f32_16x16x32_bf16 v[8:11], v[128:131], v[188:191], v[8:11]
	v_mfma_f32_16x16x32_bf16 v[12:15], v[120:123], v[188:191], v[12:15]
	s_setprio 0
	s_setprio 1
	v_mfma_f32_16x16x32_bf16 v[52:55], v[136:139], v[160:163], 0
	v_mfma_f32_16x16x32_bf16 v[48:51], v[144:147], v[160:163], 0
	v_mfma_f32_16x16x32_bf16 v[32:35], v[144:147], v[168:171], 0
	v_mfma_f32_16x16x32_bf16 v[36:39], v[136:139], v[168:171], 0
	v_mfma_f32_16x16x32_bf16 v[20:23], v[136:139], v[176:179], 0
	v_mfma_f32_16x16x32_bf16 v[16:19], v[144:147], v[176:179], 0
	v_mfma_f32_16x16x32_bf16 v[0:3], v[144:147], v[184:187], 0
	v_mfma_f32_16x16x32_bf16 v[4:7], v[136:139], v[184:187], 0
	v_mfma_f32_16x16x32_bf16 v[52:55], v[140:143], v[164:167], v[52:55]
	v_mfma_f32_16x16x32_bf16 v[48:51], v[156:159], v[164:167], v[48:51]
	v_mfma_f32_16x16x32_bf16 v[32:35], v[156:159], v[172:175], v[32:35]
	v_mfma_f32_16x16x32_bf16 v[36:39], v[140:143], v[172:175], v[36:39]
	v_mfma_f32_16x16x32_bf16 v[20:23], v[140:143], v[180:183], v[20:23]
	v_mfma_f32_16x16x32_bf16 v[16:19], v[156:159], v[180:183], v[16:19]
	v_mfma_f32_16x16x32_bf16 v[0:3], v[156:159], v[188:191], v[0:3]
	v_mfma_f32_16x16x32_bf16 v[4:7], v[140:143], v[188:191], v[4:7]
	s_setprio 0
	s_barrier
	s_add_i32 s44, s65, 0x100
	s_add_i32 s45, s52, 0x100
	v_add_u32_e32 v128, s44, v249
	v_add_u32_e32 v156, s45, v249
	ds_read_b128 v[112:115], v128
	ds_read_b128 v[120:123], v128 offset:1024
	ds_read_b128 v[124:127], v128 offset:2048
	ds_read_b128 v[128:131], v128 offset:3072
	ds_read_b128 v[136:139], v156
	ds_read_b128 v[140:143], v156 offset:1024
	ds_read_b128 v[144:147], v156 offset:2048
	ds_read_b128 v[156:159], v156 offset:3072
	s_add_u32 s26, s26, 0x40000
	s_addc_u32 s27, s27, 0
	s_mov_b32 m0, s47
	v_lshl_add_u64 v[212:213], s[26:27], 0, v[202:203]
	ds_read_b128 v[160:163], v251 offset:32768
	ds_read_b128 v[164:167], v251 offset:33792
	ds_read_b128 v[168:171], v251 offset:34816
	ds_read_b128 v[172:175], v251 offset:35840
	ds_read_b128 v[176:179], v251 offset:36864
	ds_read_b128 v[180:183], v251 offset:37888
	ds_read_b128 v[184:187], v251 offset:38912
	ds_read_b128 v[188:191], v251 offset:39936
	global_load_lds_dwordx4 v[212:213], off
	v_lshl_add_u64 v[212:213], s[26:27], 0, v[200:201]
	s_mov_b32 m0, s60
	s_nop 0
	global_load_lds_dwordx4 v[212:213], off
	s_waitcnt vmcnt(8)
	s_waitcnt lgkmcnt(0)
	s_barrier
	s_setprio 1
	s_waitcnt lgkmcnt(0)
	v_mfma_f32_16x16x32_bf16 v[152:155], v[112:115], v[160:163], v[152:155]
	v_mfma_f32_16x16x32_bf16 v[148:151], v[124:127], v[160:163], v[148:151]
	v_mfma_f32_16x16x32_bf16 v[104:107], v[124:127], v[168:171], v[104:107]
	v_mfma_f32_16x16x32_bf16 v[108:111], v[112:115], v[168:171], v[108:111]
	v_mfma_f32_16x16x32_bf16 v[92:95], v[112:115], v[176:179], v[92:95]
	v_mfma_f32_16x16x32_bf16 v[88:91], v[124:127], v[176:179], v[88:91]
	v_mfma_f32_16x16x32_bf16 v[72:75], v[124:127], v[184:187], v[72:75]
	v_mfma_f32_16x16x32_bf16 v[76:79], v[112:115], v[184:187], v[76:79]
	v_mfma_f32_16x16x32_bf16 v[152:155], v[120:123], v[164:167], v[152:155]
	v_mfma_f32_16x16x32_bf16 v[148:151], v[128:131], v[164:167], v[148:151]
	v_mfma_f32_16x16x32_bf16 v[104:107], v[128:131], v[172:175], v[104:107]
	v_mfma_f32_16x16x32_bf16 v[108:111], v[120:123], v[172:175], v[108:111]
	v_mfma_f32_16x16x32_bf16 v[92:95], v[120:123], v[180:183], v[92:95]
	v_mfma_f32_16x16x32_bf16 v[88:91], v[128:131], v[180:183], v[88:91]
	v_mfma_f32_16x16x32_bf16 v[72:75], v[128:131], v[188:191], v[72:75]
	v_mfma_f32_16x16x32_bf16 v[76:79], v[120:123], v[188:191], v[76:79]
	s_setprio 0
	s_setprio 1
	v_mfma_f32_16x16x32_bf16 v[132:135], v[136:139], v[160:163], v[132:135]
	v_mfma_f32_16x16x32_bf16 v[116:119], v[144:147], v[160:163], v[116:119]
	v_mfma_f32_16x16x32_bf16 v[96:99], v[144:147], v[168:171], v[96:99]
	v_mfma_f32_16x16x32_bf16 v[100:103], v[136:139], v[168:171], v[100:103]
	v_mfma_f32_16x16x32_bf16 v[84:87], v[136:139], v[176:179], v[84:87]
	v_mfma_f32_16x16x32_bf16 v[80:83], v[144:147], v[176:179], v[80:83]
	v_mfma_f32_16x16x32_bf16 v[64:67], v[144:147], v[184:187], v[64:67]
	v_mfma_f32_16x16x32_bf16 v[68:71], v[136:139], v[184:187], v[68:71]
	v_mfma_f32_16x16x32_bf16 v[132:135], v[140:143], v[164:167], v[132:135]
	v_mfma_f32_16x16x32_bf16 v[116:119], v[156:159], v[164:167], v[116:119]
	v_mfma_f32_16x16x32_bf16 v[96:99], v[156:159], v[172:175], v[96:99]
	v_mfma_f32_16x16x32_bf16 v[100:103], v[140:143], v[172:175], v[100:103]
	v_mfma_f32_16x16x32_bf16 v[84:87], v[140:143], v[180:183], v[84:87]
	v_mfma_f32_16x16x32_bf16 v[80:83], v[156:159], v[180:183], v[80:83]
	v_mfma_f32_16x16x32_bf16 v[64:67], v[156:159], v[188:191], v[64:67]
	v_mfma_f32_16x16x32_bf16 v[68:71], v[140:143], v[188:191], v[68:71]
	s_setprio 0
	s_barrier
; #define PG8_STAGE(bufoff, gbase, voff) do { _Pragma("unroll") for (int _i = 0; _i < 2; ++_i) \
;         __builtin_amdgcn_global_load_lds((const unsigned*)((const char*)(gbase) + (voff)[_i]), (PG8_LAS unsigned*)(lds + (bufoff) + ldsw + _i * 8192), 16, 0, 0); } while (0)
; #define PG8_LDA(dst, b, h) do { _Pragma("unroll") for (int m = 0; m < 4; ++m) _Pragma("unroll") for (int k = 0; k < 2; ++k) dst[m][k] = *(const PG8_LAS bf16x8*)(lds + PG8_SA(b, h) + aoff + m * 2048 + k * 1024); } while (0)
; #define PG8_LDB(dst, b, h) do { _Pragma("unroll") for (int n = 0; n < 2; ++n) _Pragma("unroll") for (int k = 0; k < 2; ++k) dst[n][k] = *(const PG8_LAS bf16x8*)(lds + PG8_SB(b, h) + boff + n * 2048 + k * 1024); } while (0)
; #define PG8_MMA(ai, bj, At, Bt) do { __builtin_amdgcn_s_setprio(1); _Pragma("unroll") for (int m = 0; m < 4; ++m) _Pragma("unroll") for (int n = 0; n < 2; ++n) _Pragma("unroll") for (int k = 0; k < 2; ++k) \
;         acc[ai][bj][m][n] = __builtin_amdgcn_mfma_f32_16x16x32_bf16(Bt[n][k], At[m][k], acc[ai][bj][m][n], 0, 0, 0); __builtin_amdgcn_s_setprio(0); } while (0)
; #define PG8_WAIT_V(n) asm volatile("s_waitcnt vmcnt(" #n ")" ::: "memory")
; #define PG8_WAIT_L(n) asm volatile("s_waitcnt lgkmcnt(" #n ")" ::: "memory")
; #define PG8_BAR __builtin_amdgcn_s_barrier()
; #define PG8_SCHED __builtin_amdgcn_sched_barrier(0)
; template <class Epi, class Sched, bool ALIGN_EPI = false, bool SP2 = false>
; __device__ __forceinline__ void gemm_phase(PG8_LAS unsigned char* lds, const Gemm g, const Sched& S, const Epi& E, int wave_in) {
;     ...
;             PG8_LDB(B0, 1, 0); PG8_LDB(B1, 1, 1); PG8_SCHED; PG8_LDA(At, 1, 0); PG8_STAGE(PG8_SA(0, 1), a2 + hstep, voffA);
;             PG8_WAIT_V(8); PG8_WAIT_L(0); PG8_BAR; PG8_MMA(0, 0, At, B0); PG8_MMA(0, 1, At, B1); PG8_BAR; PG8_SCHED;
;             PG8_LDA(At, 1, 1); PG8_STAGE(PG8_SB(1, 0), b3, voffB); PG8_STAGE(PG8_SB(1, 1), b3 + hstep, voffB); PG8_STAGE(PG8_SA(1, 0), a3, voffA);
;             PG8_WAIT_V(8); PG8_WAIT_L(0); PG8_BAR; PG8_MMA(1, 0, At, B0); PG8_MMA(1, 1, At, B1); PG8_BAR; PG8_SCHED;
	s_add_i32 s26, s44, s38
	v_lshl_add_u64 v[194:195], v[194:195], 0, s[88:89]
	s_mov_b32 m0, s26
	ds_read_b128 v[160:163], v251 offset:49152
	ds_read_b128 v[164:167], v251 offset:50176
	ds_read_b128 v[168:171], v251 offset:51200
	ds_read_b128 v[172:175], v251 offset:52224
	ds_read_b128 v[176:179], v251 offset:53248
	ds_read_b128 v[180:183], v251 offset:54272
	ds_read_b128 v[184:187], v251 offset:55296
	ds_read_b128 v[188:191], v251 offset:56320
	global_load_lds_dwordx4 v[194:195], off
	s_add_i32 m0, s26, 0x2000
	s_add_u32 s24, s24, 0x40080
	v_lshl_add_u64 v[194:195], v[196:197], 0, s[88:89]
	s_addc_u32 s25, s25, 0
	s_add_i32 s26, s45, s38
	global_load_lds_dwordx4 v[194:195], off
	v_lshl_add_u64 v[194:195], s[24:25], 0, v[192:193]
	s_mov_b32 m0, s26
	s_nop 0
	global_load_lds_dwordx4 v[194:195], off
	v_lshl_add_u64 v[194:195], s[24:25], 0, v[198:199]
	s_add_i32 m0, s26, 0x2000
	s_nop 0
	global_load_lds_dwordx4 v[194:195], off
	v_lshl_add_u64 v[194:195], v[208:209], 0, s[88:89]
	s_mov_b32 m0, s62
	s_nop 0
	global_load_lds_dwordx4 v[194:195], off
	v_lshl_add_u64 v[194:195], v[210:211], 0, s[88:89]
	s_mov_b32 m0, s63
	s_nop 0
	global_load_lds_dwordx4 v[194:195], off
	s_waitcnt vmcnt(8)
	s_waitcnt lgkmcnt(0)
	s_barrier
	s_setprio 1
	s_waitcnt lgkmcnt(0)
	v_mfma_f32_16x16x32_bf16 v[60:63], v[112:115], v[160:163], v[60:63]
	v_mfma_f32_16x16x32_bf16 v[56:59], v[124:127], v[160:163], v[56:59]
	v_mfma_f32_16x16x32_bf16 v[40:43], v[124:127], v[168:171], v[40:43]
	v_mfma_f32_16x16x32_bf16 v[44:47], v[112:115], v[168:171], v[44:47]
	v_mfma_f32_16x16x32_bf16 v[28:31], v[112:115], v[176:179], v[28:31]
	v_mfma_f32_16x16x32_bf16 v[24:27], v[124:127], v[176:179], v[24:27]
	v_mfma_f32_16x16x32_bf16 v[8:11], v[124:127], v[184:187], v[8:11]
	v_mfma_f32_16x16x32_bf16 v[12:15], v[112:115], v[184:187], v[12:15]
	v_mfma_f32_16x16x32_bf16 v[60:63], v[120:123], v[164:167], v[60:63]
	v_mfma_f32_16x16x32_bf16 v[56:59], v[128:131], v[164:167], v[56:59]
	v_mfma_f32_16x16x32_bf16 v[40:43], v[128:131], v[172:175], v[40:43]
	v_mfma_f32_16x16x32_bf16 v[44:47], v[120:123], v[172:175], v[44:47]
	v_mfma_f32_16x16x32_bf16 v[28:31], v[120:123], v[180:183], v[28:31]
	v_mfma_f32_16x16x32_bf16 v[24:27], v[128:131], v[180:183], v[24:27]
	v_mfma_f32_16x16x32_bf16 v[8:11], v[128:131], v[188:191], v[8:11]
	v_mfma_f32_16x16x32_bf16 v[12:15], v[120:123], v[188:191], v[12:15]
	s_setprio 0
	s_setprio 1
	v_mfma_f32_16x16x32_bf16 v[52:55], v[136:139], v[160:163], v[52:55]
	v_mfma_f32_16x16x32_bf16 v[48:51], v[144:147], v[160:163], v[48:51]
	v_mfma_f32_16x16x32_bf16 v[32:35], v[144:147], v[168:171], v[32:35]
	v_mfma_f32_16x16x32_bf16 v[36:39], v[136:139], v[168:171], v[36:39]
	v_mfma_f32_16x16x32_bf16 v[20:23], v[136:139], v[176:179], v[20:23]
	v_mfma_f32_16x16x32_bf16 v[16:19], v[144:147], v[176:179], v[16:19]
	v_mfma_f32_16x16x32_bf16 v[0:3], v[144:147], v[184:187], v[0:3]
	v_mfma_f32_16x16x32_bf16 v[4:7], v[136:139], v[184:187], v[4:7]
	v_mfma_f32_16x16x32_bf16 v[52:55], v[140:143], v[164:167], v[52:55]
	v_mfma_f32_16x16x32_bf16 v[48:51], v[156:159], v[164:167], v[48:51]
	v_mfma_f32_16x16x32_bf16 v[32:35], v[156:159], v[172:175], v[32:35]
	v_mfma_f32_16x16x32_bf16 v[36:39], v[140:143], v[172:175], v[36:39]
	v_mfma_f32_16x16x32_bf16 v[20:23], v[140:143], v[180:183], v[20:23]
	v_mfma_f32_16x16x32_bf16 v[16:19], v[156:159], v[180:183], v[16:19]
	v_mfma_f32_16x16x32_bf16 v[0:3], v[156:159], v[188:191], v[0:3]
	v_mfma_f32_16x16x32_bf16 v[4:7], v[140:143], v[188:191], v[4:7]
	s_setprio 0
	s_barrier
	s_add_i32 s34, s34, 2
	s_add_u32 s15, s15, 0x100
	s_addc_u32 s17, s17, 0
	s_add_u32 s22, s22, 0x100
	s_addc_u32 s23, s23, 0
	s_cmp_gt_u32 s34, 13
	s_cbranch_scc1 .Lkexit_5
.LBB0_804:
	s_add_u32 s24, s22, 0xfffc0080
	s_addc_u32 s25, s23, -1
	s_add_i32 s44, s35, 0x100
	s_cmp_eq_u32 s34, 12
	s_cselect_b32 s27, s19, s25
	s_cselect_b32 s26, s18, s24
	s_cselect_b32 s25, s21, s17
	s_cselect_b32 s24, s20, s15
	s_add_i32 s53, s90, 0x100
	v_add_u32_e32 v128, s44, v249
	v_add_u32_e32 v156, s53, v249
	ds_read_b128 v[112:115], v128
	ds_read_b128 v[120:123], v128 offset:1024
	ds_read_b128 v[124:127], v128 offset:2048
	ds_read_b128 v[128:131], v128 offset:3072
	ds_read_b128 v[136:139], v156
	ds_read_b128 v[140:143], v156 offset:1024
	ds_read_b128 v[144:147], v156 offset:2048
	ds_read_b128 v[156:159], v156 offset:3072
	v_lshl_add_u64 v[194:195], s[22:23], 0, v[206:207]
	s_add_i32 m0, s39, 0xc000
	ds_read_b128 v[160:163], v251
	ds_read_b128 v[164:167], v251 offset:1024
	ds_read_b128 v[168:171], v251 offset:2048
	ds_read_b128 v[172:175], v251 offset:3072
	ds_read_b128 v[176:179], v251 offset:4096
	ds_read_b128 v[180:183], v251 offset:5120
	ds_read_b128 v[184:187], v251 offset:6144
	ds_read_b128 v[188:191], v251 offset:7168
	global_load_lds_dwordx4 v[194:195], off
	v_lshl_add_u64 v[194:195], s[22:23], 0, v[204:205]
	s_add_i32 m0, s39, 0xe000
	s_nop 0
	global_load_lds_dwordx4 v[194:195], off
	s_waitcnt vmcnt(8)
	s_waitcnt lgkmcnt(0)
	s_barrier
; #define PG8_STAGE(bufoff, gbase, voff) do { _Pragma("unroll") for (int _i = 0; _i < 2; ++_i) \
;         __builtin_amdgcn_global_load_lds((const unsigned*)((const char*)(gbase) + (voff)[_i]), (PG8_LAS unsigned*)(lds + (bufoff) + ldsw + _i * 8192), 16, 0, 0); } while (0)
; #define PG8_LDA(dst, b, h) do { _Pragma("unroll") for (int m = 0; m < 4; ++m) _Pragma("unroll") for (int k = 0; k < 2; ++k) dst[m][k] = *(const PG8_LAS bf16x8*)(lds + PG8_SA(b, h) + aoff + m * 2048 + k * 1024); } while (0)
; #define PG8_LDB(dst, b, h) do { _Pragma("unroll") for (int n = 0; n < 2; ++n) _Pragma("unroll") for (int k = 0; k < 2; ++k) dst[n][k] = *(const PG8_LAS bf16x8*)(lds + PG8_SB(b, h) + boff + n * 2048 + k * 1024); } while (0)
; #define PG8_MMA(ai, bj, At, Bt) do { __builtin_amdgcn_s_setprio(1); _Pragma("unroll") for (int m = 0; m < 4; ++m) _Pragma("unroll") for (int n = 0; n < 2; ++n) _Pragma("unroll") for (int k = 0; k < 2; ++k) \
;         acc[ai][bj][m][n] = __builtin_amdgcn_mfma_f32_16x16x32_bf16(Bt[n][k], At[m][k], acc[ai][bj][m][n], 0, 0, 0); __builtin_amdgcn_s_setprio(0); } while (0)
; #define PG8_WAIT_V(n) asm volatile("s_waitcnt vmcnt(" #n ")" ::: "memory")
; #define PG8_WAIT_L(n) asm volatile("s_waitcnt lgkmcnt(" #n ")" ::: "memory")
; #define PG8_BAR __builtin_amdgcn_s_barrier()
; #define PG8_SCHED __builtin_amdgcn_sched_barrier(0)
; template <class Epi, class Sched, bool ALIGN_EPI = false, bool SP2 = false>
; __device__ __forceinline__ void gemm_phase(PG8_LAS unsigned char* lds, const Gemm g, const Sched& S, const Epi& E, int wave_in) {
;     ...
;             PG8_LDB(B0, 0, 0); PG8_LDB(B1, 0, 1); PG8_SCHED; PG8_LDA(At, 0, 0); PG8_STAGE(PG8_SA(1, 1), a1 + hstep, voffA);
;             PG8_WAIT_V(8); PG8_WAIT_L(0); PG8_BAR; PG8_MMA(0, 0, At, B0); PG8_MMA(0, 1, At, B1); PG8_BAR; PG8_SCHED;
;             PG8_LDA(At, 0, 1); PG8_STAGE(PG8_SB(0, 0), b2, voffB); PG8_STAGE(PG8_SB(0, 1), b2 + hstep, voffB); PG8_STAGE(PG8_SA(0, 0), a2, voffA);
;             PG8_WAIT_V(8); PG8_WAIT_L(0); PG8_BAR; PG8_MMA(1, 0, At, B0); PG8_MMA(1, 1, At, B1); PG8_BAR; PG8_SCHED;
	s_setprio 1
	s_waitcnt lgkmcnt(0)
	v_mfma_f32_16x16x32_bf16 v[152:155], v[112:115], v[160:163], v[152:155]
	v_mfma_f32_16x16x32_bf16 v[148:151], v[124:127], v[160:163], v[148:151]
	v_mfma_f32_16x16x32_bf16 v[104:107], v[124:127], v[168:171], v[104:107]
	v_mfma_f32_16x16x32_bf16 v[108:111], v[112:115], v[168:171], v[108:111]
	v_mfma_f32_16x16x32_bf16 v[92:95], v[112:115], v[176:179], v[92:95]
	v_mfma_f32_16x16x32_bf16 v[88:91], v[124:127], v[176:179], v[88:91]
	v_mfma_f32_16x16x32_bf16 v[72:75], v[124:127], v[184:187], v[72:75]
	v_mfma_f32_16x16x32_bf16 v[76:79], v[112:115], v[184:187], v[76:79]
	v_mfma_f32_16x16x32_bf16 v[152:155], v[120:123], v[164:167], v[152:155]
	v_mfma_f32_16x16x32_bf16 v[148:151], v[128:131], v[164:167], v[148:151]
	v_mfma_f32_16x16x32_bf16 v[104:107], v[128:131], v[172:175], v[104:107]
	v_mfma_f32_16x16x32_bf16 v[108:111], v[120:123], v[172:175], v[108:111]
	v_mfma_f32_16x16x32_bf16 v[92:95], v[120:123], v[180:183], v[92:95]
	v_mfma_f32_16x16x32_bf16 v[88:91], v[128:131], v[180:183], v[88:91]
	v_mfma_f32_16x16x32_bf16 v[72:75], v[128:131], v[188:191], v[72:75]
	v_mfma_f32_16x16x32_bf16 v[76:79], v[120:123], v[188:191], v[76:79]
	s_setprio 0
	s_setprio 1
	v_mfma_f32_16x16x32_bf16 v[132:135], v[136:139], v[160:163], v[132:135]
	v_mfma_f32_16x16x32_bf16 v[116:119], v[144:147], v[160:163], v[116:119]
	v_mfma_f32_16x16x32_bf16 v[96:99], v[144:147], v[168:171], v[96:99]
	v_mfma_f32_16x16x32_bf16 v[100:103], v[136:139], v[168:171], v[100:103]
	v_mfma_f32_16x16x32_bf16 v[84:87], v[136:139], v[176:179], v[84:87]
	v_mfma_f32_16x16x32_bf16 v[80:83], v[144:147], v[176:179], v[80:83]
	v_mfma_f32_16x16x32_bf16 v[64:67], v[144:147], v[184:187], v[64:67]
	v_mfma_f32_16x16x32_bf16 v[68:71], v[136:139], v[184:187], v[68:71]
	v_mfma_f32_16x16x32_bf16 v[132:135], v[140:143], v[164:167], v[132:135]
	v_mfma_f32_16x16x32_bf16 v[116:119], v[156:159], v[164:167], v[116:119]
	v_mfma_f32_16x16x32_bf16 v[96:99], v[156:159], v[172:175], v[96:99]
	v_mfma_f32_16x16x32_bf16 v[100:103], v[140:143], v[172:175], v[100:103]
	v_mfma_f32_16x16x32_bf16 v[84:87], v[140:143], v[180:183], v[84:87]
	v_mfma_f32_16x16x32_bf16 v[80:83], v[156:159], v[180:183], v[80:83]
	v_mfma_f32_16x16x32_bf16 v[64:67], v[156:159], v[188:191], v[64:67]
	v_mfma_f32_16x16x32_bf16 v[68:71], v[140:143], v[188:191], v[68:71]
	s_setprio 0
	s_barrier
	s_add_i32 s44, s44, s38
	v_lshl_add_u64 v[194:195], s[24:25], 0, v[192:193]
	s_mov_b32 m0, s44
	ds_read_b128 v[160:163], v251 offset:16384
	ds_read_b128 v[164:167], v251 offset:17408
	ds_read_b128 v[168:171], v251 offset:18432
	ds_read_b128 v[172:175], v251 offset:19456
	ds_read_b128 v[176:179], v251 offset:20480
	ds_read_b128 v[180:183], v251 offset:21504
	ds_read_b128 v[184:187], v251 offset:22528
	ds_read_b128 v[188:191], v251 offset:23552
	global_load_lds_dwordx4 v[194:195], off
	s_add_i32 m0, s44, 0x2000
	s_add_u32 s44, s24, 0x40000
	v_lshl_add_u64 v[196:197], s[24:25], 0, v[198:199]
	s_addc_u32 s45, s25, 0
	s_add_i32 s53, s53, s38
	global_load_lds_dwordx4 v[196:197], off
	v_lshl_add_u64 v[208:209], s[44:45], 0, v[192:193]
	s_mov_b32 m0, s53
	v_lshl_add_u64 v[210:211], s[26:27], 0, v[200:201]
	global_load_lds_dwordx4 v[208:209], off
	v_lshl_add_u64 v[208:209], s[44:45], 0, v[198:199]
	s_add_i32 m0, s53, 0x2000
	s_nop 0
	global_load_lds_dwordx4 v[208:209], off
	v_lshl_add_u64 v[208:209], s[26:27], 0, v[202:203]
	s_mov_b32 m0, s39
	s_nop 0
	global_load_lds_dwordx4 v[208:209], off
	s_mov_b32 m0, s46
	s_nop 0
	global_load_lds_dwordx4 v[210:211], off
	s_waitcnt vmcnt(8)
	s_waitcnt lgkmcnt(0)
	s_barrier
	s_setprio 1
	s_waitcnt lgkmcnt(0)
	v_mfma_f32_16x16x32_bf16 v[60:63], v[112:115], v[160:163], v[60:63]
	v_mfma_f32_16x16x32_bf16 v[56:59], v[124:127], v[160:163], v[56:59]
	v_mfma_f32_16x16x32_bf16 v[40:43], v[124:127], v[168:171], v[40:43]
	v_mfma_f32_16x16x32_bf16 v[44:47], v[112:115], v[168:171], v[44:47]
	v_mfma_f32_16x16x32_bf16 v[28:31], v[112:115], v[176:179], v[28:31]
	v_mfma_f32_16x16x32_bf16 v[24:27], v[124:127], v[176:179], v[24:27]
	v_mfma_f32_16x16x32_bf16 v[8:11], v[124:127], v[184:187], v[8:11]
	v_mfma_f32_16x16x32_bf16 v[12:15], v[112:115], v[184:187], v[12:15]
	v_mfma_f32_16x16x32_bf16 v[60:63], v[120:123], v[164:167], v[60:63]
	v_mfma_f32_16x16x32_bf16 v[56:59], v[128:131], v[164:167], v[56:59]
	v_mfma_f32_16x16x32_bf16 v[40:43], v[128:131], v[172:175], v[40:43]
	v_mfma_f32_16x16x32_bf16 v[44:47], v[120:123], v[172:175], v[44:47]
	v_mfma_f32_16x16x32_bf16 v[28:31], v[120:123], v[180:183], v[28:31]
	v_mfma_f32_16x16x32_bf16 v[24:27], v[128:131], v[180:183], v[24:27]
	v_mfma_f32_16x16x32_bf16 v[8:11], v[128:131], v[188:191], v[8:11]
	v_mfma_f32_16x16x32_bf16 v[12:15], v[120:123], v[188:191], v[12:15]
	s_setprio 0
	s_setprio 1
	v_mfma_f32_16x16x32_bf16 v[52:55], v[136:139], v[160:163], v[52:55]
	v_mfma_f32_16x16x32_bf16 v[48:51], v[144:147], v[160:163], v[48:51]
	v_mfma_f32_16x16x32_bf16 v[32:35], v[144:147], v[168:171], v[32:35]
	v_mfma_f32_16x16x32_bf16 v[36:39], v[136:139], v[168:171], v[36:39]
	v_mfma_f32_16x16x32_bf16 v[20:23], v[136:139], v[176:179], v[20:23]
	v_mfma_f32_16x16x32_bf16 v[16:19], v[144:147], v[176:179], v[16:19]
	v_mfma_f32_16x16x32_bf16 v[0:3], v[144:147], v[184:187], v[0:3]
	v_mfma_f32_16x16x32_bf16 v[4:7], v[136:139], v[184:187], v[4:7]
	v_mfma_f32_16x16x32_bf16 v[52:55], v[140:143], v[164:167], v[52:55]
	v_mfma_f32_16x16x32_bf16 v[48:51], v[156:159], v[164:167], v[48:51]
	v_mfma_f32_16x16x32_bf16 v[32:35], v[156:159], v[172:175], v[32:35]
	v_mfma_f32_16x16x32_bf16 v[36:39], v[140:143], v[172:175], v[36:39]
	v_mfma_f32_16x16x32_bf16 v[20:23], v[140:143], v[180:183], v[20:23]
	v_mfma_f32_16x16x32_bf16 v[16:19], v[156:159], v[180:183], v[16:19]
	v_mfma_f32_16x16x32_bf16 v[0:3], v[156:159], v[188:191], v[0:3]
	v_mfma_f32_16x16x32_bf16 v[4:7], v[140:143], v[188:191], v[4:7]
	s_setprio 0
	s_barrier
; #define PG8_STAGE(bufoff, gbase, voff) do { _Pragma("unroll") for (int _i = 0; _i < 2; ++_i) \
;         __builtin_amdgcn_global_load_lds((const unsigned*)((const char*)(gbase) + (voff)[_i]), (PG8_LAS unsigned*)(lds + (bufoff) + ldsw + _i * 8192), 16, 0, 0); } while (0)
; #define PG8_LDA(dst, b, h) do { _Pragma("unroll") for (int m = 0; m < 4; ++m) _Pragma("unroll") for (int k = 0; k < 2; ++k) dst[m][k] = *(const PG8_LAS bf16x8*)(lds + PG8_SA(b, h) + aoff + m * 2048 + k * 1024); } while (0)
; #define PG8_LDB(dst, b, h) do { _Pragma("unroll") for (int n = 0; n < 2; ++n) _Pragma("unroll") for (int k = 0; k < 2; ++k) dst[n][k] = *(const PG8_LAS bf16x8*)(lds + PG8_SB(b, h) + boff + n * 2048 + k * 1024); } while (0)
; #define PG8_MMA(ai, bj, At, Bt) do { __builtin_amdgcn_s_setprio(1); _Pragma("unroll") for (int m = 0; m < 4; ++m) _Pragma("unroll") for (int n = 0; n < 2; ++n) _Pragma("unroll") for (int k = 0; k < 2; ++k) \
;         acc[ai][bj][m][n] = __builtin_amdgcn_mfma_f32_16x16x32_bf16(Bt[n][k], At[m][k], acc[ai][bj][m][n], 0, 0, 0); __builtin_amdgcn_s_setprio(0); } while (0)
; #define PG8_WAIT_V(n) asm volatile("s_waitcnt vmcnt(" #n ")" ::: "memory")
; #define PG8_WAIT_L(n) asm volatile("s_waitcnt lgkmcnt(" #n ")" ::: "memory")
; #define PG8_BAR __builtin_amdgcn_s_barrier()
; #define PG8_SCHED __builtin_amdgcn_sched_barrier(0)
; template <class Epi, class Sched, bool ALIGN_EPI = false, bool SP2 = false>
; __device__ __forceinline__ void gemm_phase(PG8_LAS unsigned char* lds, const Gemm g, const Sched& S, const Epi& E, int wave_in) {
;     ...
;             PG8_LDB(B0, 1, 0); PG8_LDB(B1, 1, 1); PG8_SCHED; PG8_LDA(At, 1, 0); PG8_STAGE(PG8_SA(0, 1), a2 + hstep, voffA);
;             PG8_WAIT_V(8); PG8_WAIT_L(0); PG8_BAR; PG8_MMA(0, 0, At, B0); PG8_MMA(0, 1, At, B1); PG8_BAR; PG8_SCHED;
	s_add_i32 s44, s65, 0x100
	s_add_i32 s45, s52, 0x100
	v_add_u32_e32 v128, s44, v249
	v_add_u32_e32 v156, s45, v249
	ds_read_b128 v[112:115], v128
	ds_read_b128 v[120:123], v128 offset:1024
	ds_read_b128 v[124:127], v128 offset:2048
	ds_read_b128 v[128:131], v128 offset:3072
	ds_read_b128 v[136:139], v156
	ds_read_b128 v[140:143], v156 offset:1024
	ds_read_b128 v[144:147], v156 offset:2048
	ds_read_b128 v[156:159], v156 offset:3072
	s_add_u32 s26, s26, 0x40000
	s_addc_u32 s27, s27, 0
	s_mov_b32 m0, s47
	v_lshl_add_u64 v[212:213], s[26:27], 0, v[202:203]
	ds_read_b128 v[160:163], v251 offset:32768
	ds_read_b128 v[164:167], v251 offset:33792
	ds_read_b128 v[168:171], v251 offset:34816
	ds_read_b128 v[172:175], v251 offset:35840
	ds_read_b128 v[176:179], v251 offset:36864
	ds_read_b128 v[180:183], v251 offset:37888
	ds_read_b128 v[184:187], v251 offset:38912
	ds_read_b128 v[188:191], v251 offset:39936
	global_load_lds_dwordx4 v[212:213], off
	v_lshl_add_u64 v[212:213], s[26:27], 0, v[200:201]
	s_mov_b32 m0, s60
	s_nop 0
	global_load_lds_dwordx4 v[212:213], off
	s_waitcnt vmcnt(8)
	s_waitcnt lgkmcnt(0)
	s_barrier
	s_setprio 1
	s_waitcnt lgkmcnt(0)
	v_mfma_f32_16x16x32_bf16 v[152:155], v[112:115], v[160:163], v[152:155]
	v_mfma_f32_16x16x32_bf16 v[148:151], v[124:127], v[160:163], v[148:151]
	v_mfma_f32_16x16x32_bf16 v[104:107], v[124:127], v[168:171], v[104:107]
	v_mfma_f32_16x16x32_bf16 v[108:111], v[112:115], v[168:171], v[108:111]
	v_mfma_f32_16x16x32_bf16 v[92:95], v[112:115], v[176:179], v[92:95]
	v_mfma_f32_16x16x32_bf16 v[88:91], v[124:127], v[176:179], v[88:91]
	v_mfma_f32_16x16x32_bf16 v[72:75], v[124:127], v[184:187], v[72:75]
	v_mfma_f32_16x16x32_bf16 v[76:79], v[112:115], v[184:187], v[76:79]
	v_mfma_f32_16x16x32_bf16 v[152:155], v[120:123], v[164:167], v[152:155]
	v_mfma_f32_16x16x32_bf16 v[148:151], v[128:131], v[164:167], v[148:151]
	v_mfma_f32_16x16x32_bf16 v[104:107], v[128:131], v[172:175], v[104:107]
	v_mfma_f32_16x16x32_bf16 v[108:111], v[120:123], v[172:175], v[108:111]
	v_mfma_f32_16x16x32_bf16 v[92:95], v[120:123], v[180:183], v[92:95]
	v_mfma_f32_16x16x32_bf16 v[88:91], v[128:131], v[180:183], v[88:91]
	v_mfma_f32_16x16x32_bf16 v[72:75], v[128:131], v[188:191], v[72:75]
	v_mfma_f32_16x16x32_bf16 v[76:79], v[120:123], v[188:191], v[76:79]
	s_setprio 0
	s_setprio 1
	v_mfma_f32_16x16x32_bf16 v[132:135], v[136:139], v[160:163], v[132:135]
	v_mfma_f32_16x16x32_bf16 v[116:119], v[144:147], v[160:163], v[116:119]
	v_mfma_f32_16x16x32_bf16 v[96:99], v[144:147], v[168:171], v[96:99]
	v_mfma_f32_16x16x32_bf16 v[100:103], v[136:139], v[168:171], v[100:103]
	v_mfma_f32_16x16x32_bf16 v[84:87], v[136:139], v[176:179], v[84:87]
	v_mfma_f32_16x16x32_bf16 v[80:83], v[144:147], v[176:179], v[80:83]
	v_mfma_f32_16x16x32_bf16 v[64:67], v[144:147], v[184:187], v[64:67]
	v_mfma_f32_16x16x32_bf16 v[68:71], v[136:139], v[184:187], v[68:71]
	v_mfma_f32_16x16x32_bf16 v[132:135], v[140:143], v[164:167], v[132:135]
	v_mfma_f32_16x16x32_bf16 v[116:119], v[156:159], v[164:167], v[116:119]
	v_mfma_f32_16x16x32_bf16 v[96:99], v[156:159], v[172:175], v[96:99]
	v_mfma_f32_16x16x32_bf16 v[100:103], v[140:143], v[172:175], v[100:103]
	v_mfma_f32_16x16x32_bf16 v[84:87], v[140:143], v[180:183], v[84:87]
	v_mfma_f32_16x16x32_bf16 v[80:83], v[156:159], v[180:183], v[80:83]
	v_mfma_f32_16x16x32_bf16 v[64:67], v[156:159], v[188:191], v[64:67]
	v_mfma_f32_16x16x32_bf16 v[68:71], v[140:143], v[188:191], v[68:71]
	s_setprio 0
	s_barrier
; #define PG8_STAGE(bufoff, gbase, voff) do { _Pragma("unroll") for (int _i = 0; _i < 2; ++_i) \
;         __builtin_amdgcn_global_load_lds((const unsigned*)((const char*)(gbase) + (voff)[_i]), (PG8_LAS unsigned*)(lds + (bufoff) + ldsw + _i * 8192), 16, 0, 0); } while (0)
; #define PG8_LDA(dst, b, h) do { _Pragma("unroll") for (int m = 0; m < 4; ++m) _Pragma("unroll") for (int k = 0; k < 2; ++k) dst[m][k] = *(const PG8_LAS bf16x8*)(lds + PG8_SA(b, h) + aoff + m * 2048 + k * 1024); } while (0)
; #define PG8_MMA(ai, bj, At, Bt) do { __builtin_amdgcn_s_setprio(1); _Pragma("unroll") for (int m = 0; m < 4; ++m) _Pragma("unroll") for (int n = 0; n < 2; ++n) _Pragma("unroll") for (int k = 0; k < 2; ++k) \
;         acc[ai][bj][m][n] = __builtin_amdgcn_mfma_f32_16x16x32_bf16(Bt[n][k], At[m][k], acc[ai][bj][m][n], 0, 0, 0); __builtin_amdgcn_s_setprio(0); } while (0)
; #define PG8_WAIT_V(n) asm volatile("s_waitcnt vmcnt(" #n ")" ::: "memory")
; #define PG8_WAIT_L(n) asm volatile("s_waitcnt lgkmcnt(" #n ")" ::: "memory")
; #define PG8_BAR __builtin_amdgcn_s_barrier()
; #define PG8_SCHED __builtin_amdgcn_sched_barrier(0)
; template <class Epi, class Sched, bool ALIGN_EPI = false, bool SP2 = false>
; __device__ __forceinline__ void gemm_phase(PG8_LAS unsigned char* lds, const Gemm g, const Sched& S, const Epi& E, int wave_in) {
;     ...
;             PG8_LDA(At, 1, 1); PG8_STAGE(PG8_SB(1, 0), b3, voffB); PG8_STAGE(PG8_SB(1, 1), b3 + hstep, voffB); PG8_STAGE(PG8_SA(1, 0), a3, voffA);
;             PG8_WAIT_V(8); PG8_WAIT_L(0); PG8_BAR; PG8_MMA(1, 0, At, B0); PG8_MMA(1, 1, At, B1); PG8_BAR; PG8_SCHED;
	s_add_i32 s26, s44, s38
	v_lshl_add_u64 v[194:195], v[194:195], 0, s[88:89]
	s_mov_b32 m0, s26
	ds_read_b128 v[160:163], v251 offset:49152
	ds_read_b128 v[164:167], v251 offset:50176
	ds_read_b128 v[168:171], v251 offset:51200
	ds_read_b128 v[172:175], v251 offset:52224
	ds_read_b128 v[176:179], v251 offset:53248
	ds_read_b128 v[180:183], v251 offset:54272
	ds_read_b128 v[184:187], v251 offset:55296
	ds_read_b128 v[188:191], v251 offset:56320
	global_load_lds_dwordx4 v[194:195], off
	s_add_i32 m0, s26, 0x2000
	s_add_u32 s24, s24, 0x40080
	v_lshl_add_u64 v[194:195], v[196:197], 0, s[88:89]
	s_addc_u32 s25, s25, 0
	s_add_i32 s26, s45, s38
	global_load_lds_dwordx4 v[194:195], off
	v_lshl_add_u64 v[194:195], s[24:25], 0, v[192:193]
	s_mov_b32 m0, s26
	s_nop 0
	global_load_lds_dwordx4 v[194:195], off
	v_lshl_add_u64 v[194:195], s[24:25], 0, v[198:199]
	s_add_i32 m0, s26, 0x2000
	s_nop 0
	global_load_lds_dwordx4 v[194:195], off
	v_lshl_add_u64 v[194:195], v[208:209], 0, s[88:89]
	s_mov_b32 m0, s62
	s_nop 0
	global_load_lds_dwordx4 v[194:195], off
	v_lshl_add_u64 v[194:195], v[210:211], 0, s[88:89]
	s_mov_b32 m0, s63
	s_nop 0
	global_load_lds_dwordx4 v[194:195], off
	s_waitcnt vmcnt(8)
	s_waitcnt lgkmcnt(0)
	s_barrier
	s_setprio 1
	s_waitcnt lgkmcnt(0)
	v_mfma_f32_16x16x32_bf16 v[60:63], v[112:115], v[160:163], v[60:63]
	v_mfma_f32_16x16x32_bf16 v[56:59], v[124:127], v[160:163], v[56:59]
	v_mfma_f32_16x16x32_bf16 v[40:43], v[124:127], v[168:171], v[40:43]
	v_mfma_f32_16x16x32_bf16 v[44:47], v[112:115], v[168:171], v[44:47]
	v_mfma_f32_16x16x32_bf16 v[28:31], v[112:115], v[176:179], v[28:31]
	v_mfma_f32_16x16x32_bf16 v[24:27], v[124:127], v[176:179], v[24:27]
	v_mfma_f32_16x16x32_bf16 v[8:11], v[124:127], v[184:187], v[8:11]
	v_mfma_f32_16x16x32_bf16 v[12:15], v[112:115], v[184:187], v[12:15]
	v_mfma_f32_16x16x32_bf16 v[60:63], v[120:123], v[164:167], v[60:63]
	v_mfma_f32_16x16x32_bf16 v[56:59], v[128:131], v[164:167], v[56:59]
	v_mfma_f32_16x16x32_bf16 v[40:43], v[128:131], v[172:175], v[40:43]
	v_mfma_f32_16x16x32_bf16 v[44:47], v[120:123], v[172:175], v[44:47]
	v_mfma_f32_16x16x32_bf16 v[28:31], v[120:123], v[180:183], v[28:31]
	v_mfma_f32_16x16x32_bf16 v[24:27], v[128:131], v[180:183], v[24:27]
	v_mfma_f32_16x16x32_bf16 v[8:11], v[128:131], v[188:191], v[8:11]
	v_mfma_f32_16x16x32_bf16 v[12:15], v[120:123], v[188:191], v[12:15]
	s_setprio 0
	s_setprio 1
	v_mfma_f32_16x16x32_bf16 v[52:55], v[136:139], v[160:163], v[52:55]
	v_mfma_f32_16x16x32_bf16 v[48:51], v[144:147], v[160:163], v[48:51]
	v_mfma_f32_16x16x32_bf16 v[32:35], v[144:147], v[168:171], v[32:35]
	v_mfma_f32_16x16x32_bf16 v[36:39], v[136:139], v[168:171], v[36:39]
	v_mfma_f32_16x16x32_bf16 v[20:23], v[136:139], v[176:179], v[20:23]
	v_mfma_f32_16x16x32_bf16 v[16:19], v[144:147], v[176:179], v[16:19]
	v_mfma_f32_16x16x32_bf16 v[0:3], v[144:147], v[184:187], v[0:3]
	v_mfma_f32_16x16x32_bf16 v[4:7], v[136:139], v[184:187], v[4:7]
	v_mfma_f32_16x16x32_bf16 v[52:55], v[140:143], v[164:167], v[52:55]
	v_mfma_f32_16x16x32_bf16 v[48:51], v[156:159], v[164:167], v[48:51]
	v_mfma_f32_16x16x32_bf16 v[32:35], v[156:159], v[172:175], v[32:35]
	v_mfma_f32_16x16x32_bf16 v[36:39], v[140:143], v[172:175], v[36:39]
	v_mfma_f32_16x16x32_bf16 v[20:23], v[140:143], v[180:183], v[20:23]
	v_mfma_f32_16x16x32_bf16 v[16:19], v[156:159], v[180:183], v[16:19]
	v_mfma_f32_16x16x32_bf16 v[0:3], v[156:159], v[188:191], v[0:3]
	v_mfma_f32_16x16x32_bf16 v[4:7], v[140:143], v[188:191], v[4:7]
	s_setprio 0
	s_barrier
	s_add_i32 s34, s34, 2
	s_add_u32 s15, s15, 0x100
	s_addc_u32 s17, s17, 0
	s_add_u32 s22, s22, 0x100
	s_addc_u32 s23, s23, 0
	s_cmp_gt_u32 s34, 13
	s_cbranch_scc0 .LBB0_804

; #define PG8_STAGE(bufoff, gbase, voff) do { _Pragma("unroll") for (int _i = 0; _i < 2; ++_i) \
;         __builtin_amdgcn_global_load_lds((const unsigned*)((const char*)(gbase) + (voff)[_i]), (PG8_LAS unsigned*)(lds + (bufoff) + ldsw + _i * 8192), 16, 0, 0); } while (0)
; #define PG8_LDA(dst, b, h) do { _Pragma("unroll") for (int m = 0; m < 4; ++m) _Pragma("unroll") for (int k = 0; k < 2; ++k) dst[m][k] = *(const PG8_LAS bf16x8*)(lds + PG8_SA(b, h) + aoff + m * 2048 + k * 1024); } while (0)
; #define PG8_LDB(dst, b, h) do { _Pragma("unroll") for (int n = 0; n < 2; ++n) _Pragma("unroll") for (int k = 0; k < 2; ++k) dst[n][k] = *(const PG8_LAS bf16x8*)(lds + PG8_SB(b, h) + boff + n * 2048 + k * 1024); } while (0)
; #define PG8_WAIT_V(n) asm volatile("s_waitcnt vmcnt(" #n ")" ::: "memory")
; #define PG8_WAIT_L(n) asm volatile("s_waitcnt lgkmcnt(" #n ")" ::: "memory")
; #define PG8_BAR __builtin_amdgcn_s_barrier()
; #define PG8_SCHED __builtin_amdgcn_sched_barrier(0)
; template <class Epi, class Sched, bool ALIGN_EPI = false, bool SP2 = false>
; __device__ __forceinline__ void gemm_phase(PG8_LAS unsigned char* lds, const Gemm g, const Sched& S, const Epi& E, int wave_in) {
;     ...
;         const bool has_next = S.next(ui + 1, nxt);
;         const char* nA = has_next ? (const char*)g.A + (size_t)(nxt.pm >> g.ash) * g.astride + (size_t)nxt.pm * tstep : cA; const char* nB = has_next ? (const char*)g.Bt + (size_t)(nxt.pm >> g.bsh) * g.bstride + (size_t)nxt.pn * tstep : cB;
;         for (int t = 0; t < nt; t += 2) {
;             const bool last = (t == nt - 2);
;             const char* a1 = cA + (size_t)(t + 1) * kstep;
;             const char* a2 = last ? nA : cA + (size_t)(t + 2) * kstep; const char* b2 = last ? nB : cB + (size_t)(t + 2) * kstep;
;             const char* a3 = a2 + kstep; const char* b3 = b2 + kstep;
;             if (last && has_next) S.a_ready(nxt);
;             if constexpr (SP2) {
;             PG8_LDB(B0, 0, 0); PG8_LDB(B1, 0, 1); PG8_SCHED; PG8_LDA(At, 0, 0); PG8_STAGE(PG8_SA(1, 1), a1 + hstep, voffA);
;             PG8_WAIT_V(8); PG8_WAIT_L(0); PG8_BAR; PG8_MMA(0, 0, At, B0); PG8_MMA(0, 1, At, B1); PG8_BAR; PG8_SCHED;
;             PG8_LDA(At, 0, 1); PG8_STAGE(PG8_SB(0, 0), b2, voffB); PG8_STAGE(PG8_SB(0, 1), b2 + hstep, voffB); PG8_STAGE(PG8_SA(0, 0), a2, voffA);
.LBB0_896:
	s_ashr_i32 s11, s10, 31
	s_lshl_b64 s[18:19], s[10:11], 19
	s_add_u32 s66, s6, s18
	s_addc_u32 s67, s72, s19
	s_and_b64 s[18:19], s[46:47], exec
	s_cselect_b32 s11, s67, s1
	s_cselect_b32 s34, s66, s0
	s_ashr_i32 s5, s4, 31
	s_lshl_b64 s[18:19], s[4:5], 19
	s_add_u32 s38, s73, s18
	s_addc_u32 s39, s74, s19
	s_and_b64 s[18:19], s[46:47], exec
	s_cselect_b32 s5, s39, s79
	s_cselect_b32 s53, s38, s78
	s_add_u32 s81, s78, 0x100
	s_addc_u32 s18, s79, 0
	s_add_u32 vcc_lo, s0, 0x40080
	s_addc_u32 vcc_hi, s1, 0
	s_mov_b32 s19, -2
	s_add_u32 s0, vcc_lo, 0xfffc0080
	s_addc_u32 s1, vcc_hi, -1
	s_add_i32 s76, s35, 0x100
	s_cmp_eq_u32 s19, 12
	s_cselect_b32 s79, s11, s1
	s_cselect_b32 s78, s34, s0
	s_cselect_b32 s1, s5, s18
	s_cselect_b32 s0, s53, s81
	s_add_i32 s29, s90, 0x100
	v_add_u32_e32 v140, s76, v207
	v_add_u32_e32 v156, s29, v207
	ds_read_b128 v[128:131], v140
	ds_read_b128 v[132:135], v140 offset:1024
	ds_read_b128 v[136:139], v140 offset:2048
	ds_read_b128 v[140:143], v140 offset:3072
	ds_read_b128 v[144:147], v156
	ds_read_b128 v[148:151], v156 offset:1024
	ds_read_b128 v[152:155], v156 offset:2048
	ds_read_b128 v[156:159], v156 offset:3072
	v_lshl_add_u64 v[190:191], vcc, 0, v[176:177]
	s_add_i32 m0, s33, 0xc000
	ds_read_b128 v[160:163], v219
	ds_read_b128 v[164:167], v219 offset:1024
	ds_read_b128 v[178:181], v219 offset:2048
	ds_read_b128 v[182:185], v219 offset:3072
	ds_read_b128 v[186:189], v219 offset:4096
	ds_read_b128 v[198:201], v219 offset:5120
	ds_read_b128 v[202:205], v219 offset:6144
	ds_read_b128 v[220:223], v219 offset:7168
	global_load_lds_dwordx4 v[190:191], off
	v_lshl_add_u64 v[190:191], vcc, 0, v[174:175]
	s_add_i32 m0, s33, 0xe000
	s_nop 0
	global_load_lds_dwordx4 v[190:191], off
	s_waitcnt vmcnt(8)
	s_waitcnt lgkmcnt(0)
	s_barrier
	s_setprio 1
	s_waitcnt lgkmcnt(0)
	v_mfma_f32_16x16x32_bf16 v[124:127], v[128:131], v[160:163], 0
	v_mfma_f32_16x16x32_bf16 v[60:63], v[136:139], v[160:163], 0
	v_mfma_f32_16x16x32_bf16 v[52:55], v[136:139], v[178:181], 0
	v_mfma_f32_16x16x32_bf16 v[116:119], v[128:131], v[178:181], 0
	v_mfma_f32_16x16x32_bf16 v[108:111], v[128:131], v[186:189], 0
	v_mfma_f32_16x16x32_bf16 v[44:47], v[136:139], v[186:189], 0
	v_mfma_f32_16x16x32_bf16 v[36:39], v[136:139], v[202:205], 0
	v_mfma_f32_16x16x32_bf16 v[100:103], v[128:131], v[202:205], 0
	v_mfma_f32_16x16x32_bf16 v[124:127], v[132:135], v[164:167], v[124:127]
	v_mfma_f32_16x16x32_bf16 v[60:63], v[140:143], v[164:167], v[60:63]
	v_mfma_f32_16x16x32_bf16 v[52:55], v[140:143], v[182:185], v[52:55]
	v_mfma_f32_16x16x32_bf16 v[116:119], v[132:135], v[182:185], v[116:119]
	v_mfma_f32_16x16x32_bf16 v[108:111], v[132:135], v[198:201], v[108:111]
	v_mfma_f32_16x16x32_bf16 v[44:47], v[140:143], v[198:201], v[44:47]
	v_mfma_f32_16x16x32_bf16 v[36:39], v[140:143], v[220:223], v[36:39]
	v_mfma_f32_16x16x32_bf16 v[100:103], v[132:135], v[220:223], v[100:103]
	s_setprio 0
	s_setprio 1
	v_mfma_f32_16x16x32_bf16 v[120:123], v[144:147], v[160:163], 0
	v_mfma_f32_16x16x32_bf16 v[56:59], v[152:155], v[160:163], 0
	v_mfma_f32_16x16x32_bf16 v[48:51], v[152:155], v[178:181], 0
	v_mfma_f32_16x16x32_bf16 v[112:115], v[144:147], v[178:181], 0
	v_mfma_f32_16x16x32_bf16 v[104:107], v[144:147], v[186:189], 0
	v_mfma_f32_16x16x32_bf16 v[40:43], v[152:155], v[186:189], 0
	v_mfma_f32_16x16x32_bf16 v[32:35], v[152:155], v[202:205], 0
	v_mfma_f32_16x16x32_bf16 v[96:99], v[144:147], v[202:205], 0
	v_mfma_f32_16x16x32_bf16 v[120:123], v[148:151], v[164:167], v[120:123]
	v_mfma_f32_16x16x32_bf16 v[56:59], v[156:159], v[164:167], v[56:59]
	v_mfma_f32_16x16x32_bf16 v[48:51], v[156:159], v[182:185], v[48:51]
	v_mfma_f32_16x16x32_bf16 v[112:115], v[148:151], v[182:185], v[112:115]
	v_mfma_f32_16x16x32_bf16 v[104:107], v[148:151], v[198:201], v[104:107]
	v_mfma_f32_16x16x32_bf16 v[40:43], v[156:159], v[198:201], v[40:43]
	v_mfma_f32_16x16x32_bf16 v[32:35], v[156:159], v[220:223], v[32:35]
	v_mfma_f32_16x16x32_bf16 v[96:99], v[148:151], v[220:223], v[96:99]
	s_setprio 0
	s_barrier
	s_add_i32 s76, s76, s75
	v_lshl_add_u64 v[190:191], s[0:1], 0, v[192:193]
	s_mov_b32 m0, s76
	ds_read_b128 v[160:163], v219 offset:16384
	ds_read_b128 v[164:167], v219 offset:17408
	ds_read_b128 v[178:181], v219 offset:18432
	ds_read_b128 v[182:185], v219 offset:19456
	ds_read_b128 v[186:189], v219 offset:20480
	ds_read_b128 v[198:201], v219 offset:21504
	ds_read_b128 v[202:205], v219 offset:22528
	ds_read_b128 v[220:223], v219 offset:23552
	global_load_lds_dwordx4 v[190:191], off
	s_add_i32 m0, s76, 0x2000
	s_add_u32 s76, s0, 0x40000
	v_lshl_add_u64 v[194:195], s[0:1], 0, v[168:169]
	s_addc_u32 s77, s1, 0
	s_add_i32 s29, s29, s75
	global_load_lds_dwordx4 v[194:195], off
	v_lshl_add_u64 v[196:197], s[76:77], 0, v[192:193]
	s_mov_b32 m0, s29
	v_lshl_add_u64 v[224:225], s[78:79], 0, v[170:171]
	global_load_lds_dwordx4 v[196:197], off
	v_lshl_add_u64 v[196:197], s[76:77], 0, v[168:169]
	s_add_i32 m0, s29, 0x2000
	s_nop 0
	global_load_lds_dwordx4 v[196:197], off
	v_lshl_add_u64 v[196:197], s[78:79], 0, v[172:173]
	s_mov_b32 m0, s33
	s_nop 0
	global_load_lds_dwordx4 v[196:197], off
	s_mov_b32 m0, s62
	s_nop 0
	global_load_lds_dwordx4 v[224:225], off
	s_waitcnt vmcnt(8)
	s_waitcnt lgkmcnt(0)
	s_barrier
; #define PG8_STAGE(bufoff, gbase, voff) do { _Pragma("unroll") for (int _i = 0; _i < 2; ++_i) \
;         __builtin_amdgcn_global_load_lds((const unsigned*)((const char*)(gbase) + (voff)[_i]), (PG8_LAS unsigned*)(lds + (bufoff) + ldsw + _i * 8192), 16, 0, 0); } while (0)
; #define PG8_LDA(dst, b, h) do { _Pragma("unroll") for (int m = 0; m < 4; ++m) _Pragma("unroll") for (int k = 0; k < 2; ++k) dst[m][k] = *(const PG8_LAS bf16x8*)(lds + PG8_SA(b, h) + aoff + m * 2048 + k * 1024); } while (0)
; #define PG8_LDB(dst, b, h) do { _Pragma("unroll") for (int n = 0; n < 2; ++n) _Pragma("unroll") for (int k = 0; k < 2; ++k) dst[n][k] = *(const PG8_LAS bf16x8*)(lds + PG8_SB(b, h) + boff + n * 2048 + k * 1024); } while (0)
; #define PG8_MMA(ai, bj, At, Bt) do { __builtin_amdgcn_s_setprio(1); _Pragma("unroll") for (int m = 0; m < 4; ++m) _Pragma("unroll") for (int n = 0; n < 2; ++n) _Pragma("unroll") for (int k = 0; k < 2; ++k) \
;         acc[ai][bj][m][n] = __builtin_amdgcn_mfma_f32_16x16x32_bf16(Bt[n][k], At[m][k], acc[ai][bj][m][n], 0, 0, 0); __builtin_amdgcn_s_setprio(0); } while (0)
; #define PG8_WAIT_V(n) asm volatile("s_waitcnt vmcnt(" #n ")" ::: "memory")
; #define PG8_WAIT_L(n) asm volatile("s_waitcnt lgkmcnt(" #n ")" ::: "memory")
; #define PG8_BAR __builtin_amdgcn_s_barrier()
; #define PG8_SCHED __builtin_amdgcn_sched_barrier(0)
; template <class Epi, class Sched, bool ALIGN_EPI = false, bool SP2 = false>
; __device__ __forceinline__ void gemm_phase(PG8_LAS unsigned char* lds, const Gemm g, const Sched& S, const Epi& E, int wave_in) {
;     ...
;             PG8_WAIT_V(8); PG8_WAIT_L(0); PG8_BAR; PG8_MMA(1, 0, At, B0); PG8_MMA(1, 1, At, B1); PG8_BAR; PG8_SCHED;
;             PG8_LDB(B0, 1, 0); PG8_LDB(B1, 1, 1); PG8_SCHED; PG8_LDA(At, 1, 0); PG8_STAGE(PG8_SA(0, 1), a2 + hstep, voffA);
;             PG8_WAIT_V(8); PG8_WAIT_L(0); PG8_BAR; PG8_MMA(0, 0, At, B0); PG8_MMA(0, 1, At, B1); PG8_BAR; PG8_SCHED;
	s_setprio 1
	s_waitcnt lgkmcnt(0)
	v_mfma_f32_16x16x32_bf16 v[92:95], v[128:131], v[160:163], 0
	v_mfma_f32_16x16x32_bf16 v[28:31], v[136:139], v[160:163], 0
	v_mfma_f32_16x16x32_bf16 v[20:23], v[136:139], v[178:181], 0
	v_mfma_f32_16x16x32_bf16 v[84:87], v[128:131], v[178:181], 0
	v_mfma_f32_16x16x32_bf16 v[76:79], v[128:131], v[186:189], 0
	v_mfma_f32_16x16x32_bf16 v[12:15], v[136:139], v[186:189], 0
	v_mfma_f32_16x16x32_bf16 v[4:7], v[136:139], v[202:205], 0
	v_mfma_f32_16x16x32_bf16 v[68:71], v[128:131], v[202:205], 0
	v_mfma_f32_16x16x32_bf16 v[92:95], v[132:135], v[164:167], v[92:95]
	v_mfma_f32_16x16x32_bf16 v[28:31], v[140:143], v[164:167], v[28:31]
	v_mfma_f32_16x16x32_bf16 v[20:23], v[140:143], v[182:185], v[20:23]
	v_mfma_f32_16x16x32_bf16 v[84:87], v[132:135], v[182:185], v[84:87]
	v_mfma_f32_16x16x32_bf16 v[76:79], v[132:135], v[198:201], v[76:79]
	v_mfma_f32_16x16x32_bf16 v[12:15], v[140:143], v[198:201], v[12:15]
	v_mfma_f32_16x16x32_bf16 v[4:7], v[140:143], v[220:223], v[4:7]
	v_mfma_f32_16x16x32_bf16 v[68:71], v[132:135], v[220:223], v[68:71]
	s_setprio 0
	s_setprio 1
	v_mfma_f32_16x16x32_bf16 v[88:91], v[144:147], v[160:163], 0
	v_mfma_f32_16x16x32_bf16 v[24:27], v[152:155], v[160:163], 0
	v_mfma_f32_16x16x32_bf16 v[16:19], v[152:155], v[178:181], 0
	v_mfma_f32_16x16x32_bf16 v[80:83], v[144:147], v[178:181], 0
	v_mfma_f32_16x16x32_bf16 v[72:75], v[144:147], v[186:189], 0
	v_mfma_f32_16x16x32_bf16 v[8:11], v[152:155], v[186:189], 0
	v_mfma_f32_16x16x32_bf16 v[0:3], v[152:155], v[202:205], 0
	v_mfma_f32_16x16x32_bf16 v[64:67], v[144:147], v[202:205], 0
	v_mfma_f32_16x16x32_bf16 v[88:91], v[148:151], v[164:167], v[88:91]
	v_mfma_f32_16x16x32_bf16 v[24:27], v[156:159], v[164:167], v[24:27]
	v_mfma_f32_16x16x32_bf16 v[16:19], v[156:159], v[182:185], v[16:19]
	v_mfma_f32_16x16x32_bf16 v[80:83], v[148:151], v[182:185], v[80:83]
	v_mfma_f32_16x16x32_bf16 v[72:75], v[148:151], v[198:201], v[72:75]
	v_mfma_f32_16x16x32_bf16 v[8:11], v[156:159], v[198:201], v[8:11]
	v_mfma_f32_16x16x32_bf16 v[0:3], v[156:159], v[220:223], v[0:3]
	v_mfma_f32_16x16x32_bf16 v[64:67], v[148:151], v[220:223], v[64:67]
	s_setprio 0
	s_barrier
	s_add_i32 s29, s65, 0x100
	s_add_i32 s2, s52, 0x100
	v_add_u32_e32 v140, s29, v207
	v_add_u32_e32 v156, s2, v207
	ds_read_b128 v[128:131], v140
	ds_read_b128 v[132:135], v140 offset:1024
	ds_read_b128 v[136:139], v140 offset:2048
	ds_read_b128 v[140:143], v140 offset:3072
	ds_read_b128 v[144:147], v156
	ds_read_b128 v[148:151], v156 offset:1024
	ds_read_b128 v[152:155], v156 offset:2048
	ds_read_b128 v[156:159], v156 offset:3072
	s_add_u32 s76, s78, 0x40000
	s_addc_u32 s77, s79, 0
	s_mov_b32 m0, s63
	v_lshl_add_u64 v[226:227], s[76:77], 0, v[172:173]
	ds_read_b128 v[160:163], v219 offset:32768
	ds_read_b128 v[164:167], v219 offset:33792
	ds_read_b128 v[178:181], v219 offset:34816
	ds_read_b128 v[182:185], v219 offset:35840
	ds_read_b128 v[186:189], v219 offset:36864
	ds_read_b128 v[198:201], v219 offset:37888
	ds_read_b128 v[202:205], v219 offset:38912
	ds_read_b128 v[220:223], v219 offset:39936
	global_load_lds_dwordx4 v[226:227], off
	v_lshl_add_u64 v[226:227], s[76:77], 0, v[170:171]
	s_mov_b32 m0, s31
	s_nop 0
	global_load_lds_dwordx4 v[226:227], off
	s_waitcnt vmcnt(8)
	s_waitcnt lgkmcnt(0)
	s_barrier
	s_setprio 1
	s_waitcnt lgkmcnt(0)
	v_mfma_f32_16x16x32_bf16 v[124:127], v[128:131], v[160:163], v[124:127]
	v_mfma_f32_16x16x32_bf16 v[60:63], v[136:139], v[160:163], v[60:63]
	v_mfma_f32_16x16x32_bf16 v[52:55], v[136:139], v[178:181], v[52:55]
	v_mfma_f32_16x16x32_bf16 v[116:119], v[128:131], v[178:181], v[116:119]
	v_mfma_f32_16x16x32_bf16 v[108:111], v[128:131], v[186:189], v[108:111]
	v_mfma_f32_16x16x32_bf16 v[44:47], v[136:139], v[186:189], v[44:47]
	v_mfma_f32_16x16x32_bf16 v[36:39], v[136:139], v[202:205], v[36:39]
	v_mfma_f32_16x16x32_bf16 v[100:103], v[128:131], v[202:205], v[100:103]
	v_mfma_f32_16x16x32_bf16 v[124:127], v[132:135], v[164:167], v[124:127]
	v_mfma_f32_16x16x32_bf16 v[60:63], v[140:143], v[164:167], v[60:63]
	v_mfma_f32_16x16x32_bf16 v[52:55], v[140:143], v[182:185], v[52:55]
	v_mfma_f32_16x16x32_bf16 v[116:119], v[132:135], v[182:185], v[116:119]
	v_mfma_f32_16x16x32_bf16 v[108:111], v[132:135], v[198:201], v[108:111]
	v_mfma_f32_16x16x32_bf16 v[44:47], v[140:143], v[198:201], v[44:47]
	v_mfma_f32_16x16x32_bf16 v[36:39], v[140:143], v[220:223], v[36:39]
	v_mfma_f32_16x16x32_bf16 v[100:103], v[132:135], v[220:223], v[100:103]
	s_setprio 0
	s_setprio 1
	v_mfma_f32_16x16x32_bf16 v[120:123], v[144:147], v[160:163], v[120:123]
	v_mfma_f32_16x16x32_bf16 v[56:59], v[152:155], v[160:163], v[56:59]
	v_mfma_f32_16x16x32_bf16 v[48:51], v[152:155], v[178:181], v[48:51]
	v_mfma_f32_16x16x32_bf16 v[112:115], v[144:147], v[178:181], v[112:115]
	v_mfma_f32_16x16x32_bf16 v[104:107], v[144:147], v[186:189], v[104:107]
	v_mfma_f32_16x16x32_bf16 v[40:43], v[152:155], v[186:189], v[40:43]
	v_mfma_f32_16x16x32_bf16 v[32:35], v[152:155], v[202:205], v[32:35]
	v_mfma_f32_16x16x32_bf16 v[96:99], v[144:147], v[202:205], v[96:99]
	v_mfma_f32_16x16x32_bf16 v[120:123], v[148:151], v[164:167], v[120:123]
	v_mfma_f32_16x16x32_bf16 v[56:59], v[156:159], v[164:167], v[56:59]
	v_mfma_f32_16x16x32_bf16 v[48:51], v[156:159], v[182:185], v[48:51]
	v_mfma_f32_16x16x32_bf16 v[112:115], v[148:151], v[182:185], v[112:115]
	v_mfma_f32_16x16x32_bf16 v[104:107], v[148:151], v[198:201], v[104:107]
	v_mfma_f32_16x16x32_bf16 v[40:43], v[156:159], v[198:201], v[40:43]
	v_mfma_f32_16x16x32_bf16 v[32:35], v[156:159], v[220:223], v[32:35]
	v_mfma_f32_16x16x32_bf16 v[96:99], v[148:151], v[220:223], v[96:99]
	s_setprio 0
	s_barrier
; #define PG8_STAGE(bufoff, gbase, voff) do { _Pragma("unroll") for (int _i = 0; _i < 2; ++_i) \
;         __builtin_amdgcn_global_load_lds((const unsigned*)((const char*)(gbase) + (voff)[_i]), (PG8_LAS unsigned*)(lds + (bufoff) + ldsw + _i * 8192), 16, 0, 0); } while (0)
; #define PG8_LDA(dst, b, h) do { _Pragma("unroll") for (int m = 0; m < 4; ++m) _Pragma("unroll") for (int k = 0; k < 2; ++k) dst[m][k] = *(const PG8_LAS bf16x8*)(lds + PG8_SA(b, h) + aoff + m * 2048 + k * 1024); } while (0)
; #define PG8_WAIT_V(n) asm volatile("s_waitcnt vmcnt(" #n ")" ::: "memory")
; #define PG8_WAIT_L(n) asm volatile("s_waitcnt lgkmcnt(" #n ")" ::: "memory")
; #define PG8_BAR __builtin_amdgcn_s_barrier()
; template <class Epi, class Sched, bool ALIGN_EPI = false, bool SP2 = false>
; __device__ __forceinline__ void gemm_phase(PG8_LAS unsigned char* lds, const Gemm g, const Sched& S, const Epi& E, int wave_in) {
;     ...
;         for (int t = 0; t < nt; t += 2) {
;             const bool last = (t == nt - 2);
;             const char* a1 = cA + (size_t)(t + 1) * kstep;
;             const char* a2 = last ? nA : cA + (size_t)(t + 2) * kstep; const char* b2 = last ? nB : cB + (size_t)(t + 2) * kstep;
;             const char* a3 = a2 + kstep; const char* b3 = b2 + kstep;
;             if (last && has_next) S.a_ready(nxt);
;             if constexpr (SP2) {
;             PG8_LDB(B0, 0, 0); PG8_LDB(B1, 0, 1); PG8_SCHED; PG8_LDA(At, 0, 0); PG8_STAGE(PG8_SA(1, 1), a1 + hstep, voffA);
;             PG8_WAIT_V(8); PG8_WAIT_L(0); PG8_BAR; PG8_MMA(0, 0, At, B0); PG8_MMA(0, 1, At, B1); PG8_BAR; PG8_SCHED;
;             PG8_LDA(At, 0, 1); PG8_STAGE(PG8_SB(0, 0), b2, voffB); PG8_STAGE(PG8_SB(0, 1), b2 + hstep, voffB); PG8_STAGE(PG8_SA(0, 0), a2, voffA);
;             PG8_WAIT_V(8); PG8_WAIT_L(0); PG8_BAR; PG8_MMA(1, 0, At, B0); PG8_MMA(1, 1, At, B1); PG8_BAR; PG8_SCHED;
;             PG8_LDB(B0, 1, 0); PG8_LDB(B1, 1, 1); PG8_SCHED; PG8_LDA(At, 1, 0); PG8_STAGE(PG8_SA(0, 1), a2 + hstep, voffA);
;             PG8_WAIT_V(8); PG8_WAIT_L(0); PG8_BAR; PG8_MMA(0, 0, At, B0); PG8_MMA(0, 1, At, B1); PG8_BAR; PG8_SCHED;
;             PG8_LDA(At, 1, 1); PG8_STAGE(PG8_SB(1, 0), b3, voffB); PG8_STAGE(PG8_SB(1, 1), b3 + hstep, voffB); PG8_STAGE(PG8_SA(1, 0), a3, voffA);
;             PG8_WAIT_V(8); PG8_WAIT_L(0); PG8_BAR; PG8_MMA(1, 0, At, B0); PG8_MMA(1, 1, At, B1); PG8_BAR; PG8_SCHED;
	s_add_i32 s29, s29, s75
	v_lshl_add_u64 v[190:191], v[190:191], 0, s[88:89]
	s_mov_b32 m0, s29
	ds_read_b128 v[160:163], v219 offset:49152
	ds_read_b128 v[164:167], v219 offset:50176
	ds_read_b128 v[178:181], v219 offset:51200
	ds_read_b128 v[182:185], v219 offset:52224
	ds_read_b128 v[186:189], v219 offset:53248
	ds_read_b128 v[198:201], v219 offset:54272
	ds_read_b128 v[202:205], v219 offset:55296
	ds_read_b128 v[220:223], v219 offset:56320
	global_load_lds_dwordx4 v[190:191], off
	s_add_i32 m0, s29, 0x2000
	s_add_u32 s0, s0, 0x40080
	v_lshl_add_u64 v[190:191], v[194:195], 0, s[88:89]
	s_addc_u32 s1, s1, 0
	s_add_i32 s2, s2, s75
	global_load_lds_dwordx4 v[190:191], off
	v_lshl_add_u64 v[190:191], s[0:1], 0, v[192:193]
	s_mov_b32 m0, s2
	s_nop 0
	global_load_lds_dwordx4 v[190:191], off
	v_lshl_add_u64 v[190:191], s[0:1], 0, v[168:169]
	s_add_i32 m0, s2, 0x2000
	s_nop 0
	global_load_lds_dwordx4 v[190:191], off
	v_lshl_add_u64 v[190:191], v[196:197], 0, s[88:89]
	s_mov_b32 m0, s9
	s_nop 0
	global_load_lds_dwordx4 v[190:191], off
	v_lshl_add_u64 v[190:191], v[224:225], 0, s[88:89]
	s_mov_b32 m0, s96
	s_nop 0
	global_load_lds_dwordx4 v[190:191], off
	s_waitcnt vmcnt(8)
	s_waitcnt lgkmcnt(0)
	s_barrier
	s_setprio 1
	s_waitcnt lgkmcnt(0)
	v_mfma_f32_16x16x32_bf16 v[92:95], v[128:131], v[160:163], v[92:95]
	v_mfma_f32_16x16x32_bf16 v[28:31], v[136:139], v[160:163], v[28:31]
	v_mfma_f32_16x16x32_bf16 v[20:23], v[136:139], v[178:181], v[20:23]
	v_mfma_f32_16x16x32_bf16 v[84:87], v[128:131], v[178:181], v[84:87]
	v_mfma_f32_16x16x32_bf16 v[76:79], v[128:131], v[186:189], v[76:79]
	v_mfma_f32_16x16x32_bf16 v[12:15], v[136:139], v[186:189], v[12:15]
	v_mfma_f32_16x16x32_bf16 v[4:7], v[136:139], v[202:205], v[4:7]
	v_mfma_f32_16x16x32_bf16 v[68:71], v[128:131], v[202:205], v[68:71]
	v_mfma_f32_16x16x32_bf16 v[92:95], v[132:135], v[164:167], v[92:95]
	v_mfma_f32_16x16x32_bf16 v[28:31], v[140:143], v[164:167], v[28:31]
	v_mfma_f32_16x16x32_bf16 v[20:23], v[140:143], v[182:185], v[20:23]
	v_mfma_f32_16x16x32_bf16 v[84:87], v[132:135], v[182:185], v[84:87]
	v_mfma_f32_16x16x32_bf16 v[76:79], v[132:135], v[198:201], v[76:79]
	v_mfma_f32_16x16x32_bf16 v[12:15], v[140:143], v[198:201], v[12:15]
	v_mfma_f32_16x16x32_bf16 v[4:7], v[140:143], v[220:223], v[4:7]
	v_mfma_f32_16x16x32_bf16 v[68:71], v[132:135], v[220:223], v[68:71]
	s_setprio 0
	s_setprio 1
	v_mfma_f32_16x16x32_bf16 v[88:91], v[144:147], v[160:163], v[88:91]
	v_mfma_f32_16x16x32_bf16 v[24:27], v[152:155], v[160:163], v[24:27]
	v_mfma_f32_16x16x32_bf16 v[16:19], v[152:155], v[178:181], v[16:19]
	v_mfma_f32_16x16x32_bf16 v[80:83], v[144:147], v[178:181], v[80:83]
	v_mfma_f32_16x16x32_bf16 v[72:75], v[144:147], v[186:189], v[72:75]
	v_mfma_f32_16x16x32_bf16 v[8:11], v[152:155], v[186:189], v[8:11]
	v_mfma_f32_16x16x32_bf16 v[0:3], v[152:155], v[202:205], v[0:3]
	v_mfma_f32_16x16x32_bf16 v[64:67], v[144:147], v[202:205], v[64:67]
	v_mfma_f32_16x16x32_bf16 v[88:91], v[148:151], v[164:167], v[88:91]
	v_mfma_f32_16x16x32_bf16 v[24:27], v[156:159], v[164:167], v[24:27]
	v_mfma_f32_16x16x32_bf16 v[16:19], v[156:159], v[182:185], v[16:19]
	v_mfma_f32_16x16x32_bf16 v[80:83], v[148:151], v[182:185], v[80:83]
	v_mfma_f32_16x16x32_bf16 v[72:75], v[148:151], v[198:201], v[72:75]
	v_mfma_f32_16x16x32_bf16 v[8:11], v[156:159], v[198:201], v[8:11]
	v_mfma_f32_16x16x32_bf16 v[0:3], v[156:159], v[220:223], v[0:3]
	v_mfma_f32_16x16x32_bf16 v[64:67], v[148:151], v[220:223], v[64:67]
	s_setprio 0
	s_barrier
	s_add_i32 s19, s19, 2
	s_add_u32 s81, s81, 0x100
	s_addc_u32 s18, s18, 0
	s_add_u32 vcc_lo, vcc_lo, 0x100
	s_addc_u32 vcc_hi, vcc_hi, 0
	s_cmp_gt_u32 s19, 13
	s_cbranch_scc1 .Lkexit_6
.LBB0_897:
	s_add_u32 s0, vcc_lo, 0xfffc0080
	s_addc_u32 s1, vcc_hi, -1
	s_add_i32 s76, s35, 0x100
	s_cmp_eq_u32 s19, 12
	s_cselect_b32 s79, s11, s1
	s_cselect_b32 s78, s34, s0
	s_cselect_b32 s1, s5, s18
	s_cselect_b32 s0, s53, s81
	s_add_i32 s29, s90, 0x100
	v_add_u32_e32 v140, s76, v207
	v_add_u32_e32 v156, s29, v207
	ds_read_b128 v[128:131], v140
	ds_read_b128 v[132:135], v140 offset:1024
	ds_read_b128 v[136:139], v140 offset:2048
	ds_read_b128 v[140:143], v140 offset:3072
	ds_read_b128 v[144:147], v156
	ds_read_b128 v[148:151], v156 offset:1024
	ds_read_b128 v[152:155], v156 offset:2048
	ds_read_b128 v[156:159], v156 offset:3072
	v_lshl_add_u64 v[190:191], vcc, 0, v[176:177]
	s_add_i32 m0, s33, 0xc000
	ds_read_b128 v[160:163], v219
	ds_read_b128 v[164:167], v219 offset:1024
	ds_read_b128 v[178:181], v219 offset:2048
	ds_read_b128 v[182:185], v219 offset:3072
	ds_read_b128 v[186:189], v219 offset:4096
	ds_read_b128 v[198:201], v219 offset:5120
	ds_read_b128 v[202:205], v219 offset:6144
	ds_read_b128 v[220:223], v219 offset:7168
	global_load_lds_dwordx4 v[190:191], off
	v_lshl_add_u64 v[190:191], vcc, 0, v[174:175]
	s_add_i32 m0, s33, 0xe000
	s_nop 0
	global_load_lds_dwordx4 v[190:191], off
	s_waitcnt vmcnt(8)
	s_waitcnt lgkmcnt(0)
	s_barrier
; #define PG8_STAGE(bufoff, gbase, voff) do { _Pragma("unroll") for (int _i = 0; _i < 2; ++_i) \
;         __builtin_amdgcn_global_load_lds((const unsigned*)((const char*)(gbase) + (voff)[_i]), (PG8_LAS unsigned*)(lds + (bufoff) + ldsw + _i * 8192), 16, 0, 0); } while (0)
; #define PG8_LDA(dst, b, h) do { _Pragma("unroll") for (int m = 0; m < 4; ++m) _Pragma("unroll") for (int k = 0; k < 2; ++k) dst[m][k] = *(const PG8_LAS bf16x8*)(lds + PG8_SA(b, h) + aoff + m * 2048 + k * 1024); } while (0)
; #define PG8_MMA(ai, bj, At, Bt) do { __builtin_amdgcn_s_setprio(1); _Pragma("unroll") for (int m = 0; m < 4; ++m) _Pragma("unroll") for (int n = 0; n < 2; ++n) _Pragma("unroll") for (int k = 0; k < 2; ++k) \
;         acc[ai][bj][m][n] = __builtin_amdgcn_mfma_f32_16x16x32_bf16(Bt[n][k], At[m][k], acc[ai][bj][m][n], 0, 0, 0); __builtin_amdgcn_s_setprio(0); } while (0)
; #define PG8_WAIT_V(n) asm volatile("s_waitcnt vmcnt(" #n ")" ::: "memory")
; #define PG8_WAIT_L(n) asm volatile("s_waitcnt lgkmcnt(" #n ")" ::: "memory")
; #define PG8_BAR __builtin_amdgcn_s_barrier()
; #define PG8_SCHED __builtin_amdgcn_sched_barrier(0)
; template <class Epi, class Sched, bool ALIGN_EPI = false, bool SP2 = false>
; __device__ __forceinline__ void gemm_phase(PG8_LAS unsigned char* lds, const Gemm g, const Sched& S, const Epi& E, int wave_in) {
;     ...
;             PG8_WAIT_V(8); PG8_WAIT_L(0); PG8_BAR; PG8_MMA(0, 0, At, B0); PG8_MMA(0, 1, At, B1); PG8_BAR; PG8_SCHED;
;             PG8_LDA(At, 0, 1); PG8_STAGE(PG8_SB(0, 0), b2, voffB); PG8_STAGE(PG8_SB(0, 1), b2 + hstep, voffB); PG8_STAGE(PG8_SA(0, 0), a2, voffA);
;             PG8_WAIT_V(8); PG8_WAIT_L(0); PG8_BAR; PG8_MMA(1, 0, At, B0); PG8_MMA(1, 1, At, B1); PG8_BAR; PG8_SCHED;
	s_setprio 1
	s_waitcnt lgkmcnt(0)
	v_mfma_f32_16x16x32_bf16 v[124:127], v[128:131], v[160:163], v[124:127]
	v_mfma_f32_16x16x32_bf16 v[60:63], v[136:139], v[160:163], v[60:63]
	v_mfma_f32_16x16x32_bf16 v[52:55], v[136:139], v[178:181], v[52:55]
	v_mfma_f32_16x16x32_bf16 v[116:119], v[128:131], v[178:181], v[116:119]
	v_mfma_f32_16x16x32_bf16 v[108:111], v[128:131], v[186:189], v[108:111]
	v_mfma_f32_16x16x32_bf16 v[44:47], v[136:139], v[186:189], v[44:47]
	v_mfma_f32_16x16x32_bf16 v[36:39], v[136:139], v[202:205], v[36:39]
	v_mfma_f32_16x16x32_bf16 v[100:103], v[128:131], v[202:205], v[100:103]
	v_mfma_f32_16x16x32_bf16 v[124:127], v[132:135], v[164:167], v[124:127]
	v_mfma_f32_16x16x32_bf16 v[60:63], v[140:143], v[164:167], v[60:63]
	v_mfma_f32_16x16x32_bf16 v[52:55], v[140:143], v[182:185], v[52:55]
	v_mfma_f32_16x16x32_bf16 v[116:119], v[132:135], v[182:185], v[116:119]
	v_mfma_f32_16x16x32_bf16 v[108:111], v[132:135], v[198:201], v[108:111]
	v_mfma_f32_16x16x32_bf16 v[44:47], v[140:143], v[198:201], v[44:47]
	v_mfma_f32_16x16x32_bf16 v[36:39], v[140:143], v[220:223], v[36:39]
	v_mfma_f32_16x16x32_bf16 v[100:103], v[132:135], v[220:223], v[100:103]
	s_setprio 0
	s_setprio 1
	v_mfma_f32_16x16x32_bf16 v[120:123], v[144:147], v[160:163], v[120:123]
	v_mfma_f32_16x16x32_bf16 v[56:59], v[152:155], v[160:163], v[56:59]
	v_mfma_f32_16x16x32_bf16 v[48:51], v[152:155], v[178:181], v[48:51]
	v_mfma_f32_16x16x32_bf16 v[112:115], v[144:147], v[178:181], v[112:115]
	v_mfma_f32_16x16x32_bf16 v[104:107], v[144:147], v[186:189], v[104:107]
	v_mfma_f32_16x16x32_bf16 v[40:43], v[152:155], v[186:189], v[40:43]
	v_mfma_f32_16x16x32_bf16 v[32:35], v[152:155], v[202:205], v[32:35]
	v_mfma_f32_16x16x32_bf16 v[96:99], v[144:147], v[202:205], v[96:99]
	v_mfma_f32_16x16x32_bf16 v[120:123], v[148:151], v[164:167], v[120:123]
	v_mfma_f32_16x16x32_bf16 v[56:59], v[156:159], v[164:167], v[56:59]
	v_mfma_f32_16x16x32_bf16 v[48:51], v[156:159], v[182:185], v[48:51]
	v_mfma_f32_16x16x32_bf16 v[112:115], v[148:151], v[182:185], v[112:115]
	v_mfma_f32_16x16x32_bf16 v[104:107], v[148:151], v[198:201], v[104:107]
	v_mfma_f32_16x16x32_bf16 v[40:43], v[156:159], v[198:201], v[40:43]
	v_mfma_f32_16x16x32_bf16 v[32:35], v[156:159], v[220:223], v[32:35]
	v_mfma_f32_16x16x32_bf16 v[96:99], v[148:151], v[220:223], v[96:99]
	s_setprio 0
	s_barrier
	s_add_i32 s76, s76, s75
	v_lshl_add_u64 v[190:191], s[0:1], 0, v[192:193]
	s_mov_b32 m0, s76
	ds_read_b128 v[160:163], v219 offset:16384
	ds_read_b128 v[164:167], v219 offset:17408
	ds_read_b128 v[178:181], v219 offset:18432
	ds_read_b128 v[182:185], v219 offset:19456
	ds_read_b128 v[186:189], v219 offset:20480
	ds_read_b128 v[198:201], v219 offset:21504
	ds_read_b128 v[202:205], v219 offset:22528
	ds_read_b128 v[220:223], v219 offset:23552
	global_load_lds_dwordx4 v[190:191], off
	s_add_i32 m0, s76, 0x2000
	s_add_u32 s76, s0, 0x40000
	v_lshl_add_u64 v[194:195], s[0:1], 0, v[168:169]
	s_addc_u32 s77, s1, 0
	s_add_i32 s29, s29, s75
	global_load_lds_dwordx4 v[194:195], off
	v_lshl_add_u64 v[196:197], s[76:77], 0, v[192:193]
	s_mov_b32 m0, s29
	v_lshl_add_u64 v[224:225], s[78:79], 0, v[170:171]
	global_load_lds_dwordx4 v[196:197], off
	v_lshl_add_u64 v[196:197], s[76:77], 0, v[168:169]
	s_add_i32 m0, s29, 0x2000
	s_nop 0
	global_load_lds_dwordx4 v[196:197], off
	v_lshl_add_u64 v[196:197], s[78:79], 0, v[172:173]
	s_mov_b32 m0, s33
	s_nop 0
	global_load_lds_dwordx4 v[196:197], off
	s_mov_b32 m0, s62
	s_nop 0
	global_load_lds_dwordx4 v[224:225], off
	s_waitcnt vmcnt(8)
	s_waitcnt lgkmcnt(0)
	s_barrier
	s_setprio 1
	s_waitcnt lgkmcnt(0)
	v_mfma_f32_16x16x32_bf16 v[92:95], v[128:131], v[160:163], v[92:95]
	v_mfma_f32_16x16x32_bf16 v[28:31], v[136:139], v[160:163], v[28:31]
	v_mfma_f32_16x16x32_bf16 v[20:23], v[136:139], v[178:181], v[20:23]
	v_mfma_f32_16x16x32_bf16 v[84:87], v[128:131], v[178:181], v[84:87]
	v_mfma_f32_16x16x32_bf16 v[76:79], v[128:131], v[186:189], v[76:79]
	v_mfma_f32_16x16x32_bf16 v[12:15], v[136:139], v[186:189], v[12:15]
	v_mfma_f32_16x16x32_bf16 v[4:7], v[136:139], v[202:205], v[4:7]
	v_mfma_f32_16x16x32_bf16 v[68:71], v[128:131], v[202:205], v[68:71]
	v_mfma_f32_16x16x32_bf16 v[92:95], v[132:135], v[164:167], v[92:95]
	v_mfma_f32_16x16x32_bf16 v[28:31], v[140:143], v[164:167], v[28:31]
	v_mfma_f32_16x16x32_bf16 v[20:23], v[140:143], v[182:185], v[20:23]
	v_mfma_f32_16x16x32_bf16 v[84:87], v[132:135], v[182:185], v[84:87]
	v_mfma_f32_16x16x32_bf16 v[76:79], v[132:135], v[198:201], v[76:79]
	v_mfma_f32_16x16x32_bf16 v[12:15], v[140:143], v[198:201], v[12:15]
	v_mfma_f32_16x16x32_bf16 v[4:7], v[140:143], v[220:223], v[4:7]
	v_mfma_f32_16x16x32_bf16 v[68:71], v[132:135], v[220:223], v[68:71]
	s_setprio 0
	s_setprio 1
	v_mfma_f32_16x16x32_bf16 v[88:91], v[144:147], v[160:163], v[88:91]
	v_mfma_f32_16x16x32_bf16 v[24:27], v[152:155], v[160:163], v[24:27]
	v_mfma_f32_16x16x32_bf16 v[16:19], v[152:155], v[178:181], v[16:19]
	v_mfma_f32_16x16x32_bf16 v[80:83], v[144:147], v[178:181], v[80:83]
	v_mfma_f32_16x16x32_bf16 v[72:75], v[144:147], v[186:189], v[72:75]
	v_mfma_f32_16x16x32_bf16 v[8:11], v[152:155], v[186:189], v[8:11]
	v_mfma_f32_16x16x32_bf16 v[0:3], v[152:155], v[202:205], v[0:3]
	v_mfma_f32_16x16x32_bf16 v[64:67], v[144:147], v[202:205], v[64:67]
	v_mfma_f32_16x16x32_bf16 v[88:91], v[148:151], v[164:167], v[88:91]
	v_mfma_f32_16x16x32_bf16 v[24:27], v[156:159], v[164:167], v[24:27]
	v_mfma_f32_16x16x32_bf16 v[16:19], v[156:159], v[182:185], v[16:19]
	v_mfma_f32_16x16x32_bf16 v[80:83], v[148:151], v[182:185], v[80:83]
	v_mfma_f32_16x16x32_bf16 v[72:75], v[148:151], v[198:201], v[72:75]
	v_mfma_f32_16x16x32_bf16 v[8:11], v[156:159], v[198:201], v[8:11]
	v_mfma_f32_16x16x32_bf16 v[0:3], v[156:159], v[220:223], v[0:3]
	v_mfma_f32_16x16x32_bf16 v[64:67], v[148:151], v[220:223], v[64:67]
	s_setprio 0
	s_barrier
; #define PG8_STAGE(bufoff, gbase, voff) do { _Pragma("unroll") for (int _i = 0; _i < 2; ++_i) \
;         __builtin_amdgcn_global_load_lds((const unsigned*)((const char*)(gbase) + (voff)[_i]), (PG8_LAS unsigned*)(lds + (bufoff) + ldsw + _i * 8192), 16, 0, 0); } while (0)
; #define PG8_LDA(dst, b, h) do { _Pragma("unroll") for (int m = 0; m < 4; ++m) _Pragma("unroll") for (int k = 0; k < 2; ++k) dst[m][k] = *(const PG8_LAS bf16x8*)(lds + PG8_SA(b, h) + aoff + m * 2048 + k * 1024); } while (0)
; #define PG8_LDB(dst, b, h) do { _Pragma("unroll") for (int n = 0; n < 2; ++n) _Pragma("unroll") for (int k = 0; k < 2; ++k) dst[n][k] = *(const PG8_LAS bf16x8*)(lds + PG8_SB(b, h) + boff + n * 2048 + k * 1024); } while (0)
; #define PG8_MMA(ai, bj, At, Bt) do { __builtin_amdgcn_s_setprio(1); _Pragma("unroll") for (int m = 0; m < 4; ++m) _Pragma("unroll") for (int n = 0; n < 2; ++n) _Pragma("unroll") for (int k = 0; k < 2; ++k) \
;         acc[ai][bj][m][n] = __builtin_amdgcn_mfma_f32_16x16x32_bf16(Bt[n][k], At[m][k], acc[ai][bj][m][n], 0, 0, 0); __builtin_amdgcn_s_setprio(0); } while (0)
; #define PG8_WAIT_V(n) asm volatile("s_waitcnt vmcnt(" #n ")" ::: "memory")
; #define PG8_WAIT_L(n) asm volatile("s_waitcnt lgkmcnt(" #n ")" ::: "memory")
; #define PG8_BAR __builtin_amdgcn_s_barrier()
; #define PG8_SCHED __builtin_amdgcn_sched_barrier(0)
; template <class Epi, class Sched, bool ALIGN_EPI = false, bool SP2 = false>
; __device__ __forceinline__ void gemm_phase(PG8_LAS unsigned char* lds, const Gemm g, const Sched& S, const Epi& E, int wave_in) {
;     ...
;             PG8_LDB(B0, 1, 0); PG8_LDB(B1, 1, 1); PG8_SCHED; PG8_LDA(At, 1, 0); PG8_STAGE(PG8_SA(0, 1), a2 + hstep, voffA);
;             PG8_WAIT_V(8); PG8_WAIT_L(0); PG8_BAR; PG8_MMA(0, 0, At, B0); PG8_MMA(0, 1, At, B1); PG8_BAR; PG8_SCHED;
	s_add_i32 s29, s65, 0x100
	s_add_i32 s2, s52, 0x100
	v_add_u32_e32 v140, s29, v207
	v_add_u32_e32 v156, s2, v207
	ds_read_b128 v[128:131], v140
	ds_read_b128 v[132:135], v140 offset:1024
	ds_read_b128 v[136:139], v140 offset:2048
	ds_read_b128 v[140:143], v140 offset:3072
	ds_read_b128 v[144:147], v156
	ds_read_b128 v[148:151], v156 offset:1024
	ds_read_b128 v[152:155], v156 offset:2048
	ds_read_b128 v[156:159], v156 offset:3072
	s_add_u32 s76, s78, 0x40000
	s_addc_u32 s77, s79, 0
	s_mov_b32 m0, s63
	v_lshl_add_u64 v[226:227], s[76:77], 0, v[172:173]
	ds_read_b128 v[160:163], v219 offset:32768
	ds_read_b128 v[164:167], v219 offset:33792
	ds_read_b128 v[178:181], v219 offset:34816
	ds_read_b128 v[182:185], v219 offset:35840
	ds_read_b128 v[186:189], v219 offset:36864
	ds_read_b128 v[198:201], v219 offset:37888
	ds_read_b128 v[202:205], v219 offset:38912
	ds_read_b128 v[220:223], v219 offset:39936
	global_load_lds_dwordx4 v[226:227], off
	v_lshl_add_u64 v[226:227], s[76:77], 0, v[170:171]
	s_mov_b32 m0, s31
	s_nop 0
	global_load_lds_dwordx4 v[226:227], off
	s_waitcnt vmcnt(8)
	s_waitcnt lgkmcnt(0)
	s_barrier
	s_setprio 1
	s_waitcnt lgkmcnt(0)
	v_mfma_f32_16x16x32_bf16 v[124:127], v[128:131], v[160:163], v[124:127]
	v_mfma_f32_16x16x32_bf16 v[60:63], v[136:139], v[160:163], v[60:63]
	v_mfma_f32_16x16x32_bf16 v[52:55], v[136:139], v[178:181], v[52:55]
	v_mfma_f32_16x16x32_bf16 v[116:119], v[128:131], v[178:181], v[116:119]
	v_mfma_f32_16x16x32_bf16 v[108:111], v[128:131], v[186:189], v[108:111]
	v_mfma_f32_16x16x32_bf16 v[44:47], v[136:139], v[186:189], v[44:47]
	v_mfma_f32_16x16x32_bf16 v[36:39], v[136:139], v[202:205], v[36:39]
	v_mfma_f32_16x16x32_bf16 v[100:103], v[128:131], v[202:205], v[100:103]
	v_mfma_f32_16x16x32_bf16 v[124:127], v[132:135], v[164:167], v[124:127]
	v_mfma_f32_16x16x32_bf16 v[60:63], v[140:143], v[164:167], v[60:63]
	v_mfma_f32_16x16x32_bf16 v[52:55], v[140:143], v[182:185], v[52:55]
	v_mfma_f32_16x16x32_bf16 v[116:119], v[132:135], v[182:185], v[116:119]
	v_mfma_f32_16x16x32_bf16 v[108:111], v[132:135], v[198:201], v[108:111]
	v_mfma_f32_16x16x32_bf16 v[44:47], v[140:143], v[198:201], v[44:47]
	v_mfma_f32_16x16x32_bf16 v[36:39], v[140:143], v[220:223], v[36:39]
	v_mfma_f32_16x16x32_bf16 v[100:103], v[132:135], v[220:223], v[100:103]
	s_setprio 0
	s_setprio 1
	v_mfma_f32_16x16x32_bf16 v[120:123], v[144:147], v[160:163], v[120:123]
	v_mfma_f32_16x16x32_bf16 v[56:59], v[152:155], v[160:163], v[56:59]
	v_mfma_f32_16x16x32_bf16 v[48:51], v[152:155], v[178:181], v[48:51]
	v_mfma_f32_16x16x32_bf16 v[112:115], v[144:147], v[178:181], v[112:115]
	v_mfma_f32_16x16x32_bf16 v[104:107], v[144:147], v[186:189], v[104:107]
	v_mfma_f32_16x16x32_bf16 v[40:43], v[152:155], v[186:189], v[40:43]
	v_mfma_f32_16x16x32_bf16 v[32:35], v[152:155], v[202:205], v[32:35]
	v_mfma_f32_16x16x32_bf16 v[96:99], v[144:147], v[202:205], v[96:99]
	v_mfma_f32_16x16x32_bf16 v[120:123], v[148:151], v[164:167], v[120:123]
	v_mfma_f32_16x16x32_bf16 v[56:59], v[156:159], v[164:167], v[56:59]
	v_mfma_f32_16x16x32_bf16 v[48:51], v[156:159], v[182:185], v[48:51]
	v_mfma_f32_16x16x32_bf16 v[112:115], v[148:151], v[182:185], v[112:115]
	v_mfma_f32_16x16x32_bf16 v[104:107], v[148:151], v[198:201], v[104:107]
	v_mfma_f32_16x16x32_bf16 v[40:43], v[156:159], v[198:201], v[40:43]
	v_mfma_f32_16x16x32_bf16 v[32:35], v[156:159], v[220:223], v[32:35]
	v_mfma_f32_16x16x32_bf16 v[96:99], v[148:151], v[220:223], v[96:99]
	s_setprio 0
	s_barrier
; #define PG8_STAGE(bufoff, gbase, voff) do { _Pragma("unroll") for (int _i = 0; _i < 2; ++_i) \
;         __builtin_amdgcn_global_load_lds((const unsigned*)((const char*)(gbase) + (voff)[_i]), (PG8_LAS unsigned*)(lds + (bufoff) + ldsw + _i * 8192), 16, 0, 0); } while (0)
; #define PG8_LDA(dst, b, h) do { _Pragma("unroll") for (int m = 0; m < 4; ++m) _Pragma("unroll") for (int k = 0; k < 2; ++k) dst[m][k] = *(const PG8_LAS bf16x8*)(lds + PG8_SA(b, h) + aoff + m * 2048 + k * 1024); } while (0)
; #define PG8_MMA(ai, bj, At, Bt) do { __builtin_amdgcn_s_setprio(1); _Pragma("unroll") for (int m = 0; m < 4; ++m) _Pragma("unroll") for (int n = 0; n < 2; ++n) _Pragma("unroll") for (int k = 0; k < 2; ++k) \
;         acc[ai][bj][m][n] = __builtin_amdgcn_mfma_f32_16x16x32_bf16(Bt[n][k], At[m][k], acc[ai][bj][m][n], 0, 0, 0); __builtin_amdgcn_s_setprio(0); } while (0)
; #define PG8_WAIT_V(n) asm volatile("s_waitcnt vmcnt(" #n ")" ::: "memory")
; #define PG8_WAIT_L(n) asm volatile("s_waitcnt lgkmcnt(" #n ")" ::: "memory")
; #define PG8_BAR __builtin_amdgcn_s_barrier()
; #define PG8_SCHED __builtin_amdgcn_sched_barrier(0)
; template <class Epi, class Sched, bool ALIGN_EPI = false, bool SP2 = false>
; __device__ __forceinline__ void gemm_phase(PG8_LAS unsigned char* lds, const Gemm g, const Sched& S, const Epi& E, int wave_in) {
;     ...
;             PG8_LDA(At, 1, 1); PG8_STAGE(PG8_SB(1, 0), b3, voffB); PG8_STAGE(PG8_SB(1, 1), b3 + hstep, voffB); PG8_STAGE(PG8_SA(1, 0), a3, voffA);
;             PG8_WAIT_V(8); PG8_WAIT_L(0); PG8_BAR; PG8_MMA(1, 0, At, B0); PG8_MMA(1, 1, At, B1); PG8_BAR; PG8_SCHED;
	s_add_i32 s29, s29, s75
	v_lshl_add_u64 v[190:191], v[190:191], 0, s[88:89]
	s_mov_b32 m0, s29
	ds_read_b128 v[160:163], v219 offset:49152
	ds_read_b128 v[164:167], v219 offset:50176
	ds_read_b128 v[178:181], v219 offset:51200
	ds_read_b128 v[182:185], v219 offset:52224
	ds_read_b128 v[186:189], v219 offset:53248
	ds_read_b128 v[198:201], v219 offset:54272
	ds_read_b128 v[202:205], v219 offset:55296
	ds_read_b128 v[220:223], v219 offset:56320
	global_load_lds_dwordx4 v[190:191], off
	s_add_i32 m0, s29, 0x2000
	s_add_u32 s0, s0, 0x40080
	v_lshl_add_u64 v[190:191], v[194:195], 0, s[88:89]
	s_addc_u32 s1, s1, 0
	s_add_i32 s2, s2, s75
	global_load_lds_dwordx4 v[190:191], off
	v_lshl_add_u64 v[190:191], s[0:1], 0, v[192:193]
	s_mov_b32 m0, s2
	s_nop 0
	global_load_lds_dwordx4 v[190:191], off
	v_lshl_add_u64 v[190:191], s[0:1], 0, v[168:169]
	s_add_i32 m0, s2, 0x2000
	s_nop 0
	global_load_lds_dwordx4 v[190:191], off
	v_lshl_add_u64 v[190:191], v[196:197], 0, s[88:89]
	s_mov_b32 m0, s9
	s_nop 0
	global_load_lds_dwordx4 v[190:191], off
	v_lshl_add_u64 v[190:191], v[224:225], 0, s[88:89]
	s_mov_b32 m0, s96
	s_nop 0
	global_load_lds_dwordx4 v[190:191], off
	s_waitcnt vmcnt(8)
	s_waitcnt lgkmcnt(0)
	s_barrier
	s_setprio 1
	s_waitcnt lgkmcnt(0)
	v_mfma_f32_16x16x32_bf16 v[92:95], v[128:131], v[160:163], v[92:95]
	v_mfma_f32_16x16x32_bf16 v[28:31], v[136:139], v[160:163], v[28:31]
	v_mfma_f32_16x16x32_bf16 v[20:23], v[136:139], v[178:181], v[20:23]
	v_mfma_f32_16x16x32_bf16 v[84:87], v[128:131], v[178:181], v[84:87]
	v_mfma_f32_16x16x32_bf16 v[76:79], v[128:131], v[186:189], v[76:79]
	v_mfma_f32_16x16x32_bf16 v[12:15], v[136:139], v[186:189], v[12:15]
	v_mfma_f32_16x16x32_bf16 v[4:7], v[136:139], v[202:205], v[4:7]
	v_mfma_f32_16x16x32_bf16 v[68:71], v[128:131], v[202:205], v[68:71]
	v_mfma_f32_16x16x32_bf16 v[92:95], v[132:135], v[164:167], v[92:95]
	v_mfma_f32_16x16x32_bf16 v[28:31], v[140:143], v[164:167], v[28:31]
	v_mfma_f32_16x16x32_bf16 v[20:23], v[140:143], v[182:185], v[20:23]
	v_mfma_f32_16x16x32_bf16 v[84:87], v[132:135], v[182:185], v[84:87]
	v_mfma_f32_16x16x32_bf16 v[76:79], v[132:135], v[198:201], v[76:79]
	v_mfma_f32_16x16x32_bf16 v[12:15], v[140:143], v[198:201], v[12:15]
	v_mfma_f32_16x16x32_bf16 v[4:7], v[140:143], v[220:223], v[4:7]
	v_mfma_f32_16x16x32_bf16 v[68:71], v[132:135], v[220:223], v[68:71]
	s_setprio 0
	s_setprio 1
	v_mfma_f32_16x16x32_bf16 v[88:91], v[144:147], v[160:163], v[88:91]
	v_mfma_f32_16x16x32_bf16 v[24:27], v[152:155], v[160:163], v[24:27]
	v_mfma_f32_16x16x32_bf16 v[16:19], v[152:155], v[178:181], v[16:19]
	v_mfma_f32_16x16x32_bf16 v[80:83], v[144:147], v[178:181], v[80:83]
	v_mfma_f32_16x16x32_bf16 v[72:75], v[144:147], v[186:189], v[72:75]
	v_mfma_f32_16x16x32_bf16 v[8:11], v[152:155], v[186:189], v[8:11]
	v_mfma_f32_16x16x32_bf16 v[0:3], v[152:155], v[202:205], v[0:3]
	v_mfma_f32_16x16x32_bf16 v[64:67], v[144:147], v[202:205], v[64:67]
	v_mfma_f32_16x16x32_bf16 v[88:91], v[148:151], v[164:167], v[88:91]
	v_mfma_f32_16x16x32_bf16 v[24:27], v[156:159], v[164:167], v[24:27]
	v_mfma_f32_16x16x32_bf16 v[16:19], v[156:159], v[182:185], v[16:19]
	v_mfma_f32_16x16x32_bf16 v[80:83], v[148:151], v[182:185], v[80:83]
	v_mfma_f32_16x16x32_bf16 v[72:75], v[148:151], v[198:201], v[72:75]
	v_mfma_f32_16x16x32_bf16 v[8:11], v[156:159], v[198:201], v[8:11]
	v_mfma_f32_16x16x32_bf16 v[0:3], v[156:159], v[220:223], v[0:3]
	v_mfma_f32_16x16x32_bf16 v[64:67], v[148:151], v[220:223], v[64:67]
	s_setprio 0
	s_barrier
	s_add_i32 s19, s19, 2
	s_add_u32 s81, s81, 0x100
	s_addc_u32 s18, s18, 0
	s_add_u32 vcc_lo, vcc_lo, 0x100
	s_addc_u32 vcc_hi, vcc_hi, 0
	s_cmp_gt_u32 s19, 13
	s_cbranch_scc0 .LBB0_897

; #define PG8_STAGE(bufoff, gbase, voff) do { _Pragma("unroll") for (int _i = 0; _i < 2; ++_i) \
;         __builtin_amdgcn_global_load_lds((const unsigned*)((const char*)(gbase) + (voff)[_i]), (PG8_LAS unsigned*)(lds + (bufoff) + ldsw + _i * 8192), 16, 0, 0); } while (0)
; #define PG8_LDA(dst, b, h) do { _Pragma("unroll") for (int m = 0; m < 4; ++m) _Pragma("unroll") for (int k = 0; k < 2; ++k) dst[m][k] = *(const PG8_LAS bf16x8*)(lds + PG8_SA(b, h) + aoff + m * 2048 + k * 1024); } while (0)
; #define PG8_LDB(dst, b, h) do { _Pragma("unroll") for (int n = 0; n < 2; ++n) _Pragma("unroll") for (int k = 0; k < 2; ++k) dst[n][k] = *(const PG8_LAS bf16x8*)(lds + PG8_SB(b, h) + boff + n * 2048 + k * 1024); } while (0)
; #define PG8_WAIT_V(n) asm volatile("s_waitcnt vmcnt(" #n ")" ::: "memory")
; #define PG8_WAIT_L(n) asm volatile("s_waitcnt lgkmcnt(" #n ")" ::: "memory")
; #define PG8_BAR __builtin_amdgcn_s_barrier()
; #define PG8_SCHED __builtin_amdgcn_sched_barrier(0)
; template <class Epi, class Sched, bool ALIGN_EPI = false, bool SP2 = false>
; __device__ __forceinline__ void gemm_phase(PG8_LAS unsigned char* lds, const Gemm g, const Sched& S, const Epi& E, int wave_in) {
;     ...
;         const bool has_next = S.next(ui + 1, nxt);
;         const char* nA = has_next ? (const char*)g.A + (size_t)(nxt.pm >> g.ash) * g.astride + (size_t)nxt.pm * tstep : cA; const char* nB = has_next ? (const char*)g.Bt + (size_t)(nxt.pm >> g.bsh) * g.bstride + (size_t)nxt.pn * tstep : cB;
;         for (int t = 0; t < nt; t += 2) {
;             const bool last = (t == nt - 2);
;             const char* a1 = cA + (size_t)(t + 1) * kstep;
;             const char* a2 = last ? nA : cA + (size_t)(t + 2) * kstep; const char* b2 = last ? nB : cB + (size_t)(t + 2) * kstep;
;             const char* a3 = a2 + kstep; const char* b3 = b2 + kstep;
;             if (last && has_next) S.a_ready(nxt);
;             if constexpr (SP2) {
;             PG8_LDB(B0, 0, 0); PG8_LDB(B1, 0, 1); PG8_SCHED; PG8_LDA(At, 0, 0); PG8_STAGE(PG8_SA(1, 1), a1 + hstep, voffA);
;             PG8_WAIT_V(8); PG8_WAIT_L(0); PG8_BAR; PG8_MMA(0, 0, At, B0); PG8_MMA(0, 1, At, B1); PG8_BAR; PG8_SCHED;
;             PG8_LDA(At, 0, 1); PG8_STAGE(PG8_SB(0, 0), b2, voffB); PG8_STAGE(PG8_SB(0, 1), b2 + hstep, voffB); PG8_STAGE(PG8_SA(0, 0), a2, voffA);
.LBB0_1030:
	s_add_u32 s34, s20, 0x100
	s_addc_u32 s42, s21, 0
	s_mov_b32 s43, -2
	s_add_u32 s20, s16, 0x100
	s_addc_u32 s21, s17, 0
	s_add_i32 s2, s35, 0x100
	s_cmp_eq_u32 s43, 40
	s_cselect_b32 s25, s13, s21
	s_cselect_b32 s24, s12, s20
	s_cselect_b32 s23, s15, s42
	s_cselect_b32 s22, s14, s34
	s_add_i32 s29, s90, 0x100
	v_add_u32_e32 v128, s2, v249
	v_add_u32_e32 v156, s29, v249
	ds_read_b128 v[112:115], v128
	ds_read_b128 v[120:123], v128 offset:1024
	ds_read_b128 v[124:127], v128 offset:2048
	ds_read_b128 v[128:131], v128 offset:3072
	ds_read_b128 v[136:139], v156
	ds_read_b128 v[140:143], v156 offset:1024
	ds_read_b128 v[144:147], v156 offset:2048
	ds_read_b128 v[156:159], v156 offset:3072
	v_lshl_add_u64 v[194:195], s[16:17], 0, v[206:207]
	s_add_i32 m0, s45, 0xc000
	ds_read_b128 v[160:163], v251
	ds_read_b128 v[164:167], v251 offset:1024
	ds_read_b128 v[168:171], v251 offset:2048
	ds_read_b128 v[172:175], v251 offset:3072
	ds_read_b128 v[176:179], v251 offset:4096
	ds_read_b128 v[180:183], v251 offset:5120
	ds_read_b128 v[184:187], v251 offset:6144
	ds_read_b128 v[188:191], v251 offset:7168
	global_load_lds_dwordx4 v[194:195], off
	v_lshl_add_u64 v[194:195], s[16:17], 0, v[204:205]
	s_add_i32 m0, s45, 0xe000
	s_nop 0
	global_load_lds_dwordx4 v[194:195], off
	s_waitcnt vmcnt(8)
	s_waitcnt lgkmcnt(0)
	s_barrier
	s_setprio 1
	s_waitcnt lgkmcnt(0)
	v_mfma_f32_16x16x32_bf16 v[152:155], v[112:115], v[160:163], 0
	v_mfma_f32_16x16x32_bf16 v[148:151], v[124:127], v[160:163], 0
	v_mfma_f32_16x16x32_bf16 v[104:107], v[124:127], v[168:171], 0
	v_mfma_f32_16x16x32_bf16 v[108:111], v[112:115], v[168:171], 0
	v_mfma_f32_16x16x32_bf16 v[92:95], v[112:115], v[176:179], 0
	v_mfma_f32_16x16x32_bf16 v[88:91], v[124:127], v[176:179], 0
	v_mfma_f32_16x16x32_bf16 v[72:75], v[124:127], v[184:187], 0
	v_mfma_f32_16x16x32_bf16 v[76:79], v[112:115], v[184:187], 0
	v_mfma_f32_16x16x32_bf16 v[152:155], v[120:123], v[164:167], v[152:155]
	v_mfma_f32_16x16x32_bf16 v[148:151], v[128:131], v[164:167], v[148:151]
	v_mfma_f32_16x16x32_bf16 v[104:107], v[128:131], v[172:175], v[104:107]
	v_mfma_f32_16x16x32_bf16 v[108:111], v[120:123], v[172:175], v[108:111]
	v_mfma_f32_16x16x32_bf16 v[92:95], v[120:123], v[180:183], v[92:95]
	v_mfma_f32_16x16x32_bf16 v[88:91], v[128:131], v[180:183], v[88:91]
	v_mfma_f32_16x16x32_bf16 v[72:75], v[128:131], v[188:191], v[72:75]
	v_mfma_f32_16x16x32_bf16 v[76:79], v[120:123], v[188:191], v[76:79]
	s_setprio 0
	s_setprio 1
	v_mfma_f32_16x16x32_bf16 v[132:135], v[136:139], v[160:163], 0
	v_mfma_f32_16x16x32_bf16 v[116:119], v[144:147], v[160:163], 0
	v_mfma_f32_16x16x32_bf16 v[96:99], v[144:147], v[168:171], 0
	v_mfma_f32_16x16x32_bf16 v[100:103], v[136:139], v[168:171], 0
	v_mfma_f32_16x16x32_bf16 v[84:87], v[136:139], v[176:179], 0
	v_mfma_f32_16x16x32_bf16 v[80:83], v[144:147], v[176:179], 0
	v_mfma_f32_16x16x32_bf16 v[64:67], v[144:147], v[184:187], 0
	v_mfma_f32_16x16x32_bf16 v[68:71], v[136:139], v[184:187], 0
	v_mfma_f32_16x16x32_bf16 v[132:135], v[140:143], v[164:167], v[132:135]
	v_mfma_f32_16x16x32_bf16 v[116:119], v[156:159], v[164:167], v[116:119]
	v_mfma_f32_16x16x32_bf16 v[96:99], v[156:159], v[172:175], v[96:99]
	v_mfma_f32_16x16x32_bf16 v[100:103], v[140:143], v[172:175], v[100:103]
	v_mfma_f32_16x16x32_bf16 v[84:87], v[140:143], v[180:183], v[84:87]
	v_mfma_f32_16x16x32_bf16 v[80:83], v[156:159], v[180:183], v[80:83]
	v_mfma_f32_16x16x32_bf16 v[64:67], v[156:159], v[188:191], v[64:67]
	v_mfma_f32_16x16x32_bf16 v[68:71], v[140:143], v[188:191], v[68:71]
	s_setprio 0
	s_barrier
	s_add_i32 s2, s2, s44
	v_lshl_add_u64 v[194:195], s[22:23], 0, v[192:193]
	s_mov_b32 m0, s2
	ds_read_b128 v[160:163], v251 offset:16384
	ds_read_b128 v[164:167], v251 offset:17408
	ds_read_b128 v[168:171], v251 offset:18432
	ds_read_b128 v[172:175], v251 offset:19456
	ds_read_b128 v[176:179], v251 offset:20480
	ds_read_b128 v[180:183], v251 offset:21504
	ds_read_b128 v[184:187], v251 offset:22528
	ds_read_b128 v[188:191], v251 offset:23552
	global_load_lds_dwordx4 v[194:195], off
	s_add_i32 m0, s2, 0x2000
	s_add_u32 s16, s22, 0xb0000
	v_lshl_add_u64 v[196:197], s[22:23], 0, v[198:199]
	s_addc_u32 s17, s23, 0
	s_add_i32 s2, s29, s44
	global_load_lds_dwordx4 v[196:197], off
	v_lshl_add_u64 v[208:209], s[16:17], 0, v[192:193]
	s_mov_b32 m0, s2
	v_lshl_add_u64 v[210:211], s[24:25], 0, v[200:201]
	global_load_lds_dwordx4 v[208:209], off
	v_lshl_add_u64 v[208:209], s[16:17], 0, v[198:199]
	s_add_i32 m0, s2, 0x2000
	s_nop 0
	global_load_lds_dwordx4 v[208:209], off
	v_lshl_add_u64 v[208:209], s[24:25], 0, v[202:203]
	s_mov_b32 m0, s45
	s_nop 0
	global_load_lds_dwordx4 v[208:209], off
	s_mov_b32 m0, s46
	s_nop 0
	global_load_lds_dwordx4 v[210:211], off
	s_waitcnt vmcnt(8)
	s_waitcnt lgkmcnt(0)
	s_barrier
; #define PG8_STAGE(bufoff, gbase, voff) do { _Pragma("unroll") for (int _i = 0; _i < 2; ++_i) \
;         __builtin_amdgcn_global_load_lds((const unsigned*)((const char*)(gbase) + (voff)[_i]), (PG8_LAS unsigned*)(lds + (bufoff) + ldsw + _i * 8192), 16, 0, 0); } while (0)
; #define PG8_LDA(dst, b, h) do { _Pragma("unroll") for (int m = 0; m < 4; ++m) _Pragma("unroll") for (int k = 0; k < 2; ++k) dst[m][k] = *(const PG8_LAS bf16x8*)(lds + PG8_SA(b, h) + aoff + m * 2048 + k * 1024); } while (0)
; #define PG8_LDB(dst, b, h) do { _Pragma("unroll") for (int n = 0; n < 2; ++n) _Pragma("unroll") for (int k = 0; k < 2; ++k) dst[n][k] = *(const PG8_LAS bf16x8*)(lds + PG8_SB(b, h) + boff + n * 2048 + k * 1024); } while (0)
; #define PG8_MMA(ai, bj, At, Bt) do { __builtin_amdgcn_s_setprio(1); _Pragma("unroll") for (int m = 0; m < 4; ++m) _Pragma("unroll") for (int n = 0; n < 2; ++n) _Pragma("unroll") for (int k = 0; k < 2; ++k) \
;         acc[ai][bj][m][n] = __builtin_amdgcn_mfma_f32_16x16x32_bf16(Bt[n][k], At[m][k], acc[ai][bj][m][n], 0, 0, 0); __builtin_amdgcn_s_setprio(0); } while (0)
; #define PG8_WAIT_V(n) asm volatile("s_waitcnt vmcnt(" #n ")" ::: "memory")
; #define PG8_WAIT_L(n) asm volatile("s_waitcnt lgkmcnt(" #n ")" ::: "memory")
; #define PG8_BAR __builtin_amdgcn_s_barrier()
; #define PG8_SCHED __builtin_amdgcn_sched_barrier(0)
; template <class Epi, class Sched, bool ALIGN_EPI = false, bool SP2 = false>
; __device__ __forceinline__ void gemm_phase(PG8_LAS unsigned char* lds, const Gemm g, const Sched& S, const Epi& E, int wave_in) {
;     ...
;             PG8_WAIT_V(8); PG8_WAIT_L(0); PG8_BAR; PG8_MMA(1, 0, At, B0); PG8_MMA(1, 1, At, B1); PG8_BAR; PG8_SCHED;
;             PG8_LDB(B0, 1, 0); PG8_LDB(B1, 1, 1); PG8_SCHED; PG8_LDA(At, 1, 0); PG8_STAGE(PG8_SA(0, 1), a2 + hstep, voffA);
;             PG8_WAIT_V(8); PG8_WAIT_L(0); PG8_BAR; PG8_MMA(0, 0, At, B0); PG8_MMA(0, 1, At, B1); PG8_BAR; PG8_SCHED;
	s_setprio 1
	s_waitcnt lgkmcnt(0)
	v_mfma_f32_16x16x32_bf16 v[60:63], v[112:115], v[160:163], 0
	v_mfma_f32_16x16x32_bf16 v[56:59], v[124:127], v[160:163], 0
	v_mfma_f32_16x16x32_bf16 v[40:43], v[124:127], v[168:171], 0
	v_mfma_f32_16x16x32_bf16 v[44:47], v[112:115], v[168:171], 0
	v_mfma_f32_16x16x32_bf16 v[28:31], v[112:115], v[176:179], 0
	v_mfma_f32_16x16x32_bf16 v[24:27], v[124:127], v[176:179], 0
	v_mfma_f32_16x16x32_bf16 v[8:11], v[124:127], v[184:187], 0
	v_mfma_f32_16x16x32_bf16 v[12:15], v[112:115], v[184:187], 0
	v_mfma_f32_16x16x32_bf16 v[60:63], v[120:123], v[164:167], v[60:63]
	v_mfma_f32_16x16x32_bf16 v[56:59], v[128:131], v[164:167], v[56:59]
	v_mfma_f32_16x16x32_bf16 v[40:43], v[128:131], v[172:175], v[40:43]
	v_mfma_f32_16x16x32_bf16 v[44:47], v[120:123], v[172:175], v[44:47]
	v_mfma_f32_16x16x32_bf16 v[28:31], v[120:123], v[180:183], v[28:31]
	v_mfma_f32_16x16x32_bf16 v[24:27], v[128:131], v[180:183], v[24:27]
	v_mfma_f32_16x16x32_bf16 v[8:11], v[128:131], v[188:191], v[8:11]
	v_mfma_f32_16x16x32_bf16 v[12:15], v[120:123], v[188:191], v[12:15]
	s_setprio 0
	s_setprio 1
	v_mfma_f32_16x16x32_bf16 v[52:55], v[136:139], v[160:163], 0
	v_mfma_f32_16x16x32_bf16 v[48:51], v[144:147], v[160:163], 0
	v_mfma_f32_16x16x32_bf16 v[32:35], v[144:147], v[168:171], 0
	v_mfma_f32_16x16x32_bf16 v[36:39], v[136:139], v[168:171], 0
	v_mfma_f32_16x16x32_bf16 v[20:23], v[136:139], v[176:179], 0
	v_mfma_f32_16x16x32_bf16 v[16:19], v[144:147], v[176:179], 0
	v_mfma_f32_16x16x32_bf16 v[0:3], v[144:147], v[184:187], 0
	v_mfma_f32_16x16x32_bf16 v[4:7], v[136:139], v[184:187], 0
	v_mfma_f32_16x16x32_bf16 v[52:55], v[140:143], v[164:167], v[52:55]
	v_mfma_f32_16x16x32_bf16 v[48:51], v[156:159], v[164:167], v[48:51]
	v_mfma_f32_16x16x32_bf16 v[32:35], v[156:159], v[172:175], v[32:35]
	v_mfma_f32_16x16x32_bf16 v[36:39], v[140:143], v[172:175], v[36:39]
	v_mfma_f32_16x16x32_bf16 v[20:23], v[140:143], v[180:183], v[20:23]
	v_mfma_f32_16x16x32_bf16 v[16:19], v[156:159], v[180:183], v[16:19]
	v_mfma_f32_16x16x32_bf16 v[0:3], v[156:159], v[188:191], v[0:3]
	v_mfma_f32_16x16x32_bf16 v[4:7], v[140:143], v[188:191], v[4:7]
	s_setprio 0
	s_barrier
	s_add_i32 s2, s65, 0x100
	s_add_i32 s29, s52, 0x100
	v_add_u32_e32 v128, s2, v249
	v_add_u32_e32 v156, s29, v249
	ds_read_b128 v[112:115], v128
	ds_read_b128 v[120:123], v128 offset:1024
	ds_read_b128 v[124:127], v128 offset:2048
	ds_read_b128 v[128:131], v128 offset:3072
	ds_read_b128 v[136:139], v156
	ds_read_b128 v[140:143], v156 offset:1024
	ds_read_b128 v[144:147], v156 offset:2048
	ds_read_b128 v[156:159], v156 offset:3072
	s_add_u32 s16, s24, 0xb0000
	s_addc_u32 s17, s25, 0
	s_mov_b32 m0, s47
	v_lshl_add_u64 v[212:213], s[16:17], 0, v[202:203]
	ds_read_b128 v[160:163], v251 offset:32768
	ds_read_b128 v[164:167], v251 offset:33792
	ds_read_b128 v[168:171], v251 offset:34816
	ds_read_b128 v[172:175], v251 offset:35840
	ds_read_b128 v[176:179], v251 offset:36864
	ds_read_b128 v[180:183], v251 offset:37888
	ds_read_b128 v[184:187], v251 offset:38912
	ds_read_b128 v[188:191], v251 offset:39936
	global_load_lds_dwordx4 v[212:213], off
	v_lshl_add_u64 v[212:213], s[16:17], 0, v[200:201]
	s_mov_b32 m0, s60
	s_nop 0
	global_load_lds_dwordx4 v[212:213], off
	s_waitcnt vmcnt(8)
	s_waitcnt lgkmcnt(0)
	s_barrier
	s_setprio 1
	s_waitcnt lgkmcnt(0)
	v_mfma_f32_16x16x32_bf16 v[152:155], v[112:115], v[160:163], v[152:155]
	v_mfma_f32_16x16x32_bf16 v[148:151], v[124:127], v[160:163], v[148:151]
	v_mfma_f32_16x16x32_bf16 v[104:107], v[124:127], v[168:171], v[104:107]
	v_mfma_f32_16x16x32_bf16 v[108:111], v[112:115], v[168:171], v[108:111]
	v_mfma_f32_16x16x32_bf16 v[92:95], v[112:115], v[176:179], v[92:95]
	v_mfma_f32_16x16x32_bf16 v[88:91], v[124:127], v[176:179], v[88:91]
	v_mfma_f32_16x16x32_bf16 v[72:75], v[124:127], v[184:187], v[72:75]
	v_mfma_f32_16x16x32_bf16 v[76:79], v[112:115], v[184:187], v[76:79]
	v_mfma_f32_16x16x32_bf16 v[152:155], v[120:123], v[164:167], v[152:155]
	v_mfma_f32_16x16x32_bf16 v[148:151], v[128:131], v[164:167], v[148:151]
	v_mfma_f32_16x16x32_bf16 v[104:107], v[128:131], v[172:175], v[104:107]
	v_mfma_f32_16x16x32_bf16 v[108:111], v[120:123], v[172:175], v[108:111]
	v_mfma_f32_16x16x32_bf16 v[92:95], v[120:123], v[180:183], v[92:95]
	v_mfma_f32_16x16x32_bf16 v[88:91], v[128:131], v[180:183], v[88:91]
	v_mfma_f32_16x16x32_bf16 v[72:75], v[128:131], v[188:191], v[72:75]
	v_mfma_f32_16x16x32_bf16 v[76:79], v[120:123], v[188:191], v[76:79]
	s_setprio 0
	s_setprio 1
	v_mfma_f32_16x16x32_bf16 v[132:135], v[136:139], v[160:163], v[132:135]
	v_mfma_f32_16x16x32_bf16 v[116:119], v[144:147], v[160:163], v[116:119]
	v_mfma_f32_16x16x32_bf16 v[96:99], v[144:147], v[168:171], v[96:99]
	v_mfma_f32_16x16x32_bf16 v[100:103], v[136:139], v[168:171], v[100:103]
	v_mfma_f32_16x16x32_bf16 v[84:87], v[136:139], v[176:179], v[84:87]
	v_mfma_f32_16x16x32_bf16 v[80:83], v[144:147], v[176:179], v[80:83]
	v_mfma_f32_16x16x32_bf16 v[64:67], v[144:147], v[184:187], v[64:67]
	v_mfma_f32_16x16x32_bf16 v[68:71], v[136:139], v[184:187], v[68:71]
	v_mfma_f32_16x16x32_bf16 v[132:135], v[140:143], v[164:167], v[132:135]
	v_mfma_f32_16x16x32_bf16 v[116:119], v[156:159], v[164:167], v[116:119]
	v_mfma_f32_16x16x32_bf16 v[96:99], v[156:159], v[172:175], v[96:99]
	v_mfma_f32_16x16x32_bf16 v[100:103], v[140:143], v[172:175], v[100:103]
	v_mfma_f32_16x16x32_bf16 v[84:87], v[140:143], v[180:183], v[84:87]
	v_mfma_f32_16x16x32_bf16 v[80:83], v[156:159], v[180:183], v[80:83]
	v_mfma_f32_16x16x32_bf16 v[64:67], v[156:159], v[188:191], v[64:67]
	v_mfma_f32_16x16x32_bf16 v[68:71], v[140:143], v[188:191], v[68:71]
	s_setprio 0
	s_barrier
; #define PG8_STAGE(bufoff, gbase, voff) do { _Pragma("unroll") for (int _i = 0; _i < 2; ++_i) \
;         __builtin_amdgcn_global_load_lds((const unsigned*)((const char*)(gbase) + (voff)[_i]), (PG8_LAS unsigned*)(lds + (bufoff) + ldsw + _i * 8192), 16, 0, 0); } while (0)
; #define PG8_LDA(dst, b, h) do { _Pragma("unroll") for (int m = 0; m < 4; ++m) _Pragma("unroll") for (int k = 0; k < 2; ++k) dst[m][k] = *(const PG8_LAS bf16x8*)(lds + PG8_SA(b, h) + aoff + m * 2048 + k * 1024); } while (0)
; #define PG8_WAIT_V(n) asm volatile("s_waitcnt vmcnt(" #n ")" ::: "memory")
; #define PG8_WAIT_L(n) asm volatile("s_waitcnt lgkmcnt(" #n ")" ::: "memory")
; #define PG8_BAR __builtin_amdgcn_s_barrier()
; template <class Epi, class Sched, bool ALIGN_EPI = false, bool SP2 = false>
; __device__ __forceinline__ void gemm_phase(PG8_LAS unsigned char* lds, const Gemm g, const Sched& S, const Epi& E, int wave_in) {
;     ...
;         for (int t = 0; t < nt; t += 2) {
;             const bool last = (t == nt - 2);
;             const char* a1 = cA + (size_t)(t + 1) * kstep;
;             const char* a2 = last ? nA : cA + (size_t)(t + 2) * kstep; const char* b2 = last ? nB : cB + (size_t)(t + 2) * kstep;
;             const char* a3 = a2 + kstep; const char* b3 = b2 + kstep;
;             if (last && has_next) S.a_ready(nxt);
;             if constexpr (SP2) {
;             PG8_LDB(B0, 0, 0); PG8_LDB(B1, 0, 1); PG8_SCHED; PG8_LDA(At, 0, 0); PG8_STAGE(PG8_SA(1, 1), a1 + hstep, voffA);
;             PG8_WAIT_V(8); PG8_WAIT_L(0); PG8_BAR; PG8_MMA(0, 0, At, B0); PG8_MMA(0, 1, At, B1); PG8_BAR; PG8_SCHED;
;             PG8_LDA(At, 0, 1); PG8_STAGE(PG8_SB(0, 0), b2, voffB); PG8_STAGE(PG8_SB(0, 1), b2 + hstep, voffB); PG8_STAGE(PG8_SA(0, 0), a2, voffA);
;             PG8_WAIT_V(8); PG8_WAIT_L(0); PG8_BAR; PG8_MMA(1, 0, At, B0); PG8_MMA(1, 1, At, B1); PG8_BAR; PG8_SCHED;
;             PG8_LDB(B0, 1, 0); PG8_LDB(B1, 1, 1); PG8_SCHED; PG8_LDA(At, 1, 0); PG8_STAGE(PG8_SA(0, 1), a2 + hstep, voffA);
;             PG8_WAIT_V(8); PG8_WAIT_L(0); PG8_BAR; PG8_MMA(0, 0, At, B0); PG8_MMA(0, 1, At, B1); PG8_BAR; PG8_SCHED;
;             PG8_LDA(At, 1, 1); PG8_STAGE(PG8_SB(1, 0), b3, voffB); PG8_STAGE(PG8_SB(1, 1), b3 + hstep, voffB); PG8_STAGE(PG8_SA(1, 0), a3, voffA);
;             PG8_WAIT_V(8); PG8_WAIT_L(0); PG8_BAR; PG8_MMA(1, 0, At, B0); PG8_MMA(1, 1, At, B1); PG8_BAR; PG8_SCHED;
	s_add_i32 s2, s2, s44
	v_lshl_add_u64 v[194:195], v[194:195], 0, s[88:89]
	s_mov_b32 m0, s2
	ds_read_b128 v[160:163], v251 offset:49152
	ds_read_b128 v[164:167], v251 offset:50176
	ds_read_b128 v[168:171], v251 offset:51200
	ds_read_b128 v[172:175], v251 offset:52224
	ds_read_b128 v[176:179], v251 offset:53248
	ds_read_b128 v[180:183], v251 offset:54272
	ds_read_b128 v[184:187], v251 offset:55296
	ds_read_b128 v[188:191], v251 offset:56320
	global_load_lds_dwordx4 v[194:195], off
	s_add_i32 m0, s2, 0x2000
	s_add_u32 s16, s22, 0xb0080
	v_lshl_add_u64 v[194:195], v[196:197], 0, s[88:89]
	s_addc_u32 s17, s23, 0
	s_add_i32 s2, s29, s44
	global_load_lds_dwordx4 v[194:195], off
	v_lshl_add_u64 v[194:195], s[16:17], 0, v[192:193]
	s_mov_b32 m0, s2
	s_nop 0
	global_load_lds_dwordx4 v[194:195], off
	v_lshl_add_u64 v[194:195], s[16:17], 0, v[198:199]
	s_add_i32 m0, s2, 0x2000
	s_nop 0
	global_load_lds_dwordx4 v[194:195], off
	v_lshl_add_u64 v[194:195], v[208:209], 0, s[88:89]
	s_mov_b32 m0, s62
	s_nop 0
	global_load_lds_dwordx4 v[194:195], off
	v_lshl_add_u64 v[194:195], v[210:211], 0, s[88:89]
	s_mov_b32 m0, s63
	s_nop 0
	global_load_lds_dwordx4 v[194:195], off
	s_waitcnt vmcnt(8)
	s_waitcnt lgkmcnt(0)
	s_barrier
	s_setprio 1
	s_waitcnt lgkmcnt(0)
	v_mfma_f32_16x16x32_bf16 v[60:63], v[112:115], v[160:163], v[60:63]
	v_mfma_f32_16x16x32_bf16 v[56:59], v[124:127], v[160:163], v[56:59]
	v_mfma_f32_16x16x32_bf16 v[40:43], v[124:127], v[168:171], v[40:43]
	v_mfma_f32_16x16x32_bf16 v[44:47], v[112:115], v[168:171], v[44:47]
	v_mfma_f32_16x16x32_bf16 v[28:31], v[112:115], v[176:179], v[28:31]
	v_mfma_f32_16x16x32_bf16 v[24:27], v[124:127], v[176:179], v[24:27]
	v_mfma_f32_16x16x32_bf16 v[8:11], v[124:127], v[184:187], v[8:11]
	v_mfma_f32_16x16x32_bf16 v[12:15], v[112:115], v[184:187], v[12:15]
	v_mfma_f32_16x16x32_bf16 v[60:63], v[120:123], v[164:167], v[60:63]
	v_mfma_f32_16x16x32_bf16 v[56:59], v[128:131], v[164:167], v[56:59]
	v_mfma_f32_16x16x32_bf16 v[40:43], v[128:131], v[172:175], v[40:43]
	v_mfma_f32_16x16x32_bf16 v[44:47], v[120:123], v[172:175], v[44:47]
	v_mfma_f32_16x16x32_bf16 v[28:31], v[120:123], v[180:183], v[28:31]
	v_mfma_f32_16x16x32_bf16 v[24:27], v[128:131], v[180:183], v[24:27]
	v_mfma_f32_16x16x32_bf16 v[8:11], v[128:131], v[188:191], v[8:11]
	v_mfma_f32_16x16x32_bf16 v[12:15], v[120:123], v[188:191], v[12:15]
	s_setprio 0
	s_setprio 1
	v_mfma_f32_16x16x32_bf16 v[52:55], v[136:139], v[160:163], v[52:55]
	v_mfma_f32_16x16x32_bf16 v[48:51], v[144:147], v[160:163], v[48:51]
	v_mfma_f32_16x16x32_bf16 v[32:35], v[144:147], v[168:171], v[32:35]
	v_mfma_f32_16x16x32_bf16 v[36:39], v[136:139], v[168:171], v[36:39]
	v_mfma_f32_16x16x32_bf16 v[20:23], v[136:139], v[176:179], v[20:23]
	v_mfma_f32_16x16x32_bf16 v[16:19], v[144:147], v[176:179], v[16:19]
	v_mfma_f32_16x16x32_bf16 v[0:3], v[144:147], v[184:187], v[0:3]
	v_mfma_f32_16x16x32_bf16 v[4:7], v[136:139], v[184:187], v[4:7]
	v_mfma_f32_16x16x32_bf16 v[52:55], v[140:143], v[164:167], v[52:55]
	v_mfma_f32_16x16x32_bf16 v[48:51], v[156:159], v[164:167], v[48:51]
	v_mfma_f32_16x16x32_bf16 v[32:35], v[156:159], v[172:175], v[32:35]
	v_mfma_f32_16x16x32_bf16 v[36:39], v[140:143], v[172:175], v[36:39]
	v_mfma_f32_16x16x32_bf16 v[20:23], v[140:143], v[180:183], v[20:23]
	v_mfma_f32_16x16x32_bf16 v[16:19], v[156:159], v[180:183], v[16:19]
	v_mfma_f32_16x16x32_bf16 v[0:3], v[156:159], v[188:191], v[0:3]
	v_mfma_f32_16x16x32_bf16 v[4:7], v[140:143], v[188:191], v[4:7]
	s_setprio 0
	s_barrier
	s_add_i32 s43, s43, 2
	s_add_u32 s34, s34, 0x100
	s_addc_u32 s42, s42, 0
	s_cmp_gt_u32 s43, 41
	s_mov_b64 s[16:17], s[20:21]
	s_cbranch_scc1 .Lkexit_7
.LBB0_1031:
	s_add_u32 s20, s16, 0x100
	s_addc_u32 s21, s17, 0
	s_add_i32 s2, s35, 0x100
	s_cmp_eq_u32 s43, 40
	s_cselect_b32 s25, s13, s21
	s_cselect_b32 s24, s12, s20
	s_cselect_b32 s23, s15, s42
	s_cselect_b32 s22, s14, s34
	s_add_i32 s29, s90, 0x100
	v_add_u32_e32 v128, s2, v249
	v_add_u32_e32 v156, s29, v249
	ds_read_b128 v[112:115], v128
	ds_read_b128 v[120:123], v128 offset:1024
	ds_read_b128 v[124:127], v128 offset:2048
	ds_read_b128 v[128:131], v128 offset:3072
	ds_read_b128 v[136:139], v156
	ds_read_b128 v[140:143], v156 offset:1024
	ds_read_b128 v[144:147], v156 offset:2048
	ds_read_b128 v[156:159], v156 offset:3072
	v_lshl_add_u64 v[194:195], s[16:17], 0, v[206:207]
	s_add_i32 m0, s45, 0xc000
	ds_read_b128 v[160:163], v251
	ds_read_b128 v[164:167], v251 offset:1024
	ds_read_b128 v[168:171], v251 offset:2048
	ds_read_b128 v[172:175], v251 offset:3072
	ds_read_b128 v[176:179], v251 offset:4096
	ds_read_b128 v[180:183], v251 offset:5120
	ds_read_b128 v[184:187], v251 offset:6144
	ds_read_b128 v[188:191], v251 offset:7168
	global_load_lds_dwordx4 v[194:195], off
	v_lshl_add_u64 v[194:195], s[16:17], 0, v[204:205]
	s_add_i32 m0, s45, 0xe000
	s_nop 0
	global_load_lds_dwordx4 v[194:195], off
	s_waitcnt vmcnt(8)
	s_waitcnt lgkmcnt(0)
	s_barrier
; #define PG8_STAGE(bufoff, gbase, voff) do { _Pragma("unroll") for (int _i = 0; _i < 2; ++_i) \
;         __builtin_amdgcn_global_load_lds((const unsigned*)((const char*)(gbase) + (voff)[_i]), (PG8_LAS unsigned*)(lds + (bufoff) + ldsw + _i * 8192), 16, 0, 0); } while (0)
; #define PG8_LDA(dst, b, h) do { _Pragma("unroll") for (int m = 0; m < 4; ++m) _Pragma("unroll") for (int k = 0; k < 2; ++k) dst[m][k] = *(const PG8_LAS bf16x8*)(lds + PG8_SA(b, h) + aoff + m * 2048 + k * 1024); } while (0)
; #define PG8_MMA(ai, bj, At, Bt) do { __builtin_amdgcn_s_setprio(1); _Pragma("unroll") for (int m = 0; m < 4; ++m) _Pragma("unroll") for (int n = 0; n < 2; ++n) _Pragma("unroll") for (int k = 0; k < 2; ++k) \
;         acc[ai][bj][m][n] = __builtin_amdgcn_mfma_f32_16x16x32_bf16(Bt[n][k], At[m][k], acc[ai][bj][m][n], 0, 0, 0); __builtin_amdgcn_s_setprio(0); } while (0)
; #define PG8_WAIT_V(n) asm volatile("s_waitcnt vmcnt(" #n ")" ::: "memory")
; #define PG8_WAIT_L(n) asm volatile("s_waitcnt lgkmcnt(" #n ")" ::: "memory")
; #define PG8_BAR __builtin_amdgcn_s_barrier()
; #define PG8_SCHED __builtin_amdgcn_sched_barrier(0)
; template <class Epi, class Sched, bool ALIGN_EPI = false, bool SP2 = false>
; __device__ __forceinline__ void gemm_phase(PG8_LAS unsigned char* lds, const Gemm g, const Sched& S, const Epi& E, int wave_in) {
;     ...
;             PG8_WAIT_V(8); PG8_WAIT_L(0); PG8_BAR; PG8_MMA(0, 0, At, B0); PG8_MMA(0, 1, At, B1); PG8_BAR; PG8_SCHED;
;             PG8_LDA(At, 0, 1); PG8_STAGE(PG8_SB(0, 0), b2, voffB); PG8_STAGE(PG8_SB(0, 1), b2 + hstep, voffB); PG8_STAGE(PG8_SA(0, 0), a2, voffA);
;             PG8_WAIT_V(8); PG8_WAIT_L(0); PG8_BAR; PG8_MMA(1, 0, At, B0); PG8_MMA(1, 1, At, B1); PG8_BAR; PG8_SCHED;
	s_setprio 1
	s_waitcnt lgkmcnt(0)
	v_mfma_f32_16x16x32_bf16 v[152:155], v[112:115], v[160:163], v[152:155]
	v_mfma_f32_16x16x32_bf16 v[148:151], v[124:127], v[160:163], v[148:151]
	v_mfma_f32_16x16x32_bf16 v[104:107], v[124:127], v[168:171], v[104:107]
	v_mfma_f32_16x16x32_bf16 v[108:111], v[112:115], v[168:171], v[108:111]
	v_mfma_f32_16x16x32_bf16 v[92:95], v[112:115], v[176:179], v[92:95]
	v_mfma_f32_16x16x32_bf16 v[88:91], v[124:127], v[176:179], v[88:91]
	v_mfma_f32_16x16x32_bf16 v[72:75], v[124:127], v[184:187], v[72:75]
	v_mfma_f32_16x16x32_bf16 v[76:79], v[112:115], v[184:187], v[76:79]
	v_mfma_f32_16x16x32_bf16 v[152:155], v[120:123], v[164:167], v[152:155]
	v_mfma_f32_16x16x32_bf16 v[148:151], v[128:131], v[164:167], v[148:151]
	v_mfma_f32_16x16x32_bf16 v[104:107], v[128:131], v[172:175], v[104:107]
	v_mfma_f32_16x16x32_bf16 v[108:111], v[120:123], v[172:175], v[108:111]
	v_mfma_f32_16x16x32_bf16 v[92:95], v[120:123], v[180:183], v[92:95]
	v_mfma_f32_16x16x32_bf16 v[88:91], v[128:131], v[180:183], v[88:91]
	v_mfma_f32_16x16x32_bf16 v[72:75], v[128:131], v[188:191], v[72:75]
	v_mfma_f32_16x16x32_bf16 v[76:79], v[120:123], v[188:191], v[76:79]
	s_setprio 0
	s_setprio 1
	v_mfma_f32_16x16x32_bf16 v[132:135], v[136:139], v[160:163], v[132:135]
	v_mfma_f32_16x16x32_bf16 v[116:119], v[144:147], v[160:163], v[116:119]
	v_mfma_f32_16x16x32_bf16 v[96:99], v[144:147], v[168:171], v[96:99]
	v_mfma_f32_16x16x32_bf16 v[100:103], v[136:139], v[168:171], v[100:103]
	v_mfma_f32_16x16x32_bf16 v[84:87], v[136:139], v[176:179], v[84:87]
	v_mfma_f32_16x16x32_bf16 v[80:83], v[144:147], v[176:179], v[80:83]
	v_mfma_f32_16x16x32_bf16 v[64:67], v[144:147], v[184:187], v[64:67]
	v_mfma_f32_16x16x32_bf16 v[68:71], v[136:139], v[184:187], v[68:71]
	v_mfma_f32_16x16x32_bf16 v[132:135], v[140:143], v[164:167], v[132:135]
	v_mfma_f32_16x16x32_bf16 v[116:119], v[156:159], v[164:167], v[116:119]
	v_mfma_f32_16x16x32_bf16 v[96:99], v[156:159], v[172:175], v[96:99]
	v_mfma_f32_16x16x32_bf16 v[100:103], v[140:143], v[172:175], v[100:103]
	v_mfma_f32_16x16x32_bf16 v[84:87], v[140:143], v[180:183], v[84:87]
	v_mfma_f32_16x16x32_bf16 v[80:83], v[156:159], v[180:183], v[80:83]
	v_mfma_f32_16x16x32_bf16 v[64:67], v[156:159], v[188:191], v[64:67]
	v_mfma_f32_16x16x32_bf16 v[68:71], v[140:143], v[188:191], v[68:71]
	s_setprio 0
	s_barrier
	s_add_i32 s2, s2, s44
	v_lshl_add_u64 v[194:195], s[22:23], 0, v[192:193]
	s_mov_b32 m0, s2
	ds_read_b128 v[160:163], v251 offset:16384
	ds_read_b128 v[164:167], v251 offset:17408
	ds_read_b128 v[168:171], v251 offset:18432
	ds_read_b128 v[172:175], v251 offset:19456
	ds_read_b128 v[176:179], v251 offset:20480
	ds_read_b128 v[180:183], v251 offset:21504
	ds_read_b128 v[184:187], v251 offset:22528
	ds_read_b128 v[188:191], v251 offset:23552
	global_load_lds_dwordx4 v[194:195], off
	s_add_i32 m0, s2, 0x2000
	s_add_u32 s16, s22, 0xb0000
	v_lshl_add_u64 v[196:197], s[22:23], 0, v[198:199]
	s_addc_u32 s17, s23, 0
	s_add_i32 s2, s29, s44
	global_load_lds_dwordx4 v[196:197], off
	v_lshl_add_u64 v[208:209], s[16:17], 0, v[192:193]
	s_mov_b32 m0, s2
	v_lshl_add_u64 v[210:211], s[24:25], 0, v[200:201]
	global_load_lds_dwordx4 v[208:209], off
	v_lshl_add_u64 v[208:209], s[16:17], 0, v[198:199]
	s_add_i32 m0, s2, 0x2000
	s_nop 0
	global_load_lds_dwordx4 v[208:209], off
	v_lshl_add_u64 v[208:209], s[24:25], 0, v[202:203]
	s_mov_b32 m0, s45
	s_nop 0
	global_load_lds_dwordx4 v[208:209], off
	s_mov_b32 m0, s46
	s_nop 0
	global_load_lds_dwordx4 v[210:211], off
	s_waitcnt vmcnt(8)
	s_waitcnt lgkmcnt(0)
	s_barrier
	s_setprio 1
	s_waitcnt lgkmcnt(0)
	v_mfma_f32_16x16x32_bf16 v[60:63], v[112:115], v[160:163], v[60:63]
	v_mfma_f32_16x16x32_bf16 v[56:59], v[124:127], v[160:163], v[56:59]
	v_mfma_f32_16x16x32_bf16 v[40:43], v[124:127], v[168:171], v[40:43]
	v_mfma_f32_16x16x32_bf16 v[44:47], v[112:115], v[168:171], v[44:47]
	v_mfma_f32_16x16x32_bf16 v[28:31], v[112:115], v[176:179], v[28:31]
	v_mfma_f32_16x16x32_bf16 v[24:27], v[124:127], v[176:179], v[24:27]
	v_mfma_f32_16x16x32_bf16 v[8:11], v[124:127], v[184:187], v[8:11]
	v_mfma_f32_16x16x32_bf16 v[12:15], v[112:115], v[184:187], v[12:15]
	v_mfma_f32_16x16x32_bf16 v[60:63], v[120:123], v[164:167], v[60:63]
	v_mfma_f32_16x16x32_bf16 v[56:59], v[128:131], v[164:167], v[56:59]
	v_mfma_f32_16x16x32_bf16 v[40:43], v[128:131], v[172:175], v[40:43]
	v_mfma_f32_16x16x32_bf16 v[44:47], v[120:123], v[172:175], v[44:47]
	v_mfma_f32_16x16x32_bf16 v[28:31], v[120:123], v[180:183], v[28:31]
	v_mfma_f32_16x16x32_bf16 v[24:27], v[128:131], v[180:183], v[24:27]
	v_mfma_f32_16x16x32_bf16 v[8:11], v[128:131], v[188:191], v[8:11]
	v_mfma_f32_16x16x32_bf16 v[12:15], v[120:123], v[188:191], v[12:15]
	s_setprio 0
	s_setprio 1
	v_mfma_f32_16x16x32_bf16 v[52:55], v[136:139], v[160:163], v[52:55]
	v_mfma_f32_16x16x32_bf16 v[48:51], v[144:147], v[160:163], v[48:51]
	v_mfma_f32_16x16x32_bf16 v[32:35], v[144:147], v[168:171], v[32:35]
	v_mfma_f32_16x16x32_bf16 v[36:39], v[136:139], v[168:171], v[36:39]
	v_mfma_f32_16x16x32_bf16 v[20:23], v[136:139], v[176:179], v[20:23]
	v_mfma_f32_16x16x32_bf16 v[16:19], v[144:147], v[176:179], v[16:19]
	v_mfma_f32_16x16x32_bf16 v[0:3], v[144:147], v[184:187], v[0:3]
	v_mfma_f32_16x16x32_bf16 v[4:7], v[136:139], v[184:187], v[4:7]
	v_mfma_f32_16x16x32_bf16 v[52:55], v[140:143], v[164:167], v[52:55]
	v_mfma_f32_16x16x32_bf16 v[48:51], v[156:159], v[164:167], v[48:51]
	v_mfma_f32_16x16x32_bf16 v[32:35], v[156:159], v[172:175], v[32:35]
	v_mfma_f32_16x16x32_bf16 v[36:39], v[140:143], v[172:175], v[36:39]
	v_mfma_f32_16x16x32_bf16 v[20:23], v[140:143], v[180:183], v[20:23]
	v_mfma_f32_16x16x32_bf16 v[16:19], v[156:159], v[180:183], v[16:19]
	v_mfma_f32_16x16x32_bf16 v[0:3], v[156:159], v[188:191], v[0:3]
	v_mfma_f32_16x16x32_bf16 v[4:7], v[140:143], v[188:191], v[4:7]
	s_setprio 0
	s_barrier
; #define PG8_STAGE(bufoff, gbase, voff) do { _Pragma("unroll") for (int _i = 0; _i < 2; ++_i) \
;         __builtin_amdgcn_global_load_lds((const unsigned*)((const char*)(gbase) + (voff)[_i]), (PG8_LAS unsigned*)(lds + (bufoff) + ldsw + _i * 8192), 16, 0, 0); } while (0)
; #define PG8_LDA(dst, b, h) do { _Pragma("unroll") for (int m = 0; m < 4; ++m) _Pragma("unroll") for (int k = 0; k < 2; ++k) dst[m][k] = *(const PG8_LAS bf16x8*)(lds + PG8_SA(b, h) + aoff + m * 2048 + k * 1024); } while (0)
; #define PG8_LDB(dst, b, h) do { _Pragma("unroll") for (int n = 0; n < 2; ++n) _Pragma("unroll") for (int k = 0; k < 2; ++k) dst[n][k] = *(const PG8_LAS bf16x8*)(lds + PG8_SB(b, h) + boff + n * 2048 + k * 1024); } while (0)
; #define PG8_MMA(ai, bj, At, Bt) do { __builtin_amdgcn_s_setprio(1); _Pragma("unroll") for (int m = 0; m < 4; ++m) _Pragma("unroll") for (int n = 0; n < 2; ++n) _Pragma("unroll") for (int k = 0; k < 2; ++k) \
;         acc[ai][bj][m][n] = __builtin_amdgcn_mfma_f32_16x16x32_bf16(Bt[n][k], At[m][k], acc[ai][bj][m][n], 0, 0, 0); __builtin_amdgcn_s_setprio(0); } while (0)
; #define PG8_WAIT_V(n) asm volatile("s_waitcnt vmcnt(" #n ")" ::: "memory")
; #define PG8_WAIT_L(n) asm volatile("s_waitcnt lgkmcnt(" #n ")" ::: "memory")
; #define PG8_BAR __builtin_amdgcn_s_barrier()
; #define PG8_SCHED __builtin_amdgcn_sched_barrier(0)
; template <class Epi, class Sched, bool ALIGN_EPI = false, bool SP2 = false>
; __device__ __forceinline__ void gemm_phase(PG8_LAS unsigned char* lds, const Gemm g, const Sched& S, const Epi& E, int wave_in) {
;     ...
;             PG8_LDB(B0, 1, 0); PG8_LDB(B1, 1, 1); PG8_SCHED; PG8_LDA(At, 1, 0); PG8_STAGE(PG8_SA(0, 1), a2 + hstep, voffA);
;             PG8_WAIT_V(8); PG8_WAIT_L(0); PG8_BAR; PG8_MMA(0, 0, At, B0); PG8_MMA(0, 1, At, B1); PG8_BAR; PG8_SCHED;
	s_add_i32 s2, s65, 0x100
	s_add_i32 s29, s52, 0x100
	v_add_u32_e32 v128, s2, v249
	v_add_u32_e32 v156, s29, v249
	ds_read_b128 v[112:115], v128
	ds_read_b128 v[120:123], v128 offset:1024
	ds_read_b128 v[124:127], v128 offset:2048
	ds_read_b128 v[128:131], v128 offset:3072
	ds_read_b128 v[136:139], v156
	ds_read_b128 v[140:143], v156 offset:1024
	ds_read_b128 v[144:147], v156 offset:2048
	ds_read_b128 v[156:159], v156 offset:3072
	s_add_u32 s16, s24, 0xb0000
	s_addc_u32 s17, s25, 0
	s_mov_b32 m0, s47
	v_lshl_add_u64 v[212:213], s[16:17], 0, v[202:203]
	ds_read_b128 v[160:163], v251 offset:32768
	ds_read_b128 v[164:167], v251 offset:33792
	ds_read_b128 v[168:171], v251 offset:34816
	ds_read_b128 v[172:175], v251 offset:35840
	ds_read_b128 v[176:179], v251 offset:36864
	ds_read_b128 v[180:183], v251 offset:37888
	ds_read_b128 v[184:187], v251 offset:38912
	ds_read_b128 v[188:191], v251 offset:39936
	global_load_lds_dwordx4 v[212:213], off
	v_lshl_add_u64 v[212:213], s[16:17], 0, v[200:201]
	s_mov_b32 m0, s60
	s_nop 0
	global_load_lds_dwordx4 v[212:213], off
	s_waitcnt vmcnt(8)
	s_waitcnt lgkmcnt(0)
	s_barrier
	s_setprio 1
	s_waitcnt lgkmcnt(0)
	v_mfma_f32_16x16x32_bf16 v[152:155], v[112:115], v[160:163], v[152:155]
	v_mfma_f32_16x16x32_bf16 v[148:151], v[124:127], v[160:163], v[148:151]
	v_mfma_f32_16x16x32_bf16 v[104:107], v[124:127], v[168:171], v[104:107]
	v_mfma_f32_16x16x32_bf16 v[108:111], v[112:115], v[168:171], v[108:111]
	v_mfma_f32_16x16x32_bf16 v[92:95], v[112:115], v[176:179], v[92:95]
	v_mfma_f32_16x16x32_bf16 v[88:91], v[124:127], v[176:179], v[88:91]
	v_mfma_f32_16x16x32_bf16 v[72:75], v[124:127], v[184:187], v[72:75]
	v_mfma_f32_16x16x32_bf16 v[76:79], v[112:115], v[184:187], v[76:79]
	v_mfma_f32_16x16x32_bf16 v[152:155], v[120:123], v[164:167], v[152:155]
	v_mfma_f32_16x16x32_bf16 v[148:151], v[128:131], v[164:167], v[148:151]
	v_mfma_f32_16x16x32_bf16 v[104:107], v[128:131], v[172:175], v[104:107]
	v_mfma_f32_16x16x32_bf16 v[108:111], v[120:123], v[172:175], v[108:111]
	v_mfma_f32_16x16x32_bf16 v[92:95], v[120:123], v[180:183], v[92:95]
	v_mfma_f32_16x16x32_bf16 v[88:91], v[128:131], v[180:183], v[88:91]
	v_mfma_f32_16x16x32_bf16 v[72:75], v[128:131], v[188:191], v[72:75]
	v_mfma_f32_16x16x32_bf16 v[76:79], v[120:123], v[188:191], v[76:79]
	s_setprio 0
	s_setprio 1
	v_mfma_f32_16x16x32_bf16 v[132:135], v[136:139], v[160:163], v[132:135]
	v_mfma_f32_16x16x32_bf16 v[116:119], v[144:147], v[160:163], v[116:119]
	v_mfma_f32_16x16x32_bf16 v[96:99], v[144:147], v[168:171], v[96:99]
	v_mfma_f32_16x16x32_bf16 v[100:103], v[136:139], v[168:171], v[100:103]
	v_mfma_f32_16x16x32_bf16 v[84:87], v[136:139], v[176:179], v[84:87]
	v_mfma_f32_16x16x32_bf16 v[80:83], v[144:147], v[176:179], v[80:83]
	v_mfma_f32_16x16x32_bf16 v[64:67], v[144:147], v[184:187], v[64:67]
	v_mfma_f32_16x16x32_bf16 v[68:71], v[136:139], v[184:187], v[68:71]
	v_mfma_f32_16x16x32_bf16 v[132:135], v[140:143], v[164:167], v[132:135]
	v_mfma_f32_16x16x32_bf16 v[116:119], v[156:159], v[164:167], v[116:119]
	v_mfma_f32_16x16x32_bf16 v[96:99], v[156:159], v[172:175], v[96:99]
	v_mfma_f32_16x16x32_bf16 v[100:103], v[140:143], v[172:175], v[100:103]
	v_mfma_f32_16x16x32_bf16 v[84:87], v[140:143], v[180:183], v[84:87]
	v_mfma_f32_16x16x32_bf16 v[80:83], v[156:159], v[180:183], v[80:83]
	v_mfma_f32_16x16x32_bf16 v[64:67], v[156:159], v[188:191], v[64:67]
	v_mfma_f32_16x16x32_bf16 v[68:71], v[140:143], v[188:191], v[68:71]
	s_setprio 0
	s_barrier
; #define PG8_STAGE(bufoff, gbase, voff) do { _Pragma("unroll") for (int _i = 0; _i < 2; ++_i) \
;         __builtin_amdgcn_global_load_lds((const unsigned*)((const char*)(gbase) + (voff)[_i]), (PG8_LAS unsigned*)(lds + (bufoff) + ldsw + _i * 8192), 16, 0, 0); } while (0)
; #define PG8_LDA(dst, b, h) do { _Pragma("unroll") for (int m = 0; m < 4; ++m) _Pragma("unroll") for (int k = 0; k < 2; ++k) dst[m][k] = *(const PG8_LAS bf16x8*)(lds + PG8_SA(b, h) + aoff + m * 2048 + k * 1024); } while (0)
; #define PG8_MMA(ai, bj, At, Bt) do { __builtin_amdgcn_s_setprio(1); _Pragma("unroll") for (int m = 0; m < 4; ++m) _Pragma("unroll") for (int n = 0; n < 2; ++n) _Pragma("unroll") for (int k = 0; k < 2; ++k) \
;         acc[ai][bj][m][n] = __builtin_amdgcn_mfma_f32_16x16x32_bf16(Bt[n][k], At[m][k], acc[ai][bj][m][n], 0, 0, 0); __builtin_amdgcn_s_setprio(0); } while (0)
; #define PG8_WAIT_V(n) asm volatile("s_waitcnt vmcnt(" #n ")" ::: "memory")
; #define PG8_WAIT_L(n) asm volatile("s_waitcnt lgkmcnt(" #n ")" ::: "memory")
; #define PG8_BAR __builtin_amdgcn_s_barrier()
; #define PG8_SCHED __builtin_amdgcn_sched_barrier(0)
; template <class Epi, class Sched, bool ALIGN_EPI = false, bool SP2 = false>
; __device__ __forceinline__ void gemm_phase(PG8_LAS unsigned char* lds, const Gemm g, const Sched& S, const Epi& E, int wave_in) {
;     ...
;             PG8_LDA(At, 1, 1); PG8_STAGE(PG8_SB(1, 0), b3, voffB); PG8_STAGE(PG8_SB(1, 1), b3 + hstep, voffB); PG8_STAGE(PG8_SA(1, 0), a3, voffA);
;             PG8_WAIT_V(8); PG8_WAIT_L(0); PG8_BAR; PG8_MMA(1, 0, At, B0); PG8_MMA(1, 1, At, B1); PG8_BAR; PG8_SCHED;
	s_add_i32 s2, s2, s44
	v_lshl_add_u64 v[194:195], v[194:195], 0, s[88:89]
	s_mov_b32 m0, s2
	ds_read_b128 v[160:163], v251 offset:49152
	ds_read_b128 v[164:167], v251 offset:50176
	ds_read_b128 v[168:171], v251 offset:51200
	ds_read_b128 v[172:175], v251 offset:52224
	ds_read_b128 v[176:179], v251 offset:53248
	ds_read_b128 v[180:183], v251 offset:54272
	ds_read_b128 v[184:187], v251 offset:55296
	ds_read_b128 v[188:191], v251 offset:56320
	global_load_lds_dwordx4 v[194:195], off
	s_add_i32 m0, s2, 0x2000
	s_add_u32 s16, s22, 0xb0080
	v_lshl_add_u64 v[194:195], v[196:197], 0, s[88:89]
	s_addc_u32 s17, s23, 0
	s_add_i32 s2, s29, s44
	global_load_lds_dwordx4 v[194:195], off
	v_lshl_add_u64 v[194:195], s[16:17], 0, v[192:193]
	s_mov_b32 m0, s2
	s_nop 0
	global_load_lds_dwordx4 v[194:195], off
	v_lshl_add_u64 v[194:195], s[16:17], 0, v[198:199]
	s_add_i32 m0, s2, 0x2000
	s_nop 0
	global_load_lds_dwordx4 v[194:195], off
	v_lshl_add_u64 v[194:195], v[208:209], 0, s[88:89]
	s_mov_b32 m0, s62
	s_nop 0
	global_load_lds_dwordx4 v[194:195], off
	v_lshl_add_u64 v[194:195], v[210:211], 0, s[88:89]
	s_mov_b32 m0, s63
	s_nop 0
	global_load_lds_dwordx4 v[194:195], off
	s_waitcnt vmcnt(8)
	s_waitcnt lgkmcnt(0)
	s_barrier
	s_setprio 1
	s_waitcnt lgkmcnt(0)
	v_mfma_f32_16x16x32_bf16 v[60:63], v[112:115], v[160:163], v[60:63]
	v_mfma_f32_16x16x32_bf16 v[56:59], v[124:127], v[160:163], v[56:59]
	v_mfma_f32_16x16x32_bf16 v[40:43], v[124:127], v[168:171], v[40:43]
	v_mfma_f32_16x16x32_bf16 v[44:47], v[112:115], v[168:171], v[44:47]
	v_mfma_f32_16x16x32_bf16 v[28:31], v[112:115], v[176:179], v[28:31]
	v_mfma_f32_16x16x32_bf16 v[24:27], v[124:127], v[176:179], v[24:27]
	v_mfma_f32_16x16x32_bf16 v[8:11], v[124:127], v[184:187], v[8:11]
	v_mfma_f32_16x16x32_bf16 v[12:15], v[112:115], v[184:187], v[12:15]
	v_mfma_f32_16x16x32_bf16 v[60:63], v[120:123], v[164:167], v[60:63]
	v_mfma_f32_16x16x32_bf16 v[56:59], v[128:131], v[164:167], v[56:59]
	v_mfma_f32_16x16x32_bf16 v[40:43], v[128:131], v[172:175], v[40:43]
	v_mfma_f32_16x16x32_bf16 v[44:47], v[120:123], v[172:175], v[44:47]
	v_mfma_f32_16x16x32_bf16 v[28:31], v[120:123], v[180:183], v[28:31]
	v_mfma_f32_16x16x32_bf16 v[24:27], v[128:131], v[180:183], v[24:27]
	v_mfma_f32_16x16x32_bf16 v[8:11], v[128:131], v[188:191], v[8:11]
	v_mfma_f32_16x16x32_bf16 v[12:15], v[120:123], v[188:191], v[12:15]
	s_setprio 0
	s_setprio 1
	v_mfma_f32_16x16x32_bf16 v[52:55], v[136:139], v[160:163], v[52:55]
	v_mfma_f32_16x16x32_bf16 v[48:51], v[144:147], v[160:163], v[48:51]
	v_mfma_f32_16x16x32_bf16 v[32:35], v[144:147], v[168:171], v[32:35]
	v_mfma_f32_16x16x32_bf16 v[36:39], v[136:139], v[168:171], v[36:39]
	v_mfma_f32_16x16x32_bf16 v[20:23], v[136:139], v[176:179], v[20:23]
	v_mfma_f32_16x16x32_bf16 v[16:19], v[144:147], v[176:179], v[16:19]
	v_mfma_f32_16x16x32_bf16 v[0:3], v[144:147], v[184:187], v[0:3]
	v_mfma_f32_16x16x32_bf16 v[4:7], v[136:139], v[184:187], v[4:7]
	v_mfma_f32_16x16x32_bf16 v[52:55], v[140:143], v[164:167], v[52:55]
	v_mfma_f32_16x16x32_bf16 v[48:51], v[156:159], v[164:167], v[48:51]
	v_mfma_f32_16x16x32_bf16 v[32:35], v[156:159], v[172:175], v[32:35]
	v_mfma_f32_16x16x32_bf16 v[36:39], v[140:143], v[172:175], v[36:39]
	v_mfma_f32_16x16x32_bf16 v[20:23], v[140:143], v[180:183], v[20:23]
	v_mfma_f32_16x16x32_bf16 v[16:19], v[156:159], v[180:183], v[16:19]
	v_mfma_f32_16x16x32_bf16 v[0:3], v[156:159], v[188:191], v[0:3]
	v_mfma_f32_16x16x32_bf16 v[4:7], v[140:143], v[188:191], v[4:7]
	s_setprio 0
	s_barrier
	s_add_i32 s43, s43, 2
	s_add_u32 s34, s34, 0x100
	s_addc_u32 s42, s42, 0
	s_cmp_gt_u32 s43, 41
	s_mov_b64 s[16:17], s[20:21]
	s_cbranch_scc0 .LBB0_1031
